# flat_ loads, stores and 64-bit atomics to global memory rewritten as global_ (vmcnt only), on top of the fragment layouts for X16 and HID
# baseline (speedup 1.0000x reference)
; __device__ __forceinline__ int opaque_tid(int wave_s) { int l; asm volatile("v_mbcnt_lo_u32_b32 %0, -1, 0\n\tv_mbcnt_hi_u32_b32 %0, -1, %0" : "=v"(l)); return (wave_s << 6) | l; }
; __device__ __forceinline__ unsigned cvtpk(float lo, float hi) { unsigned r; asm volatile("v_cvt_pk_bf16_f32 %0, %1, %2" : "=v"(r) : "v"(lo), "v"(hi)); return r; }
; __device__ __forceinline__ void shw_tasks(const float* modp, const bf16_t* win, const bf16_t* wgu, float* shw, int vcu, int ngw, const int wave_s) {
;     const int tid_ = opaque_tid(wave_s), lane = tid_ & 63, gw = vcu * NWAVES + (tid_ >> 6), r32 = lane & 31, hi = lane >> 5;
;     for (int task = gw; task < DEPTH * 240; task += ngw) {
;         const int l = task / 240, n0 = 32 * (task % 240);
;         const bf16_t* wrow = (n0 < PJ) ? (win + l * WIN_L + (size_t)(n0 + r32) * DM) : (wgu + l * WGU_L + (size_t)(n0 - PJ + r32) * DM);
;         const float* shp = modp + ((size_t)l * 16 + (r32 & 15)) * NMOD + (n0 < PJ ? 0 : 3 * DM) + 8 * hi;
;         f32x16 acc;
; #pragma unroll
;         for (int r = 0; r < 16; ++r) acc[r] = 0.f;
; #pragma unroll 16
;         for (int k = 0; k < 64; ++k) {
;             const f32x4 a0 = *(const f32x4*)(shp + 16 * k), a1 = *(const f32x4*)(shp + 16 * k + 4);
;             u32x4 aw; aw.x = cvtpk(a0.x, a0.y); aw.y = cvtpk(a0.z, a0.w); aw.z = cvtpk(a1.x, a1.y); aw.w = cvtpk(a1.z, a1.w);
;             const bf16x8 bfr = *(const bf16x8*)(wrow + 16 * k + 8 * hi);
;             acc = __builtin_amdgcn_mfma_f32_32x32x16_bf16(__builtin_bit_cast(bf16x8, aw), bfr, acc, 0, 0, 0);
;         }
.LBB0_344:
	v_lshl_add_u64 v[48:49], v[46:47], 0, s[16:17]
	v_add_co_u32_e32 v48, vcc, s20, v48
	s_add_u32 s16, s16, 0x400
	s_nop 0
	v_addc_co_u32_e32 v49, vcc, 0, v49, vcc
	global_load_dwordx4 v[50:53], v[48:49], off
	global_load_dwordx4 v[54:57], v[48:49], off offset:16
	s_addc_u32 s17, s17, 0
	s_cmpk_eq_i32 s16, 0x1000
	s_waitcnt vmcnt(0) lgkmcnt(0)
	v_cvt_pk_bf16_f32 v50, v50, v51
	v_cvt_pk_bf16_f32 v51, v52, v53
	v_cvt_pk_bf16_f32 v52, v54, v55
	v_cvt_pk_bf16_f32 v53, v56, v57
	global_load_dwordx4 v[54:57], v[48:49], off offset:64
	global_load_dwordx4 v[58:61], v[48:49], off offset:80
	global_load_dwordx4 v[62:65], v[44:45], off
	s_waitcnt vmcnt(0) lgkmcnt(0)
	v_cvt_pk_bf16_f32 v54, v54, v55
	v_cvt_pk_bf16_f32 v55, v56, v57
	v_cvt_pk_bf16_f32 v56, v58, v59
	v_cvt_pk_bf16_f32 v57, v60, v61
	global_load_dwordx4 v[58:61], v[48:49], off offset:128
	global_load_dwordx4 v[66:69], v[48:49], off offset:144
	global_load_dwordx4 v[70:73], v[44:45], off offset:32
	v_mfma_f32_32x32x16_bf16 v[0:15], v[50:53], v[62:65], v[0:15]
	s_waitcnt vmcnt(0) lgkmcnt(0)
	v_cvt_pk_bf16_f32 v50, v58, v59
	v_cvt_pk_bf16_f32 v51, v60, v61
	v_cvt_pk_bf16_f32 v52, v66, v67
	v_cvt_pk_bf16_f32 v53, v68, v69
	global_load_dwordx4 v[58:61], v[48:49], off offset:192
	global_load_dwordx4 v[62:65], v[48:49], off offset:208
	v_mfma_f32_32x32x16_bf16 v[0:15], v[54:57], v[70:73], v[0:15]
	global_load_dwordx4 v[54:57], v[44:45], off offset:64
	s_waitcnt vmcnt(0) lgkmcnt(0)
	v_cvt_pk_bf16_f32 v58, v58, v59
	v_cvt_pk_bf16_f32 v59, v60, v61
	v_cvt_pk_bf16_f32 v60, v62, v63
	v_cvt_pk_bf16_f32 v61, v64, v65
	global_load_dwordx4 v[62:65], v[44:45], off offset:96
	global_load_dwordx4 v[66:69], v[48:49], off offset:256
	v_mfma_f32_32x32x16_bf16 v[0:15], v[50:53], v[54:57], v[0:15]
	global_load_dwordx4 v[50:53], v[48:49], off offset:272
	s_waitcnt vmcnt(0) lgkmcnt(0)
	v_cvt_pk_bf16_f32 v54, v66, v67
	v_mfma_f32_32x32x16_bf16 v[0:15], v[58:61], v[62:65], v[0:15]
	v_cvt_pk_bf16_f32 v55, v68, v69
	v_cvt_pk_bf16_f32 v56, v50, v51
	v_cvt_pk_bf16_f32 v57, v52, v53
	global_load_dwordx4 v[50:53], v[48:49], off offset:320
	global_load_dwordx4 v[58:61], v[48:49], off offset:336
	global_load_dwordx4 v[62:65], v[44:45], off offset:128
	s_waitcnt vmcnt(0) lgkmcnt(0)
	v_cvt_pk_bf16_f32 v50, v50, v51
	v_mfma_f32_32x32x16_bf16 v[0:15], v[54:57], v[62:65], v[0:15]
	v_cvt_pk_bf16_f32 v51, v52, v53
	v_cvt_pk_bf16_f32 v52, v58, v59
	v_cvt_pk_bf16_f32 v53, v60, v61
	global_load_dwordx4 v[54:57], v[48:49], off offset:384
	global_load_dwordx4 v[58:61], v[48:49], off offset:400
	global_load_dwordx4 v[62:65], v[44:45], off offset:160
	s_waitcnt vmcnt(0) lgkmcnt(0)
	v_mfma_f32_32x32x16_bf16 v[0:15], v[50:53], v[62:65], v[0:15]
	v_cvt_pk_bf16_f32 v50, v54, v55
	v_cvt_pk_bf16_f32 v51, v56, v57
	v_cvt_pk_bf16_f32 v52, v58, v59
	v_cvt_pk_bf16_f32 v53, v60, v61
	global_load_dwordx4 v[54:57], v[48:49], off offset:448
	global_load_dwordx4 v[58:61], v[48:49], off offset:464
	global_load_dwordx4 v[62:65], v[44:45], off offset:192
	s_waitcnt vmcnt(0) lgkmcnt(0)
	v_mfma_f32_32x32x16_bf16 v[0:15], v[50:53], v[62:65], v[0:15]
	v_cvt_pk_bf16_f32 v50, v54, v55
	v_cvt_pk_bf16_f32 v51, v56, v57
	v_cvt_pk_bf16_f32 v52, v58, v59
	v_cvt_pk_bf16_f32 v53, v60, v61
	global_load_dwordx4 v[54:57], v[48:49], off offset:512
	global_load_dwordx4 v[58:61], v[48:49], off offset:528
	global_load_dwordx4 v[62:65], v[44:45], off offset:224
	s_waitcnt vmcnt(0) lgkmcnt(0)
	v_mfma_f32_32x32x16_bf16 v[0:15], v[50:53], v[62:65], v[0:15]
	v_cvt_pk_bf16_f32 v50, v54, v55
	v_cvt_pk_bf16_f32 v51, v56, v57
	v_cvt_pk_bf16_f32 v52, v58, v59
	v_cvt_pk_bf16_f32 v53, v60, v61
	global_load_dwordx4 v[54:57], v[48:49], off offset:576
	global_load_dwordx4 v[58:61], v[48:49], off offset:592
	global_load_dwordx4 v[62:65], v[44:45], off offset:256
	s_waitcnt vmcnt(0) lgkmcnt(0)
	v_mfma_f32_32x32x16_bf16 v[0:15], v[50:53], v[62:65], v[0:15]
	v_cvt_pk_bf16_f32 v50, v54, v55
	v_cvt_pk_bf16_f32 v51, v56, v57
	v_cvt_pk_bf16_f32 v52, v58, v59
	v_cvt_pk_bf16_f32 v53, v60, v61
	global_load_dwordx4 v[54:57], v[48:49], off offset:640
	global_load_dwordx4 v[58:61], v[48:49], off offset:656
	global_load_dwordx4 v[62:65], v[44:45], off offset:288
	s_waitcnt vmcnt(0) lgkmcnt(0)
	v_mfma_f32_32x32x16_bf16 v[0:15], v[50:53], v[62:65], v[0:15]
	v_cvt_pk_bf16_f32 v50, v54, v55
	v_cvt_pk_bf16_f32 v51, v56, v57
	v_cvt_pk_bf16_f32 v52, v58, v59
	v_cvt_pk_bf16_f32 v53, v60, v61
	global_load_dwordx4 v[54:57], v[48:49], off offset:704
	global_load_dwordx4 v[58:61], v[48:49], off offset:720
	global_load_dwordx4 v[62:65], v[44:45], off offset:320
	s_waitcnt vmcnt(0) lgkmcnt(0)
	v_mfma_f32_32x32x16_bf16 v[0:15], v[50:53], v[62:65], v[0:15]
	v_cvt_pk_bf16_f32 v50, v54, v55
	v_cvt_pk_bf16_f32 v51, v56, v57
	v_cvt_pk_bf16_f32 v52, v58, v59
	v_cvt_pk_bf16_f32 v53, v60, v61
	global_load_dwordx4 v[54:57], v[48:49], off offset:768
	global_load_dwordx4 v[58:61], v[48:49], off offset:784
	global_load_dwordx4 v[62:65], v[44:45], off offset:352
	s_waitcnt vmcnt(0) lgkmcnt(0)
	v_mfma_f32_32x32x16_bf16 v[0:15], v[50:53], v[62:65], v[0:15]
	v_cvt_pk_bf16_f32 v50, v54, v55
	v_cvt_pk_bf16_f32 v51, v56, v57
	v_cvt_pk_bf16_f32 v52, v58, v59
	v_cvt_pk_bf16_f32 v53, v60, v61
	global_load_dwordx4 v[54:57], v[48:49], off offset:832
	global_load_dwordx4 v[58:61], v[48:49], off offset:848
	global_load_dwordx4 v[62:65], v[44:45], off offset:384
	s_waitcnt vmcnt(0) lgkmcnt(0)
	v_mfma_f32_32x32x16_bf16 v[0:15], v[50:53], v[62:65], v[0:15]
	v_cvt_pk_bf16_f32 v50, v54, v55
	v_cvt_pk_bf16_f32 v51, v56, v57
	v_cvt_pk_bf16_f32 v52, v58, v59
	v_cvt_pk_bf16_f32 v53, v60, v61
	global_load_dwordx4 v[54:57], v[48:49], off offset:896
	global_load_dwordx4 v[58:61], v[48:49], off offset:912
	global_load_dwordx4 v[62:65], v[44:45], off offset:416
	s_waitcnt vmcnt(0) lgkmcnt(0)
	v_mfma_f32_32x32x16_bf16 v[0:15], v[50:53], v[62:65], v[0:15]
	v_cvt_pk_bf16_f32 v50, v54, v55
	v_cvt_pk_bf16_f32 v51, v56, v57
	v_cvt_pk_bf16_f32 v52, v58, v59
	v_cvt_pk_bf16_f32 v53, v60, v61
	global_load_dwordx4 v[54:57], v[48:49], off offset:960
	global_load_dwordx4 v[58:61], v[48:49], off offset:976
	global_load_dwordx4 v[62:65], v[44:45], off offset:448
	s_waitcnt vmcnt(0) lgkmcnt(0)
	v_cvt_pk_bf16_f32 v48, v54, v55
	v_mfma_f32_32x32x16_bf16 v[0:15], v[50:53], v[62:65], v[0:15]
	v_cvt_pk_bf16_f32 v49, v56, v57
	v_cvt_pk_bf16_f32 v50, v58, v59
	v_cvt_pk_bf16_f32 v51, v60, v61
	global_load_dwordx4 v[52:55], v[44:45], off offset:480
	v_lshl_add_u64 v[44:45], v[44:45], 0, s[14:15]
	s_waitcnt vmcnt(0) lgkmcnt(0)
	v_mfma_f32_32x32x16_bf16 v[0:15], v[48:51], v[52:55], v[0:15]
	s_cbranch_scc0 .LBB0_344
; __device__ __forceinline__ int crow(int r, int hi) { return (r & 3) + 8 * (r >> 2) + 4 * hi; }
; __device__ __forceinline__ void shw_tasks(const float* modp, const bf16_t* win, const bf16_t* wgu, float* shw, int vcu, int ngw, const int wave_s) {
;     ...
; #pragma unroll
;         for (int r = 0; r < 8; ++r) shw[((size_t)l * 16 + crow(r, hi)) * 7680 + n0 + r32] = acc[r];
	s_nop 10
	v_lshlrev_b32_e32 v12, 4, v42
	v_ashrrev_i32_e32 v41, 31, v40
	v_lshl_add_u64 v[8:9], v[40:41], 2, v[20:21]
	v_or_b32_e32 v10, v12, v18
	v_mad_i64_i32 v[10:11], s[2:3], v10, s21, v[8:9]
	flat_store_dword v[10:11], v0
	v_or_b32_e32 v0, v12, v22
	v_mad_i64_i32 v[10:11], s[2:3], v0, s21, v[8:9]
	v_or_b32_e32 v0, v12, v24
	flat_store_dword v[10:11], v1
	v_mad_i64_i32 v[0:1], s[2:3], v0, s21, v[8:9]
	flat_store_dword v[0:1], v2
	v_or_b32_e32 v0, v12, v26
	v_mad_i64_i32 v[0:1], s[2:3], v0, s21, v[8:9]
	flat_store_dword v[0:1], v3
	v_or_b32_e32 v0, v12, v28
	v_mad_i64_i32 v[0:1], s[2:3], v0, s21, v[8:9]
	flat_store_dword v[0:1], v4
	v_or_b32_e32 v0, v12, v30
	v_mad_i64_i32 v[0:1], s[2:3], v0, s21, v[8:9]
	flat_store_dword v[0:1], v5
	v_or_b32_e32 v0, v12, v32
	v_mad_i64_i32 v[0:1], s[2:3], v0, s21, v[8:9]
	v_add_u32_e32 v19, s42, v19
	flat_store_dword v[0:1], v6
	v_or_b32_e32 v0, v12, v34
	v_cmp_lt_i32_e32 vcc, s22, v19
	v_mad_i64_i32 v[0:1], s[2:3], v0, s21, v[8:9]
	s_or_b64 s[12:13], vcc, s[12:13]
	flat_store_dword v[0:1], v7
	s_andn2_b64 exec, exec, s[12:13]
	s_cbranch_execnz .LBB0_339

; __device__ __forceinline__ unsigned cvtpk(float lo, float hi) { unsigned r; asm volatile("v_cvt_pk_bf16_f32 %0, %1, %2" : "=v"(r) : "v"(lo), "v"(hi)); return r; }
; __device__ __forceinline__ void xg_pass(const float* x, const float* nw, const float* sc, bf16_t* XGp, bf16_t* X16p, unsigned long long* ssq, int vcu, int ngw, const int wave_s) {
;     ...
;     for (int m0 = 2 * gw; m0 < MTOK; m0 += 2 * ngw) {
;         const int b = m0 >> 12;
;         f32x4 v[2][4], scv[4];
; #pragma unroll
;         for (int i = 0; i < 2; ++i)
; #pragma unroll
;             for (int j = 0; j < 4; ++j) v[i][j] = ((const f32x4*)(x + (size_t)(m0 + i) * DM) + lane)[64 * j];
; #pragma unroll
;         for (int j = 0; j < 4; ++j) scv[j] = *(const f32x4*)(sc + (size_t)b * NMOD + 4 * lane + 256 * j);
; #pragma unroll
;         for (int i = 0; i < 2; ++i) {
;             const int m = m0 + i; float s = 0.f;
; #pragma unroll
;             for (int j = 0; j < 4; ++j) s += (v[i][j].x * v[i][j].x + v[i][j].y * v[i][j].y) + (v[i][j].z * v[i][j].z + v[i][j].w * v[i][j].w);
;             s = wave_sum(s, lane);
;             if (lane == 0) ssq[m] = (unsigned long long)(s * 16777216.0f);
;             unsigned long long* o8 = (unsigned long long*)(XGp + (size_t)m * DM) + lane;
;             unsigned long long* x8 = (unsigned long long*)(X16p + (size_t)m * DM) + lane;
; #pragma unroll
;             for (int j = 0; j < 4; ++j) {
;                 const f32x4 h = v[i][j] * wv[j] * (scv[j] + 1.0f);
;                 o8[64 * j] = (unsigned long long)cvtpk(h.x, h.y) | ((unsigned long long)cvtpk(h.z, h.w) << 32);
;                 x8[64 * j] = (unsigned long long)cvtpk(v[i][j].x, v[i][j].y) | ((unsigned long long)cvtpk(v[i][j].z, v[i][j].w) << 32);
;             }
;         }
.LBB0_350:
	s_or_b64 exec, exec, s[2:3]
	v_pk_mul_f32 v[34:35], v[0:1], v[28:29]
	v_pk_mul_f32 v[32:33], v[2:3], v[30:31]
	v_pk_mul_f32 v[34:35], v[34:35], v[78:79]
	v_pk_mul_f32 v[32:33], v[32:33], v[62:63]
	v_cvt_pk_bf16_f32 v34, v34, v35
	v_add_u32_e32 v64, s10, v64
	v_cvt_pk_bf16_f32 v35, v32, v33
	global_store_dwordx2 v[60:61], v[34:35], off offset:2048
	v_cvt_pk_bf16_f32 v28, v28, v29
	v_cvt_pk_bf16_f32 v29, v30, v31
	v_pk_mul_f32 v[30:31], v[4:5], v[24:25]
	global_store_dwordx2 v[56:57], v[28:29], off offset:64
	v_pk_mul_f32 v[28:29], v[6:7], v[26:27]
	v_pk_mul_f32 v[30:31], v[30:31], v[52:53]
	v_pk_mul_f32 v[28:29], v[28:29], v[54:55]
	v_cvt_pk_bf16_f32 v30, v30, v31
	v_cmp_lt_i32_e64 s[6:7], s11, v64
	v_cvt_pk_bf16_f32 v31, v28, v29
	global_store_dwordx2 v[60:61], v[30:31], off offset:2560
	v_cvt_pk_bf16_f32 v24, v24, v25
	v_cvt_pk_bf16_f32 v25, v26, v27
	v_pk_mul_f32 v[26:27], v[8:9], v[20:21]
	global_store_dwordx2 v[98:99], v[24:25], off offset:64
	v_pk_mul_f32 v[24:25], v[10:11], v[22:23]
	v_pk_mul_f32 v[26:27], v[26:27], v[44:45]
	v_pk_mul_f32 v[24:25], v[24:25], v[46:47]
	v_cvt_pk_bf16_f32 v26, v26, v27
	v_lshl_add_u64 v[68:69], v[68:69], 0, s[12:13]
	v_cvt_pk_bf16_f32 v27, v24, v25
	global_store_dwordx2 v[60:61], v[26:27], off offset:3072
	v_cvt_pk_bf16_f32 v20, v20, v21
	v_cvt_pk_bf16_f32 v21, v22, v23
	v_pk_mul_f32 v[22:23], v[12:13], v[16:17]
	global_store_dwordx2 v[100:101], v[20:21], off offset:64
	v_pk_mul_f32 v[20:21], v[14:15], v[18:19]
	v_pk_mul_f32 v[22:23], v[22:23], v[38:39]
	v_lshl_add_u64 v[72:73], v[72:73], 0, s[14:15]
	v_lshl_add_u64 v[74:75], v[74:75], 0, s[14:15]
	s_or_b64 s[18:19], s[6:7], s[18:19]
	v_lshl_add_u64 v[76:77], v[76:77], 0, s[16:17]
	v_pk_mul_f32 v[20:21], v[20:21], v[36:37]
	v_cvt_pk_bf16_f32 v22, v22, v23
	s_nop 0
	v_cvt_pk_bf16_f32 v23, v20, v21
	global_store_dwordx2 v[60:61], v[22:23], off offset:3584
	v_cvt_pk_bf16_f32 v16, v16, v17
	v_cvt_pk_bf16_f32 v17, v18, v19
	global_store_dwordx2 v[102:103], v[16:17], off offset:64
	s_andn2_b64 exec, exec, s[18:19]
	s_cbranch_execz .LBB0_355
.LBB0_351:
	global_load_dwordx4 v[56:59], v[76:77], off offset:-4096
	global_load_dwordx4 v[48:51], v[76:77], off offset:-3072
	global_load_dwordx4 v[36:39], v[76:77], off offset:-2048
	global_load_dwordx4 v[32:35], v[76:77], off offset:-1024
	global_load_dwordx4 v[28:31], v[76:77], off
	global_load_dwordx4 v[24:27], v[76:77], off offset:1024
	global_load_dwordx4 v[20:23], v[76:77], off offset:2048
	global_load_dwordx4 v[16:19], v[76:77], off offset:3072
	v_ashrrev_i32_e32 v40, 12, v64
	s_waitcnt lgkmcnt(0)
	v_mul_hi_i32_i24_e32 v41, 0x6000, v40
	v_mul_i32_i24_e32 v40, 0x6000, v40
	v_lshl_add_u64 v[78:79], v[66:67], 0, v[40:41]
	global_load_dwordx4 v[60:63], v[78:79], off
	global_load_dwordx4 v[52:55], v[78:79], off offset:1024
	global_load_dwordx4 v[44:47], v[78:79], off offset:2048
	global_load_dwordx4 v[40:43], v[78:79], off offset:3072
	s_waitcnt vmcnt(0)
	v_mul_f32_e32 v65, v57, v57
	v_mul_f32_e32 v78, v59, v59
	v_mul_f32_e32 v79, v49, v49
	v_mul_f32_e32 v86, v51, v51
	v_mul_f32_e32 v87, v37, v37
	v_mul_f32_e32 v88, v39, v39
	v_fmac_f32_e32 v65, v56, v56
	v_fmac_f32_e32 v78, v58, v58
	v_fmac_f32_e32 v79, v48, v48
	v_fmac_f32_e32 v86, v50, v50
	v_mul_f32_e32 v89, v33, v33
	v_mul_f32_e32 v90, v35, v35
	v_fmac_f32_e32 v87, v36, v36
	v_fmac_f32_e32 v88, v38, v38
	v_add_f32_e32 v65, v65, v78
	v_add_f32_e32 v78, v79, v86
	v_fmac_f32_e32 v89, v32, v32
	v_fmac_f32_e32 v90, v34, v34
	v_add_f32_e32 v79, v87, v88
	v_add_f32_e32 v65, v65, v78
	v_add_f32_e32 v65, v65, v79
	v_add_f32_e32 v78, v89, v90
	v_add_f32_e32 v65, v65, v78
	ds_bpermute_b32 v78, v80, v65
	s_waitcnt lgkmcnt(0)
	v_add_f32_e32 v65, v65, v78
	ds_bpermute_b32 v78, v81, v65
	s_waitcnt lgkmcnt(0)
	v_add_f32_e32 v65, v65, v78
	ds_bpermute_b32 v78, v82, v65
	s_waitcnt lgkmcnt(0)
	v_add_f32_e32 v65, v65, v78
	ds_bpermute_b32 v78, v83, v65
	s_waitcnt lgkmcnt(0)
	v_add_f32_e32 v65, v65, v78
	ds_bpermute_b32 v78, v84, v65
	s_waitcnt lgkmcnt(0)
	v_add_f32_e32 v65, v65, v78
	ds_bpermute_b32 v78, v85, v65
	s_and_saveexec_b64 s[2:3], vcc
	s_cbranch_execz .LBB0_353
	s_waitcnt lgkmcnt(0)
	v_add_f32_e32 v65, v65, v78
	v_mul_f32_e32 v65, 0x4b800000, v65
	v_trunc_f32_e32 v65, v65
	v_mul_f32_e32 v78, 0x2f800000, v65
	v_floor_f32_e32 v79, v78
	v_fmac_f32_e32 v65, 0xcf800000, v79
	v_cvt_u32_f32_e32 v78, v65
	v_cvt_u32_f32_e32 v79, v79
	v_add_co_u32_e64 v86, s[6:7], -8, v68
	s_nop 1
	v_addc_co_u32_e64 v87, s[6:7], -1, v69, s[6:7]
	global_store_dwordx2 v[86:87], v[78:79], off
; __device__ __forceinline__ unsigned cvtpk(float lo, float hi) { unsigned r; asm volatile("v_cvt_pk_bf16_f32 %0, %1, %2" : "=v"(r) : "v"(lo), "v"(hi)); return r; }
; __device__ __forceinline__ float shfl_x(float v, int m, int lane) { return __builtin_bit_cast(float, __builtin_amdgcn_ds_bpermute((lane ^ m) << 2, __builtin_bit_cast(int, v))); }
; __device__ __forceinline__ float wave_sum(float v, int lane) {
; #pragma unroll
;     for (int o = 1; o < 64; o <<= 1) v += shfl_x(v, o, lane);
;     return v;
; __device__ __forceinline__ void xg_pass(const float* x, const float* nw, const float* sc, bf16_t* XGp, bf16_t* X16p, unsigned long long* ssq, int vcu, int ngw, const int wave_s) {
;     ...
;         for (int i = 0; i < 2; ++i) {
;             const int m = m0 + i; float s = 0.f;
; #pragma unroll
;             for (int j = 0; j < 4; ++j) s += (v[i][j].x * v[i][j].x + v[i][j].y * v[i][j].y) + (v[i][j].z * v[i][j].z + v[i][j].w * v[i][j].w);
;             s = wave_sum(s, lane);
;             if (lane == 0) ssq[m] = (unsigned long long)(s * 16777216.0f);
;             unsigned long long* o8 = (unsigned long long*)(XGp + (size_t)m * DM) + lane;
;             unsigned long long* x8 = (unsigned long long*)(X16p + (size_t)m * DM) + lane;
; #pragma unroll
;             for (int j = 0; j < 4; ++j) {
;                 const f32x4 h = v[i][j] * wv[j] * (scv[j] + 1.0f);
;                 o8[64 * j] = (unsigned long long)cvtpk(h.x, h.y) | ((unsigned long long)cvtpk(h.z, h.w) << 32);
;                 x8[64 * j] = (unsigned long long)cvtpk(v[i][j].x, v[i][j].y) | ((unsigned long long)cvtpk(v[i][j].z, v[i][j].w) << 32);
;             }
.LBB0_353:
	s_or_b64 exec, exec, s[2:3]
	v_pk_mul_f32 v[90:91], v[2:3], v[58:59]
	v_pk_mul_f32 v[92:93], v[0:1], v[56:57]
	v_pk_add_f32 v[62:63], v[62:63], 1.0 op_sel_hi:[1,0]
	s_waitcnt lgkmcnt(0)
	v_pk_add_f32 v[78:79], v[60:61], 1.0 op_sel_hi:[1,0]
	v_lshl_add_u64 v[86:87], v[74:75], 0, v[70:71]
	v_pk_mul_f32 v[60:61], v[90:91], v[62:63]
	v_pk_mul_f32 v[90:91], v[92:93], v[78:79]
	v_lshl_add_u64 v[88:89], v[72:73], 0, v[70:71]
	v_lshl_add_u64 v[96:97], v[72:73], 0, v[94:95]
	v_cvt_pk_bf16_f32 v90, v90, v91
	v_cvt_pk_bf16_f32 v91, v60, v61
	v_add_co_u32_e64 v60, s[6:7], s4, v86
	v_pk_add_f32 v[52:53], v[52:53], 1.0 op_sel_hi:[1,0]
	s_nop 0
	v_addc_co_u32_e64 v61, s[6:7], 0, v87, s[6:7]
	global_store_dwordx2 v[60:61], v[90:91], off
	v_cvt_pk_bf16_f32 v86, v56, v57
	v_add_co_u32_e64 v56, s[6:7], s5, v96
	v_cvt_pk_bf16_f32 v87, v58, v59
	v_pk_mul_f32 v[58:59], v[6:7], v[50:51]
	s_nop 0
	v_addc_co_u32_e64 v57, s[6:7], 0, v97, s[6:7]
	v_add_co_u32_e64 v98, s[6:7], v104, v56
	s_nop 1
	v_addc_co_u32_e64 v99, s[6:7], 0, v57, s[6:7]
	v_add_co_u32_e64 v100, s[6:7], v105, v56
	s_nop 1
	v_addc_co_u32_e64 v101, s[6:7], 0, v57, s[6:7]
	v_add_co_u32_e64 v102, s[6:7], v106, v56
	s_nop 1
	v_addc_co_u32_e64 v103, s[6:7], 0, v57, s[6:7]
	global_store_dwordx2 v[56:57], v[86:87], off
	v_pk_mul_f32 v[86:87], v[4:5], v[48:49]
	v_pk_add_f32 v[54:55], v[54:55], 1.0 op_sel_hi:[1,0]
	v_pk_mul_f32 v[86:87], v[86:87], v[52:53]
	v_pk_mul_f32 v[58:59], v[58:59], v[54:55]
	v_cvt_pk_bf16_f32 v86, v86, v87
	v_pk_add_f32 v[46:47], v[46:47], 1.0 op_sel_hi:[1,0]
	v_cvt_pk_bf16_f32 v87, v58, v59
	global_store_dwordx2 v[60:61], v[86:87], off offset:512
	v_cvt_pk_bf16_f32 v48, v48, v49
	v_cvt_pk_bf16_f32 v49, v50, v51
	global_store_dwordx2 v[98:99], v[48:49], off
	v_mul_f32_e32 v48, v29, v29
	v_mul_f32_e32 v49, v31, v31
	v_fmac_f32_e32 v48, v28, v28
	v_fmac_f32_e32 v49, v30, v30
	v_add_f32_e32 v48, v48, v49
	v_mul_f32_e32 v49, v25, v25
	v_mul_f32_e32 v50, v27, v27
	v_fmac_f32_e32 v49, v24, v24
	v_fmac_f32_e32 v50, v26, v26
	v_add_f32_e32 v49, v49, v50
	v_add_f32_e32 v48, v48, v49
	v_mul_f32_e32 v49, v21, v21
	v_mul_f32_e32 v50, v23, v23
	v_fmac_f32_e32 v49, v20, v20
	v_fmac_f32_e32 v50, v22, v22
	v_add_f32_e32 v49, v49, v50
	v_add_f32_e32 v48, v48, v49
	v_mul_f32_e32 v49, v17, v17
	v_mul_f32_e32 v50, v19, v19
	v_fmac_f32_e32 v49, v16, v16
	v_fmac_f32_e32 v50, v18, v18
	v_add_f32_e32 v49, v49, v50
	v_add_f32_e32 v58, v48, v49
	ds_bpermute_b32 v59, v80, v58
	v_pk_mul_f32 v[48:49], v[10:11], v[38:39]
	v_pk_mul_f32 v[50:51], v[8:9], v[36:37]
	v_pk_add_f32 v[44:45], v[44:45], 1.0 op_sel_hi:[1,0]
	v_pk_mul_f32 v[48:49], v[48:49], v[46:47]
	s_waitcnt lgkmcnt(0)
	v_add_f32_e32 v58, v58, v59
	ds_bpermute_b32 v59, v81, v58
	v_pk_mul_f32 v[50:51], v[50:51], v[44:45]
	s_nop 0
	v_cvt_pk_bf16_f32 v50, v50, v51
	v_cvt_pk_bf16_f32 v51, v48, v49
	s_waitcnt lgkmcnt(0)
	v_add_f32_e32 v48, v58, v59
	ds_bpermute_b32 v49, v82, v48
	global_store_dwordx2 v[60:61], v[50:51], off offset:1024
	v_cvt_pk_bf16_f32 v36, v36, v37
	v_cvt_pk_bf16_f32 v37, v38, v39
	global_store_dwordx2 v[100:101], v[36:37], off
	s_waitcnt lgkmcnt(0)
	v_add_f32_e32 v58, v48, v49
	ds_bpermute_b32 v59, v83, v58
	v_pk_mul_f32 v[48:49], v[14:15], v[34:35]
	v_pk_mul_f32 v[50:51], v[12:13], v[32:33]
	v_pk_add_f32 v[36:37], v[42:43], 1.0 op_sel_hi:[1,0]
	v_pk_add_f32 v[38:39], v[40:41], 1.0 op_sel_hi:[1,0]
	s_waitcnt lgkmcnt(0)
	v_add_f32_e32 v58, v58, v59
	ds_bpermute_b32 v59, v84, v58
	v_pk_mul_f32 v[40:41], v[48:49], v[36:37]
	v_pk_mul_f32 v[42:43], v[50:51], v[38:39]
	s_nop 0
	v_cvt_pk_bf16_f32 v42, v42, v43
	v_cvt_pk_bf16_f32 v43, v40, v41
	s_waitcnt lgkmcnt(0)
	v_add_f32_e32 v40, v58, v59
	ds_bpermute_b32 v41, v85, v40
	global_store_dwordx2 v[60:61], v[42:43], off offset:1536
	v_cvt_pk_bf16_f32 v32, v32, v33
	v_cvt_pk_bf16_f32 v33, v34, v35
	global_store_dwordx2 v[102:103], v[32:33], off
	s_and_saveexec_b64 s[2:3], vcc
	s_cbranch_execz .LBB0_350
	s_waitcnt lgkmcnt(0)
	v_add_f32_e32 v32, v40, v41
	v_mul_f32_e32 v32, 0x4b800000, v32
	v_trunc_f32_e32 v32, v32
	v_mul_f32_e32 v33, 0x2f800000, v32
	v_floor_f32_e32 v33, v33
	v_fmac_f32_e32 v32, 0xcf800000, v33
	v_cvt_u32_f32_e32 v32, v32
	v_cvt_u32_f32_e32 v33, v33
	global_store_dwordx2 v[68:69], v[32:33], off
	s_branch .LBB0_350

; __device__ __forceinline__ float ssq_val(ssq_t v) { return (float)v * SSQ_IFX; }
;     __device__ __forceinline__ void operator()(const f32x4 (&acc)[2][2][4][2], const Unit& u, int wr, int wc, int fr, int fq) const {
;         const int row0 = u.pm * BM + wr * 64 + fr; const int b = (u.pm * BM) >> 12;
;         ssq_t sv[8]; float rsv[8];
; #pragma unroll
;         for (int i = 0; i < 8; ++i) sv[i] = ssqx[row0 + (i >> 2) * HALF + (i & 3) * 16];
; #pragma unroll
;         for (int i = 0; i < 8; ++i) rsv[i] = 1.0f / sqrtf(ssq_val(sv[i]) * (1.0f / DM) + EPS);
; #pragma unroll
;         for (int bj = 0; bj < 2; ++bj) {
;             const int colw = u.pn * BM + bj * HALF + wc * 32, col0 = colw + 8 * fq;
;             const int mode = colw < 512 ? 1 : (colw < 640 ? 0 : (colw < 672 ? 2 : (colw < 1536 ? 0 : 3)));
;             const int stat = (colw >= PC_CQ && colw < PC_CKV) ? 1 : ((colw >= PC_CKV && colw < PC_CKV + 256) ? 2 : 0);
;             const float sc = colw < 384 ? QS_A : 1.f;
;             const f32x4 s0 = *(const f32x4*)(shw + (size_t)b * 7680 + col0), s1 = *(const f32x4*)(shw + (size_t)b * 7680 + col0 + 4);
; #pragma unroll
;             for (int ai = 0; ai < 2; ++ai)
; #pragma unroll
;                 for (int m = 0; m < 4; ++m) {
;                     const int row = row0 + ai * HALF + m * 16;
;                     const float rs = rsv[ai * 4 + m];
;                     f32x4 v0 = acc[ai][bj][m][0] * rs + s0, v1 = acc[ai][bj][m][1] * rs + s1;
.LBB0_425:
	s_lshl_b32 s2, s12, 8
	v_mbcnt_lo_u32_b32 v0, -1, 0
	v_mbcnt_hi_u32_b32 v0, -1, v0
	s_add_i32 s2, s2, s83
	v_and_b32_e32 v203, 15, v0
	v_or_b32_e32 v152, s2, v203
	v_ashrrev_i32_e32 v153, 31, v152
	v_lshl_add_u64 v[86:87], v[152:153], 3, s[28:29]
	global_load_dwordx2 v[88:89], v[86:87], off
	global_load_dwordx2 v[170:171], v[86:87], off offset:128
	global_load_dwordx2 v[168:169], v[86:87], off offset:256
	global_load_dwordx2 v[166:167], v[86:87], off offset:384
	global_load_dwordx2 v[164:165], v[86:87], off offset:1024
	global_load_dwordx2 v[162:163], v[86:87], off offset:1152
	global_load_dwordx2 v[160:161], v[86:87], off offset:1280
	global_load_dwordx2 v[158:159], v[86:87], off offset:1408
	v_bfe_u32 v202, v0, 4, 2
	s_lshl_b32 s35, s10, 8
	s_waitcnt vmcnt(0) lgkmcnt(0)
	v_ffbh_u32_e32 v0, v89
	v_min_u32_e32 v0, 32, v0
	v_lshlrev_b64 v[86:87], v0, v[88:89]
	v_min_u32_e32 v86, 1, v86
	v_or_b32_e32 v86, v87, v86
	v_cvt_f32_u32_e32 v86, v86
	v_sub_u32_e32 v0, 32, v0
	v_ldexp_f32 v0, v86, v0
	v_mul_f32_e32 v0, 0x33800000, v0
	v_fmamk_f32 v0, v0, 0x3a800000, v226
	v_cmp_gt_f32_e32 vcc, s71, v0
	v_mul_f32_e32 v86, 0x4f800000, v0
	s_nop 0
	v_cndmask_b32_e32 v0, v0, v86, vcc
	v_sqrt_f32_e32 v86, v0
	s_nop 0
	v_add_u32_e32 v87, -1, v86
	v_fma_f32 v88, -v87, v86, v0
	v_cmp_ge_f32_e64 s[8:9], 0, v88
	v_add_u32_e32 v88, 1, v86
	s_nop 0
	v_cndmask_b32_e64 v87, v86, v87, s[8:9]
	v_fma_f32 v86, -v88, v86, v0
	v_cmp_lt_f32_e64 s[8:9], 0, v86
	s_nop 1
	v_cndmask_b32_e64 v86, v87, v88, s[8:9]
	v_mul_f32_e32 v87, 0x37800000, v86
	v_cndmask_b32_e32 v86, v86, v87, vcc
	v_cmp_class_f32_e32 vcc, v0, v223
	s_nop 1
	v_cndmask_b32_e32 v0, v86, v0, vcc
	v_div_scale_f32 v86, s[2:3], v0, v0, 1.0
	v_rcp_f32_e32 v87, v86
	s_ashr_i32 s2, s12, 4
	s_mul_hi_i32 s3, s2, 0x7800
	s_mul_i32 s11, s2, 0x7800
	v_fma_f32 v88, -v86, v87, 1.0
	s_or_b32 s2, s35, s66
	v_fmac_f32_e32 v87, v88, v87
	v_div_scale_f32 v88, vcc, 1.0, v0, 1.0
	s_cmpk_lt_u32 s35, 0x600
	v_mul_f32_e32 v89, v88, v87
	s_cselect_b32 s37, 0, 3
	s_cmpk_gt_u32 s2, 0x29f
	v_fma_f32 v90, -v86, v89, v88
	s_cselect_b32 s4, s37, 2
	s_cmpk_gt_u32 s35, 0x27f
	v_fmac_f32_e32 v89, v90, v87
	s_cselect_b32 s8, s4, 0
	s_cmpk_gt_i32 s2, 0x1ff
	v_fma_f32 v86, -v86, v89, v88
	s_cselect_b64 s[16:17], -1, 0
	v_div_fmas_f32 v86, v86, v87, v89
	s_and_b64 s[4:5], s[16:17], exec
	v_div_fixup_f32 v154, v86, v0, 1.0
	v_lshlrev_b32_e32 v0, 3, v202
	s_cselect_b32 s4, s8, 1
	s_cmpk_lt_i32 s2, 0x180
	v_or_b32_e32 v156, s2, v0
	s_cselect_b64 s[8:9], -1, 0
	s_add_u32 s86, s96, s11
	s_addc_u32 s87, s97, s3
	v_ashrrev_i32_e32 v157, 31, v156
	v_lshl_add_u64 v[90:91], v[156:157], 2, s[86:87]
	global_load_dwordx4 v[86:89], v[90:91], off
	s_nop 0
	global_load_dwordx4 v[90:93], v[90:91], off offset:16
	s_add_i32 s3, s4, -1
	s_cmp_gt_u32 s3, 1
	s_cselect_b64 s[18:19], -1, 0
	s_cmp_eq_u32 s4, 3
	s_cselect_b64 s[10:11], -1, 0
	s_mov_b64 s[4:5], -1
	s_and_b64 vcc, exec, s[18:19]
	s_waitcnt vmcnt(0) lgkmcnt(0)
	v_pk_fma_f32 v[176:177], v[140:141], v[154:155], v[88:89] op_sel_hi:[1,0,1]
	v_pk_fma_f32 v[174:175], v[136:137], v[154:155], v[92:93] op_sel_hi:[1,0,1]
	v_cndmask_b32_e64 v136, 0, 1, s[10:11]
	v_pk_fma_f32 v[194:195], v[138:139], v[154:155], v[86:87] op_sel_hi:[1,0,1]
	v_pk_fma_f32 v[134:135], v[134:135], v[154:155], v[90:91] op_sel_hi:[1,0,1]
	v_cmp_ne_u32_e64 s[10:11], 1, v136
	s_cbranch_vccz .LBB0_429
	s_and_b64 vcc, exec, s[10:11]
	v_mov_b32_e32 v173, v177
	v_mov_b32_e32 v172, v176
	v_mov_b32_e32 v141, v195
	v_mov_b32_e32 v140, v194
	v_mov_b32_e32 v199, v175
	v_mov_b32_e32 v198, v174
	v_mov_b32_e32 v197, v135
	v_mov_b32_e32 v196, v134
	s_cbranch_vccnz .LBB0_428
; __device__ __forceinline__ f32x2 gelu_pk(f32x2 v) {
;     const f32x2 av = __builtin_elementwise_abs(v), d = av * 0.2316418882f + 1.0f;
;     f32x2 t; t.x = __builtin_amdgcn_rcpf(d.x); t.y = __builtin_amdgcn_rcpf(d.y);
;     f32x2 q = t * 0.5307027145f + (-0.7265760135f); q = q * t + 0.7107068705f; q = q * t + (-0.142248368f); q = q * t + 0.127414796f; q = q * t;
;     const f32x2 s = (v * v) * (-0.72134752044f);
;     f32x2 e; e.x = __builtin_amdgcn_exp2f(s.x); e.y = __builtin_amdgcn_exp2f(s.y);
;     const f32x2 m = v * (q * e), r = v - m;
;     f32x2 o; o.x = v.x < 0.f ? m.x : r.x; o.y = v.y < 0.f ? m.y : r.y; return o;
; }
;     __device__ __forceinline__ void operator()(const f32x4 (&acc)[2][2][4][2], const Unit& u, int wr, int wc, int fr, int fq) const {
;     ...
;                     } else if (mode == 3) {
;                         const f32x2 a = gelu_pk((f32x2){v0[0], v0[1]}), bb = gelu_pk((f32x2){v0[2], v0[3]}), c = gelu_pk((f32x2){v1[0], v1[1]}), d = gelu_pk((f32x2){v1[2], v1[3]});
;                         v0 = (f32x4){a.x, a.y, bb.x, bb.y}; v1 = (f32x4){c.x, c.y, d.x, d.y};
	v_and_b32_e32 v137, 0x7fffffff, v195
	v_and_b32_e32 v136, 0x7fffffff, v194
	v_pk_fma_f32 v[136:137], v[136:137], s[62:63], 1.0 op_sel_hi:[1,0,0]
	s_mov_b32 s4, 0xbf3a00e3
	v_rcp_f32_e32 v136, v136
	v_rcp_f32_e32 v137, v137
	v_mov_b64_e32 v[138:139], s[4:5]
	v_cmp_gt_f32_e32 vcc, 0, v194
	v_pk_mul_f32 v[172:173], v[176:177], v[176:177]
	v_pk_fma_f32 v[140:141], v[136:137], s[64:65], v[138:139] op_sel_hi:[1,0,0]
	v_pk_mul_f32 v[172:173], v[172:173], s[74:75] op_sel_hi:[1,0]
	v_pk_fma_f32 v[140:141], v[136:137], v[140:141], s[68:69] op_sel_hi:[1,1,0]
	v_exp_f32_e32 v172, v172
	v_pk_fma_f32 v[140:141], v[136:137], v[140:141], s[70:71] op_sel_hi:[1,1,0]
	v_exp_f32_e32 v173, v173
	v_pk_fma_f32 v[140:141], v[136:137], v[140:141], s[72:73] op_sel_hi:[1,1,0]
	v_pk_mul_f32 v[180:181], v[134:135], v[134:135]
	v_pk_mul_f32 v[136:137], v[136:137], v[140:141]
	v_pk_mul_f32 v[140:141], v[194:195], v[194:195]
	v_pk_mul_f32 v[180:181], v[180:181], s[74:75] op_sel_hi:[1,0]
	v_pk_mul_f32 v[140:141], v[140:141], s[74:75] op_sel_hi:[1,0]
	v_exp_f32_e32 v180, v180
	v_exp_f32_e32 v140, v140
	v_exp_f32_e32 v141, v141
	v_exp_f32_e32 v181, v181
	v_pk_mul_f32 v[136:137], v[140:141], v[136:137]
	s_nop 0
	v_pk_mul_f32 v[140:141], v[194:195], v[136:137]
	v_pk_fma_f32 v[136:137], v[194:195], v[136:137], v[194:195] neg_lo:[1,0,0] neg_hi:[1,0,0]
	s_nop 0
	v_cndmask_b32_e32 v140, v136, v140, vcc
	v_cmp_gt_f32_e32 vcc, 0, v195
	v_and_b32_e32 v136, 0x7fffffff, v176
	s_nop 0
	v_cndmask_b32_e32 v141, v137, v141, vcc
	v_and_b32_e32 v137, 0x7fffffff, v177
	v_pk_fma_f32 v[136:137], v[136:137], s[62:63], 1.0 op_sel_hi:[1,0,0]
	v_cmp_gt_f32_e32 vcc, 0, v176
	v_rcp_f32_e32 v136, v136
	v_rcp_f32_e32 v137, v137
	s_nop 0
	v_pk_fma_f32 v[178:179], v[136:137], s[64:65], v[138:139] op_sel_hi:[1,0,0]
	s_nop 0
	v_pk_fma_f32 v[178:179], v[136:137], v[178:179], s[68:69] op_sel_hi:[1,1,0]
	s_nop 0
	v_pk_fma_f32 v[178:179], v[136:137], v[178:179], s[70:71] op_sel_hi:[1,1,0]
	s_nop 0
	v_pk_fma_f32 v[178:179], v[136:137], v[178:179], s[72:73] op_sel_hi:[1,1,0]
	s_nop 0
	v_pk_mul_f32 v[136:137], v[136:137], v[178:179]
	s_nop 0
	v_pk_mul_f32 v[136:137], v[172:173], v[136:137]
	s_nop 0
	v_pk_mul_f32 v[172:173], v[176:177], v[136:137]
	v_pk_fma_f32 v[136:137], v[176:177], v[136:137], v[176:177] neg_lo:[1,0,0] neg_hi:[1,0,0]
	s_nop 0
	v_cndmask_b32_e32 v172, v136, v172, vcc
	v_cmp_gt_f32_e32 vcc, 0, v177
	v_and_b32_e32 v136, 0x7fffffff, v134
	s_nop 0
	v_cndmask_b32_e32 v173, v137, v173, vcc
	v_and_b32_e32 v137, 0x7fffffff, v135
	v_pk_fma_f32 v[136:137], v[136:137], s[62:63], 1.0 op_sel_hi:[1,0,0]
	v_cmp_gt_f32_e32 vcc, 0, v134
	v_rcp_f32_e32 v136, v136
	v_rcp_f32_e32 v137, v137
	s_nop 0
	v_pk_fma_f32 v[178:179], v[136:137], s[64:65], v[138:139] op_sel_hi:[1,0,0]
	s_nop 0
	v_pk_fma_f32 v[178:179], v[136:137], v[178:179], s[68:69] op_sel_hi:[1,1,0]
	s_nop 0
	v_pk_fma_f32 v[178:179], v[136:137], v[178:179], s[70:71] op_sel_hi:[1,1,0]
	s_nop 0
	v_pk_fma_f32 v[178:179], v[136:137], v[178:179], s[72:73] op_sel_hi:[1,1,0]
	s_nop 0
	v_pk_mul_f32 v[136:137], v[136:137], v[178:179]
	v_pk_mul_f32 v[178:179], v[174:175], v[174:175]
	v_pk_mul_f32 v[136:137], v[180:181], v[136:137]
	s_nop 0
	v_pk_mul_f32 v[180:181], v[134:135], v[136:137]
	v_pk_fma_f32 v[136:137], v[134:135], v[136:137], v[134:135] neg_lo:[1,0,0] neg_hi:[1,0,0]
	s_nop 0
	v_cndmask_b32_e32 v196, v136, v180, vcc
	v_cmp_gt_f32_e32 vcc, 0, v135
	v_and_b32_e32 v136, 0x7fffffff, v174
	s_nop 0
	v_cndmask_b32_e32 v197, v137, v181, vcc
	v_and_b32_e32 v137, 0x7fffffff, v175
	v_pk_fma_f32 v[136:137], v[136:137], s[62:63], 1.0 op_sel_hi:[1,0,0]
	v_cmp_gt_f32_e32 vcc, 0, v174
	v_rcp_f32_e32 v136, v136
	v_rcp_f32_e32 v137, v137
	s_nop 0
	v_pk_fma_f32 v[138:139], v[136:137], s[64:65], v[138:139] op_sel_hi:[1,0,0]
	s_nop 0
	v_pk_fma_f32 v[138:139], v[136:137], v[138:139], s[68:69] op_sel_hi:[1,1,0]
	s_nop 0
	v_pk_fma_f32 v[138:139], v[136:137], v[138:139], s[70:71] op_sel_hi:[1,1,0]
	s_nop 0
	v_pk_fma_f32 v[138:139], v[136:137], v[138:139], s[72:73] op_sel_hi:[1,1,0]
	s_nop 0
	v_pk_mul_f32 v[136:137], v[136:137], v[138:139]
	v_pk_mul_f32 v[138:139], v[178:179], s[74:75] op_sel_hi:[1,0]
	s_nop 0
	v_exp_f32_e32 v138, v138
	v_exp_f32_e32 v139, v139
	s_nop 0
	v_pk_mul_f32 v[136:137], v[138:139], v[136:137]
	s_nop 0
	v_pk_mul_f32 v[138:139], v[174:175], v[136:137]
	v_pk_fma_f32 v[136:137], v[174:175], v[136:137], v[174:175] neg_lo:[1,0,0] neg_hi:[1,0,0]
	s_nop 0
	v_cndmask_b32_e32 v198, v136, v138, vcc
	v_cmp_gt_f32_e32 vcc, 0, v175
	s_nop 1
	v_cndmask_b32_e32 v199, v137, v139, vcc

; __device__ __forceinline__ float shfl_x(float v, int m, int lane) { return __builtin_bit_cast(float, __builtin_amdgcn_ds_bpermute((lane ^ m) << 2, __builtin_bit_cast(int, v))); }
; __device__ __forceinline__ void ssq_put(ssq_t* p, int row, float q, int fr, int fq) {
;     const int lane = fr + 16 * fq;
;     q += shfl_x(q, 16, lane); q += shfl_x(q, 32, lane);
;     if (fq == 0) __hip_atomic_fetch_add(p + row, (ssq_t)(q * SSQ_FX), __ATOMIC_RELAXED, __HIP_MEMORY_SCOPE_AGENT);
; }
;     __device__ __forceinline__ void operator()(const f32x4 (&acc)[2][2][4][2], const Unit& u, int wr, int wc, int fr, int fq) const {
;     ...
;                     if (mode == 1 || mode == 2) {
;                         const float* tp = (mode == 1) ? (ropA + ((size_t)row * 32 + ((col0 & 63) >> 1)) * 2) : (ropB + ((size_t)row * 16 + ((col0 - PC_KR) >> 1)) * 2);
;                         const f32x4 c0 = *(const f32x4*)tp, c1 = *(const f32x4*)(tp + 4);
;                         f32x4 w0, w1;
;                         w0[0] = v0[0] * c0[0] - v0[1] * c0[1]; w0[1] = v0[1] * c0[0] + v0[0] * c0[1];
;                         w0[2] = v0[2] * c0[2] - v0[3] * c0[3]; w0[3] = v0[3] * c0[2] + v0[2] * c0[3];
;                         w1[0] = v1[0] * c1[0] - v1[1] * c1[1]; w1[1] = v1[1] * c1[0] + v1[0] * c1[1];
;                         w1[2] = v1[2] * c1[2] - v1[3] * c1[3]; w1[3] = v1[3] * c1[2] + v1[2] * c1[3];
;                         v0 = w0 * sc; v1 = w1 * sc;
;                     } else if (mode == 3) {
;                         const f32x2 a = gelu_pk((f32x2){v0[0], v0[1]}), bb = gelu_pk((f32x2){v0[2], v0[3]}), c = gelu_pk((f32x2){v1[0], v1[1]}), d = gelu_pk((f32x2){v1[2], v1[3]});
;                         v0 = (f32x4){a.x, a.y, bb.x, bb.y}; v1 = (f32x4){c.x, c.y, d.x, d.y};
;                     }
;                     if (stat) {
;                         const float q = (v0[0] * v0[0] + v0[1] * v0[1]) + (v0[2] * v0[2] + v0[3] * v0[3]) + (v1[0] * v1[0] + v1[1] * v1[1]) + (v1[2] * v1[2] + v1[3] * v1[3]);
;                         ssq_put(stat == 1 ? ssq_cq : ssq_ckv, row, q, fr, fq);
;                     }
.LBB0_434:
	global_load_dwordx4 v[196:199], v[140:141], off
	global_load_dwordx4 v[204:207], v[140:141], off offset:16
	s_waitcnt vmcnt(0) lgkmcnt(0)
	v_pk_mul_f32 v[140:141], v[194:195], v[196:197] op_sel:[1,1] op_sel_hi:[0,1]
	v_pk_fma_f32 v[178:179], v[194:195], v[196:197], v[140:141] op_sel_hi:[1,0,1] neg_lo:[0,0,1] neg_hi:[0,0,1]
	v_pk_fma_f32 v[140:141], v[194:195], v[196:197], v[140:141] op_sel_hi:[1,0,1]
	s_nop 0
	v_mov_b32_e32 v140, v199
	v_pk_mul_f32 v[172:173], v[176:177], v[140:141] op_sel:[1,0] op_sel_hi:[0,0]
	v_pk_fma_f32 v[180:181], v[176:177], v[198:199], v[172:173] op_sel_hi:[1,0,1] neg_lo:[0,0,1] neg_hi:[0,0,1]
	v_pk_fma_f32 v[172:173], v[176:177], v[198:199], v[172:173] op_sel_hi:[1,0,1]
	v_pk_mul_f32 v[176:177], v[134:135], v[204:205] op_sel:[1,1] op_sel_hi:[0,1]
	v_pk_fma_f32 v[182:183], v[134:135], v[204:205], v[176:177] op_sel_hi:[1,0,1] neg_lo:[0,0,1] neg_hi:[0,0,1]
	v_pk_fma_f32 v[134:135], v[134:135], v[204:205], v[176:177] op_sel_hi:[1,0,1]
	v_mov_b32_e32 v181, v173
	v_mov_b32_e32 v134, v207
	v_pk_mul_f32 v[176:177], v[174:175], v[134:135] op_sel:[1,0] op_sel_hi:[0,0]
	v_pk_fma_f32 v[184:185], v[174:175], v[206:207], v[176:177] op_sel_hi:[1,0,1] neg_lo:[0,0,1] neg_hi:[0,0,1]
	v_pk_fma_f32 v[174:175], v[174:175], v[206:207], v[176:177] op_sel_hi:[1,0,1]
	v_mov_b32_e32 v176, v136
	v_mov_b32_e32 v177, v136
	v_mov_b32_e32 v179, v141
	v_mov_b32_e32 v185, v175
	v_mov_b32_e32 v183, v135
	v_pk_mul_f32 v[172:173], v[176:177], v[180:181]
	v_pk_mul_f32 v[140:141], v[136:137], v[178:179]
	v_pk_mul_f32 v[198:199], v[176:177], v[184:185]
	v_pk_mul_f32 v[196:197], v[136:137], v[182:183]
.LBB0_435:
	v_lshlrev_b32_e32 v134, 6, v202
	v_lshlrev_b32_e32 v135, 2, v203
	s_movk_i32 s2, 0x80
	v_bitop3_b32 v194, v134, s2, v135 bitop3:0x36
	s_add_i32 s2, s35, 0xfffffb80
	s_cmp_lt_u32 s2, 0xfffffe80
	s_cselect_b64 s[88:89], -1, 0
	s_add_i32 s2, s35, 0xfffffa80
	s_cmp_gt_u32 s2, 0xfffffd7f
	v_mov_b32_e32 v155, v154
	v_bitop3_b32 v157, v134, 64, v135 bitop3:0x36
	s_cselect_b64 s[40:41], -1, 0
	s_cmp_lt_u32 s2, 0xfffffd80
	v_cmp_eq_u32_e64 s[8:9], 0, v202
	s_cbranch_scc1 .LBB0_439
	v_mul_f32_e32 v134, v141, v141
	v_mul_f32_e32 v135, v173, v173
	v_fmac_f32_e32 v134, v140, v140
	v_fmac_f32_e32 v135, v172, v172
	v_add_f32_e32 v134, v134, v135
	v_mul_f32_e32 v135, v197, v197
	v_fmac_f32_e32 v135, v196, v196
	v_add_f32_e32 v134, v135, v134
	v_mul_f32_e32 v135, v199, v199
	v_fmac_f32_e32 v135, v198, v198
	v_add_f32_e32 v134, v135, v134
	ds_bpermute_b32 v135, v157, v134
	s_waitcnt lgkmcnt(0)
	v_add_f32_e32 v134, v134, v135
	ds_bpermute_b32 v135, v194, v134
	s_and_saveexec_b64 s[2:3], s[8:9]
	s_cbranch_execz .LBB0_438
	s_waitcnt lgkmcnt(0)
	v_add_f32_e32 v134, v134, v135
	v_mul_f32_e32 v134, 0x4b800000, v134
	v_trunc_f32_e32 v134, v134
	v_mul_f32_e32 v135, 0x2f800000, v134
	v_floor_f32_e32 v135, v135
	v_fmac_f32_e32 v134, 0xcf800000, v135
	s_and_b64 s[4:5], s[88:89], exec
	v_cvt_u32_f32_e32 v134, v134
	v_cvt_u32_f32_e32 v135, v135
	s_cselect_b32 s4, s82, s80
	s_cselect_b32 s5, s81, s73
	v_mov_b32_e32 v174, s5
	v_mov_b32_e32 v175, s4
	v_lshl_add_u64 v[174:175], v[152:153], 3, v[174:175]
	global_atomic_add_x2 v[174:175], v[134:135], off

; __device__ __forceinline__ float shfl_x(float v, int m, int lane) { return __builtin_bit_cast(float, __builtin_amdgcn_ds_bpermute((lane ^ m) << 2, __builtin_bit_cast(int, v))); }
; __device__ __forceinline__ void ssq_put(ssq_t* p, int row, float q, int fr, int fq) {
;     const int lane = fr + 16 * fq;
;     q += shfl_x(q, 16, lane); q += shfl_x(q, 32, lane);
;     if (fq == 0) __hip_atomic_fetch_add(p + row, (ssq_t)(q * SSQ_FX), __ATOMIC_RELAXED, __HIP_MEMORY_SCOPE_AGENT);
; }
;     __device__ __forceinline__ void operator()(const f32x4 (&acc)[2][2][4][2], const Unit& u, int wr, int wc, int fr, int fq) const {
;     ...
;                     if (mode == 1 || mode == 2) {
;                         const float* tp = (mode == 1) ? (ropA + ((size_t)row * 32 + ((col0 & 63) >> 1)) * 2) : (ropB + ((size_t)row * 16 + ((col0 - PC_KR) >> 1)) * 2);
;                         const f32x4 c0 = *(const f32x4*)tp, c1 = *(const f32x4*)(tp + 4);
;                         f32x4 w0, w1;
;                         w0[0] = v0[0] * c0[0] - v0[1] * c0[1]; w0[1] = v0[1] * c0[0] + v0[0] * c0[1];
;                         w0[2] = v0[2] * c0[2] - v0[3] * c0[3]; w0[3] = v0[3] * c0[2] + v0[2] * c0[3];
;                         w1[0] = v1[0] * c1[0] - v1[1] * c1[1]; w1[1] = v1[1] * c1[0] + v1[0] * c1[1];
;                         w1[2] = v1[2] * c1[2] - v1[3] * c1[3]; w1[3] = v1[3] * c1[2] + v1[2] * c1[3];
;                         v0 = w0 * sc; v1 = w1 * sc;
;                     } else if (mode == 3) {
;                         const f32x2 a = gelu_pk((f32x2){v0[0], v0[1]}), bb = gelu_pk((f32x2){v0[2], v0[3]}), c = gelu_pk((f32x2){v1[0], v1[1]}), d = gelu_pk((f32x2){v1[2], v1[3]});
;                         v0 = (f32x4){a.x, a.y, bb.x, bb.y}; v1 = (f32x4){c.x, c.y, d.x, d.y};
;                     }
;                     if (stat) {
;                         const float q = (v0[0] * v0[0] + v0[1] * v0[1]) + (v0[2] * v0[2] + v0[3] * v0[3]) + (v1[0] * v1[0] + v1[1] * v1[1]) + (v1[2] * v1[2] + v1[3] * v1[3]);
;                         ssq_put(stat == 1 ? ssq_cq : ssq_ckv, row, q, fr, fq);
;                     }
.LBB0_448:
	global_load_dwordx4 v[174:177], v[130:131], off
	s_nop 0
	global_load_dwordx4 v[130:133], v[130:131], off offset:16
	s_waitcnt vmcnt(0) lgkmcnt(0)
	v_pk_mul_f32 v[178:179], v[170:171], v[174:175] op_sel:[1,1] op_sel_hi:[0,1]
	v_pk_fma_f32 v[180:181], v[170:171], v[174:175], v[178:179] op_sel_hi:[1,0,1] neg_lo:[0,0,1] neg_hi:[0,0,1]
	v_pk_fma_f32 v[170:171], v[170:171], v[174:175], v[178:179] op_sel_hi:[1,0,1]
	s_nop 0
	v_mov_b32_e32 v170, v177
	v_pk_mul_f32 v[174:175], v[140:141], v[170:171] op_sel:[1,0] op_sel_hi:[0,0]
	v_pk_fma_f32 v[178:179], v[140:141], v[176:177], v[174:175] op_sel_hi:[1,0,1] neg_lo:[0,0,1] neg_hi:[0,0,1]
	v_pk_fma_f32 v[140:141], v[140:141], v[176:177], v[174:175] op_sel_hi:[1,0,1]
	v_pk_mul_f32 v[174:175], v[172:173], v[130:131] op_sel:[1,1] op_sel_hi:[0,1]
	v_pk_fma_f32 v[182:183], v[172:173], v[130:131], v[174:175] op_sel_hi:[1,0,1] neg_lo:[0,0,1] neg_hi:[0,0,1]
	v_pk_fma_f32 v[172:173], v[172:173], v[130:131], v[174:175] op_sel_hi:[1,0,1]
	v_mov_b32_e32 v130, v133
	v_pk_mul_f32 v[130:131], v[128:129], v[130:131] op_sel:[1,0] op_sel_hi:[0,0]
	v_pk_fma_f32 v[174:175], v[128:129], v[132:133], v[130:131] op_sel_hi:[1,0,1] neg_lo:[0,0,1] neg_hi:[0,0,1]
	v_pk_fma_f32 v[128:129], v[128:129], v[132:133], v[130:131] op_sel_hi:[1,0,1]
	v_mov_b32_e32 v179, v141
	v_mov_b32_e32 v140, v136
	v_mov_b32_e32 v141, v136
	v_mov_b32_e32 v181, v171
	v_mov_b32_e32 v175, v129
	v_mov_b32_e32 v183, v173
	v_pk_mul_f32 v[132:133], v[140:141], v[178:179]
	v_pk_mul_f32 v[130:131], v[136:137], v[180:181]
	v_pk_mul_f32 v[176:177], v[140:141], v[174:175]
	v_pk_mul_f32 v[174:175], v[136:137], v[182:183]
.LBB0_449:
	v_cndmask_b32_e64 v128, 0, 1, s[40:41]
	v_mov_b32_e32 v135, v134
	v_cmp_ne_u32_e64 s[16:17], 1, v128
	s_andn2_b64 vcc, exec, s[40:41]
	s_cbranch_vccnz .LBB0_453
	v_mul_f32_e32 v128, v131, v131
	v_mul_f32_e32 v129, v133, v133
	v_fmac_f32_e32 v128, v130, v130
	v_fmac_f32_e32 v129, v132, v132
	v_add_f32_e32 v128, v128, v129
	v_mul_f32_e32 v129, v175, v175
	v_fmac_f32_e32 v129, v174, v174
	v_add_f32_e32 v128, v129, v128
	v_mul_f32_e32 v129, v177, v177
	v_fmac_f32_e32 v129, v176, v176
	v_add_f32_e32 v128, v129, v128
	ds_bpermute_b32 v129, v157, v128
	s_waitcnt lgkmcnt(0)
	v_add_f32_e32 v128, v128, v129
	ds_bpermute_b32 v129, v194, v128
	s_and_saveexec_b64 s[2:3], s[8:9]
	s_cbranch_execz .LBB0_452
	s_waitcnt lgkmcnt(0)
	v_add_f32_e32 v128, v128, v129
	v_mul_f32_e32 v128, 0x4b800000, v128
	v_trunc_f32_e32 v128, v128
	v_mul_f32_e32 v129, 0x2f800000, v128
	v_floor_f32_e32 v129, v129
	v_fmac_f32_e32 v128, 0xcf800000, v129
	s_and_b64 s[4:5], s[88:89], exec
	v_cvt_u32_f32_e32 v128, v128
	v_cvt_u32_f32_e32 v129, v129
	s_cselect_b32 s4, s82, s80
	s_cselect_b32 s5, s81, s73
	v_mov_b32_e32 v140, s5
	v_mov_b32_e32 v141, s4
	v_lshl_add_u64 v[140:141], v[152:153], 3, v[140:141]
	global_atomic_add_x2 v[140:141], v[128:129], off offset:128

; __device__ __forceinline__ float shfl_x(float v, int m, int lane) { return __builtin_bit_cast(float, __builtin_amdgcn_ds_bpermute((lane ^ m) << 2, __builtin_bit_cast(int, v))); }
; __device__ __forceinline__ void ssq_put(ssq_t* p, int row, float q, int fr, int fq) {
;     const int lane = fr + 16 * fq;
;     q += shfl_x(q, 16, lane); q += shfl_x(q, 32, lane);
;     if (fq == 0) __hip_atomic_fetch_add(p + row, (ssq_t)(q * SSQ_FX), __ATOMIC_RELAXED, __HIP_MEMORY_SCOPE_AGENT);
; }
;     __device__ __forceinline__ void operator()(const f32x4 (&acc)[2][2][4][2], const Unit& u, int wr, int wc, int fr, int fq) const {
;     ...
;                     if (mode == 1 || mode == 2) {
;                         const float* tp = (mode == 1) ? (ropA + ((size_t)row * 32 + ((col0 & 63) >> 1)) * 2) : (ropB + ((size_t)row * 16 + ((col0 - PC_KR) >> 1)) * 2);
;                         const f32x4 c0 = *(const f32x4*)tp, c1 = *(const f32x4*)(tp + 4);
;                         f32x4 w0, w1;
;                         w0[0] = v0[0] * c0[0] - v0[1] * c0[1]; w0[1] = v0[1] * c0[0] + v0[0] * c0[1];
;                         w0[2] = v0[2] * c0[2] - v0[3] * c0[3]; w0[3] = v0[3] * c0[2] + v0[2] * c0[3];
;                         w1[0] = v1[0] * c1[0] - v1[1] * c1[1]; w1[1] = v1[1] * c1[0] + v1[0] * c1[1];
;                         w1[2] = v1[2] * c1[2] - v1[3] * c1[3]; w1[3] = v1[3] * c1[2] + v1[2] * c1[3];
;                         v0 = w0 * sc; v1 = w1 * sc;
;                     } else if (mode == 3) {
;                         const f32x2 a = gelu_pk((f32x2){v0[0], v0[1]}), bb = gelu_pk((f32x2){v0[2], v0[3]}), c = gelu_pk((f32x2){v1[0], v1[1]}), d = gelu_pk((f32x2){v1[2], v1[3]});
;                         v0 = (f32x4){a.x, a.y, bb.x, bb.y}; v1 = (f32x4){c.x, c.y, d.x, d.y};
;                     }
;                     if (stat) {
;                         const float q = (v0[0] * v0[0] + v0[1] * v0[1]) + (v0[2] * v0[2] + v0[3] * v0[3]) + (v1[0] * v1[0] + v1[1] * v1[1]) + (v1[2] * v1[2] + v1[3] * v1[3]);
;                         ssq_put(stat == 1 ? ssq_cq : ssq_ckv, row, q, fr, fq);
;                     }
.LBB0_463:
	global_load_dwordx4 v[168:171], v[122:123], off
	s_nop 0
	global_load_dwordx4 v[122:125], v[122:123], off offset:16
	s_waitcnt vmcnt(0) lgkmcnt(0)
	v_pk_mul_f32 v[174:175], v[132:133], v[168:169] op_sel:[1,1] op_sel_hi:[0,1]
	v_pk_fma_f32 v[176:177], v[132:133], v[168:169], v[174:175] op_sel_hi:[1,0,1] neg_lo:[0,0,1] neg_hi:[0,0,1]
	v_pk_fma_f32 v[132:133], v[132:133], v[168:169], v[174:175] op_sel_hi:[1,0,1]
	s_nop 0
	v_mov_b32_e32 v132, v171
	v_pk_mul_f32 v[168:169], v[130:131], v[132:133] op_sel:[1,0] op_sel_hi:[0,0]
	v_pk_fma_f32 v[174:175], v[130:131], v[170:171], v[168:169] op_sel_hi:[1,0,1] neg_lo:[0,0,1] neg_hi:[0,0,1]
	v_pk_fma_f32 v[130:131], v[130:131], v[170:171], v[168:169] op_sel_hi:[1,0,1]
	v_pk_mul_f32 v[168:169], v[140:141], v[122:123] op_sel:[1,1] op_sel_hi:[0,1]
	v_pk_fma_f32 v[178:179], v[140:141], v[122:123], v[168:169] op_sel_hi:[1,0,1] neg_lo:[0,0,1] neg_hi:[0,0,1]
	v_pk_fma_f32 v[140:141], v[140:141], v[122:123], v[168:169] op_sel_hi:[1,0,1]
	v_mov_b32_e32 v122, v125
	v_pk_mul_f32 v[122:123], v[120:121], v[122:123] op_sel:[1,0] op_sel_hi:[0,0]
	v_pk_fma_f32 v[168:169], v[120:121], v[124:125], v[122:123] op_sel_hi:[1,0,1] neg_lo:[0,0,1] neg_hi:[0,0,1]
	v_pk_fma_f32 v[120:121], v[120:121], v[124:125], v[122:123] op_sel_hi:[1,0,1]
	v_mov_b32_e32 v175, v131
	v_mov_b32_e32 v130, v136
	v_mov_b32_e32 v131, v136
	v_mov_b32_e32 v177, v133
	v_mov_b32_e32 v169, v121
	v_mov_b32_e32 v179, v141
	v_pk_mul_f32 v[124:125], v[130:131], v[174:175]
	v_pk_mul_f32 v[122:123], v[136:137], v[176:177]
	v_pk_mul_f32 v[170:171], v[130:131], v[168:169]
	v_pk_mul_f32 v[168:169], v[136:137], v[178:179]
	v_mov_b32_e32 v129, v128
	s_and_b64 vcc, exec, s[16:17]
	s_cbranch_vccnz .LBB0_467
.LBB0_464:
	v_mul_f32_e32 v120, v123, v123
	v_mul_f32_e32 v121, v125, v125
	v_fmac_f32_e32 v120, v122, v122
	v_fmac_f32_e32 v121, v124, v124
	v_add_f32_e32 v120, v120, v121
	v_mul_f32_e32 v121, v169, v169
	v_fmac_f32_e32 v121, v168, v168
	v_add_f32_e32 v120, v121, v120
	v_mul_f32_e32 v121, v171, v171
	v_fmac_f32_e32 v121, v170, v170
	v_add_f32_e32 v120, v121, v120
	ds_bpermute_b32 v121, v157, v120
	s_waitcnt lgkmcnt(0)
	v_add_f32_e32 v120, v120, v121
	ds_bpermute_b32 v121, v194, v120
	s_and_saveexec_b64 s[2:3], s[8:9]
	s_cbranch_execz .LBB0_466
	s_waitcnt lgkmcnt(0)
	v_add_f32_e32 v120, v120, v121
	v_mul_f32_e32 v120, 0x4b800000, v120
	v_trunc_f32_e32 v120, v120
	v_mul_f32_e32 v121, 0x2f800000, v120
	v_floor_f32_e32 v121, v121
	v_fmac_f32_e32 v120, 0xcf800000, v121
	s_and_b64 s[4:5], s[88:89], exec
	v_cvt_u32_f32_e32 v120, v120
	v_cvt_u32_f32_e32 v121, v121
	s_cselect_b32 s4, s82, s80
	s_cselect_b32 s5, s81, s73
	v_mov_b32_e32 v130, s5
	v_mov_b32_e32 v131, s4
	v_lshl_add_u64 v[130:131], v[152:153], 3, v[130:131]
	global_atomic_add_x2 v[130:131], v[120:121], off offset:256

; __device__ __forceinline__ float shfl_x(float v, int m, int lane) { return __builtin_bit_cast(float, __builtin_amdgcn_ds_bpermute((lane ^ m) << 2, __builtin_bit_cast(int, v))); }
; __device__ __forceinline__ void ssq_put(ssq_t* p, int row, float q, int fr, int fq) {
;     const int lane = fr + 16 * fq;
;     q += shfl_x(q, 16, lane); q += shfl_x(q, 32, lane);
;     if (fq == 0) __hip_atomic_fetch_add(p + row, (ssq_t)(q * SSQ_FX), __ATOMIC_RELAXED, __HIP_MEMORY_SCOPE_AGENT);
; }
;     __device__ __forceinline__ void operator()(const f32x4 (&acc)[2][2][4][2], const Unit& u, int wr, int wc, int fr, int fq) const {
;     ...
;                     if (mode == 1 || mode == 2) {
;                         const float* tp = (mode == 1) ? (ropA + ((size_t)row * 32 + ((col0 & 63) >> 1)) * 2) : (ropB + ((size_t)row * 16 + ((col0 - PC_KR) >> 1)) * 2);
;                         const f32x4 c0 = *(const f32x4*)tp, c1 = *(const f32x4*)(tp + 4);
;                         f32x4 w0, w1;
;                         w0[0] = v0[0] * c0[0] - v0[1] * c0[1]; w0[1] = v0[1] * c0[0] + v0[0] * c0[1];
;                         w0[2] = v0[2] * c0[2] - v0[3] * c0[3]; w0[3] = v0[3] * c0[2] + v0[2] * c0[3];
;                         w1[0] = v1[0] * c1[0] - v1[1] * c1[1]; w1[1] = v1[1] * c1[0] + v1[0] * c1[1];
;                         w1[2] = v1[2] * c1[2] - v1[3] * c1[3]; w1[3] = v1[3] * c1[2] + v1[2] * c1[3];
;                         v0 = w0 * sc; v1 = w1 * sc;
;                     } else if (mode == 3) {
;                         const f32x2 a = gelu_pk((f32x2){v0[0], v0[1]}), bb = gelu_pk((f32x2){v0[2], v0[3]}), c = gelu_pk((f32x2){v1[0], v1[1]}), d = gelu_pk((f32x2){v1[2], v1[3]});
;                         v0 = (f32x4){a.x, a.y, bb.x, bb.y}; v1 = (f32x4){c.x, c.y, d.x, d.y};
;                     }
;                     if (stat) {
;                         const float q = (v0[0] * v0[0] + v0[1] * v0[1]) + (v0[2] * v0[2] + v0[3] * v0[3]) + (v1[0] * v1[0] + v1[1] * v1[1]) + (v1[2] * v1[2] + v1[3] * v1[3]);
;                         ssq_put(stat == 1 ? ssq_cq : ssq_ckv, row, q, fr, fq);
;                     }
.LBB0_477:
	global_load_dwordx4 v[168:171], v[114:115], off
	s_nop 0
	global_load_dwordx4 v[114:117], v[114:115], off offset:16
	s_waitcnt vmcnt(0) lgkmcnt(0)
	v_pk_mul_f32 v[132:133], v[124:125], v[168:169] op_sel:[1,1] op_sel_hi:[0,1]
	v_pk_fma_f32 v[140:141], v[124:125], v[168:169], v[132:133] op_sel_hi:[1,0,1] neg_lo:[0,0,1] neg_hi:[0,0,1]
	v_pk_fma_f32 v[124:125], v[124:125], v[168:169], v[132:133] op_sel_hi:[1,0,1]
	s_nop 0
	v_mov_b32_e32 v124, v171
	v_pk_mul_f32 v[132:133], v[122:123], v[124:125] op_sel:[1,0] op_sel_hi:[0,0]
	v_pk_fma_f32 v[168:169], v[122:123], v[170:171], v[132:133] op_sel_hi:[1,0,1] neg_lo:[0,0,1] neg_hi:[0,0,1]
	v_pk_fma_f32 v[122:123], v[122:123], v[170:171], v[132:133] op_sel_hi:[1,0,1]
	v_pk_mul_f32 v[132:133], v[130:131], v[114:115] op_sel:[1,1] op_sel_hi:[0,1]
	v_pk_fma_f32 v[170:171], v[130:131], v[114:115], v[132:133] op_sel_hi:[1,0,1] neg_lo:[0,0,1] neg_hi:[0,0,1]
	v_pk_fma_f32 v[130:131], v[130:131], v[114:115], v[132:133] op_sel_hi:[1,0,1]
	v_mov_b32_e32 v114, v117
	v_pk_mul_f32 v[114:115], v[112:113], v[114:115] op_sel:[1,0] op_sel_hi:[0,0]
	v_pk_fma_f32 v[132:133], v[112:113], v[116:117], v[114:115] op_sel_hi:[1,0,1] neg_lo:[0,0,1] neg_hi:[0,0,1]
	v_pk_fma_f32 v[112:113], v[112:113], v[116:117], v[114:115] op_sel_hi:[1,0,1]
	v_mov_b32_e32 v169, v123
	v_mov_b32_e32 v122, v136
	v_mov_b32_e32 v123, v136
	v_mov_b32_e32 v141, v125
	v_mov_b32_e32 v133, v113
	v_mov_b32_e32 v171, v131
	v_pk_mul_f32 v[116:117], v[122:123], v[168:169]
	v_pk_mul_f32 v[114:115], v[136:137], v[140:141]
	v_pk_mul_f32 v[140:141], v[122:123], v[132:133]
	v_pk_mul_f32 v[132:133], v[136:137], v[170:171]
	v_mov_b32_e32 v121, v120
	s_and_b64 vcc, exec, s[16:17]
	s_cbranch_vccnz .LBB0_481
.LBB0_478:
	v_mul_f32_e32 v112, v115, v115
	v_mul_f32_e32 v113, v117, v117
	v_fmac_f32_e32 v112, v114, v114
	v_fmac_f32_e32 v113, v116, v116
	v_add_f32_e32 v112, v112, v113
	v_mul_f32_e32 v113, v133, v133
	v_fmac_f32_e32 v113, v132, v132
	v_add_f32_e32 v112, v113, v112
	v_mul_f32_e32 v113, v141, v141
	v_fmac_f32_e32 v113, v140, v140
	v_add_f32_e32 v112, v113, v112
	ds_bpermute_b32 v113, v157, v112
	s_waitcnt lgkmcnt(0)
	v_add_f32_e32 v112, v112, v113
	ds_bpermute_b32 v113, v194, v112
	s_and_saveexec_b64 s[2:3], s[8:9]
	s_cbranch_execz .LBB0_480
	s_waitcnt lgkmcnt(0)
	v_add_f32_e32 v112, v112, v113
	v_mul_f32_e32 v112, 0x4b800000, v112
	v_trunc_f32_e32 v112, v112
	v_mul_f32_e32 v113, 0x2f800000, v112
	v_floor_f32_e32 v113, v113
	v_fmac_f32_e32 v112, 0xcf800000, v113
	s_and_b64 s[4:5], s[88:89], exec
	v_cvt_u32_f32_e32 v112, v112
	v_cvt_u32_f32_e32 v113, v113
	s_cselect_b32 s4, s82, s80
	s_cselect_b32 s5, s81, s73
	v_mov_b32_e32 v122, s5
	v_mov_b32_e32 v123, s4
	v_lshl_add_u64 v[122:123], v[152:153], 3, v[122:123]
	global_atomic_add_x2 v[122:123], v[112:113], off offset:384

; __device__ __forceinline__ float shfl_x(float v, int m, int lane) { return __builtin_bit_cast(float, __builtin_amdgcn_ds_bpermute((lane ^ m) << 2, __builtin_bit_cast(int, v))); }
; __device__ __forceinline__ void ssq_put(ssq_t* p, int row, float q, int fr, int fq) {
;     const int lane = fr + 16 * fq;
;     q += shfl_x(q, 16, lane); q += shfl_x(q, 32, lane);
;     if (fq == 0) __hip_atomic_fetch_add(p + row, (ssq_t)(q * SSQ_FX), __ATOMIC_RELAXED, __HIP_MEMORY_SCOPE_AGENT);
; }
;     __device__ __forceinline__ void operator()(const f32x4 (&acc)[2][2][4][2], const Unit& u, int wr, int wc, int fr, int fq) const {
;     ...
;                     if (mode == 1 || mode == 2) {
;                         const float* tp = (mode == 1) ? (ropA + ((size_t)row * 32 + ((col0 & 63) >> 1)) * 2) : (ropB + ((size_t)row * 16 + ((col0 - PC_KR) >> 1)) * 2);
;                         const f32x4 c0 = *(const f32x4*)tp, c1 = *(const f32x4*)(tp + 4);
;                         f32x4 w0, w1;
;                         w0[0] = v0[0] * c0[0] - v0[1] * c0[1]; w0[1] = v0[1] * c0[0] + v0[0] * c0[1];
;                         w0[2] = v0[2] * c0[2] - v0[3] * c0[3]; w0[3] = v0[3] * c0[2] + v0[2] * c0[3];
;                         w1[0] = v1[0] * c1[0] - v1[1] * c1[1]; w1[1] = v1[1] * c1[0] + v1[0] * c1[1];
;                         w1[2] = v1[2] * c1[2] - v1[3] * c1[3]; w1[3] = v1[3] * c1[2] + v1[2] * c1[3];
;                         v0 = w0 * sc; v1 = w1 * sc;
;                     } else if (mode == 3) {
;                         const f32x2 a = gelu_pk((f32x2){v0[0], v0[1]}), bb = gelu_pk((f32x2){v0[2], v0[3]}), c = gelu_pk((f32x2){v1[0], v1[1]}), d = gelu_pk((f32x2){v1[2], v1[3]});
;                         v0 = (f32x4){a.x, a.y, bb.x, bb.y}; v1 = (f32x4){c.x, c.y, d.x, d.y};
;                     }
;                     if (stat) {
;                         const float q = (v0[0] * v0[0] + v0[1] * v0[1]) + (v0[2] * v0[2] + v0[3] * v0[3]) + (v1[0] * v1[0] + v1[1] * v1[1]) + (v1[2] * v1[2] + v1[3] * v1[3]);
;                         ssq_put(stat == 1 ? ssq_cq : ssq_ckv, row, q, fr, fq);
;                     }
.LBB0_491:
	global_load_dwordx4 v[168:171], v[106:107], off
	s_nop 0
	global_load_dwordx4 v[106:109], v[106:107], off offset:16
	s_waitcnt vmcnt(0) lgkmcnt(0)
	v_pk_mul_f32 v[124:125], v[116:117], v[168:169] op_sel:[1,1] op_sel_hi:[0,1]
	v_pk_fma_f32 v[130:131], v[116:117], v[168:169], v[124:125] op_sel_hi:[1,0,1] neg_lo:[0,0,1] neg_hi:[0,0,1]
	v_pk_fma_f32 v[116:117], v[116:117], v[168:169], v[124:125] op_sel_hi:[1,0,1]
	s_nop 0
	v_mov_b32_e32 v116, v171
	v_pk_mul_f32 v[124:125], v[114:115], v[116:117] op_sel:[1,0] op_sel_hi:[0,0]
	v_pk_fma_f32 v[140:141], v[114:115], v[170:171], v[124:125] op_sel_hi:[1,0,1] neg_lo:[0,0,1] neg_hi:[0,0,1]
	v_pk_fma_f32 v[114:115], v[114:115], v[170:171], v[124:125] op_sel_hi:[1,0,1]
	v_pk_mul_f32 v[124:125], v[122:123], v[106:107] op_sel:[1,1] op_sel_hi:[0,1]
	v_pk_fma_f32 v[164:165], v[122:123], v[106:107], v[124:125] op_sel_hi:[1,0,1] neg_lo:[0,0,1] neg_hi:[0,0,1]
	v_pk_fma_f32 v[122:123], v[122:123], v[106:107], v[124:125] op_sel_hi:[1,0,1]
	v_mov_b32_e32 v106, v109
	v_pk_mul_f32 v[106:107], v[104:105], v[106:107] op_sel:[1,0] op_sel_hi:[0,0]
	v_pk_fma_f32 v[124:125], v[104:105], v[108:109], v[106:107] op_sel_hi:[1,0,1] neg_lo:[0,0,1] neg_hi:[0,0,1]
	v_pk_fma_f32 v[104:105], v[104:105], v[108:109], v[106:107] op_sel_hi:[1,0,1]
	v_mov_b32_e32 v141, v115
	v_mov_b32_e32 v114, v136
	v_mov_b32_e32 v115, v136
	v_mov_b32_e32 v131, v117
	v_mov_b32_e32 v125, v105
	v_mov_b32_e32 v165, v123
	v_pk_mul_f32 v[108:109], v[114:115], v[140:141]
	v_pk_mul_f32 v[106:107], v[136:137], v[130:131]
	v_pk_mul_f32 v[130:131], v[114:115], v[124:125]
	v_pk_mul_f32 v[124:125], v[136:137], v[164:165]
	v_mov_b32_e32 v113, v112
	s_and_b64 vcc, exec, s[16:17]
	s_cbranch_vccnz .LBB0_495
.LBB0_492:
	v_mul_f32_e32 v104, v107, v107
	v_mul_f32_e32 v105, v109, v109
	v_fmac_f32_e32 v104, v106, v106
	v_fmac_f32_e32 v105, v108, v108
	v_add_f32_e32 v104, v104, v105
	v_mul_f32_e32 v105, v125, v125
	v_fmac_f32_e32 v105, v124, v124
	v_add_f32_e32 v104, v105, v104
	v_mul_f32_e32 v105, v131, v131
	v_fmac_f32_e32 v105, v130, v130
	v_add_f32_e32 v104, v105, v104
	ds_bpermute_b32 v105, v157, v104
	s_waitcnt lgkmcnt(0)
	v_add_f32_e32 v104, v104, v105
	ds_bpermute_b32 v105, v194, v104
	s_and_saveexec_b64 s[2:3], s[8:9]
	s_cbranch_execz .LBB0_494
	s_waitcnt lgkmcnt(0)
	v_add_f32_e32 v104, v104, v105
	v_mul_f32_e32 v104, 0x4b800000, v104
	v_trunc_f32_e32 v104, v104
	v_mul_f32_e32 v105, 0x2f800000, v104
	v_floor_f32_e32 v105, v105
	v_fmac_f32_e32 v104, 0xcf800000, v105
	s_and_b64 s[4:5], s[88:89], exec
	v_cvt_u32_f32_e32 v104, v104
	v_cvt_u32_f32_e32 v105, v105
	s_cselect_b32 s4, s82, s80
	s_cselect_b32 s5, s81, s73
	v_mov_b32_e32 v114, s5
	v_mov_b32_e32 v115, s4
	v_lshl_add_u64 v[114:115], v[152:153], 3, v[114:115]
	global_atomic_add_x2 v[114:115], v[104:105], off offset:1024

; __device__ __forceinline__ float shfl_x(float v, int m, int lane) { return __builtin_bit_cast(float, __builtin_amdgcn_ds_bpermute((lane ^ m) << 2, __builtin_bit_cast(int, v))); }
; __device__ __forceinline__ void ssq_put(ssq_t* p, int row, float q, int fr, int fq) {
;     const int lane = fr + 16 * fq;
;     q += shfl_x(q, 16, lane); q += shfl_x(q, 32, lane);
;     if (fq == 0) __hip_atomic_fetch_add(p + row, (ssq_t)(q * SSQ_FX), __ATOMIC_RELAXED, __HIP_MEMORY_SCOPE_AGENT);
; }
;     __device__ __forceinline__ void operator()(const f32x4 (&acc)[2][2][4][2], const Unit& u, int wr, int wc, int fr, int fq) const {
;     ...
;                     if (mode == 1 || mode == 2) {
;                         const float* tp = (mode == 1) ? (ropA + ((size_t)row * 32 + ((col0 & 63) >> 1)) * 2) : (ropB + ((size_t)row * 16 + ((col0 - PC_KR) >> 1)) * 2);
;                         const f32x4 c0 = *(const f32x4*)tp, c1 = *(const f32x4*)(tp + 4);
;                         f32x4 w0, w1;
;                         w0[0] = v0[0] * c0[0] - v0[1] * c0[1]; w0[1] = v0[1] * c0[0] + v0[0] * c0[1];
;                         w0[2] = v0[2] * c0[2] - v0[3] * c0[3]; w0[3] = v0[3] * c0[2] + v0[2] * c0[3];
;                         w1[0] = v1[0] * c1[0] - v1[1] * c1[1]; w1[1] = v1[1] * c1[0] + v1[0] * c1[1];
;                         w1[2] = v1[2] * c1[2] - v1[3] * c1[3]; w1[3] = v1[3] * c1[2] + v1[2] * c1[3];
;                         v0 = w0 * sc; v1 = w1 * sc;
;                     } else if (mode == 3) {
;                         const f32x2 a = gelu_pk((f32x2){v0[0], v0[1]}), bb = gelu_pk((f32x2){v0[2], v0[3]}), c = gelu_pk((f32x2){v1[0], v1[1]}), d = gelu_pk((f32x2){v1[2], v1[3]});
;                         v0 = (f32x4){a.x, a.y, bb.x, bb.y}; v1 = (f32x4){c.x, c.y, d.x, d.y};
;                     }
;                     if (stat) {
;                         const float q = (v0[0] * v0[0] + v0[1] * v0[1]) + (v0[2] * v0[2] + v0[3] * v0[3]) + (v1[0] * v1[0] + v1[1] * v1[1]) + (v1[2] * v1[2] + v1[3] * v1[3]);
;                         ssq_put(stat == 1 ? ssq_cq : ssq_ckv, row, q, fr, fq);
;                     }
.LBB0_505:
	global_load_dwordx4 v[162:165], v[98:99], off
	s_nop 0
	global_load_dwordx4 v[98:101], v[98:99], off offset:16
	s_waitcnt vmcnt(0) lgkmcnt(0)
	v_pk_mul_f32 v[116:117], v[108:109], v[162:163] op_sel:[1,1] op_sel_hi:[0,1]
	v_pk_fma_f32 v[122:123], v[108:109], v[162:163], v[116:117] op_sel_hi:[1,0,1] neg_lo:[0,0,1] neg_hi:[0,0,1]
	v_pk_fma_f32 v[108:109], v[108:109], v[162:163], v[116:117] op_sel_hi:[1,0,1]
	s_nop 0
	v_mov_b32_e32 v108, v165
	v_pk_mul_f32 v[116:117], v[106:107], v[108:109] op_sel:[1,0] op_sel_hi:[0,0]
	v_pk_fma_f32 v[130:131], v[106:107], v[164:165], v[116:117] op_sel_hi:[1,0,1] neg_lo:[0,0,1] neg_hi:[0,0,1]
	v_pk_fma_f32 v[106:107], v[106:107], v[164:165], v[116:117] op_sel_hi:[1,0,1]
	v_pk_mul_f32 v[116:117], v[114:115], v[98:99] op_sel:[1,1] op_sel_hi:[0,1]
	v_pk_fma_f32 v[140:141], v[114:115], v[98:99], v[116:117] op_sel_hi:[1,0,1] neg_lo:[0,0,1] neg_hi:[0,0,1]
	v_pk_fma_f32 v[114:115], v[114:115], v[98:99], v[116:117] op_sel_hi:[1,0,1]
	v_mov_b32_e32 v98, v101
	v_pk_mul_f32 v[98:99], v[96:97], v[98:99] op_sel:[1,0] op_sel_hi:[0,0]
	v_pk_fma_f32 v[116:117], v[96:97], v[100:101], v[98:99] op_sel_hi:[1,0,1] neg_lo:[0,0,1] neg_hi:[0,0,1]
	v_pk_fma_f32 v[96:97], v[96:97], v[100:101], v[98:99] op_sel_hi:[1,0,1]
	v_mov_b32_e32 v131, v107
	v_mov_b32_e32 v106, v136
	v_mov_b32_e32 v107, v136
	v_mov_b32_e32 v123, v109
	v_mov_b32_e32 v117, v97
	v_mov_b32_e32 v141, v115
	v_pk_mul_f32 v[100:101], v[106:107], v[130:131]
	v_pk_mul_f32 v[98:99], v[136:137], v[122:123]
	v_pk_mul_f32 v[122:123], v[106:107], v[116:117]
	v_pk_mul_f32 v[116:117], v[136:137], v[140:141]
	v_mov_b32_e32 v105, v104
	s_and_b64 vcc, exec, s[16:17]
	s_cbranch_vccnz .LBB0_509
.LBB0_506:
	v_mul_f32_e32 v96, v99, v99
	v_mul_f32_e32 v97, v101, v101
	v_fmac_f32_e32 v96, v98, v98
	v_fmac_f32_e32 v97, v100, v100
	v_add_f32_e32 v96, v96, v97
	v_mul_f32_e32 v97, v117, v117
	v_fmac_f32_e32 v97, v116, v116
	v_add_f32_e32 v96, v97, v96
	v_mul_f32_e32 v97, v123, v123
	v_fmac_f32_e32 v97, v122, v122
	v_add_f32_e32 v96, v97, v96
	ds_bpermute_b32 v97, v157, v96
	s_waitcnt lgkmcnt(0)
	v_add_f32_e32 v96, v96, v97
	ds_bpermute_b32 v97, v194, v96
	s_and_saveexec_b64 s[2:3], s[8:9]
	s_cbranch_execz .LBB0_508
	s_waitcnt lgkmcnt(0)
	v_add_f32_e32 v96, v96, v97
	v_mul_f32_e32 v96, 0x4b800000, v96
	v_trunc_f32_e32 v96, v96
	v_mul_f32_e32 v97, 0x2f800000, v96
	v_floor_f32_e32 v97, v97
	v_fmac_f32_e32 v96, 0xcf800000, v97
	s_and_b64 s[4:5], s[88:89], exec
	v_cvt_u32_f32_e32 v96, v96
	v_cvt_u32_f32_e32 v97, v97
	s_cselect_b32 s4, s82, s80
	s_cselect_b32 s5, s81, s73
	v_mov_b32_e32 v106, s5
	v_mov_b32_e32 v107, s4
	v_lshl_add_u64 v[106:107], v[152:153], 3, v[106:107]
	global_atomic_add_x2 v[106:107], v[96:97], off offset:1152

; __device__ __forceinline__ float shfl_x(float v, int m, int lane) { return __builtin_bit_cast(float, __builtin_amdgcn_ds_bpermute((lane ^ m) << 2, __builtin_bit_cast(int, v))); }
; __device__ __forceinline__ void ssq_put(ssq_t* p, int row, float q, int fr, int fq) {
;     const int lane = fr + 16 * fq;
;     q += shfl_x(q, 16, lane); q += shfl_x(q, 32, lane);
;     if (fq == 0) __hip_atomic_fetch_add(p + row, (ssq_t)(q * SSQ_FX), __ATOMIC_RELAXED, __HIP_MEMORY_SCOPE_AGENT);
; }
;     __device__ __forceinline__ void operator()(const f32x4 (&acc)[2][2][4][2], const Unit& u, int wr, int wc, int fr, int fq) const {
;     ...
;                     if (mode == 1 || mode == 2) {
;                         const float* tp = (mode == 1) ? (ropA + ((size_t)row * 32 + ((col0 & 63) >> 1)) * 2) : (ropB + ((size_t)row * 16 + ((col0 - PC_KR) >> 1)) * 2);
;                         const f32x4 c0 = *(const f32x4*)tp, c1 = *(const f32x4*)(tp + 4);
;                         f32x4 w0, w1;
;                         w0[0] = v0[0] * c0[0] - v0[1] * c0[1]; w0[1] = v0[1] * c0[0] + v0[0] * c0[1];
;                         w0[2] = v0[2] * c0[2] - v0[3] * c0[3]; w0[3] = v0[3] * c0[2] + v0[2] * c0[3];
;                         w1[0] = v1[0] * c1[0] - v1[1] * c1[1]; w1[1] = v1[1] * c1[0] + v1[0] * c1[1];
;                         w1[2] = v1[2] * c1[2] - v1[3] * c1[3]; w1[3] = v1[3] * c1[2] + v1[2] * c1[3];
;                         v0 = w0 * sc; v1 = w1 * sc;
;                     } else if (mode == 3) {
;                         const f32x2 a = gelu_pk((f32x2){v0[0], v0[1]}), bb = gelu_pk((f32x2){v0[2], v0[3]}), c = gelu_pk((f32x2){v1[0], v1[1]}), d = gelu_pk((f32x2){v1[2], v1[3]});
;                         v0 = (f32x4){a.x, a.y, bb.x, bb.y}; v1 = (f32x4){c.x, c.y, d.x, d.y};
;                     }
;                     if (stat) {
;                         const float q = (v0[0] * v0[0] + v0[1] * v0[1]) + (v0[2] * v0[2] + v0[3] * v0[3]) + (v1[0] * v1[0] + v1[1] * v1[1]) + (v1[2] * v1[2] + v1[3] * v1[3]);
;                         ssq_put(stat == 1 ? ssq_cq : ssq_ckv, row, q, fr, fq);
;                     }
.LBB0_519:
	global_load_dwordx4 v[160:163], v[80:81], off
	global_load_dwordx4 v[168:171], v[80:81], off offset:16
	s_waitcnt vmcnt(0) lgkmcnt(0)
	v_pk_mul_f32 v[80:81], v[100:101], v[160:161] op_sel:[1,1] op_sel_hi:[0,1]
	v_pk_fma_f32 v[108:109], v[100:101], v[160:161], v[80:81] op_sel_hi:[1,0,1] neg_lo:[0,0,1] neg_hi:[0,0,1]
	v_pk_fma_f32 v[80:81], v[100:101], v[160:161], v[80:81] op_sel_hi:[1,0,1]
	s_nop 0
	v_mov_b32_e32 v80, v163
	v_pk_mul_f32 v[84:85], v[98:99], v[80:81] op_sel:[1,0] op_sel_hi:[0,0]
	v_pk_fma_f32 v[100:101], v[98:99], v[162:163], v[84:85] op_sel_hi:[1,0,1] neg_lo:[0,0,1] neg_hi:[0,0,1]
	v_pk_fma_f32 v[84:85], v[98:99], v[162:163], v[84:85] op_sel_hi:[1,0,1]
	v_pk_mul_f32 v[98:99], v[106:107], v[168:169] op_sel:[1,1] op_sel_hi:[0,1]
	v_mov_b32_e32 v80, v171
	v_pk_fma_f32 v[122:123], v[106:107], v[168:169], v[98:99] op_sel_hi:[1,0,1] neg_lo:[0,0,1] neg_hi:[0,0,1]
	v_pk_fma_f32 v[98:99], v[106:107], v[168:169], v[98:99] op_sel_hi:[1,0,1]
	v_pk_mul_f32 v[106:107], v[82:83], v[80:81] op_sel:[1,0] op_sel_hi:[0,0]
	v_pk_fma_f32 v[114:115], v[82:83], v[170:171], v[106:107] op_sel_hi:[1,0,1] neg_lo:[0,0,1] neg_hi:[0,0,1]
	v_pk_fma_f32 v[82:83], v[82:83], v[170:171], v[106:107] op_sel_hi:[1,0,1]
	v_mov_b32_e32 v101, v85
	v_mov_b32_e32 v106, v136
	v_mov_b32_e32 v107, v136
	v_mov_b32_e32 v109, v81
	v_mov_b32_e32 v115, v83
	v_mov_b32_e32 v123, v99
	v_pk_mul_f32 v[84:85], v[106:107], v[100:101]
	v_pk_mul_f32 v[80:81], v[136:137], v[108:109]
	v_pk_mul_f32 v[114:115], v[106:107], v[114:115]
	v_pk_mul_f32 v[108:109], v[136:137], v[122:123]
	v_mov_b32_e32 v97, v96
	s_and_b64 vcc, exec, s[16:17]
	s_cbranch_vccnz .LBB0_523
.LBB0_520:
	v_mul_f32_e32 v82, v81, v81
	v_mul_f32_e32 v83, v85, v85
	v_fmac_f32_e32 v82, v80, v80
	v_fmac_f32_e32 v83, v84, v84
	v_add_f32_e32 v82, v82, v83
	v_mul_f32_e32 v83, v109, v109
	v_fmac_f32_e32 v83, v108, v108
	v_add_f32_e32 v82, v83, v82
	v_mul_f32_e32 v83, v115, v115
	v_fmac_f32_e32 v83, v114, v114
	v_add_f32_e32 v82, v83, v82
	ds_bpermute_b32 v83, v157, v82
	s_waitcnt lgkmcnt(0)
	v_add_f32_e32 v82, v82, v83
	ds_bpermute_b32 v83, v194, v82
	s_and_saveexec_b64 s[2:3], s[8:9]
	s_cbranch_execz .LBB0_522
	s_waitcnt lgkmcnt(0)
	v_add_f32_e32 v82, v82, v83
	v_mul_f32_e32 v82, 0x4b800000, v82
	v_trunc_f32_e32 v82, v82
	v_mul_f32_e32 v83, 0x2f800000, v82
	v_floor_f32_e32 v83, v83
	v_fmac_f32_e32 v82, 0xcf800000, v83
	s_and_b64 s[4:5], s[88:89], exec
	v_cvt_u32_f32_e32 v82, v82
	v_cvt_u32_f32_e32 v83, v83
	s_cselect_b32 s4, s82, s80
	s_cselect_b32 s5, s81, s73
	v_mov_b32_e32 v98, s5
	v_mov_b32_e32 v99, s4
	v_lshl_add_u64 v[98:99], v[152:153], 3, v[98:99]
	global_atomic_add_x2 v[98:99], v[82:83], off offset:1280

;     __device__ __forceinline__ void operator()(const f32x4 (&acc)[2][2][4][2], const Unit& u, int wr, int wc, int fr, int fq) const {
;     ...
;                         const float* tp = (mode == 1) ? (ropA + ((size_t)row * 32 + ((col0 & 63) >> 1)) * 2) : (ropB + ((size_t)row * 16 + ((col0 - PC_KR) >> 1)) * 2);
;                         const f32x4 c0 = *(const f32x4*)tp, c1 = *(const f32x4*)(tp + 4);
;                         f32x4 w0, w1;
;                         w0[0] = v0[0] * c0[0] - v0[1] * c0[1]; w0[1] = v0[1] * c0[0] + v0[0] * c0[1];
;                         w0[2] = v0[2] * c0[2] - v0[3] * c0[3]; w0[3] = v0[3] * c0[2] + v0[2] * c0[3];
;                         w1[0] = v1[0] * c1[0] - v1[1] * c1[1]; w1[1] = v1[1] * c1[0] + v1[0] * c1[1];
;                         w1[2] = v1[2] * c1[2] - v1[3] * c1[3]; w1[3] = v1[3] * c1[2] + v1[2] * c1[3];
;                         v0 = w0 * sc; v1 = w1 * sc;
;                     } else if (mode == 3) {
;                         const f32x2 a = gelu_pk((f32x2){v0[0], v0[1]}), bb = gelu_pk((f32x2){v0[2], v0[3]}), c = gelu_pk((f32x2){v1[0], v1[1]}), d = gelu_pk((f32x2){v1[2], v1[3]});
;                         v0 = (f32x4){a.x, a.y, bb.x, bb.y}; v1 = (f32x4){c.x, c.y, d.x, d.y};
;                     }
;                     if (stat) {
;                         const float q = (v0[0] * v0[0] + v0[1] * v0[1]) + (v0[2] * v0[2] + v0[3] * v0[3]) + (v1[0] * v1[0] + v1[1] * v1[1]) + (v1[2] * v1[2] + v1[3] * v1[3]);
;                         ssq_put(stat == 1 ? ssq_cq : ssq_ckv, row, q, fr, fq);
.LBB0_533:
	global_load_dwordx4 v[88:91], v[70:71], off
	s_nop 0
	global_load_dwordx4 v[70:73], v[70:71], off offset:16
	s_waitcnt vmcnt(0) lgkmcnt(0)
	v_pk_mul_f32 v[92:93], v[84:85], v[88:89] op_sel:[1,1] op_sel_hi:[0,1]
	v_pk_fma_f32 v[98:99], v[84:85], v[88:89], v[92:93] op_sel_hi:[1,0,1] neg_lo:[0,0,1] neg_hi:[0,0,1]
	v_pk_fma_f32 v[84:85], v[84:85], v[88:89], v[92:93] op_sel_hi:[1,0,1]
	s_nop 0
	v_mov_b32_e32 v84, v91
	v_pk_mul_f32 v[88:89], v[76:77], v[84:85] op_sel:[1,0] op_sel_hi:[0,0]
	v_pk_fma_f32 v[92:93], v[76:77], v[90:91], v[88:89] op_sel_hi:[1,0,1] neg_lo:[0,0,1] neg_hi:[0,0,1]
	v_pk_fma_f32 v[76:77], v[76:77], v[90:91], v[88:89] op_sel_hi:[1,0,1]
	v_pk_mul_f32 v[88:89], v[86:87], v[70:71] op_sel:[1,1] op_sel_hi:[0,1]
	v_pk_fma_f32 v[106:107], v[86:87], v[70:71], v[88:89] op_sel_hi:[1,0,1] neg_lo:[0,0,1] neg_hi:[0,0,1]
	v_pk_fma_f32 v[86:87], v[86:87], v[70:71], v[88:89] op_sel_hi:[1,0,1]
	v_mov_b32_e32 v70, v73
	v_pk_mul_f32 v[70:71], v[74:75], v[70:71] op_sel:[1,0] op_sel_hi:[0,0]
	v_pk_fma_f32 v[88:89], v[74:75], v[72:73], v[70:71] op_sel_hi:[1,0,1] neg_lo:[0,0,1] neg_hi:[0,0,1]
	v_pk_fma_f32 v[74:75], v[74:75], v[72:73], v[70:71] op_sel_hi:[1,0,1]
	v_mov_b32_e32 v93, v77
	v_mov_b32_e32 v76, v136
	v_mov_b32_e32 v77, v136
	v_mov_b32_e32 v99, v85
	v_mov_b32_e32 v89, v75
	v_mov_b32_e32 v107, v87
	v_pk_mul_f32 v[72:73], v[76:77], v[92:93]
	v_pk_mul_f32 v[70:71], v[136:137], v[98:99]
	v_pk_mul_f32 v[90:91], v[76:77], v[88:89]
	v_pk_mul_f32 v[88:89], v[136:137], v[106:107]
	v_mov_b32_e32 v83, v82
	s_and_b64 vcc, exec, s[16:17]
	s_cbranch_vccnz .LBB0_537
.LBB0_534:
	v_mul_f32_e32 v74, v71, v71
	v_mul_f32_e32 v75, v73, v73
	v_fmac_f32_e32 v74, v70, v70
	v_fmac_f32_e32 v75, v72, v72
	v_add_f32_e32 v74, v74, v75
	v_mul_f32_e32 v75, v89, v89
	v_fmac_f32_e32 v75, v88, v88
	v_add_f32_e32 v74, v75, v74
	v_mul_f32_e32 v75, v91, v91
	v_fmac_f32_e32 v75, v90, v90
	v_add_f32_e32 v74, v75, v74
	ds_bpermute_b32 v75, v157, v74
	s_waitcnt lgkmcnt(0)
	v_add_f32_e32 v74, v74, v75
	ds_bpermute_b32 v75, v194, v74
	s_and_saveexec_b64 s[2:3], s[8:9]
	s_cbranch_execz .LBB0_536
	s_waitcnt lgkmcnt(0)
	v_add_f32_e32 v74, v74, v75
	v_mul_f32_e32 v74, 0x4b800000, v74
	v_trunc_f32_e32 v74, v74
	v_mul_f32_e32 v75, 0x2f800000, v74
	v_floor_f32_e32 v75, v75
	v_fmac_f32_e32 v74, 0xcf800000, v75
	s_and_b64 s[4:5], s[88:89], exec
	v_cvt_u32_f32_e32 v74, v74
	v_cvt_u32_f32_e32 v75, v75
	s_cselect_b32 s4, s82, s80
	s_cselect_b32 s5, s81, s73
	v_mov_b32_e32 v76, s5
	v_mov_b32_e32 v77, s4
	v_lshl_add_u64 v[76:77], v[152:153], 3, v[76:77]
	global_atomic_add_x2 v[76:77], v[74:75], off offset:1408

;     __device__ __forceinline__ void operator()(const f32x4 (&acc)[2][2][4][2], const Unit& u, int wr, int wc, int fr, int fq) const {
;     ...
;             const int colw = u.pn * BM + bj * HALF + wc * 32, col0 = colw + 8 * fq;
;             const int mode = colw < 512 ? 1 : (colw < 640 ? 0 : (colw < 672 ? 2 : (colw < 1536 ? 0 : 3)));
;             const int stat = (colw >= PC_CQ && colw < PC_CKV) ? 1 : ((colw >= PC_CKV && colw < PC_CKV + 256) ? 2 : 0);
;             const float sc = colw < 384 ? QS_A : 1.f;
;             const f32x4 s0 = *(const f32x4*)(shw + (size_t)b * 7680 + col0), s1 = *(const f32x4*)(shw + (size_t)b * 7680 + col0 + 4);
; #pragma unroll
;             for (int ai = 0; ai < 2; ++ai)
; #pragma unroll
;                 for (int m = 0; m < 4; ++m) {
;                     const int row = row0 + ai * HALF + m * 16;
;                     const float rs = rsv[ai * 4 + m];
;                     f32x4 v0 = acc[ai][bj][m][0] * rs + s0, v1 = acc[ai][bj][m][1] * rs + s1;
;                     if (mode == 1 || mode == 2) {
;                         const float* tp = (mode == 1) ? (ropA + ((size_t)row * 32 + ((col0 & 63) >> 1)) * 2) : (ropB + ((size_t)row * 16 + ((col0 - PC_KR) >> 1)) * 2);
;                         const f32x4 c0 = *(const f32x4*)tp, c1 = *(const f32x4*)(tp + 4);
;                         f32x4 w0, w1;
;                         w0[0] = v0[0] * c0[0] - v0[1] * c0[1]; w0[1] = v0[1] * c0[0] + v0[0] * c0[1];
;                         w0[2] = v0[2] * c0[2] - v0[3] * c0[3]; w0[3] = v0[3] * c0[2] + v0[2] * c0[3];
;                         w1[0] = v1[0] * c1[0] - v1[1] * c1[1]; w1[1] = v1[1] * c1[0] + v1[0] * c1[1];
;                         w1[2] = v1[2] * c1[2] - v1[3] * c1[3]; w1[3] = v1[3] * c1[2] + v1[2] * c1[3];
;                         v0 = w0 * sc; v1 = w1 * sc;
;                     } else if (mode == 3) {
;                         const f32x2 a = gelu_pk((f32x2){v0[0], v0[1]}), bb = gelu_pk((f32x2){v0[2], v0[3]}), c = gelu_pk((f32x2){v1[0], v1[1]}), d = gelu_pk((f32x2){v1[2], v1[3]});
;                         v0 = (f32x4){a.x, a.y, bb.x, bb.y}; v1 = (f32x4){c.x, c.y, d.x, d.y};
.LBB0_537:
	s_or_b32 s3, s35, 0x80
	s_or_b32 s2, s3, s66
	s_cmpk_gt_u32 s2, 0x29f
	s_cselect_b32 s4, s37, 2
	s_cmpk_gt_u32 s3, 0x27f
	s_cselect_b32 s3, s4, 0
	s_cmpk_gt_i32 s2, 0x1ff
	s_cselect_b64 s[14:15], -1, 0
	s_and_b64 s[4:5], s[14:15], exec
	s_cselect_b32 s3, s3, 1
	s_cmpk_lt_i32 s2, 0x180
	s_cselect_b64 s[12:13], -1, 0
	s_ashr_i32 s5, s35, 31
	v_add_u32_e32 v101, 0x8400, v100
	s_add_u32 s4, s35, s66
	v_cvt_pk_bf16_f32 v70, v70, v71
	v_cvt_pk_bf16_f32 v71, v72, v73
	v_add_lshl_u32 v74, v101, v156, 1
	s_addc_u32 s5, s5, 0
	v_cvt_pk_bf16_f32 v72, v88, v89
	v_cvt_pk_bf16_f32 v73, v90, v91
	global_store_dwordx4 v74, v[70:73], s[22:23]
	v_mov_b32_e32 v84, v154
	v_mov_b32_e32 v85, v154
	v_lshl_add_u64 v[70:71], v[0:1], 0, s[4:5]
	v_lshl_add_u64 v[70:71], v[70:71], 2, s[86:87]
	s_waitcnt lgkmcnt(0)
	global_load_dwordx4 v[74:77], v[70:71], off offset:512
	s_nop 0
	global_load_dwordx4 v[70:73], v[70:71], off offset:528
	s_add_i32 s4, s3, -1
	s_cmp_gt_u32 s4, 1
	s_cselect_b64 s[16:17], -1, 0
	s_cmp_eq_u32 s3, 3
	s_cselect_b64 s[10:11], -1, 0
	s_cmp_lt_u32 s4, 2
	s_mov_b64 s[4:5], -1
	s_waitcnt vmcnt(0) lgkmcnt(0)
	v_pk_fma_f32 v[68:69], v[68:69], v[84:85], v[76:77]
	v_pk_fma_f32 v[86:87], v[66:67], v[154:155], v[74:75]
	v_pk_fma_f32 v[66:67], v[64:65], v[84:85], v[72:73]
	v_pk_fma_f32 v[84:85], v[62:63], v[154:155], v[70:71]
	v_cndmask_b32_e64 v62, 0, 1, s[10:11]
	v_cmp_ne_u32_e64 s[10:11], 1, v62
	s_cbranch_scc1 .LBB0_541
	s_and_b64 vcc, exec, s[10:11]
	v_mov_b32_e32 v91, v69
	v_mov_b32_e32 v90, v68
	v_mov_b32_e32 v89, v87
	v_mov_b32_e32 v88, v86
	v_mov_b32_e32 v99, v67
	v_mov_b32_e32 v98, v66
	v_mov_b32_e32 v93, v85
	v_mov_b32_e32 v92, v84
	s_cbranch_vccnz .LBB0_540
	v_and_b32_e32 v63, 0x7fffffff, v87
	v_and_b32_e32 v62, 0x7fffffff, v86
	v_pk_fma_f32 v[62:63], v[62:63], s[62:63], 1.0 op_sel_hi:[1,0,0]
	s_mov_b32 s4, 0xbf3a00e3
	v_rcp_f32_e32 v62, v62
	v_rcp_f32_e32 v63, v63
	v_mov_b64_e32 v[64:65], s[4:5]
	v_cmp_gt_f32_e32 vcc, 0, v86
	v_pk_mul_f32 v[90:91], v[68:69], v[68:69]
	v_pk_fma_f32 v[88:89], v[62:63], s[64:65], v[64:65] op_sel_hi:[1,0,0]
	v_pk_mul_f32 v[90:91], v[90:91], s[74:75] op_sel_hi:[1,0]
	v_pk_fma_f32 v[88:89], v[62:63], v[88:89], s[68:69] op_sel_hi:[1,1,0]
	v_exp_f32_e32 v90, v90
	v_pk_fma_f32 v[88:89], v[62:63], v[88:89], s[70:71] op_sel_hi:[1,1,0]
	v_exp_f32_e32 v91, v91
	v_pk_fma_f32 v[88:89], v[62:63], v[88:89], s[72:73] op_sel_hi:[1,1,0]
	v_pk_mul_f32 v[98:99], v[66:67], v[66:67]
	v_pk_mul_f32 v[62:63], v[62:63], v[88:89]
	v_pk_mul_f32 v[88:89], v[86:87], v[86:87]
	s_nop 0
	v_pk_mul_f32 v[88:89], v[88:89], s[74:75] op_sel_hi:[1,0]
	s_nop 0
	v_exp_f32_e32 v88, v88
	v_exp_f32_e32 v89, v89
	s_nop 0
	v_pk_mul_f32 v[62:63], v[88:89], v[62:63]
	s_nop 0
	v_pk_mul_f32 v[88:89], v[86:87], v[62:63]
	v_pk_fma_f32 v[62:63], v[86:87], v[62:63], v[86:87] neg_lo:[1,0,0] neg_hi:[1,0,0]
	s_nop 0
	v_cndmask_b32_e32 v88, v62, v88, vcc
	v_cmp_gt_f32_e32 vcc, 0, v87
	v_and_b32_e32 v62, 0x7fffffff, v68
	s_nop 0
	v_cndmask_b32_e32 v89, v63, v89, vcc
	v_and_b32_e32 v63, 0x7fffffff, v69
	v_pk_fma_f32 v[62:63], v[62:63], s[62:63], 1.0 op_sel_hi:[1,0,0]
	v_cmp_gt_f32_e32 vcc, 0, v68
	v_rcp_f32_e32 v62, v62
	v_rcp_f32_e32 v63, v63
	s_nop 0
	v_pk_fma_f32 v[92:93], v[62:63], s[64:65], v[64:65] op_sel_hi:[1,0,0]
	s_nop 0
	v_pk_fma_f32 v[92:93], v[62:63], v[92:93], s[68:69] op_sel_hi:[1,1,0]
	s_nop 0
	v_pk_fma_f32 v[92:93], v[62:63], v[92:93], s[70:71] op_sel_hi:[1,1,0]
	s_nop 0
	v_pk_fma_f32 v[92:93], v[62:63], v[92:93], s[72:73] op_sel_hi:[1,1,0]
	s_nop 0
	v_pk_mul_f32 v[62:63], v[62:63], v[92:93]
	s_nop 0
	v_pk_mul_f32 v[62:63], v[90:91], v[62:63]
	s_nop 0
	v_pk_mul_f32 v[90:91], v[68:69], v[62:63]
	v_pk_fma_f32 v[62:63], v[68:69], v[62:63], v[68:69] neg_lo:[1,0,0] neg_hi:[1,0,0]
	s_nop 0
	v_cndmask_b32_e32 v90, v62, v90, vcc
	v_cmp_gt_f32_e32 vcc, 0, v69
	v_and_b32_e32 v62, 0x7fffffff, v84
	s_nop 0
	v_cndmask_b32_e32 v91, v63, v91, vcc
	v_and_b32_e32 v63, 0x7fffffff, v85
	v_pk_fma_f32 v[62:63], v[62:63], s[62:63], 1.0 op_sel_hi:[1,0,0]
	v_cmp_gt_f32_e32 vcc, 0, v84
	v_rcp_f32_e32 v62, v62
	v_rcp_f32_e32 v63, v63
	s_nop 0
	v_pk_fma_f32 v[92:93], v[62:63], s[64:65], v[64:65] op_sel_hi:[1,0,0]
	s_nop 0
	v_pk_fma_f32 v[92:93], v[62:63], v[92:93], s[68:69] op_sel_hi:[1,1,0]
	s_nop 0
	v_pk_fma_f32 v[92:93], v[62:63], v[92:93], s[70:71] op_sel_hi:[1,1,0]
	s_nop 0
	v_pk_fma_f32 v[92:93], v[62:63], v[92:93], s[72:73] op_sel_hi:[1,1,0]
	s_nop 0
	v_pk_mul_f32 v[62:63], v[62:63], v[92:93]
	v_pk_mul_f32 v[92:93], v[84:85], v[84:85]
	s_nop 0
	v_pk_mul_f32 v[92:93], v[92:93], s[74:75] op_sel_hi:[1,0]
	s_nop 0
	v_exp_f32_e32 v92, v92
	v_exp_f32_e32 v93, v93
	s_nop 0
	v_pk_mul_f32 v[62:63], v[92:93], v[62:63]
	s_nop 0
	v_pk_mul_f32 v[92:93], v[84:85], v[62:63]
	v_pk_fma_f32 v[62:63], v[84:85], v[62:63], v[84:85] neg_lo:[1,0,0] neg_hi:[1,0,0]
	s_nop 0
	v_cndmask_b32_e32 v92, v62, v92, vcc
	v_cmp_gt_f32_e32 vcc, 0, v85
	v_and_b32_e32 v62, 0x7fffffff, v66
	s_nop 0
	v_cndmask_b32_e32 v93, v63, v93, vcc
	v_and_b32_e32 v63, 0x7fffffff, v67
	v_pk_fma_f32 v[62:63], v[62:63], s[62:63], 1.0 op_sel_hi:[1,0,0]
	v_cmp_gt_f32_e32 vcc, 0, v66
	v_rcp_f32_e32 v62, v62
	v_rcp_f32_e32 v63, v63
	s_nop 0
	v_pk_fma_f32 v[64:65], v[62:63], s[64:65], v[64:65] op_sel_hi:[1,0,0]
	s_nop 0
	v_pk_fma_f32 v[64:65], v[62:63], v[64:65], s[68:69] op_sel_hi:[1,1,0]
	s_nop 0
	v_pk_fma_f32 v[64:65], v[62:63], v[64:65], s[70:71] op_sel_hi:[1,1,0]
	s_nop 0
	v_pk_fma_f32 v[64:65], v[62:63], v[64:65], s[72:73] op_sel_hi:[1,1,0]
	s_nop 0
	v_pk_mul_f32 v[62:63], v[62:63], v[64:65]
	v_pk_mul_f32 v[64:65], v[98:99], s[74:75] op_sel_hi:[1,0]
	s_nop 0
	v_exp_f32_e32 v64, v64
	v_exp_f32_e32 v65, v65
	s_nop 0
	v_pk_mul_f32 v[62:63], v[64:65], v[62:63]
	s_nop 0
	v_pk_mul_f32 v[64:65], v[66:67], v[62:63]
	v_pk_fma_f32 v[62:63], v[66:67], v[62:63], v[66:67] neg_lo:[1,0,0] neg_hi:[1,0,0]
	s_nop 0
	v_cndmask_b32_e32 v98, v62, v64, vcc
	v_cmp_gt_f32_e32 vcc, 0, v67
	s_nop 1
	v_cndmask_b32_e32 v99, v63, v65, vcc

;     __device__ __forceinline__ void operator()(const f32x4 (&acc)[2][2][4][2], const Unit& u, int wr, int wc, int fr, int fq) const {
;     ...
;                         const float* tp = (mode == 1) ? (ropA + ((size_t)row * 32 + ((col0 & 63) >> 1)) * 2) : (ropB + ((size_t)row * 16 + ((col0 - PC_KR) >> 1)) * 2);
;                         const f32x4 c0 = *(const f32x4*)tp, c1 = *(const f32x4*)(tp + 4);
;                         f32x4 w0, w1;
;                         w0[0] = v0[0] * c0[0] - v0[1] * c0[1]; w0[1] = v0[1] * c0[0] + v0[0] * c0[1];
;                         w0[2] = v0[2] * c0[2] - v0[3] * c0[3]; w0[3] = v0[3] * c0[2] + v0[2] * c0[3];
;                         w1[0] = v1[0] * c1[0] - v1[1] * c1[1]; w1[1] = v1[1] * c1[0] + v1[0] * c1[1];
;                         w1[2] = v1[2] * c1[2] - v1[3] * c1[3]; w1[3] = v1[3] * c1[2] + v1[2] * c1[3];
;                         v0 = w0 * sc; v1 = w1 * sc;
;                     } else if (mode == 3) {
;                         const f32x2 a = gelu_pk((f32x2){v0[0], v0[1]}), bb = gelu_pk((f32x2){v0[2], v0[3]}), c = gelu_pk((f32x2){v1[0], v1[1]}), d = gelu_pk((f32x2){v1[2], v1[3]});
;                         v0 = (f32x4){a.x, a.y, bb.x, bb.y}; v1 = (f32x4){c.x, c.y, d.x, d.y};
;                     }
;                     if (stat) {
;                         const float q = (v0[0] * v0[0] + v0[1] * v0[1]) + (v0[2] * v0[2] + v0[3] * v0[3]) + (v1[0] * v1[0] + v1[1] * v1[1]) + (v1[2] * v1[2] + v1[3] * v1[3]);
;                         ssq_put(stat == 1 ? ssq_cq : ssq_ckv, row, q, fr, fq);
.LBB0_546:
	global_load_dwordx4 v[90:93], v[88:89], off
	global_load_dwordx4 v[136:139], v[88:89], off offset:16
	s_waitcnt vmcnt(0) lgkmcnt(0)
	v_pk_mul_f32 v[88:89], v[86:87], v[90:91] op_sel:[1,1] op_sel_hi:[0,1]
	v_mov_b32_e32 v0, v93
	v_pk_fma_f32 v[98:99], v[86:87], v[90:91], v[88:89] op_sel_hi:[1,0,1] neg_lo:[0,0,1] neg_hi:[0,0,1]
	v_pk_fma_f32 v[86:87], v[86:87], v[90:91], v[88:89] op_sel_hi:[1,0,1]
	v_pk_mul_f32 v[88:89], v[68:69], v[0:1] op_sel:[1,0] op_sel_hi:[0,0]
	v_pk_fma_f32 v[90:91], v[68:69], v[92:93], v[88:89] op_sel_hi:[1,0,1] neg_lo:[0,0,1] neg_hi:[0,0,1]
	v_pk_fma_f32 v[68:69], v[68:69], v[92:93], v[88:89] op_sel_hi:[1,0,1]
	v_pk_mul_f32 v[88:89], v[84:85], v[136:137] op_sel:[1,1] op_sel_hi:[0,1]
	v_mov_b32_e32 v0, v139
	v_pk_fma_f32 v[92:93], v[84:85], v[136:137], v[88:89] op_sel_hi:[1,0,1] neg_lo:[0,0,1] neg_hi:[0,0,1]
	v_pk_fma_f32 v[84:85], v[84:85], v[136:137], v[88:89] op_sel_hi:[1,0,1]
	v_pk_mul_f32 v[88:89], v[66:67], v[0:1] op_sel:[1,0] op_sel_hi:[0,0]
	v_pk_fma_f32 v[108:109], v[66:67], v[138:139], v[88:89] op_sel_hi:[1,0,1] neg_lo:[0,0,1] neg_hi:[0,0,1]
	v_pk_fma_f32 v[66:67], v[66:67], v[138:139], v[88:89] op_sel_hi:[1,0,1]
	v_mov_b32_e32 v91, v69
	v_mov_b32_e32 v68, v62
	v_mov_b32_e32 v69, v62
	v_mov_b32_e32 v99, v87
	v_mov_b32_e32 v109, v67
	v_mov_b32_e32 v93, v85
	v_pk_mul_f32 v[90:91], v[68:69], v[90:91]
	v_pk_mul_f32 v[88:89], v[62:63], v[98:99]
	v_pk_mul_f32 v[98:99], v[68:69], v[108:109]
	v_pk_mul_f32 v[92:93], v[62:63], v[92:93]
.LBB0_547:
	s_add_i32 s2, s35, 0xfffffc00
	s_cmp_lt_u32 s2, 0xfffffe80
	s_cselect_b64 s[18:19], -1, 0
	s_addk_i32 s35, 0xfb00
	s_cmp_gt_u32 s35, 0xfffffd7f
	s_cselect_b64 s[40:41], -1, 0
	s_cmp_lt_u32 s35, 0xfffffd80
	s_cbranch_scc1 .LBB0_551
	v_mul_f32_e32 v0, v89, v89
	v_mul_f32_e32 v66, v91, v91
	v_fmac_f32_e32 v0, v88, v88
	v_fmac_f32_e32 v66, v90, v90
	v_add_f32_e32 v0, v0, v66
	v_mul_f32_e32 v66, v93, v93
	v_fmac_f32_e32 v66, v92, v92
	v_add_f32_e32 v0, v66, v0
	v_mul_f32_e32 v66, v99, v99
	v_fmac_f32_e32 v66, v98, v98
	v_add_f32_e32 v0, v66, v0
	ds_bpermute_b32 v66, v157, v0
	s_waitcnt lgkmcnt(0)
	v_add_f32_e32 v0, v0, v66
	ds_bpermute_b32 v66, v194, v0
	s_and_saveexec_b64 s[2:3], s[8:9]
	s_cbranch_execz .LBB0_550
	s_waitcnt lgkmcnt(0)
	v_add_f32_e32 v0, v0, v66
	v_mul_f32_e32 v0, 0x4b800000, v0
	v_trunc_f32_e32 v0, v0
	v_mul_f32_e32 v66, 0x2f800000, v0
	v_floor_f32_e32 v67, v66
	v_fmac_f32_e32 v0, 0xcf800000, v67
	s_and_b64 s[4:5], s[18:19], exec
	v_cvt_u32_f32_e32 v66, v0
	v_cvt_u32_f32_e32 v67, v67
	s_cselect_b32 s4, s82, s80
	s_cselect_b32 s5, s81, s73
	v_mov_b32_e32 v68, s5
	v_mov_b32_e32 v69, s4
	v_lshl_add_u64 v[68:69], v[152:153], 3, v[68:69]
	global_atomic_add_x2 v[68:69], v[66:67], off

;     __device__ __forceinline__ void operator()(const f32x4 (&acc)[2][2][4][2], const Unit& u, int wr, int wc, int fr, int fq) const {
;     ...
;                         const float* tp = (mode == 1) ? (ropA + ((size_t)row * 32 + ((col0 & 63) >> 1)) * 2) : (ropB + ((size_t)row * 16 + ((col0 - PC_KR) >> 1)) * 2);
;                         const f32x4 c0 = *(const f32x4*)tp, c1 = *(const f32x4*)(tp + 4);
;                         f32x4 w0, w1;
;                         w0[0] = v0[0] * c0[0] - v0[1] * c0[1]; w0[1] = v0[1] * c0[0] + v0[0] * c0[1];
;                         w0[2] = v0[2] * c0[2] - v0[3] * c0[3]; w0[3] = v0[3] * c0[2] + v0[2] * c0[3];
;                         w1[0] = v1[0] * c1[0] - v1[1] * c1[1]; w1[1] = v1[1] * c1[0] + v1[0] * c1[1];
;                         w1[2] = v1[2] * c1[2] - v1[3] * c1[3]; w1[3] = v1[3] * c1[2] + v1[2] * c1[3];
;                         v0 = w0 * sc; v1 = w1 * sc;
;                     } else if (mode == 3) {
;                         const f32x2 a = gelu_pk((f32x2){v0[0], v0[1]}), bb = gelu_pk((f32x2){v0[2], v0[3]}), c = gelu_pk((f32x2){v1[0], v1[1]}), d = gelu_pk((f32x2){v1[2], v1[3]});
;                         v0 = (f32x4){a.x, a.y, bb.x, bb.y}; v1 = (f32x4){c.x, c.y, d.x, d.y};
;                     }
;                     if (stat) {
;                         const float q = (v0[0] * v0[0] + v0[1] * v0[1]) + (v0[2] * v0[2] + v0[3] * v0[3]) + (v1[0] * v1[0] + v1[1] * v1[1]) + (v1[2] * v1[2] + v1[3] * v1[3]);
;                         ssq_put(stat == 1 ? ssq_cq : ssq_ckv, row, q, fr, fq);
.LBB0_561:
	global_load_dwordx4 v[84:87], v[54:55], off
	global_load_dwordx4 v[88:91], v[54:55], off offset:16
	s_waitcnt vmcnt(0) lgkmcnt(0)
	v_mov_b32_e32 v0, v87
	v_pk_mul_f32 v[54:55], v[66:67], v[84:85] op_sel:[1,1] op_sel_hi:[0,1]
	v_pk_mul_f32 v[58:59], v[60:61], v[0:1] op_sel:[1,0] op_sel_hi:[0,0]
	v_pk_fma_f32 v[92:93], v[66:67], v[84:85], v[54:55] op_sel_hi:[1,0,1] neg_lo:[0,0,1] neg_hi:[0,0,1]
	v_pk_fma_f32 v[54:55], v[66:67], v[84:85], v[54:55] op_sel_hi:[1,0,1]
	v_pk_fma_f32 v[66:67], v[60:61], v[86:87], v[58:59] op_sel_hi:[1,0,1] neg_lo:[0,0,1] neg_hi:[0,0,1]
	v_pk_fma_f32 v[58:59], v[60:61], v[86:87], v[58:59] op_sel_hi:[1,0,1]
	v_pk_mul_f32 v[60:61], v[68:69], v[88:89] op_sel:[1,1] op_sel_hi:[0,1]
	v_mov_b32_e32 v0, v91
	v_pk_fma_f32 v[84:85], v[68:69], v[88:89], v[60:61] op_sel_hi:[1,0,1] neg_lo:[0,0,1] neg_hi:[0,0,1]
	v_pk_fma_f32 v[60:61], v[68:69], v[88:89], v[60:61] op_sel_hi:[1,0,1]
	v_pk_mul_f32 v[68:69], v[56:57], v[0:1] op_sel:[1,0] op_sel_hi:[0,0]
	v_pk_fma_f32 v[86:87], v[56:57], v[90:91], v[68:69] op_sel_hi:[1,0,1] neg_lo:[0,0,1] neg_hi:[0,0,1]
	v_pk_fma_f32 v[56:57], v[56:57], v[90:91], v[68:69] op_sel_hi:[1,0,1]
	v_mov_b32_e32 v67, v59
	v_mov_b32_e32 v68, v62
	v_mov_b32_e32 v69, v62
	v_mov_b32_e32 v93, v55
	v_mov_b32_e32 v87, v57
	v_mov_b32_e32 v85, v61
	v_pk_mul_f32 v[58:59], v[68:69], v[66:67]
	v_pk_mul_f32 v[54:55], v[62:63], v[92:93]
	v_pk_mul_f32 v[86:87], v[68:69], v[86:87]
	v_pk_mul_f32 v[84:85], v[62:63], v[84:85]
	v_cndmask_b32_e64 v0, 0, 1, s[40:41]
	v_cmp_ne_u32_e64 s[16:17], 1, v0
	s_andn2_b64 vcc, exec, s[40:41]
	s_cbranch_vccnz .LBB0_565
.LBB0_562:
	v_mul_f32_e32 v0, v55, v55
	v_mul_f32_e32 v56, v59, v59
	v_fmac_f32_e32 v0, v54, v54
	v_fmac_f32_e32 v56, v58, v58
	v_add_f32_e32 v0, v0, v56
	v_mul_f32_e32 v56, v85, v85
	v_fmac_f32_e32 v56, v84, v84
	v_add_f32_e32 v0, v56, v0
	v_mul_f32_e32 v56, v87, v87
	v_fmac_f32_e32 v56, v86, v86
	v_add_f32_e32 v0, v56, v0
	ds_bpermute_b32 v56, v157, v0
	s_waitcnt lgkmcnt(0)
	v_add_f32_e32 v0, v0, v56
	ds_bpermute_b32 v56, v194, v0
	s_and_saveexec_b64 s[2:3], s[8:9]
	s_cbranch_execz .LBB0_564
	s_waitcnt lgkmcnt(0)
	v_add_f32_e32 v0, v0, v56
	v_mul_f32_e32 v0, 0x4b800000, v0
	v_trunc_f32_e32 v0, v0
	v_mul_f32_e32 v56, 0x2f800000, v0
	v_floor_f32_e32 v57, v56
	v_fmac_f32_e32 v0, 0xcf800000, v57
	s_and_b64 s[4:5], s[18:19], exec
	v_cvt_u32_f32_e32 v56, v0
	v_cvt_u32_f32_e32 v57, v57
	s_cselect_b32 s4, s82, s80
	s_cselect_b32 s5, s81, s73
	v_mov_b32_e32 v60, s5
	v_mov_b32_e32 v61, s4
	v_lshl_add_u64 v[60:61], v[152:153], 3, v[60:61]
	global_atomic_add_x2 v[60:61], v[56:57], off offset:128

;     __device__ __forceinline__ void operator()(const f32x4 (&acc)[2][2][4][2], const Unit& u, int wr, int wc, int fr, int fq) const {
;     ...
;                         const float* tp = (mode == 1) ? (ropA + ((size_t)row * 32 + ((col0 & 63) >> 1)) * 2) : (ropB + ((size_t)row * 16 + ((col0 - PC_KR) >> 1)) * 2);
;                         const f32x4 c0 = *(const f32x4*)tp, c1 = *(const f32x4*)(tp + 4);
;                         f32x4 w0, w1;
;                         w0[0] = v0[0] * c0[0] - v0[1] * c0[1]; w0[1] = v0[1] * c0[0] + v0[0] * c0[1];
;                         w0[2] = v0[2] * c0[2] - v0[3] * c0[3]; w0[3] = v0[3] * c0[2] + v0[2] * c0[3];
;                         w1[0] = v1[0] * c1[0] - v1[1] * c1[1]; w1[1] = v1[1] * c1[0] + v1[0] * c1[1];
;                         w1[2] = v1[2] * c1[2] - v1[3] * c1[3]; w1[3] = v1[3] * c1[2] + v1[2] * c1[3];
;                         v0 = w0 * sc; v1 = w1 * sc;
;                     } else if (mode == 3) {
;                         const f32x2 a = gelu_pk((f32x2){v0[0], v0[1]}), bb = gelu_pk((f32x2){v0[2], v0[3]}), c = gelu_pk((f32x2){v1[0], v1[1]}), d = gelu_pk((f32x2){v1[2], v1[3]});
;                         v0 = (f32x4){a.x, a.y, bb.x, bb.y}; v1 = (f32x4){c.x, c.y, d.x, d.y};
;                     }
;                     if (stat) {
;                         const float q = (v0[0] * v0[0] + v0[1] * v0[1]) + (v0[2] * v0[2] + v0[3] * v0[3]) + (v1[0] * v1[0] + v1[1] * v1[1]) + (v1[2] * v1[2] + v1[3] * v1[3]);
;                         ssq_put(stat == 1 ? ssq_cq : ssq_ckv, row, q, fr, fq);
.LBB0_575:
	global_load_dwordx4 v[58:61], v[46:47], off
	global_load_dwordx4 v[66:69], v[46:47], off offset:16
	s_waitcnt vmcnt(0) lgkmcnt(0)
	v_mov_b32_e32 v0, v61
	v_pk_mul_f32 v[46:47], v[54:55], v[58:59] op_sel:[1,1] op_sel_hi:[0,1]
	v_pk_mul_f32 v[50:51], v[52:53], v[0:1] op_sel:[1,0] op_sel_hi:[0,0]
	v_pk_fma_f32 v[84:85], v[54:55], v[58:59], v[46:47] op_sel_hi:[1,0,1] neg_lo:[0,0,1] neg_hi:[0,0,1]
	v_pk_fma_f32 v[46:47], v[54:55], v[58:59], v[46:47] op_sel_hi:[1,0,1]
	v_pk_fma_f32 v[54:55], v[52:53], v[60:61], v[50:51] op_sel_hi:[1,0,1] neg_lo:[0,0,1] neg_hi:[0,0,1]
	v_pk_fma_f32 v[50:51], v[52:53], v[60:61], v[50:51] op_sel_hi:[1,0,1]
	v_pk_mul_f32 v[52:53], v[56:57], v[66:67] op_sel:[1,1] op_sel_hi:[0,1]
	v_mov_b32_e32 v0, v69
	v_pk_fma_f32 v[58:59], v[56:57], v[66:67], v[52:53] op_sel_hi:[1,0,1] neg_lo:[0,0,1] neg_hi:[0,0,1]
	v_pk_fma_f32 v[52:53], v[56:57], v[66:67], v[52:53] op_sel_hi:[1,0,1]
	v_pk_mul_f32 v[56:57], v[48:49], v[0:1] op_sel:[1,0] op_sel_hi:[0,0]
	v_pk_fma_f32 v[60:61], v[48:49], v[68:69], v[56:57] op_sel_hi:[1,0,1] neg_lo:[0,0,1] neg_hi:[0,0,1]
	v_pk_fma_f32 v[48:49], v[48:49], v[68:69], v[56:57] op_sel_hi:[1,0,1]
	v_mov_b32_e32 v55, v51
	v_mov_b32_e32 v56, v62
	v_mov_b32_e32 v57, v62
	v_mov_b32_e32 v85, v47
	v_mov_b32_e32 v61, v49
	v_mov_b32_e32 v59, v53
	v_pk_mul_f32 v[50:51], v[56:57], v[54:55]
	v_pk_mul_f32 v[46:47], v[62:63], v[84:85]
	v_pk_mul_f32 v[60:61], v[56:57], v[60:61]
	v_pk_mul_f32 v[58:59], v[62:63], v[58:59]
	s_and_b64 vcc, exec, s[16:17]
	s_cbranch_vccnz .LBB0_579
.LBB0_576:
	v_mul_f32_e32 v0, v47, v47
	v_mul_f32_e32 v48, v51, v51
	v_fmac_f32_e32 v0, v46, v46
	v_fmac_f32_e32 v48, v50, v50
	v_add_f32_e32 v0, v0, v48
	v_mul_f32_e32 v48, v59, v59
	v_fmac_f32_e32 v48, v58, v58
	v_add_f32_e32 v0, v48, v0
	v_mul_f32_e32 v48, v61, v61
	v_fmac_f32_e32 v48, v60, v60
	v_add_f32_e32 v0, v48, v0
	ds_bpermute_b32 v48, v157, v0
	s_waitcnt lgkmcnt(0)
	v_add_f32_e32 v0, v0, v48
	ds_bpermute_b32 v48, v194, v0
	s_and_saveexec_b64 s[2:3], s[8:9]
	s_cbranch_execz .LBB0_578
	s_waitcnt lgkmcnt(0)
	v_add_f32_e32 v0, v0, v48
	v_mul_f32_e32 v0, 0x4b800000, v0
	v_trunc_f32_e32 v0, v0
	v_mul_f32_e32 v48, 0x2f800000, v0
	v_floor_f32_e32 v49, v48
	v_fmac_f32_e32 v0, 0xcf800000, v49
	s_and_b64 s[4:5], s[18:19], exec
	v_cvt_u32_f32_e32 v48, v0
	v_cvt_u32_f32_e32 v49, v49
	s_cselect_b32 s4, s82, s80
	s_cselect_b32 s5, s81, s73
	v_mov_b32_e32 v52, s5
	v_mov_b32_e32 v53, s4
	v_lshl_add_u64 v[52:53], v[152:153], 3, v[52:53]
	global_atomic_add_x2 v[52:53], v[48:49], off offset:256

;     __device__ __forceinline__ void operator()(const f32x4 (&acc)[2][2][4][2], const Unit& u, int wr, int wc, int fr, int fq) const {
;     ...
;                         const float* tp = (mode == 1) ? (ropA + ((size_t)row * 32 + ((col0 & 63) >> 1)) * 2) : (ropB + ((size_t)row * 16 + ((col0 - PC_KR) >> 1)) * 2);
;                         const f32x4 c0 = *(const f32x4*)tp, c1 = *(const f32x4*)(tp + 4);
;                         f32x4 w0, w1;
;                         w0[0] = v0[0] * c0[0] - v0[1] * c0[1]; w0[1] = v0[1] * c0[0] + v0[0] * c0[1];
;                         w0[2] = v0[2] * c0[2] - v0[3] * c0[3]; w0[3] = v0[3] * c0[2] + v0[2] * c0[3];
;                         w1[0] = v1[0] * c1[0] - v1[1] * c1[1]; w1[1] = v1[1] * c1[0] + v1[0] * c1[1];
;                         w1[2] = v1[2] * c1[2] - v1[3] * c1[3]; w1[3] = v1[3] * c1[2] + v1[2] * c1[3];
;                         v0 = w0 * sc; v1 = w1 * sc;
;                     } else if (mode == 3) {
;                         const f32x2 a = gelu_pk((f32x2){v0[0], v0[1]}), bb = gelu_pk((f32x2){v0[2], v0[3]}), c = gelu_pk((f32x2){v1[0], v1[1]}), d = gelu_pk((f32x2){v1[2], v1[3]});
;                         v0 = (f32x4){a.x, a.y, bb.x, bb.y}; v1 = (f32x4){c.x, c.y, d.x, d.y};
;                     }
;                     if (stat) {
;                         const float q = (v0[0] * v0[0] + v0[1] * v0[1]) + (v0[2] * v0[2] + v0[3] * v0[3]) + (v1[0] * v1[0] + v1[1] * v1[1]) + (v1[2] * v1[2] + v1[3] * v1[3]);
;                         ssq_put(stat == 1 ? ssq_cq : ssq_ckv, row, q, fr, fq);
.LBB0_589:
	global_load_dwordx4 v[50:53], v[38:39], off
	global_load_dwordx4 v[54:57], v[38:39], off offset:16
	s_waitcnt vmcnt(0) lgkmcnt(0)
	v_mov_b32_e32 v0, v53
	v_pk_mul_f32 v[38:39], v[46:47], v[50:51] op_sel:[1,1] op_sel_hi:[0,1]
	v_pk_mul_f32 v[42:43], v[44:45], v[0:1] op_sel:[1,0] op_sel_hi:[0,0]
	v_pk_fma_f32 v[58:59], v[46:47], v[50:51], v[38:39] op_sel_hi:[1,0,1] neg_lo:[0,0,1] neg_hi:[0,0,1]
	v_pk_fma_f32 v[38:39], v[46:47], v[50:51], v[38:39] op_sel_hi:[1,0,1]
	v_pk_fma_f32 v[46:47], v[44:45], v[52:53], v[42:43] op_sel_hi:[1,0,1] neg_lo:[0,0,1] neg_hi:[0,0,1]
	v_pk_fma_f32 v[42:43], v[44:45], v[52:53], v[42:43] op_sel_hi:[1,0,1]
	v_pk_mul_f32 v[44:45], v[48:49], v[54:55] op_sel:[1,1] op_sel_hi:[0,1]
	v_mov_b32_e32 v0, v57
	v_pk_fma_f32 v[50:51], v[48:49], v[54:55], v[44:45] op_sel_hi:[1,0,1] neg_lo:[0,0,1] neg_hi:[0,0,1]
	v_pk_fma_f32 v[44:45], v[48:49], v[54:55], v[44:45] op_sel_hi:[1,0,1]
	v_pk_mul_f32 v[48:49], v[40:41], v[0:1] op_sel:[1,0] op_sel_hi:[0,0]
	v_pk_fma_f32 v[52:53], v[40:41], v[56:57], v[48:49] op_sel_hi:[1,0,1] neg_lo:[0,0,1] neg_hi:[0,0,1]
	v_pk_fma_f32 v[40:41], v[40:41], v[56:57], v[48:49] op_sel_hi:[1,0,1]
	v_mov_b32_e32 v47, v43
	v_mov_b32_e32 v48, v62
	v_mov_b32_e32 v49, v62
	v_mov_b32_e32 v59, v39
	v_mov_b32_e32 v53, v41
	v_mov_b32_e32 v51, v45
	v_pk_mul_f32 v[42:43], v[48:49], v[46:47]
	v_pk_mul_f32 v[38:39], v[62:63], v[58:59]
	v_pk_mul_f32 v[52:53], v[48:49], v[52:53]
	v_pk_mul_f32 v[50:51], v[62:63], v[50:51]
	s_and_b64 vcc, exec, s[16:17]
	s_cbranch_vccnz .LBB0_593
.LBB0_590:
	v_mul_f32_e32 v0, v39, v39
	v_mul_f32_e32 v40, v43, v43
	v_fmac_f32_e32 v0, v38, v38
	v_fmac_f32_e32 v40, v42, v42
	v_add_f32_e32 v0, v0, v40
	v_mul_f32_e32 v40, v51, v51
	v_fmac_f32_e32 v40, v50, v50
	v_add_f32_e32 v0, v40, v0
	v_mul_f32_e32 v40, v53, v53
	v_fmac_f32_e32 v40, v52, v52
	v_add_f32_e32 v0, v40, v0
	ds_bpermute_b32 v40, v157, v0
	s_waitcnt lgkmcnt(0)
	v_add_f32_e32 v0, v0, v40
	ds_bpermute_b32 v40, v194, v0
	s_and_saveexec_b64 s[2:3], s[8:9]
	s_cbranch_execz .LBB0_592
	s_waitcnt lgkmcnt(0)
	v_add_f32_e32 v0, v0, v40
	v_mul_f32_e32 v0, 0x4b800000, v0
	v_trunc_f32_e32 v0, v0
	v_mul_f32_e32 v40, 0x2f800000, v0
	v_floor_f32_e32 v41, v40
	v_fmac_f32_e32 v0, 0xcf800000, v41
	s_and_b64 s[4:5], s[18:19], exec
	v_cvt_u32_f32_e32 v40, v0
	v_cvt_u32_f32_e32 v41, v41
	s_cselect_b32 s4, s82, s80
	s_cselect_b32 s5, s81, s73
	v_mov_b32_e32 v44, s5
	v_mov_b32_e32 v45, s4
	v_lshl_add_u64 v[44:45], v[152:153], 3, v[44:45]
	global_atomic_add_x2 v[44:45], v[40:41], off offset:384

;     __device__ __forceinline__ void operator()(const f32x4 (&acc)[2][2][4][2], const Unit& u, int wr, int wc, int fr, int fq) const {
;     ...
;                         const float* tp = (mode == 1) ? (ropA + ((size_t)row * 32 + ((col0 & 63) >> 1)) * 2) : (ropB + ((size_t)row * 16 + ((col0 - PC_KR) >> 1)) * 2);
;                         const f32x4 c0 = *(const f32x4*)tp, c1 = *(const f32x4*)(tp + 4);
;                         f32x4 w0, w1;
;                         w0[0] = v0[0] * c0[0] - v0[1] * c0[1]; w0[1] = v0[1] * c0[0] + v0[0] * c0[1];
;                         w0[2] = v0[2] * c0[2] - v0[3] * c0[3]; w0[3] = v0[3] * c0[2] + v0[2] * c0[3];
;                         w1[0] = v1[0] * c1[0] - v1[1] * c1[1]; w1[1] = v1[1] * c1[0] + v1[0] * c1[1];
;                         w1[2] = v1[2] * c1[2] - v1[3] * c1[3]; w1[3] = v1[3] * c1[2] + v1[2] * c1[3];
;                         v0 = w0 * sc; v1 = w1 * sc;
;                     } else if (mode == 3) {
;                         const f32x2 a = gelu_pk((f32x2){v0[0], v0[1]}), bb = gelu_pk((f32x2){v0[2], v0[3]}), c = gelu_pk((f32x2){v1[0], v1[1]}), d = gelu_pk((f32x2){v1[2], v1[3]});
;                         v0 = (f32x4){a.x, a.y, bb.x, bb.y}; v1 = (f32x4){c.x, c.y, d.x, d.y};
;                     }
;                     if (stat) {
;                         const float q = (v0[0] * v0[0] + v0[1] * v0[1]) + (v0[2] * v0[2] + v0[3] * v0[3]) + (v1[0] * v1[0] + v1[1] * v1[1]) + (v1[2] * v1[2] + v1[3] * v1[3]);
;                         ssq_put(stat == 1 ? ssq_cq : ssq_ckv, row, q, fr, fq);
.LBB0_603:
	global_load_dwordx4 v[42:45], v[30:31], off
	s_nop 0
	global_load_dwordx4 v[30:33], v[30:31], off offset:16
	s_waitcnt vmcnt(0) lgkmcnt(0)
	v_pk_mul_f32 v[46:47], v[38:39], v[42:43] op_sel:[1,1] op_sel_hi:[0,1]
	v_mov_b32_e32 v0, v45
	v_pk_fma_f32 v[48:49], v[38:39], v[42:43], v[46:47] op_sel_hi:[1,0,1] neg_lo:[0,0,1] neg_hi:[0,0,1]
	v_pk_fma_f32 v[38:39], v[38:39], v[42:43], v[46:47] op_sel_hi:[1,0,1]
	v_pk_mul_f32 v[42:43], v[36:37], v[0:1] op_sel:[1,0] op_sel_hi:[0,0]
	v_pk_fma_f32 v[46:47], v[36:37], v[44:45], v[42:43] op_sel_hi:[1,0,1] neg_lo:[0,0,1] neg_hi:[0,0,1]
	v_pk_fma_f32 v[36:37], v[36:37], v[44:45], v[42:43] op_sel_hi:[1,0,1]
	v_pk_mul_f32 v[42:43], v[40:41], v[30:31] op_sel:[1,1] op_sel_hi:[0,1]
	v_mov_b32_e32 v0, v33
	v_pk_fma_f32 v[50:51], v[40:41], v[30:31], v[42:43] op_sel_hi:[1,0,1] neg_lo:[0,0,1] neg_hi:[0,0,1]
	v_pk_fma_f32 v[40:41], v[40:41], v[30:31], v[42:43] op_sel_hi:[1,0,1]
	v_pk_mul_f32 v[30:31], v[34:35], v[0:1] op_sel:[1,0] op_sel_hi:[0,0]
	v_pk_fma_f32 v[42:43], v[34:35], v[32:33], v[30:31] op_sel_hi:[1,0,1] neg_lo:[0,0,1] neg_hi:[0,0,1]
	v_pk_fma_f32 v[34:35], v[34:35], v[32:33], v[30:31] op_sel_hi:[1,0,1]
	v_mov_b32_e32 v47, v37
	v_mov_b32_e32 v36, v62
	v_mov_b32_e32 v37, v62
	v_mov_b32_e32 v49, v39
	v_mov_b32_e32 v43, v35
	v_mov_b32_e32 v51, v41
	v_pk_mul_f32 v[32:33], v[36:37], v[46:47]
	v_pk_mul_f32 v[30:31], v[62:63], v[48:49]
	v_pk_mul_f32 v[44:45], v[36:37], v[42:43]
	v_pk_mul_f32 v[42:43], v[62:63], v[50:51]
	s_and_b64 vcc, exec, s[16:17]
	s_cbranch_vccnz .LBB0_607
.LBB0_604:
	v_mul_f32_e32 v0, v31, v31
	v_mul_f32_e32 v34, v33, v33
	v_fmac_f32_e32 v0, v30, v30
	v_fmac_f32_e32 v34, v32, v32
	v_add_f32_e32 v0, v0, v34
	v_mul_f32_e32 v34, v43, v43
	v_fmac_f32_e32 v34, v42, v42
	v_add_f32_e32 v0, v34, v0
	v_mul_f32_e32 v34, v45, v45
	v_fmac_f32_e32 v34, v44, v44
	v_add_f32_e32 v0, v34, v0
	ds_bpermute_b32 v34, v157, v0
	s_waitcnt lgkmcnt(0)
	v_add_f32_e32 v0, v0, v34
	ds_bpermute_b32 v34, v194, v0
	s_and_saveexec_b64 s[2:3], s[8:9]
	s_cbranch_execz .LBB0_606
	s_waitcnt lgkmcnt(0)
	v_add_f32_e32 v0, v0, v34
	v_mul_f32_e32 v0, 0x4b800000, v0
	v_trunc_f32_e32 v0, v0
	v_mul_f32_e32 v34, 0x2f800000, v0
	v_floor_f32_e32 v35, v34
	v_fmac_f32_e32 v0, 0xcf800000, v35
	s_and_b64 s[4:5], s[18:19], exec
	v_cvt_u32_f32_e32 v34, v0
	v_cvt_u32_f32_e32 v35, v35
	s_cselect_b32 s4, s82, s80
	s_cselect_b32 s5, s81, s73
	v_mov_b32_e32 v36, s5
	v_mov_b32_e32 v37, s4
	v_lshl_add_u64 v[36:37], v[152:153], 3, v[36:37]
	global_atomic_add_x2 v[36:37], v[34:35], off offset:1024

;     __device__ __forceinline__ void operator()(const f32x4 (&acc)[2][2][4][2], const Unit& u, int wr, int wc, int fr, int fq) const {
;     ...
;                         const float* tp = (mode == 1) ? (ropA + ((size_t)row * 32 + ((col0 & 63) >> 1)) * 2) : (ropB + ((size_t)row * 16 + ((col0 - PC_KR) >> 1)) * 2);
;                         const f32x4 c0 = *(const f32x4*)tp, c1 = *(const f32x4*)(tp + 4);
;                         f32x4 w0, w1;
;                         w0[0] = v0[0] * c0[0] - v0[1] * c0[1]; w0[1] = v0[1] * c0[0] + v0[0] * c0[1];
;                         w0[2] = v0[2] * c0[2] - v0[3] * c0[3]; w0[3] = v0[3] * c0[2] + v0[2] * c0[3];
;                         w1[0] = v1[0] * c1[0] - v1[1] * c1[1]; w1[1] = v1[1] * c1[0] + v1[0] * c1[1];
;                         w1[2] = v1[2] * c1[2] - v1[3] * c1[3]; w1[3] = v1[3] * c1[2] + v1[2] * c1[3];
;                         v0 = w0 * sc; v1 = w1 * sc;
;                     } else if (mode == 3) {
;                         const f32x2 a = gelu_pk((f32x2){v0[0], v0[1]}), bb = gelu_pk((f32x2){v0[2], v0[3]}), c = gelu_pk((f32x2){v1[0], v1[1]}), d = gelu_pk((f32x2){v1[2], v1[3]});
;                         v0 = (f32x4){a.x, a.y, bb.x, bb.y}; v1 = (f32x4){c.x, c.y, d.x, d.y};
;                     }
;                     if (stat) {
;                         const float q = (v0[0] * v0[0] + v0[1] * v0[1]) + (v0[2] * v0[2] + v0[3] * v0[3]) + (v1[0] * v1[0] + v1[1] * v1[1]) + (v1[2] * v1[2] + v1[3] * v1[3]);
;                         ssq_put(stat == 1 ? ssq_cq : ssq_ckv, row, q, fr, fq);
.LBB0_617:
	s_waitcnt lgkmcnt(0)
	global_load_dwordx4 v[34:37], v[22:23], off
	global_load_dwordx4 v[38:41], v[22:23], off offset:16
	s_waitcnt vmcnt(0) lgkmcnt(0)
	v_mov_b32_e32 v0, v37
	v_pk_mul_f32 v[22:23], v[30:31], v[34:35] op_sel:[1,1] op_sel_hi:[0,1]
	v_pk_mul_f32 v[26:27], v[28:29], v[0:1] op_sel:[1,0] op_sel_hi:[0,0]
	v_pk_fma_f32 v[42:43], v[30:31], v[34:35], v[22:23] op_sel_hi:[1,0,1] neg_lo:[0,0,1] neg_hi:[0,0,1]
	v_pk_fma_f32 v[22:23], v[30:31], v[34:35], v[22:23] op_sel_hi:[1,0,1]
	v_pk_fma_f32 v[30:31], v[28:29], v[36:37], v[26:27] op_sel_hi:[1,0,1] neg_lo:[0,0,1] neg_hi:[0,0,1]
	v_pk_fma_f32 v[26:27], v[28:29], v[36:37], v[26:27] op_sel_hi:[1,0,1]
	v_pk_mul_f32 v[28:29], v[32:33], v[38:39] op_sel:[1,1] op_sel_hi:[0,1]
	v_mov_b32_e32 v0, v41
	v_pk_fma_f32 v[34:35], v[32:33], v[38:39], v[28:29] op_sel_hi:[1,0,1] neg_lo:[0,0,1] neg_hi:[0,0,1]
	v_pk_fma_f32 v[28:29], v[32:33], v[38:39], v[28:29] op_sel_hi:[1,0,1]
	v_pk_mul_f32 v[32:33], v[24:25], v[0:1] op_sel:[1,0] op_sel_hi:[0,0]
	v_pk_fma_f32 v[36:37], v[24:25], v[40:41], v[32:33] op_sel_hi:[1,0,1] neg_lo:[0,0,1] neg_hi:[0,0,1]
	v_pk_fma_f32 v[24:25], v[24:25], v[40:41], v[32:33] op_sel_hi:[1,0,1]
	v_mov_b32_e32 v31, v27
	v_mov_b32_e32 v32, v62
	v_mov_b32_e32 v33, v62
	v_mov_b32_e32 v43, v23
	v_mov_b32_e32 v37, v25
	v_mov_b32_e32 v35, v29
	v_pk_mul_f32 v[26:27], v[32:33], v[30:31]
	v_pk_mul_f32 v[22:23], v[62:63], v[42:43]
	v_pk_mul_f32 v[36:37], v[32:33], v[36:37]
	v_pk_mul_f32 v[34:35], v[62:63], v[34:35]
	s_and_b64 vcc, exec, s[16:17]
	s_cbranch_vccnz .LBB0_621
.LBB0_618:
	v_mul_f32_e32 v0, v23, v23
	v_mul_f32_e32 v24, v27, v27
	v_fmac_f32_e32 v0, v22, v22
	v_fmac_f32_e32 v24, v26, v26
	v_add_f32_e32 v0, v0, v24
	v_mul_f32_e32 v24, v35, v35
	s_waitcnt lgkmcnt(0)
	v_fmac_f32_e32 v24, v34, v34
	v_add_f32_e32 v0, v24, v0
	v_mul_f32_e32 v24, v37, v37
	v_fmac_f32_e32 v24, v36, v36
	v_add_f32_e32 v0, v24, v0
	ds_bpermute_b32 v24, v157, v0
	s_waitcnt lgkmcnt(0)
	v_add_f32_e32 v0, v0, v24
	ds_bpermute_b32 v24, v194, v0
	s_and_saveexec_b64 s[2:3], s[8:9]
	s_cbranch_execz .LBB0_620
	s_waitcnt lgkmcnt(0)
	v_add_f32_e32 v0, v0, v24
	v_mul_f32_e32 v0, 0x4b800000, v0
	v_trunc_f32_e32 v0, v0
	v_mul_f32_e32 v24, 0x2f800000, v0
	v_floor_f32_e32 v25, v24
	v_fmac_f32_e32 v0, 0xcf800000, v25
	s_and_b64 s[4:5], s[18:19], exec
	v_cvt_u32_f32_e32 v24, v0
	v_cvt_u32_f32_e32 v25, v25
	s_cselect_b32 s4, s82, s80
	s_cselect_b32 s5, s81, s73
	v_mov_b32_e32 v28, s5
	v_mov_b32_e32 v29, s4
	v_lshl_add_u64 v[28:29], v[152:153], 3, v[28:29]
	global_atomic_add_x2 v[28:29], v[24:25], off offset:1152

;     __device__ __forceinline__ void operator()(const f32x4 (&acc)[2][2][4][2], const Unit& u, int wr, int wc, int fr, int fq) const {
;     ...
;                         const float* tp = (mode == 1) ? (ropA + ((size_t)row * 32 + ((col0 & 63) >> 1)) * 2) : (ropB + ((size_t)row * 16 + ((col0 - PC_KR) >> 1)) * 2);
;                         const f32x4 c0 = *(const f32x4*)tp, c1 = *(const f32x4*)(tp + 4);
;                         f32x4 w0, w1;
;                         w0[0] = v0[0] * c0[0] - v0[1] * c0[1]; w0[1] = v0[1] * c0[0] + v0[0] * c0[1];
;                         w0[2] = v0[2] * c0[2] - v0[3] * c0[3]; w0[3] = v0[3] * c0[2] + v0[2] * c0[3];
;                         w1[0] = v1[0] * c1[0] - v1[1] * c1[1]; w1[1] = v1[1] * c1[0] + v1[0] * c1[1];
;                         w1[2] = v1[2] * c1[2] - v1[3] * c1[3]; w1[3] = v1[3] * c1[2] + v1[2] * c1[3];
;                         v0 = w0 * sc; v1 = w1 * sc;
;                     } else if (mode == 3) {
;                         const f32x2 a = gelu_pk((f32x2){v0[0], v0[1]}), bb = gelu_pk((f32x2){v0[2], v0[3]}), c = gelu_pk((f32x2){v1[0], v1[1]}), d = gelu_pk((f32x2){v1[2], v1[3]});
;                         v0 = (f32x4){a.x, a.y, bb.x, bb.y}; v1 = (f32x4){c.x, c.y, d.x, d.y};
;                     }
;                     if (stat) {
;                         const float q = (v0[0] * v0[0] + v0[1] * v0[1]) + (v0[2] * v0[2] + v0[3] * v0[3]) + (v1[0] * v1[0] + v1[1] * v1[1]) + (v1[2] * v1[2] + v1[3] * v1[3]);
;                         ssq_put(stat == 1 ? ssq_cq : ssq_ckv, row, q, fr, fq);
.LBB0_631:
	global_load_dwordx4 v[26:29], v[10:11], off
	global_load_dwordx4 v[30:33], v[10:11], off offset:16
	s_waitcnt vmcnt(0) lgkmcnt(0)
	v_mov_b32_e32 v0, v29
	v_pk_mul_f32 v[10:11], v[22:23], v[26:27] op_sel:[1,1] op_sel_hi:[0,1]
	v_pk_mul_f32 v[18:19], v[20:21], v[0:1] op_sel:[1,0] op_sel_hi:[0,0]
	v_pk_fma_f32 v[34:35], v[22:23], v[26:27], v[10:11] op_sel_hi:[1,0,1] neg_lo:[0,0,1] neg_hi:[0,0,1]
	v_pk_fma_f32 v[10:11], v[22:23], v[26:27], v[10:11] op_sel_hi:[1,0,1]
	v_pk_fma_f32 v[22:23], v[20:21], v[28:29], v[18:19] op_sel_hi:[1,0,1] neg_lo:[0,0,1] neg_hi:[0,0,1]
	v_pk_fma_f32 v[18:19], v[20:21], v[28:29], v[18:19] op_sel_hi:[1,0,1]
	v_pk_mul_f32 v[20:21], v[24:25], v[30:31] op_sel:[1,1] op_sel_hi:[0,1]
	v_mov_b32_e32 v0, v33
	v_pk_fma_f32 v[26:27], v[24:25], v[30:31], v[20:21] op_sel_hi:[1,0,1] neg_lo:[0,0,1] neg_hi:[0,0,1]
	v_pk_fma_f32 v[20:21], v[24:25], v[30:31], v[20:21] op_sel_hi:[1,0,1]
	v_pk_mul_f32 v[24:25], v[12:13], v[0:1] op_sel:[1,0] op_sel_hi:[0,0]
	v_pk_fma_f32 v[28:29], v[12:13], v[32:33], v[24:25] op_sel_hi:[1,0,1] neg_lo:[0,0,1] neg_hi:[0,0,1]
	v_pk_fma_f32 v[12:13], v[12:13], v[32:33], v[24:25] op_sel_hi:[1,0,1]
	v_mov_b32_e32 v23, v19
	v_mov_b32_e32 v24, v62
	v_mov_b32_e32 v25, v62
	v_mov_b32_e32 v35, v11
	v_mov_b32_e32 v29, v13
	v_mov_b32_e32 v27, v21
	v_pk_mul_f32 v[18:19], v[24:25], v[22:23]
	v_pk_mul_f32 v[10:11], v[62:63], v[34:35]
	v_pk_mul_f32 v[28:29], v[24:25], v[28:29]
	v_pk_mul_f32 v[26:27], v[62:63], v[26:27]
	s_and_b64 vcc, exec, s[16:17]
	s_cbranch_vccnz .LBB0_635
.LBB0_632:
	v_mul_f32_e32 v0, v11, v11
	v_mul_f32_e32 v12, v19, v19
	v_fmac_f32_e32 v0, v10, v10
	v_fmac_f32_e32 v12, v18, v18
	v_add_f32_e32 v0, v0, v12
	v_mul_f32_e32 v12, v27, v27
	v_fmac_f32_e32 v12, v26, v26
	v_add_f32_e32 v0, v12, v0
	v_mul_f32_e32 v12, v29, v29
	v_fmac_f32_e32 v12, v28, v28
	v_add_f32_e32 v0, v12, v0
	ds_bpermute_b32 v12, v157, v0
	s_waitcnt lgkmcnt(0)
	v_add_f32_e32 v0, v0, v12
	ds_bpermute_b32 v12, v194, v0
	s_and_saveexec_b64 s[2:3], s[8:9]
	s_cbranch_execz .LBB0_634
	s_waitcnt lgkmcnt(0)
	v_add_f32_e32 v0, v0, v12
	v_mul_f32_e32 v0, 0x4b800000, v0
	v_trunc_f32_e32 v0, v0
	v_mul_f32_e32 v12, 0x2f800000, v0
	v_floor_f32_e32 v13, v12
	v_fmac_f32_e32 v0, 0xcf800000, v13
	s_and_b64 s[4:5], s[18:19], exec
	v_cvt_u32_f32_e32 v12, v0
	v_cvt_u32_f32_e32 v13, v13
	s_cselect_b32 s4, s82, s80
	s_cselect_b32 s5, s81, s73
	v_mov_b32_e32 v20, s5
	v_mov_b32_e32 v21, s4
	v_lshl_add_u64 v[20:21], v[152:153], 3, v[20:21]
	global_atomic_add_x2 v[20:21], v[12:13], off offset:1280

;     __device__ __forceinline__ void operator()(const f32x4 (&acc)[2][2][4][2], const Unit& u, int wr, int wc, int fr, int fq) const {
;     ...
;                         const float* tp = (mode == 1) ? (ropA + ((size_t)row * 32 + ((col0 & 63) >> 1)) * 2) : (ropB + ((size_t)row * 16 + ((col0 - PC_KR) >> 1)) * 2);
;                         const f32x4 c0 = *(const f32x4*)tp, c1 = *(const f32x4*)(tp + 4);
;                         f32x4 w0, w1;
;                         w0[0] = v0[0] * c0[0] - v0[1] * c0[1]; w0[1] = v0[1] * c0[0] + v0[0] * c0[1];
;                         w0[2] = v0[2] * c0[2] - v0[3] * c0[3]; w0[3] = v0[3] * c0[2] + v0[2] * c0[3];
;                         w1[0] = v1[0] * c1[0] - v1[1] * c1[1]; w1[1] = v1[1] * c1[0] + v1[0] * c1[1];
;                         w1[2] = v1[2] * c1[2] - v1[3] * c1[3]; w1[3] = v1[3] * c1[2] + v1[2] * c1[3];
;                         v0 = w0 * sc; v1 = w1 * sc;
;                     } else if (mode == 3) {
;                         const f32x2 a = gelu_pk((f32x2){v0[0], v0[1]}), bb = gelu_pk((f32x2){v0[2], v0[3]}), c = gelu_pk((f32x2){v1[0], v1[1]}), d = gelu_pk((f32x2){v1[2], v1[3]});
;                         v0 = (f32x4){a.x, a.y, bb.x, bb.y}; v1 = (f32x4){c.x, c.y, d.x, d.y};
;                     }
;                     if (stat) {
;                         const float q = (v0[0] * v0[0] + v0[1] * v0[1]) + (v0[2] * v0[2] + v0[3] * v0[3]) + (v1[0] * v1[0] + v1[1] * v1[1]) + (v1[2] * v1[2] + v1[3] * v1[3]);
;                         ssq_put(stat == 1 ? ssq_cq : ssq_ckv, row, q, fr, fq);
.LBB0_645:
	global_load_dwordx4 v[18:21], v[2:3], off
	global_load_dwordx4 v[22:25], v[2:3], off offset:16
	s_waitcnt vmcnt(0) lgkmcnt(0)
	v_mov_b32_e32 v0, v21
	v_pk_mul_f32 v[2:3], v[10:11], v[18:19] op_sel:[1,1] op_sel_hi:[0,1]
	v_pk_mul_f32 v[6:7], v[8:9], v[0:1] op_sel:[1,0] op_sel_hi:[0,0]
	v_pk_fma_f32 v[26:27], v[10:11], v[18:19], v[2:3] op_sel_hi:[1,0,1] neg_lo:[0,0,1] neg_hi:[0,0,1]
	v_pk_fma_f32 v[2:3], v[10:11], v[18:19], v[2:3] op_sel_hi:[1,0,1]
	v_pk_fma_f32 v[10:11], v[8:9], v[20:21], v[6:7] op_sel_hi:[1,0,1] neg_lo:[0,0,1] neg_hi:[0,0,1]
	v_pk_fma_f32 v[6:7], v[8:9], v[20:21], v[6:7] op_sel_hi:[1,0,1]
	v_pk_mul_f32 v[8:9], v[12:13], v[22:23] op_sel:[1,1] op_sel_hi:[0,1]
	v_mov_b32_e32 v0, v25
	v_pk_fma_f32 v[18:19], v[12:13], v[22:23], v[8:9] op_sel_hi:[1,0,1] neg_lo:[0,0,1] neg_hi:[0,0,1]
	v_pk_fma_f32 v[8:9], v[12:13], v[22:23], v[8:9] op_sel_hi:[1,0,1]
	v_pk_mul_f32 v[12:13], v[4:5], v[0:1] op_sel:[1,0] op_sel_hi:[0,0]
	v_pk_fma_f32 v[20:21], v[4:5], v[24:25], v[12:13] op_sel_hi:[1,0,1] neg_lo:[0,0,1] neg_hi:[0,0,1]
	v_pk_fma_f32 v[4:5], v[4:5], v[24:25], v[12:13] op_sel_hi:[1,0,1]
	v_mov_b32_e32 v11, v7
	v_mov_b32_e32 v12, v62
	v_mov_b32_e32 v13, v62
	v_mov_b32_e32 v27, v3
	v_mov_b32_e32 v21, v5
	v_mov_b32_e32 v19, v9
	v_pk_mul_f32 v[6:7], v[12:13], v[10:11]
	v_pk_mul_f32 v[2:3], v[62:63], v[26:27]
	v_pk_mul_f32 v[20:21], v[12:13], v[20:21]
	v_pk_mul_f32 v[18:19], v[62:63], v[18:19]
	s_and_b64 vcc, exec, s[16:17]
	s_cbranch_vccnz .LBB0_649
.LBB0_646:
	v_mul_f32_e32 v0, v3, v3
	v_mul_f32_e32 v4, v7, v7
	v_fmac_f32_e32 v0, v2, v2
	v_fmac_f32_e32 v4, v6, v6
	v_add_f32_e32 v0, v0, v4
	v_mul_f32_e32 v4, v19, v19
	v_fmac_f32_e32 v4, v18, v18
	v_add_f32_e32 v0, v4, v0
	v_mul_f32_e32 v4, v21, v21
	v_fmac_f32_e32 v4, v20, v20
	v_add_f32_e32 v0, v4, v0
	ds_bpermute_b32 v4, v157, v0
	s_waitcnt lgkmcnt(0)
	v_add_f32_e32 v0, v0, v4
	ds_bpermute_b32 v4, v194, v0
	s_and_saveexec_b64 s[2:3], s[8:9]
	s_cbranch_execz .LBB0_648
	s_waitcnt lgkmcnt(0)
	v_add_f32_e32 v0, v0, v4
	v_mul_f32_e32 v0, 0x4b800000, v0
	v_trunc_f32_e32 v0, v0
	v_mul_f32_e32 v4, 0x2f800000, v0
	v_floor_f32_e32 v5, v4
	v_fmac_f32_e32 v0, 0xcf800000, v5
	s_and_b64 s[4:5], s[18:19], exec
	v_cvt_u32_f32_e32 v4, v0
	v_cvt_u32_f32_e32 v5, v5
	s_cselect_b32 s4, s82, s80
	s_cselect_b32 s5, s81, s73
	v_mov_b32_e32 v8, s5
	v_mov_b32_e32 v9, s4
	v_lshl_add_u64 v[8:9], v[152:153], 3, v[8:9]
	global_atomic_add_x2 v[8:9], v[4:5], off offset:1408

; __device__ __forceinline__ unsigned cvt_pk_bf16(float lo, float hi) { unsigned r; asm volatile("v_cvt_pk_bf16_f32 %0, %1, %2" : "=v"(r) : "v"(lo), "v"(hi)); return r; }
; __device__ __forceinline__ float ssq_val(ssq_t v) { return (float)v * SSQ_IFX; }
;     __device__ __forceinline__ void operator()(const f32x4 (&acc)[2][2][4][2], const Unit& u, int wr, int wc, int fr, int fq) const {
;         const int row0 = u.pm * BM + wr * 64 + fr;
;         ssq_t sv[8]; float rsv[8];
; #pragma unroll
;         for (int i = 0; i < 8; ++i) sv[i] = ssq[row0 + (i >> 2) * HALF + (i & 3) * 16];
; #pragma unroll
;         for (int i = 0; i < 8; ++i) rsv[i] = QS_B / sqrtf(ssq_val(sv[i]) * (1.0f / 384.0f) + EPS);
; #pragma unroll
;         for (int ai = 0; ai < 2; ++ai)
; #pragma unroll
;             for (int m = 0; m < 4; ++m) {
;                 const int row = row0 + ai * HALF + m * 16;
;                 const float rs = rsv[ai * 4 + m];
; #pragma unroll
;                 for (int bj = 0; bj < 2; ++bj) {
;                     const int colw = u.pn * BM + bj * HALF + wc * 32, col0 = colw + 8 * fq;
;                     const bool rope = (colw % 96) == 64 && colw < 576;
;                     f32x4 v0 = acc[ai][bj][m][0] * rs, v1 = acc[ai][bj][m][1] * rs;
;                     if (rope) {
;                         const float* tp = ropB + ((size_t)row * 16 + ((col0 - colw) >> 1)) * 2;
;                         const f32x4 c0 = *(const f32x4*)tp, c1 = *(const f32x4*)(tp + 4);
;                         f32x4 w0, w1;
;                         w0[0] = v0[0] * c0[0] - v0[1] * c0[1]; w0[1] = v0[1] * c0[0] + v0[0] * c0[1];
;                         w0[2] = v0[2] * c0[2] - v0[3] * c0[3]; w0[3] = v0[3] * c0[2] + v0[2] * c0[3];
;                         w1[0] = v1[0] * c1[0] - v1[1] * c1[1]; w1[1] = v1[1] * c1[0] + v1[0] * c1[1];
;                         w1[2] = v1[2] * c1[2] - v1[3] * c1[3]; w1[3] = v1[3] * c1[2] + v1[2] * c1[3];
;                         v0 = w0; v1 = w1;
;                     }
;                     u32x4 w; w.x = cvt_pk_bf16(v0[0], v0[1]); w.y = cvt_pk_bf16(v0[2], v0[3]); w.z = cvt_pk_bf16(v1[0], v1[1]); w.w = cvt_pk_bf16(v1[2], v1[3]);
;                     *(u32x4*)(O + (size_t)row * QMP + col0) = w;
.LBB0_713:
	s_lshl_b32 s2, s31, 8
	s_add_i32 s2, s2, s4
	v_mbcnt_lo_u32_b32 v0, -1, 0
	v_mbcnt_hi_u32_b32 v0, -1, v0
	s_nop 0
	v_and_or_b32 v140, v0, 15, s2
	v_ashrrev_i32_e32 v141, 31, v140
	v_lshl_add_u64 v[142:143], v[140:141], 3, s[18:19]
	global_load_dwordx2 v[156:157], v[142:143], off
	global_load_dwordx2 v[154:155], v[142:143], off offset:128
	global_load_dwordx2 v[152:153], v[142:143], off offset:256
	global_load_dwordx2 v[150:151], v[142:143], off offset:384
	global_load_dwordx2 v[148:149], v[142:143], off offset:1024
	global_load_dwordx2 v[146:147], v[142:143], off offset:1152
	global_load_dwordx2 v[144:145], v[142:143], off offset:1280
	s_nop 0
	global_load_dwordx2 v[142:143], v[142:143], off offset:1408
	v_lshrrev_b32_e32 v0, 1, v0
	v_and_b32_e32 v0, 24, v0
	v_lshlrev_b64 v[166:167], 7, v[140:141]
	s_waitcnt vmcnt(0) lgkmcnt(0)
	v_ffbh_u32_e32 v158, v157
	v_min_u32_e32 v158, 32, v158
	v_lshlrev_b64 v[156:157], v158, v[156:157]
	v_min_u32_e32 v156, 1, v156
	v_or_b32_e32 v156, v157, v156
	v_cvt_f32_u32_e32 v156, v156
	v_sub_u32_e32 v157, 32, v158
	v_ldexp_f32 v156, v156, v157
	v_mul_f32_e32 v156, 0x33800000, v156
	v_fmamk_f32 v156, v156, 0x3b2aaaab, v226
	v_cmp_gt_f32_e32 vcc, s71, v156
	v_mul_f32_e32 v157, 0x4f800000, v156
	s_nop 0
	v_cndmask_b32_e32 v156, v156, v157, vcc
	v_sqrt_f32_e32 v157, v156
	s_nop 0
	v_add_u32_e32 v158, -1, v157
	v_fma_f32 v159, -v158, v157, v156
	v_cmp_ge_f32_e64 s[8:9], 0, v159
	v_add_u32_e32 v159, 1, v157
	s_nop 0
	v_cndmask_b32_e64 v158, v157, v158, s[8:9]
	v_fma_f32 v157, -v159, v157, v156
	v_cmp_lt_f32_e64 s[8:9], 0, v157
	s_nop 1
	v_cndmask_b32_e64 v157, v158, v159, s[8:9]
	v_mul_f32_e32 v158, 0x37800000, v157
	v_cndmask_b32_e32 v157, v157, v158, vcc
	v_cmp_class_f32_e32 vcc, v156, v223
	s_nop 1
	v_cndmask_b32_e32 v156, v157, v156, vcc
	v_div_scale_f32 v157, s[2:3], v156, v156, s69
	v_rcp_f32_e32 v158, v157
	s_lshl_b32 s2, s30, 8
	s_or_b32 s30, s2, s5
	s_mul_hi_i32 s2, s30, 0x2aaaaaab
	v_fma_f32 v159, -v157, v158, 1.0
	s_lshr_b32 s3, s2, 31
	s_lshr_b32 s2, s2, 4
	v_fmac_f32_e32 v158, v159, v158
	v_div_scale_f32 v159, vcc, s69, v156, s69
	s_add_i32 s2, s2, s3
	v_mul_f32_e32 v160, v159, v158
	s_mulk_i32 s2, 0x60
	v_fma_f32 v161, -v157, v160, v159
	s_sub_i32 s2, s30, s2
	v_fmac_f32_e32 v160, v161, v158
	s_cmp_eq_u32 s2, 64
	v_fma_f32 v157, -v157, v160, v159
	s_cselect_b64 s[2:3], -1, 0
	s_cmpk_lt_i32 s30, 0x240
	v_div_fmas_f32 v157, v157, v158, v160
	s_cselect_b64 s[8:9], -1, 0
	v_div_fixup_f32 v156, v157, v156, s69
	s_and_b64 s[2:3], s[8:9], s[2:3]
	v_pk_mul_f32 v[158:159], v[126:127], v[156:157] op_sel_hi:[1,0]
	v_cndmask_b32_e64 v126, 0, 1, s[2:3]
	v_pk_mul_f32 v[162:163], v[128:129], v[156:157] op_sel_hi:[1,0]
	v_pk_mul_f32 v[160:161], v[132:133], v[156:157] op_sel_hi:[1,0]
	v_pk_mul_f32 v[130:131], v[130:131], v[156:157] op_sel_hi:[1,0]
	v_cmp_ne_u32_e64 s[8:9], 1, v126
	s_andn2_b64 vcc, exec, s[2:3]
	v_lshl_add_u64 v[132:133], s[20:21], 0, v[166:167]
	v_lshlrev_b32_e32 v126, 2, v0
	s_cbranch_vccnz .LBB0_715
	v_mov_b32_e32 v127, v1
	v_lshl_add_u64 v[128:129], v[132:133], 0, v[126:127]
	global_load_dwordx4 v[166:169], v[128:129], off
	global_load_dwordx4 v[170:173], v[128:129], off offset:16
	s_waitcnt vmcnt(0) lgkmcnt(0)
	v_pk_mul_f32 v[174:175], v[158:159], v[166:167] op_sel:[1,1] op_sel_hi:[0,1]
	v_pk_mul_f32 v[128:129], v[158:159], v[166:167]
	v_pk_fma_f32 v[158:159], v[158:159], v[166:167], v[174:175] op_sel_hi:[1,0,1]
	v_pk_mul_f32 v[176:177], v[130:131], v[170:171] op_sel:[1,1] op_sel_hi:[0,1]
	v_mul_f32_e32 v158, v163, v169
	v_pk_fma_f32 v[166:167], v[162:163], v[168:169], v[158:159] op_sel_hi:[1,1,0] neg_lo:[0,0,1] neg_hi:[0,0,1]
	v_mul_f32_e32 v158, v162, v169
	v_pk_fma_f32 v[168:169], v[162:163], v[168:169], v[158:159] op_sel:[1,0,0] op_sel_hi:[0,1,0]
	v_pk_mul_f32 v[162:163], v[130:131], v[170:171]
	v_pk_fma_f32 v[130:131], v[130:131], v[170:171], v[176:177] op_sel_hi:[1,0,1]
	v_sub_f32_e32 v158, v128, v174
	v_mul_f32_e32 v130, v161, v173
	v_pk_fma_f32 v[170:171], v[160:161], v[172:173], v[130:131] op_sel_hi:[1,1,0] neg_lo:[0,0,1] neg_hi:[0,0,1]
	v_mul_f32_e32 v130, v160, v173
	v_pk_fma_f32 v[172:173], v[160:161], v[172:173], v[130:131] op_sel:[1,0,0] op_sel_hi:[0,1,0]
	v_sub_f32_e32 v130, v162, v176
	v_mov_b32_e32 v162, v166
	v_mov_b32_e32 v163, v168
	v_mov_b32_e32 v160, v170
	v_mov_b32_e32 v161, v172
.LBB0_715:
	v_cvt_pk_bf16_f32 v166, v158, v159
	v_cvt_pk_bf16_f32 v167, v162, v163
	v_cvt_pk_bf16_f32 v168, v130, v131
	v_mov_b64_e32 v[130:131], s[16:17]
	v_mad_i64_i32 v[130:131], s[2:3], v140, s75, v[130:131]
	s_or_b32 s10, s30, 0x80
	s_mul_hi_i32 s2, s10, 0x2aaaaaab
	s_lshr_b32 s3, s2, 31
	s_lshr_b32 s2, s2, 4
	s_add_i32 s2, s2, s3
	s_mulk_i32 s2, 0x60
	s_sub_i32 s2, s10, s2
	s_cmp_eq_u32 s2, 64
	v_or_b32_e32 v128, s30, v0
	s_cselect_b64 s[2:3], -1, 0
	s_cmpk_lt_i32 s10, 0x240
	v_ashrrev_i32_e32 v129, 31, v128
	s_cselect_b64 s[10:11], -1, 0
	v_cvt_pk_bf16_f32 v169, v160, v161
	v_lshl_add_u64 v[158:159], v[128:129], 1, v[130:131]
	v_mov_b32_e32 v160, v156
	v_mov_b32_e32 v161, v156
	s_and_b64 s[2:3], s[10:11], s[2:3]
	v_mov_b32_e32 v157, v156
	global_store_dwordx4 v[158:159], v[166:169], off
	v_pk_mul_f32 v[158:159], v[124:125], v[160:161]
	v_pk_mul_f32 v[124:125], v[120:121], v[160:161]
	v_cndmask_b32_e64 v120, 0, 1, s[2:3]
	v_pk_mul_f32 v[122:123], v[122:123], v[156:157]
	v_cmp_ne_u32_e64 s[10:11], 1, v120
	s_andn2_b64 vcc, exec, s[2:3]
	v_pk_mul_f32 v[118:119], v[118:119], v[156:157]
	s_cbranch_vccnz .LBB0_717
	v_mov_b32_e32 v127, v1
	v_lshl_add_u64 v[120:121], v[132:133], 0, v[126:127]
	global_load_dwordx4 v[160:163], v[120:121], off
	global_load_dwordx4 v[166:169], v[120:121], off offset:16
	s_waitcnt vmcnt(0) lgkmcnt(0)
	v_pk_mul_f32 v[132:133], v[122:123], v[160:161] op_sel:[1,1] op_sel_hi:[0,1]
	v_pk_mul_f32 v[120:121], v[122:123], v[160:161]
	v_pk_fma_f32 v[122:123], v[122:123], v[160:161], v[132:133] op_sel_hi:[1,0,1]
	s_nop 0
	v_mul_f32_e32 v122, v159, v163
	v_pk_fma_f32 v[156:157], v[158:159], v[162:163], v[122:123] op_sel_hi:[1,1,0] neg_lo:[0,0,1] neg_hi:[0,0,1]
	v_mul_f32_e32 v122, v158, v163
	v_pk_fma_f32 v[160:161], v[158:159], v[162:163], v[122:123] op_sel:[1,0,0] op_sel_hi:[0,1,0]
	v_pk_mul_f32 v[162:163], v[118:119], v[166:167] op_sel:[1,1] op_sel_hi:[0,1]
	v_pk_mul_f32 v[158:159], v[118:119], v[166:167]
	v_pk_fma_f32 v[118:119], v[118:119], v[166:167], v[162:163] op_sel_hi:[1,0,1]
	v_sub_f32_e32 v122, v120, v132
	v_mul_f32_e32 v118, v125, v169
	v_pk_fma_f32 v[166:167], v[124:125], v[168:169], v[118:119] op_sel_hi:[1,1,0] neg_lo:[0,0,1] neg_hi:[0,0,1]
	v_mul_f32_e32 v118, v124, v169
	v_pk_fma_f32 v[168:169], v[124:125], v[168:169], v[118:119] op_sel:[1,0,0] op_sel_hi:[0,1,0]
	v_sub_f32_e32 v118, v158, v162
	v_mov_b32_e32 v158, v156
	v_mov_b32_e32 v159, v160
	v_mov_b32_e32 v124, v166
	v_mov_b32_e32 v125, v168
; __device__ __forceinline__ unsigned cvt_pk_bf16(float lo, float hi) { unsigned r; asm volatile("v_cvt_pk_bf16_f32 %0, %1, %2" : "=v"(r) : "v"(lo), "v"(hi)); return r; }
; __device__ __forceinline__ float ssq_val(ssq_t v) { return (float)v * SSQ_IFX; }
;     __device__ __forceinline__ void operator()(const f32x4 (&acc)[2][2][4][2], const Unit& u, int wr, int wc, int fr, int fq) const {
;     ...
;         for (int i = 0; i < 8; ++i) rsv[i] = QS_B / sqrtf(ssq_val(sv[i]) * (1.0f / 384.0f) + EPS);
; #pragma unroll
;         for (int ai = 0; ai < 2; ++ai)
; #pragma unroll
;             for (int m = 0; m < 4; ++m) {
;                 const int row = row0 + ai * HALF + m * 16;
;                 const float rs = rsv[ai * 4 + m];
; #pragma unroll
;                 for (int bj = 0; bj < 2; ++bj) {
;                     const int colw = u.pn * BM + bj * HALF + wc * 32, col0 = colw + 8 * fq;
;                     const bool rope = (colw % 96) == 64 && colw < 576;
;                     f32x4 v0 = acc[ai][bj][m][0] * rs, v1 = acc[ai][bj][m][1] * rs;
;                     if (rope) {
;                         const float* tp = ropB + ((size_t)row * 16 + ((col0 - colw) >> 1)) * 2;
;                         const f32x4 c0 = *(const f32x4*)tp, c1 = *(const f32x4*)(tp + 4);
;                         f32x4 w0, w1;
;                         w0[0] = v0[0] * c0[0] - v0[1] * c0[1]; w0[1] = v0[1] * c0[0] + v0[0] * c0[1];
;                         w0[2] = v0[2] * c0[2] - v0[3] * c0[3]; w0[3] = v0[3] * c0[2] + v0[2] * c0[3];
;                         w1[0] = v1[0] * c1[0] - v1[1] * c1[1]; w1[1] = v1[1] * c1[0] + v1[0] * c1[1];
;                         w1[2] = v1[2] * c1[2] - v1[3] * c1[3]; w1[3] = v1[3] * c1[2] + v1[2] * c1[3];
;                         v0 = w0; v1 = w1;
;                     }
;                     u32x4 w; w.x = cvt_pk_bf16(v0[0], v0[1]); w.y = cvt_pk_bf16(v0[2], v0[3]); w.z = cvt_pk_bf16(v1[0], v1[1]); w.w = cvt_pk_bf16(v1[2], v1[3]);
;                     *(u32x4*)(O + (size_t)row * QMP + col0) = w;
.LBB0_717:
	v_ffbh_u32_e32 v120, v155
	v_min_u32_e32 v127, 32, v120
	v_lshlrev_b64 v[120:121], v127, v[154:155]
	v_min_u32_e32 v120, 1, v120
	v_or_b32_e32 v120, v121, v120
	v_cvt_f32_u32_e32 v120, v120
	v_sub_u32_e32 v121, 32, v127
	s_ashr_i32 s31, s30, 31
	v_cvt_pk_bf16_f32 v154, v122, v123
	v_ldexp_f32 v120, v120, v121
	v_mul_f32_e32 v120, 0x33800000, v120
	v_fmamk_f32 v120, v120, 0x3b2aaaab, v226
	v_mul_f32_e32 v121, 0x4f800000, v120
	v_cmp_gt_f32_e32 vcc, s71, v120
	v_cvt_pk_bf16_f32 v155, v158, v159
	v_cvt_pk_bf16_f32 v156, v118, v119
	v_lshl_add_u64 v[118:119], v[0:1], 0, s[30:31]
	v_lshl_add_u64 v[122:123], v[118:119], 1, v[130:131]
	v_cndmask_b32_e32 v120, v120, v121, vcc
	v_sqrt_f32_e32 v121, v120
	v_cvt_pk_bf16_f32 v157, v124, v125
	global_store_dwordx4 v[122:123], v[154:157], off offset:256
	v_or_b32_e32 v122, 16, v140
	v_add_u32_e32 v127, -1, v121
	v_add_u32_e32 v132, 1, v121
	v_fma_f32 v133, -v127, v121, v120
	v_fma_f32 v141, -v132, v121, v120
	v_cmp_ge_f32_e64 s[12:13], 0, v133
	v_ashrrev_i32_e32 v123, 31, v122
	v_lshlrev_b64 v[130:131], 7, v[122:123]
	v_cndmask_b32_e64 v121, v121, v127, s[12:13]
	v_cmp_lt_f32_e64 s[12:13], 0, v141
	s_nop 1
	v_cndmask_b32_e64 v121, v121, v132, s[12:13]
	v_mul_f32_e32 v127, 0x37800000, v121
	v_cndmask_b32_e32 v121, v121, v127, vcc
	v_cmp_class_f32_e32 vcc, v120, v223
	s_nop 1
	v_cndmask_b32_e32 v120, v121, v120, vcc
	v_div_scale_f32 v121, s[2:3], v120, v120, s69
	v_rcp_f32_e32 v127, v121
	s_nop 0
	v_fma_f32 v132, -v121, v127, 1.0
	v_fmac_f32_e32 v127, v132, v127
	v_div_scale_f32 v132, vcc, s69, v120, s69
	v_mul_f32_e32 v133, v132, v127
	v_fma_f32 v141, -v121, v133, v132
	v_fmac_f32_e32 v133, v141, v127
	v_fma_f32 v121, -v121, v133, v132
	v_div_fmas_f32 v121, v121, v127, v133
	v_div_fixup_f32 v120, v121, v120, s69
	v_pk_mul_f32 v[124:125], v[116:117], v[120:121] op_sel_hi:[1,0]
	v_pk_mul_f32 v[114:115], v[114:115], v[120:121] op_sel_hi:[1,0]
	v_pk_mul_f32 v[116:117], v[112:113], v[120:121] op_sel_hi:[1,0]
	v_pk_mul_f32 v[110:111], v[110:111], v[120:121] op_sel_hi:[1,0]
	s_and_b64 vcc, exec, s[8:9]
	v_lshl_add_u64 v[112:113], s[20:21], 0, v[130:131]
	s_cbranch_vccnz .LBB0_719
	v_mov_b32_e32 v127, v1
	v_lshl_add_u64 v[154:155], v[112:113], 0, v[126:127]
	global_load_dwordx4 v[130:133], v[154:155], off
	s_nop 0
	global_load_dwordx4 v[154:157], v[154:155], off offset:16
	s_waitcnt vmcnt(0) lgkmcnt(0)
	v_pk_mul_f32 v[160:161], v[114:115], v[130:131] op_sel:[1,1] op_sel_hi:[0,1]
	v_mul_f32_e32 v0, v125, v133
	v_pk_mul_f32 v[158:159], v[114:115], v[130:131]
	v_pk_fma_f32 v[114:115], v[114:115], v[130:131], v[160:161] op_sel_hi:[1,0,1]
	v_pk_fma_f32 v[130:131], v[124:125], v[132:133], v[0:1] op_sel_hi:[1,1,0] neg_lo:[0,0,1] neg_hi:[0,0,1]
	v_mul_f32_e32 v0, v124, v133
	v_pk_fma_f32 v[132:133], v[124:125], v[132:133], v[0:1] op_sel:[1,0,0] op_sel_hi:[0,1,0]
	v_pk_mul_f32 v[162:163], v[110:111], v[154:155] op_sel:[1,1] op_sel_hi:[0,1]
	v_mul_f32_e32 v0, v117, v157
	v_pk_mul_f32 v[124:125], v[110:111], v[154:155]
	v_pk_fma_f32 v[110:111], v[110:111], v[154:155], v[162:163] op_sel_hi:[1,0,1]
	v_pk_fma_f32 v[154:155], v[116:117], v[156:157], v[0:1] op_sel_hi:[1,1,0] neg_lo:[0,0,1] neg_hi:[0,0,1]
	v_mul_f32_e32 v0, v116, v157
	v_pk_fma_f32 v[156:157], v[116:117], v[156:157], v[0:1] op_sel:[1,0,0] op_sel_hi:[0,1,0]
	v_sub_f32_e32 v114, v158, v160
	v_sub_f32_e32 v110, v124, v162
	v_mov_b32_e32 v124, v130
	v_mov_b32_e32 v125, v132
	v_mov_b32_e32 v116, v154
	v_mov_b32_e32 v117, v156
.LBB0_719:
	v_cvt_pk_bf16_f32 v130, v114, v115
	v_cvt_pk_bf16_f32 v131, v124, v125
	v_cvt_pk_bf16_f32 v132, v110, v111
	v_mov_b64_e32 v[110:111], s[16:17]
	v_mad_i64_i32 v[110:111], s[2:3], v122, s75, v[110:111]
	v_mov_b32_e32 v121, v120
	v_cvt_pk_bf16_f32 v133, v116, v117
	v_lshl_add_u64 v[114:115], v[128:129], 1, v[110:111]
	v_mov_b32_e32 v116, v120
	v_mov_b32_e32 v117, v120
	global_store_dwordx4 v[114:115], v[130:133], off
	v_pk_mul_f32 v[114:115], v[108:109], v[116:117]
	v_pk_mul_f32 v[106:107], v[106:107], v[120:121]
	v_pk_mul_f32 v[108:109], v[104:105], v[116:117]
	s_and_b64 vcc, exec, s[10:11]
	v_pk_mul_f32 v[102:103], v[102:103], v[120:121]
	s_cbranch_vccnz .LBB0_721
	v_mov_b32_e32 v127, v1
	v_lshl_add_u64 v[104:105], v[112:113], 0, v[126:127]
	global_load_dwordx4 v[120:123], v[104:105], off
	global_load_dwordx4 v[130:133], v[104:105], off offset:16
	s_waitcnt vmcnt(0) lgkmcnt(0)
	v_mul_f32_e32 v0, v115, v123
	v_pk_mul_f32 v[112:113], v[106:107], v[120:121] op_sel:[1,1] op_sel_hi:[0,1]
	v_pk_fma_f32 v[116:117], v[114:115], v[122:123], v[0:1] op_sel_hi:[1,1,0] neg_lo:[0,0,1] neg_hi:[0,0,1]
	v_mul_f32_e32 v0, v114, v123
	v_pk_mul_f32 v[104:105], v[106:107], v[120:121]
	v_pk_fma_f32 v[106:107], v[106:107], v[120:121], v[112:113] op_sel_hi:[1,0,1]
	v_pk_fma_f32 v[120:121], v[114:115], v[122:123], v[0:1] op_sel:[1,0,0] op_sel_hi:[0,1,0]
	v_mul_f32_e32 v0, v109, v133
	v_pk_mul_f32 v[122:123], v[102:103], v[130:131] op_sel:[1,1] op_sel_hi:[0,1]
	v_pk_fma_f32 v[124:125], v[108:109], v[132:133], v[0:1] op_sel_hi:[1,1,0] neg_lo:[0,0,1] neg_hi:[0,0,1]
	v_mul_f32_e32 v0, v108, v133
	v_pk_mul_f32 v[114:115], v[102:103], v[130:131]
	v_pk_fma_f32 v[102:103], v[102:103], v[130:131], v[122:123] op_sel_hi:[1,0,1]
	v_pk_fma_f32 v[130:131], v[108:109], v[132:133], v[0:1] op_sel:[1,0,0] op_sel_hi:[0,1,0]
	v_sub_f32_e32 v106, v104, v112
	v_sub_f32_e32 v102, v114, v122
	v_mov_b32_e32 v114, v116
	v_mov_b32_e32 v115, v120
	v_mov_b32_e32 v108, v124
	v_mov_b32_e32 v109, v130
; __device__ __forceinline__ unsigned cvt_pk_bf16(float lo, float hi) { unsigned r; asm volatile("v_cvt_pk_bf16_f32 %0, %1, %2" : "=v"(r) : "v"(lo), "v"(hi)); return r; }
; __device__ __forceinline__ float ssq_val(ssq_t v) { return (float)v * SSQ_IFX; }
;     __device__ __forceinline__ void operator()(const f32x4 (&acc)[2][2][4][2], const Unit& u, int wr, int wc, int fr, int fq) const {
;     ...
;         for (int i = 0; i < 8; ++i) rsv[i] = QS_B / sqrtf(ssq_val(sv[i]) * (1.0f / 384.0f) + EPS);
; #pragma unroll
;         for (int ai = 0; ai < 2; ++ai)
; #pragma unroll
;             for (int m = 0; m < 4; ++m) {
;                 const int row = row0 + ai * HALF + m * 16;
;                 const float rs = rsv[ai * 4 + m];
; #pragma unroll
;                 for (int bj = 0; bj < 2; ++bj) {
;                     const int colw = u.pn * BM + bj * HALF + wc * 32, col0 = colw + 8 * fq;
;                     const bool rope = (colw % 96) == 64 && colw < 576;
;                     f32x4 v0 = acc[ai][bj][m][0] * rs, v1 = acc[ai][bj][m][1] * rs;
;                     if (rope) {
;                         const float* tp = ropB + ((size_t)row * 16 + ((col0 - colw) >> 1)) * 2;
;                         const f32x4 c0 = *(const f32x4*)tp, c1 = *(const f32x4*)(tp + 4);
;                         f32x4 w0, w1;
;                         w0[0] = v0[0] * c0[0] - v0[1] * c0[1]; w0[1] = v0[1] * c0[0] + v0[0] * c0[1];
;                         w0[2] = v0[2] * c0[2] - v0[3] * c0[3]; w0[3] = v0[3] * c0[2] + v0[2] * c0[3];
;                         w1[0] = v1[0] * c1[0] - v1[1] * c1[1]; w1[1] = v1[1] * c1[0] + v1[0] * c1[1];
;                         w1[2] = v1[2] * c1[2] - v1[3] * c1[3]; w1[3] = v1[3] * c1[2] + v1[2] * c1[3];
;                         v0 = w0; v1 = w1;
;                     }
;                     u32x4 w; w.x = cvt_pk_bf16(v0[0], v0[1]); w.y = cvt_pk_bf16(v0[2], v0[3]); w.z = cvt_pk_bf16(v1[0], v1[1]); w.w = cvt_pk_bf16(v1[2], v1[3]);
;                     *(u32x4*)(O + (size_t)row * QMP + col0) = w;
.LBB0_721:
	v_ffbh_u32_e32 v0, v153
	v_min_u32_e32 v0, 32, v0
	v_lshlrev_b64 v[104:105], v0, v[152:153]
	v_min_u32_e32 v104, 1, v104
	v_or_b32_e32 v104, v105, v104
	v_cvt_f32_u32_e32 v104, v104
	v_sub_u32_e32 v0, 32, v0
	v_ldexp_f32 v0, v104, v0
	v_mul_f32_e32 v0, 0x33800000, v0
	v_fmamk_f32 v0, v0, 0x3b2aaaab, v226
	v_mul_f32_e32 v104, 0x4f800000, v0
	v_cmp_gt_f32_e32 vcc, s71, v0
	s_nop 1
	v_cndmask_b32_e32 v0, v0, v104, vcc
	v_sqrt_f32_e32 v104, v0
	s_nop 0
	v_add_u32_e32 v105, -1, v104
	v_add_u32_e32 v112, 1, v104
	v_fma_f32 v113, -v105, v104, v0
	v_fma_f32 v116, -v112, v104, v0
	v_cmp_ge_f32_e64 s[12:13], 0, v113
	s_nop 1
	v_cndmask_b32_e64 v104, v104, v105, s[12:13]
	v_cmp_lt_f32_e64 s[12:13], 0, v116
	s_nop 1
	v_cndmask_b32_e64 v104, v104, v112, s[12:13]
	v_mul_f32_e32 v105, 0x37800000, v104
	v_cndmask_b32_e32 v104, v104, v105, vcc
	v_cmp_class_f32_e32 vcc, v0, v223
	s_nop 1
	v_cndmask_b32_e32 v0, v104, v0, vcc
	v_div_scale_f32 v104, s[2:3], v0, v0, s69
	v_rcp_f32_e32 v105, v104
	s_nop 0
	v_fma_f32 v112, -v104, v105, 1.0
	v_fmac_f32_e32 v105, v112, v105
	v_div_scale_f32 v112, vcc, s69, v0, s69
	v_mul_f32_e32 v113, v112, v105
	v_fma_f32 v116, -v104, v113, v112
	v_fmac_f32_e32 v113, v116, v105
	v_fma_f32 v104, -v104, v113, v112
	v_div_fmas_f32 v104, v104, v105, v113
	v_cvt_pk_bf16_f32 v112, v106, v107
	v_cvt_pk_bf16_f32 v113, v114, v115
	v_cvt_pk_bf16_f32 v114, v102, v103
	v_lshl_add_u64 v[102:103], v[118:119], 1, v[110:111]
	v_cvt_pk_bf16_f32 v115, v108, v109
	global_store_dwordx4 v[102:103], v[112:115], off offset:256
	v_or_b32_e32 v102, 32, v140
	v_ashrrev_i32_e32 v103, 31, v102
	v_div_fixup_f32 v104, v104, v0, s69
	v_lshlrev_b64 v[108:109], 7, v[102:103]
	v_pk_mul_f32 v[106:107], v[100:101], v[104:105] op_sel_hi:[1,0]
	v_pk_mul_f32 v[98:99], v[98:99], v[104:105] op_sel_hi:[1,0]
	v_pk_mul_f32 v[100:101], v[96:97], v[104:105] op_sel_hi:[1,0]
	v_pk_mul_f32 v[94:95], v[94:95], v[104:105] op_sel_hi:[1,0]
	s_and_b64 vcc, exec, s[8:9]
	v_lshl_add_u64 v[96:97], s[20:21], 0, v[108:109]
	s_cbranch_vccnz .LBB0_723
	v_mov_b32_e32 v127, v1
	v_lshl_add_u64 v[112:113], v[96:97], 0, v[126:127]
	global_load_dwordx4 v[108:111], v[112:113], off
	s_nop 0
	global_load_dwordx4 v[112:115], v[112:113], off offset:16
	s_waitcnt vmcnt(0) lgkmcnt(0)
	v_pk_mul_f32 v[120:121], v[98:99], v[108:109] op_sel:[1,1] op_sel_hi:[0,1]
	v_mul_f32_e32 v0, v107, v111
	v_pk_mul_f32 v[116:117], v[98:99], v[108:109]
	v_pk_fma_f32 v[98:99], v[98:99], v[108:109], v[120:121] op_sel_hi:[1,0,1]
	v_pk_fma_f32 v[108:109], v[106:107], v[110:111], v[0:1] op_sel_hi:[1,1,0] neg_lo:[0,0,1] neg_hi:[0,0,1]
	v_mul_f32_e32 v0, v106, v111
	v_pk_fma_f32 v[110:111], v[106:107], v[110:111], v[0:1] op_sel:[1,0,0] op_sel_hi:[0,1,0]
	v_pk_mul_f32 v[122:123], v[94:95], v[112:113] op_sel:[1,1] op_sel_hi:[0,1]
	v_mul_f32_e32 v0, v101, v115
	v_pk_mul_f32 v[106:107], v[94:95], v[112:113]
	v_pk_fma_f32 v[94:95], v[94:95], v[112:113], v[122:123] op_sel_hi:[1,0,1]
	v_pk_fma_f32 v[112:113], v[100:101], v[114:115], v[0:1] op_sel_hi:[1,1,0] neg_lo:[0,0,1] neg_hi:[0,0,1]
	v_mul_f32_e32 v0, v100, v115
	v_pk_fma_f32 v[114:115], v[100:101], v[114:115], v[0:1] op_sel:[1,0,0] op_sel_hi:[0,1,0]
	v_sub_f32_e32 v98, v116, v120
	v_sub_f32_e32 v94, v106, v122
	v_mov_b32_e32 v106, v108
	v_mov_b32_e32 v107, v110
	v_mov_b32_e32 v100, v112
	v_mov_b32_e32 v101, v114
.LBB0_723:
	v_cvt_pk_bf16_f32 v108, v98, v99
	v_cvt_pk_bf16_f32 v109, v106, v107
	v_cvt_pk_bf16_f32 v110, v94, v95
	v_mov_b64_e32 v[94:95], s[16:17]
	v_mad_i64_i32 v[94:95], s[2:3], v102, s75, v[94:95]
	v_mov_b32_e32 v105, v104
	v_cvt_pk_bf16_f32 v111, v100, v101
	v_lshl_add_u64 v[98:99], v[128:129], 1, v[94:95]
	v_mov_b32_e32 v100, v104
	v_mov_b32_e32 v101, v104
	global_store_dwordx4 v[98:99], v[108:111], off
	v_pk_mul_f32 v[98:99], v[92:93], v[100:101]
	v_pk_mul_f32 v[90:91], v[90:91], v[104:105]
	v_pk_mul_f32 v[92:93], v[88:89], v[100:101]
	s_and_b64 vcc, exec, s[10:11]
	v_pk_mul_f32 v[86:87], v[86:87], v[104:105]
	s_cbranch_vccnz .LBB0_725
	v_mov_b32_e32 v127, v1
	v_lshl_add_u64 v[88:89], v[96:97], 0, v[126:127]
	global_load_dwordx4 v[100:103], v[88:89], off
	global_load_dwordx4 v[104:107], v[88:89], off offset:16
	s_waitcnt vmcnt(0) lgkmcnt(0)
	v_pk_mul_f32 v[96:97], v[90:91], v[100:101] op_sel:[1,1] op_sel_hi:[0,1]
	v_mul_f32_e32 v0, v99, v103
	v_pk_mul_f32 v[88:89], v[90:91], v[100:101]
	v_pk_fma_f32 v[90:91], v[90:91], v[100:101], v[96:97] op_sel_hi:[1,0,1]
	v_pk_fma_f32 v[100:101], v[98:99], v[102:103], v[0:1] op_sel_hi:[1,1,0] neg_lo:[0,0,1] neg_hi:[0,0,1]
	v_mul_f32_e32 v0, v98, v103
	v_pk_fma_f32 v[102:103], v[98:99], v[102:103], v[0:1] op_sel:[1,0,0] op_sel_hi:[0,1,0]
	v_pk_mul_f32 v[108:109], v[86:87], v[104:105] op_sel:[1,1] op_sel_hi:[0,1]
	v_mul_f32_e32 v0, v93, v107
	v_pk_mul_f32 v[98:99], v[86:87], v[104:105]
	v_pk_fma_f32 v[86:87], v[86:87], v[104:105], v[108:109] op_sel_hi:[1,0,1]
	v_pk_fma_f32 v[104:105], v[92:93], v[106:107], v[0:1] op_sel_hi:[1,1,0] neg_lo:[0,0,1] neg_hi:[0,0,1]
	v_mul_f32_e32 v0, v92, v107
	v_pk_fma_f32 v[106:107], v[92:93], v[106:107], v[0:1] op_sel:[1,0,0] op_sel_hi:[0,1,0]
	v_sub_f32_e32 v90, v88, v96
	v_sub_f32_e32 v86, v98, v108
	v_mov_b32_e32 v98, v100
	v_mov_b32_e32 v99, v102
	v_mov_b32_e32 v92, v104
	v_mov_b32_e32 v93, v106
; __device__ __forceinline__ unsigned cvt_pk_bf16(float lo, float hi) { unsigned r; asm volatile("v_cvt_pk_bf16_f32 %0, %1, %2" : "=v"(r) : "v"(lo), "v"(hi)); return r; }
; __device__ __forceinline__ float ssq_val(ssq_t v) { return (float)v * SSQ_IFX; }
;     __device__ __forceinline__ void operator()(const f32x4 (&acc)[2][2][4][2], const Unit& u, int wr, int wc, int fr, int fq) const {
;     ...
;         for (int i = 0; i < 8; ++i) rsv[i] = QS_B / sqrtf(ssq_val(sv[i]) * (1.0f / 384.0f) + EPS);
; #pragma unroll
;         for (int ai = 0; ai < 2; ++ai)
; #pragma unroll
;             for (int m = 0; m < 4; ++m) {
;                 const int row = row0 + ai * HALF + m * 16;
;                 const float rs = rsv[ai * 4 + m];
; #pragma unroll
;                 for (int bj = 0; bj < 2; ++bj) {
;                     const int colw = u.pn * BM + bj * HALF + wc * 32, col0 = colw + 8 * fq;
;                     const bool rope = (colw % 96) == 64 && colw < 576;
;                     f32x4 v0 = acc[ai][bj][m][0] * rs, v1 = acc[ai][bj][m][1] * rs;
;                     if (rope) {
;                         const float* tp = ropB + ((size_t)row * 16 + ((col0 - colw) >> 1)) * 2;
;                         const f32x4 c0 = *(const f32x4*)tp, c1 = *(const f32x4*)(tp + 4);
;                         f32x4 w0, w1;
;                         w0[0] = v0[0] * c0[0] - v0[1] * c0[1]; w0[1] = v0[1] * c0[0] + v0[0] * c0[1];
;                         w0[2] = v0[2] * c0[2] - v0[3] * c0[3]; w0[3] = v0[3] * c0[2] + v0[2] * c0[3];
;                         w1[0] = v1[0] * c1[0] - v1[1] * c1[1]; w1[1] = v1[1] * c1[0] + v1[0] * c1[1];
;                         w1[2] = v1[2] * c1[2] - v1[3] * c1[3]; w1[3] = v1[3] * c1[2] + v1[2] * c1[3];
;                         v0 = w0; v1 = w1;
;                     }
;                     u32x4 w; w.x = cvt_pk_bf16(v0[0], v0[1]); w.y = cvt_pk_bf16(v0[2], v0[3]); w.z = cvt_pk_bf16(v1[0], v1[1]); w.w = cvt_pk_bf16(v1[2], v1[3]);
;                     *(u32x4*)(O + (size_t)row * QMP + col0) = w;
.LBB0_725:
	v_ffbh_u32_e32 v0, v151
	v_min_u32_e32 v0, 32, v0
	v_lshlrev_b64 v[88:89], v0, v[150:151]
	v_min_u32_e32 v88, 1, v88
	v_or_b32_e32 v88, v89, v88
	v_cvt_f32_u32_e32 v88, v88
	v_sub_u32_e32 v0, 32, v0
	v_ldexp_f32 v0, v88, v0
	v_mul_f32_e32 v0, 0x33800000, v0
	v_fmamk_f32 v0, v0, 0x3b2aaaab, v226
	v_mul_f32_e32 v88, 0x4f800000, v0
	v_cmp_gt_f32_e32 vcc, s71, v0
	s_nop 1
	v_cndmask_b32_e32 v0, v0, v88, vcc
	v_sqrt_f32_e32 v88, v0
	s_nop 0
	v_add_u32_e32 v89, -1, v88
	v_add_u32_e32 v96, 1, v88
	v_fma_f32 v97, -v89, v88, v0
	v_fma_f32 v100, -v96, v88, v0
	v_cmp_ge_f32_e64 s[12:13], 0, v97
	s_nop 1
	v_cndmask_b32_e64 v88, v88, v89, s[12:13]
	v_cmp_lt_f32_e64 s[12:13], 0, v100
	s_nop 1
	v_cndmask_b32_e64 v88, v88, v96, s[12:13]
	v_mul_f32_e32 v89, 0x37800000, v88
	v_cndmask_b32_e32 v88, v88, v89, vcc
	v_cmp_class_f32_e32 vcc, v0, v223
	s_nop 1
	v_cndmask_b32_e32 v0, v88, v0, vcc
	v_div_scale_f32 v88, s[2:3], v0, v0, s69
	v_rcp_f32_e32 v89, v88
	s_nop 0
	v_fma_f32 v96, -v88, v89, 1.0
	v_fmac_f32_e32 v89, v96, v89
	v_div_scale_f32 v96, vcc, s69, v0, s69
	v_mul_f32_e32 v97, v96, v89
	v_fma_f32 v100, -v88, v97, v96
	v_fmac_f32_e32 v97, v100, v89
	v_fma_f32 v88, -v88, v97, v96
	v_div_fmas_f32 v88, v88, v89, v97
	v_cvt_pk_bf16_f32 v96, v90, v91
	v_cvt_pk_bf16_f32 v97, v98, v99
	v_cvt_pk_bf16_f32 v98, v86, v87
	v_lshl_add_u64 v[86:87], v[118:119], 1, v[94:95]
	v_cvt_pk_bf16_f32 v99, v92, v93
	global_store_dwordx4 v[86:87], v[96:99], off offset:256
	v_or_b32_e32 v86, 48, v140
	v_ashrrev_i32_e32 v87, 31, v86
	v_div_fixup_f32 v88, v88, v0, s69
	v_lshlrev_b64 v[92:93], 7, v[86:87]
	v_pk_mul_f32 v[90:91], v[84:85], v[88:89] op_sel_hi:[1,0]
	v_pk_mul_f32 v[82:83], v[82:83], v[88:89] op_sel_hi:[1,0]
	v_pk_mul_f32 v[84:85], v[80:81], v[88:89] op_sel_hi:[1,0]
	v_pk_mul_f32 v[78:79], v[78:79], v[88:89] op_sel_hi:[1,0]
	s_and_b64 vcc, exec, s[8:9]
	v_lshl_add_u64 v[80:81], s[20:21], 0, v[92:93]
	s_cbranch_vccnz .LBB0_727
	v_mov_b32_e32 v127, v1
	v_lshl_add_u64 v[96:97], v[80:81], 0, v[126:127]
	global_load_dwordx4 v[92:95], v[96:97], off
	s_nop 0
	global_load_dwordx4 v[96:99], v[96:97], off offset:16
	s_waitcnt vmcnt(0) lgkmcnt(0)
	v_pk_mul_f32 v[102:103], v[82:83], v[92:93] op_sel:[1,1] op_sel_hi:[0,1]
	v_mul_f32_e32 v0, v91, v95
	v_pk_mul_f32 v[100:101], v[82:83], v[92:93]
	v_pk_fma_f32 v[82:83], v[82:83], v[92:93], v[102:103] op_sel_hi:[1,0,1]
	v_pk_fma_f32 v[92:93], v[90:91], v[94:95], v[0:1] op_sel_hi:[1,1,0] neg_lo:[0,0,1] neg_hi:[0,0,1]
	v_mul_f32_e32 v0, v90, v95
	v_pk_fma_f32 v[94:95], v[90:91], v[94:95], v[0:1] op_sel:[1,0,0] op_sel_hi:[0,1,0]
	v_pk_mul_f32 v[104:105], v[78:79], v[96:97] op_sel:[1,1] op_sel_hi:[0,1]
	v_mul_f32_e32 v0, v85, v99
	v_pk_mul_f32 v[90:91], v[78:79], v[96:97]
	v_pk_fma_f32 v[78:79], v[78:79], v[96:97], v[104:105] op_sel_hi:[1,0,1]
	v_pk_fma_f32 v[96:97], v[84:85], v[98:99], v[0:1] op_sel_hi:[1,1,0] neg_lo:[0,0,1] neg_hi:[0,0,1]
	v_mul_f32_e32 v0, v84, v99
	v_pk_fma_f32 v[98:99], v[84:85], v[98:99], v[0:1] op_sel:[1,0,0] op_sel_hi:[0,1,0]
	v_sub_f32_e32 v82, v100, v102
	v_sub_f32_e32 v78, v90, v104
	v_mov_b32_e32 v90, v92
	v_mov_b32_e32 v91, v94
	v_mov_b32_e32 v84, v96
	v_mov_b32_e32 v85, v98
.LBB0_727:
	v_cvt_pk_bf16_f32 v92, v82, v83
	v_cvt_pk_bf16_f32 v93, v90, v91
	v_cvt_pk_bf16_f32 v94, v78, v79
	v_mov_b64_e32 v[78:79], s[16:17]
	v_mad_i64_i32 v[78:79], s[2:3], v86, s75, v[78:79]
	v_mov_b32_e32 v89, v88
	v_cvt_pk_bf16_f32 v95, v84, v85
	v_lshl_add_u64 v[82:83], v[128:129], 1, v[78:79]
	v_mov_b32_e32 v84, v88
	v_mov_b32_e32 v85, v88
	global_store_dwordx4 v[82:83], v[92:95], off
	v_pk_mul_f32 v[82:83], v[76:77], v[84:85]
	v_pk_mul_f32 v[74:75], v[74:75], v[88:89]
	v_pk_mul_f32 v[72:73], v[72:73], v[84:85]
	s_and_b64 vcc, exec, s[10:11]
	v_pk_mul_f32 v[70:71], v[70:71], v[88:89]
	s_cbranch_vccnz .LBB0_729
	v_mov_b32_e32 v127, v1
	v_lshl_add_u64 v[76:77], v[80:81], 0, v[126:127]
	global_load_dwordx4 v[84:87], v[76:77], off
	global_load_dwordx4 v[88:91], v[76:77], off offset:16
	s_waitcnt vmcnt(0) lgkmcnt(0)
	v_pk_mul_f32 v[80:81], v[74:75], v[84:85] op_sel:[1,1] op_sel_hi:[0,1]
	v_mul_f32_e32 v0, v83, v87
	v_pk_mul_f32 v[76:77], v[74:75], v[84:85]
	v_pk_fma_f32 v[74:75], v[74:75], v[84:85], v[80:81] op_sel_hi:[1,0,1]
	v_pk_fma_f32 v[84:85], v[82:83], v[86:87], v[0:1] op_sel_hi:[1,1,0] neg_lo:[0,0,1] neg_hi:[0,0,1]
	v_mul_f32_e32 v0, v82, v87
	v_pk_fma_f32 v[86:87], v[82:83], v[86:87], v[0:1] op_sel:[1,0,0] op_sel_hi:[0,1,0]
	v_pk_mul_f32 v[92:93], v[70:71], v[88:89] op_sel:[1,1] op_sel_hi:[0,1]
	v_mul_f32_e32 v0, v73, v91
	v_pk_mul_f32 v[82:83], v[70:71], v[88:89]
	v_pk_fma_f32 v[70:71], v[70:71], v[88:89], v[92:93] op_sel_hi:[1,0,1]
	v_pk_fma_f32 v[88:89], v[72:73], v[90:91], v[0:1] op_sel_hi:[1,1,0] neg_lo:[0,0,1] neg_hi:[0,0,1]
	v_mul_f32_e32 v0, v72, v91
	v_pk_fma_f32 v[90:91], v[72:73], v[90:91], v[0:1] op_sel:[1,0,0] op_sel_hi:[0,1,0]
	v_sub_f32_e32 v74, v76, v80
	v_sub_f32_e32 v70, v82, v92
	v_mov_b32_e32 v82, v84
	v_mov_b32_e32 v83, v86
	v_mov_b32_e32 v72, v88
	v_mov_b32_e32 v73, v90
; __device__ __forceinline__ unsigned cvt_pk_bf16(float lo, float hi) { unsigned r; asm volatile("v_cvt_pk_bf16_f32 %0, %1, %2" : "=v"(r) : "v"(lo), "v"(hi)); return r; }
; __device__ __forceinline__ float ssq_val(ssq_t v) { return (float)v * SSQ_IFX; }
;     __device__ __forceinline__ void operator()(const f32x4 (&acc)[2][2][4][2], const Unit& u, int wr, int wc, int fr, int fq) const {
;     ...
;         for (int i = 0; i < 8; ++i) rsv[i] = QS_B / sqrtf(ssq_val(sv[i]) * (1.0f / 384.0f) + EPS);
; #pragma unroll
;         for (int ai = 0; ai < 2; ++ai)
; #pragma unroll
;             for (int m = 0; m < 4; ++m) {
;                 const int row = row0 + ai * HALF + m * 16;
;                 const float rs = rsv[ai * 4 + m];
; #pragma unroll
;                 for (int bj = 0; bj < 2; ++bj) {
;                     const int colw = u.pn * BM + bj * HALF + wc * 32, col0 = colw + 8 * fq;
;                     const bool rope = (colw % 96) == 64 && colw < 576;
;                     f32x4 v0 = acc[ai][bj][m][0] * rs, v1 = acc[ai][bj][m][1] * rs;
;                     if (rope) {
;                         const float* tp = ropB + ((size_t)row * 16 + ((col0 - colw) >> 1)) * 2;
;                         const f32x4 c0 = *(const f32x4*)tp, c1 = *(const f32x4*)(tp + 4);
;                         f32x4 w0, w1;
;                         w0[0] = v0[0] * c0[0] - v0[1] * c0[1]; w0[1] = v0[1] * c0[0] + v0[0] * c0[1];
;                         w0[2] = v0[2] * c0[2] - v0[3] * c0[3]; w0[3] = v0[3] * c0[2] + v0[2] * c0[3];
;                         w1[0] = v1[0] * c1[0] - v1[1] * c1[1]; w1[1] = v1[1] * c1[0] + v1[0] * c1[1];
;                         w1[2] = v1[2] * c1[2] - v1[3] * c1[3]; w1[3] = v1[3] * c1[2] + v1[2] * c1[3];
;                         v0 = w0; v1 = w1;
;                     }
;                     u32x4 w; w.x = cvt_pk_bf16(v0[0], v0[1]); w.y = cvt_pk_bf16(v0[2], v0[3]); w.z = cvt_pk_bf16(v1[0], v1[1]); w.w = cvt_pk_bf16(v1[2], v1[3]);
;                     *(u32x4*)(O + (size_t)row * QMP + col0) = w;
.LBB0_729:
	v_ffbh_u32_e32 v0, v149
	v_min_u32_e32 v0, 32, v0
	v_lshlrev_b64 v[76:77], v0, v[148:149]
	v_min_u32_e32 v76, 1, v76
	v_or_b32_e32 v76, v77, v76
	v_cvt_f32_u32_e32 v76, v76
	v_sub_u32_e32 v0, 32, v0
	v_ldexp_f32 v0, v76, v0
	v_mul_f32_e32 v0, 0x33800000, v0
	v_fmamk_f32 v0, v0, 0x3b2aaaab, v226
	v_mul_f32_e32 v76, 0x4f800000, v0
	v_cmp_gt_f32_e32 vcc, s71, v0
	s_nop 1
	v_cndmask_b32_e32 v0, v0, v76, vcc
	v_sqrt_f32_e32 v76, v0
	s_nop 0
	v_add_u32_e32 v77, -1, v76
	v_add_u32_e32 v80, 1, v76
	v_fma_f32 v81, -v77, v76, v0
	v_fma_f32 v84, -v80, v76, v0
	v_cmp_ge_f32_e64 s[12:13], 0, v81
	s_nop 1
	v_cndmask_b32_e64 v76, v76, v77, s[12:13]
	v_cmp_lt_f32_e64 s[12:13], 0, v84
	s_nop 1
	v_cndmask_b32_e64 v76, v76, v80, s[12:13]
	v_mul_f32_e32 v77, 0x37800000, v76
	v_cndmask_b32_e32 v76, v76, v77, vcc
	v_cmp_class_f32_e32 vcc, v0, v223
	v_add_u32_e32 v80, 0x80, v140
	v_ashrrev_i32_e32 v81, 31, v80
	v_cndmask_b32_e32 v0, v76, v0, vcc
	v_div_scale_f32 v76, s[2:3], v0, v0, s69
	v_rcp_f32_e32 v77, v76
	s_nop 0
	v_fma_f32 v84, -v76, v77, 1.0
	v_fmac_f32_e32 v77, v84, v77
	v_div_scale_f32 v84, vcc, s69, v0, s69
	v_mul_f32_e32 v85, v84, v77
	v_fma_f32 v86, -v76, v85, v84
	v_fmac_f32_e32 v85, v86, v77
	v_fma_f32 v76, -v76, v85, v84
	v_div_fmas_f32 v76, v76, v77, v85
	v_div_fixup_f32 v76, v76, v0, s69
	v_cvt_pk_bf16_f32 v84, v74, v75
	v_cvt_pk_bf16_f32 v85, v82, v83
	v_cvt_pk_bf16_f32 v86, v70, v71
	v_cvt_pk_bf16_f32 v87, v72, v73
	v_lshl_add_u64 v[70:71], v[118:119], 1, v[78:79]
	v_lshlrev_b64 v[72:73], 7, v[80:81]
	global_store_dwordx4 v[70:71], v[84:87], off offset:256
	v_pk_mul_f32 v[70:71], v[68:69], v[76:77] op_sel_hi:[1,0]
	v_pk_mul_f32 v[66:67], v[66:67], v[76:77] op_sel_hi:[1,0]
	v_pk_mul_f32 v[68:69], v[64:65], v[76:77] op_sel_hi:[1,0]
	v_pk_mul_f32 v[62:63], v[62:63], v[76:77] op_sel_hi:[1,0]
	s_and_b64 vcc, exec, s[8:9]
	v_lshl_add_u64 v[64:65], s[20:21], 0, v[72:73]
	s_cbranch_vccnz .LBB0_731
	v_mov_b32_e32 v127, v1
	v_lshl_add_u64 v[78:79], v[64:65], 0, v[126:127]
	global_load_dwordx4 v[72:75], v[78:79], off
	global_load_dwordx4 v[82:85], v[78:79], off offset:16
	s_waitcnt vmcnt(0) lgkmcnt(0)
	v_pk_mul_f32 v[86:87], v[66:67], v[72:73] op_sel:[1,1] op_sel_hi:[0,1]
	v_mul_f32_e32 v0, v71, v75
	v_pk_mul_f32 v[78:79], v[66:67], v[72:73]
	v_pk_fma_f32 v[66:67], v[66:67], v[72:73], v[86:87] op_sel_hi:[1,0,1]
	v_pk_fma_f32 v[72:73], v[70:71], v[74:75], v[0:1] op_sel_hi:[1,1,0] neg_lo:[0,0,1] neg_hi:[0,0,1]
	v_mul_f32_e32 v0, v70, v75
	v_pk_fma_f32 v[74:75], v[70:71], v[74:75], v[0:1] op_sel:[1,0,0] op_sel_hi:[0,1,0]
	v_pk_mul_f32 v[88:89], v[62:63], v[82:83] op_sel:[1,1] op_sel_hi:[0,1]
	v_mul_f32_e32 v0, v69, v85
	v_pk_mul_f32 v[70:71], v[62:63], v[82:83]
	v_pk_fma_f32 v[62:63], v[62:63], v[82:83], v[88:89] op_sel_hi:[1,0,1]
	v_pk_fma_f32 v[82:83], v[68:69], v[84:85], v[0:1] op_sel_hi:[1,1,0] neg_lo:[0,0,1] neg_hi:[0,0,1]
	v_mul_f32_e32 v0, v68, v85
	v_pk_fma_f32 v[84:85], v[68:69], v[84:85], v[0:1] op_sel:[1,0,0] op_sel_hi:[0,1,0]
	v_sub_f32_e32 v66, v78, v86
	v_sub_f32_e32 v62, v70, v88
	v_mov_b32_e32 v70, v72
	v_mov_b32_e32 v71, v74
	v_mov_b32_e32 v68, v82
	v_mov_b32_e32 v69, v84
.LBB0_731:
	v_cvt_pk_bf16_f32 v72, v66, v67
	v_cvt_pk_bf16_f32 v73, v70, v71
	v_cvt_pk_bf16_f32 v74, v62, v63
	v_mov_b64_e32 v[62:63], s[16:17]
	v_mad_i64_i32 v[62:63], s[2:3], v80, s75, v[62:63]
	v_mov_b32_e32 v77, v76
	v_cvt_pk_bf16_f32 v75, v68, v69
	v_lshl_add_u64 v[66:67], v[128:129], 1, v[62:63]
	v_mov_b32_e32 v68, v76
	v_mov_b32_e32 v69, v76
	global_store_dwordx4 v[66:67], v[72:75], off
	v_pk_mul_f32 v[66:67], v[60:61], v[68:69]
	v_pk_mul_f32 v[58:59], v[58:59], v[76:77]
	v_pk_mul_f32 v[60:61], v[56:57], v[68:69]
	s_and_b64 vcc, exec, s[10:11]
	v_pk_mul_f32 v[54:55], v[54:55], v[76:77]
	s_cbranch_vccnz .LBB0_733
	v_mov_b32_e32 v127, v1
	v_lshl_add_u64 v[56:57], v[64:65], 0, v[126:127]
	global_load_dwordx4 v[68:71], v[56:57], off
	global_load_dwordx4 v[72:75], v[56:57], off offset:16
	s_waitcnt vmcnt(0) lgkmcnt(0)
	v_pk_mul_f32 v[64:65], v[58:59], v[68:69] op_sel:[1,1] op_sel_hi:[0,1]
	v_mul_f32_e32 v0, v67, v71
	v_pk_mul_f32 v[56:57], v[58:59], v[68:69]
	v_pk_fma_f32 v[58:59], v[58:59], v[68:69], v[64:65] op_sel_hi:[1,0,1]
	v_pk_fma_f32 v[68:69], v[66:67], v[70:71], v[0:1] op_sel_hi:[1,1,0] neg_lo:[0,0,1] neg_hi:[0,0,1]
	v_mul_f32_e32 v0, v66, v71
	v_pk_fma_f32 v[70:71], v[66:67], v[70:71], v[0:1] op_sel:[1,0,0] op_sel_hi:[0,1,0]
	v_pk_mul_f32 v[76:77], v[54:55], v[72:73] op_sel:[1,1] op_sel_hi:[0,1]
	v_mul_f32_e32 v0, v61, v75
	v_pk_mul_f32 v[66:67], v[54:55], v[72:73]
	v_pk_fma_f32 v[54:55], v[54:55], v[72:73], v[76:77] op_sel_hi:[1,0,1]
	v_pk_fma_f32 v[72:73], v[60:61], v[74:75], v[0:1] op_sel_hi:[1,1,0] neg_lo:[0,0,1] neg_hi:[0,0,1]
	v_mul_f32_e32 v0, v60, v75
	v_pk_fma_f32 v[74:75], v[60:61], v[74:75], v[0:1] op_sel:[1,0,0] op_sel_hi:[0,1,0]
	v_sub_f32_e32 v58, v56, v64
	v_sub_f32_e32 v54, v66, v76
	v_mov_b32_e32 v66, v68
	v_mov_b32_e32 v67, v70
	v_mov_b32_e32 v60, v72
	v_mov_b32_e32 v61, v74
; __device__ __forceinline__ unsigned cvt_pk_bf16(float lo, float hi) { unsigned r; asm volatile("v_cvt_pk_bf16_f32 %0, %1, %2" : "=v"(r) : "v"(lo), "v"(hi)); return r; }
; __device__ __forceinline__ float ssq_val(ssq_t v) { return (float)v * SSQ_IFX; }
;     __device__ __forceinline__ void operator()(const f32x4 (&acc)[2][2][4][2], const Unit& u, int wr, int wc, int fr, int fq) const {
;     ...
;         for (int i = 0; i < 8; ++i) rsv[i] = QS_B / sqrtf(ssq_val(sv[i]) * (1.0f / 384.0f) + EPS);
; #pragma unroll
;         for (int ai = 0; ai < 2; ++ai)
; #pragma unroll
;             for (int m = 0; m < 4; ++m) {
;                 const int row = row0 + ai * HALF + m * 16;
;                 const float rs = rsv[ai * 4 + m];
; #pragma unroll
;                 for (int bj = 0; bj < 2; ++bj) {
;                     const int colw = u.pn * BM + bj * HALF + wc * 32, col0 = colw + 8 * fq;
;                     const bool rope = (colw % 96) == 64 && colw < 576;
;                     f32x4 v0 = acc[ai][bj][m][0] * rs, v1 = acc[ai][bj][m][1] * rs;
;                     if (rope) {
;                         const float* tp = ropB + ((size_t)row * 16 + ((col0 - colw) >> 1)) * 2;
;                         const f32x4 c0 = *(const f32x4*)tp, c1 = *(const f32x4*)(tp + 4);
;                         f32x4 w0, w1;
;                         w0[0] = v0[0] * c0[0] - v0[1] * c0[1]; w0[1] = v0[1] * c0[0] + v0[0] * c0[1];
;                         w0[2] = v0[2] * c0[2] - v0[3] * c0[3]; w0[3] = v0[3] * c0[2] + v0[2] * c0[3];
;                         w1[0] = v1[0] * c1[0] - v1[1] * c1[1]; w1[1] = v1[1] * c1[0] + v1[0] * c1[1];
;                         w1[2] = v1[2] * c1[2] - v1[3] * c1[3]; w1[3] = v1[3] * c1[2] + v1[2] * c1[3];
;                         v0 = w0; v1 = w1;
;                     }
;                     u32x4 w; w.x = cvt_pk_bf16(v0[0], v0[1]); w.y = cvt_pk_bf16(v0[2], v0[3]); w.z = cvt_pk_bf16(v1[0], v1[1]); w.w = cvt_pk_bf16(v1[2], v1[3]);
;                     *(u32x4*)(O + (size_t)row * QMP + col0) = w;
.LBB0_733:
	v_ffbh_u32_e32 v0, v147
	v_min_u32_e32 v0, 32, v0
	v_lshlrev_b64 v[56:57], v0, v[146:147]
	v_min_u32_e32 v56, 1, v56
	v_or_b32_e32 v56, v57, v56
	v_cvt_f32_u32_e32 v56, v56
	v_sub_u32_e32 v0, 32, v0
	v_ldexp_f32 v0, v56, v0
	v_mul_f32_e32 v0, 0x33800000, v0
	v_fmamk_f32 v0, v0, 0x3b2aaaab, v226
	v_mul_f32_e32 v56, 0x4f800000, v0
	v_cmp_gt_f32_e32 vcc, s71, v0
	s_nop 1
	v_cndmask_b32_e32 v0, v0, v56, vcc
	v_sqrt_f32_e32 v56, v0
	s_nop 0
	v_add_u32_e32 v57, -1, v56
	v_add_u32_e32 v64, 1, v56
	v_fma_f32 v65, -v57, v56, v0
	v_fma_f32 v68, -v64, v56, v0
	v_cmp_ge_f32_e64 s[12:13], 0, v65
	s_nop 1
	v_cndmask_b32_e64 v56, v56, v57, s[12:13]
	v_cmp_lt_f32_e64 s[12:13], 0, v68
	s_nop 1
	v_cndmask_b32_e64 v56, v56, v64, s[12:13]
	v_mul_f32_e32 v57, 0x37800000, v56
	v_cndmask_b32_e32 v56, v56, v57, vcc
	v_cmp_class_f32_e32 vcc, v0, v223
	s_nop 1
	v_cndmask_b32_e32 v0, v56, v0, vcc
	v_div_scale_f32 v56, s[2:3], v0, v0, s69
	v_rcp_f32_e32 v57, v56
	s_nop 0
	v_fma_f32 v64, -v56, v57, 1.0
	v_fmac_f32_e32 v57, v64, v57
	v_div_scale_f32 v64, vcc, s69, v0, s69
	v_mul_f32_e32 v65, v64, v57
	v_fma_f32 v68, -v56, v65, v64
	v_fmac_f32_e32 v65, v68, v57
	v_fma_f32 v56, -v56, v65, v64
	v_div_fmas_f32 v56, v56, v57, v65
	v_cvt_pk_bf16_f32 v64, v58, v59
	v_cvt_pk_bf16_f32 v65, v66, v67
	v_cvt_pk_bf16_f32 v66, v54, v55
	v_lshl_add_u64 v[54:55], v[118:119], 1, v[62:63]
	v_cvt_pk_bf16_f32 v67, v60, v61
	global_store_dwordx4 v[54:55], v[64:67], off offset:256
	v_add_u32_e32 v54, 0x90, v140
	v_ashrrev_i32_e32 v55, 31, v54
	v_div_fixup_f32 v56, v56, v0, s69
	v_lshlrev_b64 v[60:61], 7, v[54:55]
	v_pk_mul_f32 v[58:59], v[52:53], v[56:57] op_sel_hi:[1,0]
	v_pk_mul_f32 v[50:51], v[50:51], v[56:57] op_sel_hi:[1,0]
	v_pk_mul_f32 v[52:53], v[48:49], v[56:57] op_sel_hi:[1,0]
	v_pk_mul_f32 v[46:47], v[46:47], v[56:57] op_sel_hi:[1,0]
	s_and_b64 vcc, exec, s[8:9]
	v_lshl_add_u64 v[48:49], s[20:21], 0, v[60:61]
	s_cbranch_vccnz .LBB0_735
	v_mov_b32_e32 v127, v1
	v_lshl_add_u64 v[64:65], v[48:49], 0, v[126:127]
	global_load_dwordx4 v[60:63], v[64:65], off
	s_nop 0
	global_load_dwordx4 v[64:67], v[64:65], off offset:16
	s_waitcnt vmcnt(0) lgkmcnt(0)
	v_pk_mul_f32 v[70:71], v[50:51], v[60:61] op_sel:[1,1] op_sel_hi:[0,1]
	v_mul_f32_e32 v0, v59, v63
	v_pk_mul_f32 v[68:69], v[50:51], v[60:61]
	v_pk_fma_f32 v[50:51], v[50:51], v[60:61], v[70:71] op_sel_hi:[1,0,1]
	v_pk_fma_f32 v[60:61], v[58:59], v[62:63], v[0:1] op_sel_hi:[1,1,0] neg_lo:[0,0,1] neg_hi:[0,0,1]
	v_mul_f32_e32 v0, v58, v63
	v_pk_fma_f32 v[62:63], v[58:59], v[62:63], v[0:1] op_sel:[1,0,0] op_sel_hi:[0,1,0]
	v_pk_mul_f32 v[72:73], v[46:47], v[64:65] op_sel:[1,1] op_sel_hi:[0,1]
	v_mul_f32_e32 v0, v53, v67
	v_pk_mul_f32 v[58:59], v[46:47], v[64:65]
	v_pk_fma_f32 v[46:47], v[46:47], v[64:65], v[72:73] op_sel_hi:[1,0,1]
	v_pk_fma_f32 v[64:65], v[52:53], v[66:67], v[0:1] op_sel_hi:[1,1,0] neg_lo:[0,0,1] neg_hi:[0,0,1]
	v_mul_f32_e32 v0, v52, v67
	v_pk_fma_f32 v[66:67], v[52:53], v[66:67], v[0:1] op_sel:[1,0,0] op_sel_hi:[0,1,0]
	v_sub_f32_e32 v50, v68, v70
	v_sub_f32_e32 v46, v58, v72
	v_mov_b32_e32 v58, v60
	v_mov_b32_e32 v59, v62
	v_mov_b32_e32 v52, v64
	v_mov_b32_e32 v53, v66
.LBB0_735:
	v_cvt_pk_bf16_f32 v60, v50, v51
	v_cvt_pk_bf16_f32 v61, v58, v59
	v_cvt_pk_bf16_f32 v62, v46, v47
	v_mov_b64_e32 v[46:47], s[16:17]
	v_mad_i64_i32 v[46:47], s[2:3], v54, s75, v[46:47]
	v_mov_b32_e32 v57, v56
	v_cvt_pk_bf16_f32 v63, v52, v53
	v_lshl_add_u64 v[50:51], v[128:129], 1, v[46:47]
	v_mov_b32_e32 v52, v56
	v_mov_b32_e32 v53, v56
	global_store_dwordx4 v[50:51], v[60:63], off
	v_pk_mul_f32 v[50:51], v[44:45], v[52:53]
	v_pk_mul_f32 v[42:43], v[42:43], v[56:57]
	v_pk_mul_f32 v[44:45], v[40:41], v[52:53]
	s_and_b64 vcc, exec, s[10:11]
	v_pk_mul_f32 v[38:39], v[38:39], v[56:57]
	s_cbranch_vccnz .LBB0_737
	v_mov_b32_e32 v127, v1
	v_lshl_add_u64 v[40:41], v[48:49], 0, v[126:127]
	global_load_dwordx4 v[52:55], v[40:41], off
	global_load_dwordx4 v[56:59], v[40:41], off offset:16
	s_waitcnt vmcnt(0) lgkmcnt(0)
	v_pk_mul_f32 v[48:49], v[42:43], v[52:53] op_sel:[1,1] op_sel_hi:[0,1]
	v_mul_f32_e32 v0, v51, v55
	v_pk_mul_f32 v[40:41], v[42:43], v[52:53]
	v_pk_fma_f32 v[42:43], v[42:43], v[52:53], v[48:49] op_sel_hi:[1,0,1]
	v_pk_fma_f32 v[52:53], v[50:51], v[54:55], v[0:1] op_sel_hi:[1,1,0] neg_lo:[0,0,1] neg_hi:[0,0,1]
	v_mul_f32_e32 v0, v50, v55
	v_pk_fma_f32 v[54:55], v[50:51], v[54:55], v[0:1] op_sel:[1,0,0] op_sel_hi:[0,1,0]
	v_pk_mul_f32 v[60:61], v[38:39], v[56:57] op_sel:[1,1] op_sel_hi:[0,1]
	v_mul_f32_e32 v0, v45, v59
	v_pk_mul_f32 v[50:51], v[38:39], v[56:57]
	v_pk_fma_f32 v[38:39], v[38:39], v[56:57], v[60:61] op_sel_hi:[1,0,1]
	v_pk_fma_f32 v[56:57], v[44:45], v[58:59], v[0:1] op_sel_hi:[1,1,0] neg_lo:[0,0,1] neg_hi:[0,0,1]
	v_mul_f32_e32 v0, v44, v59
	v_pk_fma_f32 v[58:59], v[44:45], v[58:59], v[0:1] op_sel:[1,0,0] op_sel_hi:[0,1,0]
	v_sub_f32_e32 v42, v40, v48
	v_sub_f32_e32 v38, v50, v60
	v_mov_b32_e32 v50, v52
	v_mov_b32_e32 v51, v54
	v_mov_b32_e32 v44, v56
	v_mov_b32_e32 v45, v58
; __device__ __forceinline__ unsigned cvt_pk_bf16(float lo, float hi) { unsigned r; asm volatile("v_cvt_pk_bf16_f32 %0, %1, %2" : "=v"(r) : "v"(lo), "v"(hi)); return r; }
; __device__ __forceinline__ float ssq_val(ssq_t v) { return (float)v * SSQ_IFX; }
;     __device__ __forceinline__ void operator()(const f32x4 (&acc)[2][2][4][2], const Unit& u, int wr, int wc, int fr, int fq) const {
;     ...
;         for (int i = 0; i < 8; ++i) rsv[i] = QS_B / sqrtf(ssq_val(sv[i]) * (1.0f / 384.0f) + EPS);
; #pragma unroll
;         for (int ai = 0; ai < 2; ++ai)
; #pragma unroll
;             for (int m = 0; m < 4; ++m) {
;                 const int row = row0 + ai * HALF + m * 16;
;                 const float rs = rsv[ai * 4 + m];
; #pragma unroll
;                 for (int bj = 0; bj < 2; ++bj) {
;                     const int colw = u.pn * BM + bj * HALF + wc * 32, col0 = colw + 8 * fq;
;                     const bool rope = (colw % 96) == 64 && colw < 576;
;                     f32x4 v0 = acc[ai][bj][m][0] * rs, v1 = acc[ai][bj][m][1] * rs;
;                     if (rope) {
;                         const float* tp = ropB + ((size_t)row * 16 + ((col0 - colw) >> 1)) * 2;
;                         const f32x4 c0 = *(const f32x4*)tp, c1 = *(const f32x4*)(tp + 4);
;                         f32x4 w0, w1;
;                         w0[0] = v0[0] * c0[0] - v0[1] * c0[1]; w0[1] = v0[1] * c0[0] + v0[0] * c0[1];
;                         w0[2] = v0[2] * c0[2] - v0[3] * c0[3]; w0[3] = v0[3] * c0[2] + v0[2] * c0[3];
;                         w1[0] = v1[0] * c1[0] - v1[1] * c1[1]; w1[1] = v1[1] * c1[0] + v1[0] * c1[1];
;                         w1[2] = v1[2] * c1[2] - v1[3] * c1[3]; w1[3] = v1[3] * c1[2] + v1[2] * c1[3];
;                         v0 = w0; v1 = w1;
;                     }
;                     u32x4 w; w.x = cvt_pk_bf16(v0[0], v0[1]); w.y = cvt_pk_bf16(v0[2], v0[3]); w.z = cvt_pk_bf16(v1[0], v1[1]); w.w = cvt_pk_bf16(v1[2], v1[3]);
;                     *(u32x4*)(O + (size_t)row * QMP + col0) = w;
.LBB0_737:
	v_ffbh_u32_e32 v0, v145
	v_min_u32_e32 v0, 32, v0
	v_lshlrev_b64 v[40:41], v0, v[144:145]
	v_min_u32_e32 v40, 1, v40
	v_or_b32_e32 v40, v41, v40
	v_cvt_f32_u32_e32 v40, v40
	v_sub_u32_e32 v0, 32, v0
	v_ldexp_f32 v0, v40, v0
	v_mul_f32_e32 v0, 0x33800000, v0
	v_fmamk_f32 v0, v0, 0x3b2aaaab, v226
	v_mul_f32_e32 v40, 0x4f800000, v0
	v_cmp_gt_f32_e32 vcc, s71, v0
	s_nop 1
	v_cndmask_b32_e32 v0, v0, v40, vcc
	v_sqrt_f32_e32 v40, v0
	s_nop 0
	v_add_u32_e32 v41, -1, v40
	v_add_u32_e32 v48, 1, v40
	v_fma_f32 v49, -v41, v40, v0
	v_fma_f32 v52, -v48, v40, v0
	v_cmp_ge_f32_e64 s[12:13], 0, v49
	s_nop 1
	v_cndmask_b32_e64 v40, v40, v41, s[12:13]
	v_cmp_lt_f32_e64 s[12:13], 0, v52
	s_nop 1
	v_cndmask_b32_e64 v40, v40, v48, s[12:13]
	v_mul_f32_e32 v41, 0x37800000, v40
	v_cndmask_b32_e32 v40, v40, v41, vcc
	v_cmp_class_f32_e32 vcc, v0, v223
	s_nop 1
	v_cndmask_b32_e32 v0, v40, v0, vcc
	v_div_scale_f32 v40, s[2:3], v0, v0, s69
	v_rcp_f32_e32 v41, v40
	s_nop 0
	v_fma_f32 v48, -v40, v41, 1.0
	v_fmac_f32_e32 v41, v48, v41
	v_div_scale_f32 v48, vcc, s69, v0, s69
	v_mul_f32_e32 v49, v48, v41
	v_fma_f32 v52, -v40, v49, v48
	v_fmac_f32_e32 v49, v52, v41
	v_fma_f32 v40, -v40, v49, v48
	v_div_fmas_f32 v40, v40, v41, v49
	v_cvt_pk_bf16_f32 v48, v42, v43
	v_cvt_pk_bf16_f32 v49, v50, v51
	v_cvt_pk_bf16_f32 v50, v38, v39
	v_lshl_add_u64 v[38:39], v[118:119], 1, v[46:47]
	v_cvt_pk_bf16_f32 v51, v44, v45
	global_store_dwordx4 v[38:39], v[48:51], off offset:256
	v_add_u32_e32 v38, 0xa0, v140
	v_ashrrev_i32_e32 v39, 31, v38
	v_div_fixup_f32 v40, v40, v0, s69
	v_lshlrev_b64 v[44:45], 7, v[38:39]
	v_pk_mul_f32 v[42:43], v[36:37], v[40:41] op_sel_hi:[1,0]
	v_pk_mul_f32 v[34:35], v[34:35], v[40:41] op_sel_hi:[1,0]
	v_pk_mul_f32 v[36:37], v[32:33], v[40:41] op_sel_hi:[1,0]
	v_pk_mul_f32 v[30:31], v[30:31], v[40:41] op_sel_hi:[1,0]
	s_and_b64 vcc, exec, s[8:9]
	v_lshl_add_u64 v[32:33], s[20:21], 0, v[44:45]
	s_cbranch_vccnz .LBB0_739
	v_mov_b32_e32 v127, v1
	v_lshl_add_u64 v[48:49], v[32:33], 0, v[126:127]
	global_load_dwordx4 v[44:47], v[48:49], off
	s_nop 0
	global_load_dwordx4 v[48:51], v[48:49], off offset:16
	s_waitcnt vmcnt(0) lgkmcnt(0)
	v_pk_mul_f32 v[54:55], v[34:35], v[44:45] op_sel:[1,1] op_sel_hi:[0,1]
	v_mul_f32_e32 v0, v43, v47
	v_pk_mul_f32 v[52:53], v[34:35], v[44:45]
	v_pk_fma_f32 v[34:35], v[34:35], v[44:45], v[54:55] op_sel_hi:[1,0,1]
	v_pk_fma_f32 v[44:45], v[42:43], v[46:47], v[0:1] op_sel_hi:[1,1,0] neg_lo:[0,0,1] neg_hi:[0,0,1]
	v_mul_f32_e32 v0, v42, v47
	v_pk_fma_f32 v[46:47], v[42:43], v[46:47], v[0:1] op_sel:[1,0,0] op_sel_hi:[0,1,0]
	v_pk_mul_f32 v[56:57], v[30:31], v[48:49] op_sel:[1,1] op_sel_hi:[0,1]
	v_mul_f32_e32 v0, v37, v51
	v_pk_mul_f32 v[42:43], v[30:31], v[48:49]
	v_pk_fma_f32 v[30:31], v[30:31], v[48:49], v[56:57] op_sel_hi:[1,0,1]
	v_pk_fma_f32 v[48:49], v[36:37], v[50:51], v[0:1] op_sel_hi:[1,1,0] neg_lo:[0,0,1] neg_hi:[0,0,1]
	v_mul_f32_e32 v0, v36, v51
	v_pk_fma_f32 v[50:51], v[36:37], v[50:51], v[0:1] op_sel:[1,0,0] op_sel_hi:[0,1,0]
	v_sub_f32_e32 v34, v52, v54
	v_sub_f32_e32 v30, v42, v56
	v_mov_b32_e32 v42, v44
	v_mov_b32_e32 v43, v46
	v_mov_b32_e32 v36, v48
	v_mov_b32_e32 v37, v50
.LBB0_739:
	v_cvt_pk_bf16_f32 v44, v34, v35
	v_cvt_pk_bf16_f32 v45, v42, v43
	v_cvt_pk_bf16_f32 v46, v30, v31
	v_mov_b64_e32 v[30:31], s[16:17]
	v_mad_i64_i32 v[30:31], s[2:3], v38, s75, v[30:31]
	v_mov_b32_e32 v41, v40
	v_cvt_pk_bf16_f32 v47, v36, v37
	v_lshl_add_u64 v[34:35], v[128:129], 1, v[30:31]
	v_mov_b32_e32 v36, v40
	v_mov_b32_e32 v37, v40
	global_store_dwordx4 v[34:35], v[44:47], off
	v_pk_mul_f32 v[34:35], v[28:29], v[36:37]
	v_pk_mul_f32 v[26:27], v[26:27], v[40:41]
	v_pk_mul_f32 v[28:29], v[24:25], v[36:37]
	s_and_b64 vcc, exec, s[10:11]
	v_pk_mul_f32 v[22:23], v[22:23], v[40:41]
	s_cbranch_vccnz .LBB0_741
	v_mov_b32_e32 v127, v1
	v_lshl_add_u64 v[24:25], v[32:33], 0, v[126:127]
	global_load_dwordx4 v[36:39], v[24:25], off
	global_load_dwordx4 v[40:43], v[24:25], off offset:16
	s_waitcnt vmcnt(0) lgkmcnt(0)
	v_pk_mul_f32 v[32:33], v[26:27], v[36:37] op_sel:[1,1] op_sel_hi:[0,1]
	v_mul_f32_e32 v0, v35, v39
	v_pk_mul_f32 v[24:25], v[26:27], v[36:37]
	v_pk_fma_f32 v[26:27], v[26:27], v[36:37], v[32:33] op_sel_hi:[1,0,1]
	v_pk_fma_f32 v[36:37], v[34:35], v[38:39], v[0:1] op_sel_hi:[1,1,0] neg_lo:[0,0,1] neg_hi:[0,0,1]
	v_mul_f32_e32 v0, v34, v39
	v_pk_fma_f32 v[38:39], v[34:35], v[38:39], v[0:1] op_sel:[1,0,0] op_sel_hi:[0,1,0]
	v_pk_mul_f32 v[44:45], v[22:23], v[40:41] op_sel:[1,1] op_sel_hi:[0,1]
	v_mul_f32_e32 v0, v29, v43
	v_pk_mul_f32 v[34:35], v[22:23], v[40:41]
	v_pk_fma_f32 v[22:23], v[22:23], v[40:41], v[44:45] op_sel_hi:[1,0,1]
	v_pk_fma_f32 v[40:41], v[28:29], v[42:43], v[0:1] op_sel_hi:[1,1,0] neg_lo:[0,0,1] neg_hi:[0,0,1]
	v_mul_f32_e32 v0, v28, v43
	v_pk_fma_f32 v[42:43], v[28:29], v[42:43], v[0:1] op_sel:[1,0,0] op_sel_hi:[0,1,0]
	v_sub_f32_e32 v26, v24, v32
	v_sub_f32_e32 v22, v34, v44
	v_mov_b32_e32 v34, v36
	v_mov_b32_e32 v35, v38
	v_mov_b32_e32 v28, v40
	v_mov_b32_e32 v29, v42
; __device__ __forceinline__ unsigned cvt_pk_bf16(float lo, float hi) { unsigned r; asm volatile("v_cvt_pk_bf16_f32 %0, %1, %2" : "=v"(r) : "v"(lo), "v"(hi)); return r; }
; #define PG8_BAR __builtin_amdgcn_s_barrier()
; __device__ __forceinline__ float ssq_val(ssq_t v) { return (float)v * SSQ_IFX; }
; template <class Epi, class Sched, bool ALIGN_EPI = false, bool SP2 = false>
; __device__ __forceinline__ void gemm_phase(PG8_LAS unsigned char* lds, const Gemm g, const Sched& S, const Epi& E, const int wave_s) {
;     ...
;         if constexpr (ALIGN_EPI) { if (wr == 1) PG8_BAR; }
;     __device__ __forceinline__ void operator()(const f32x4 (&acc)[2][2][4][2], const Unit& u, int wr, int wc, int fr, int fq) const {
;     ...
;         for (int i = 0; i < 8; ++i) rsv[i] = QS_B / sqrtf(ssq_val(sv[i]) * (1.0f / 384.0f) + EPS);
; #pragma unroll
;         for (int ai = 0; ai < 2; ++ai)
; #pragma unroll
;             for (int m = 0; m < 4; ++m) {
;                 const int row = row0 + ai * HALF + m * 16;
;                 const float rs = rsv[ai * 4 + m];
; #pragma unroll
;                 for (int bj = 0; bj < 2; ++bj) {
;                     const int colw = u.pn * BM + bj * HALF + wc * 32, col0 = colw + 8 * fq;
;                     const bool rope = (colw % 96) == 64 && colw < 576;
;                     f32x4 v0 = acc[ai][bj][m][0] * rs, v1 = acc[ai][bj][m][1] * rs;
;                     if (rope) {
;                         const float* tp = ropB + ((size_t)row * 16 + ((col0 - colw) >> 1)) * 2;
;                         const f32x4 c0 = *(const f32x4*)tp, c1 = *(const f32x4*)(tp + 4);
;                         f32x4 w0, w1;
;                         w0[0] = v0[0] * c0[0] - v0[1] * c0[1]; w0[1] = v0[1] * c0[0] + v0[0] * c0[1];
;                         w0[2] = v0[2] * c0[2] - v0[3] * c0[3]; w0[3] = v0[3] * c0[2] + v0[2] * c0[3];
;                         w1[0] = v1[0] * c1[0] - v1[1] * c1[1]; w1[1] = v1[1] * c1[0] + v1[0] * c1[1];
;                         w1[2] = v1[2] * c1[2] - v1[3] * c1[3]; w1[3] = v1[3] * c1[2] + v1[2] * c1[3];
;                         v0 = w0; v1 = w1;
;                     }
;                     u32x4 w; w.x = cvt_pk_bf16(v0[0], v0[1]); w.y = cvt_pk_bf16(v0[2], v0[3]); w.z = cvt_pk_bf16(v1[0], v1[1]); w.w = cvt_pk_bf16(v1[2], v1[3]);
;                     *(u32x4*)(O + (size_t)row * QMP + col0) = w;
.LBB0_741:
	v_ffbh_u32_e32 v0, v143
	v_min_u32_e32 v0, 32, v0
	v_lshlrev_b64 v[24:25], v0, v[142:143]
	v_min_u32_e32 v24, 1, v24
	v_or_b32_e32 v24, v25, v24
	v_cvt_f32_u32_e32 v24, v24
	v_sub_u32_e32 v0, 32, v0
	v_ldexp_f32 v0, v24, v0
	v_mul_f32_e32 v0, 0x33800000, v0
	v_fmamk_f32 v0, v0, 0x3b2aaaab, v226
	v_mul_f32_e32 v24, 0x4f800000, v0
	v_cmp_gt_f32_e32 vcc, s71, v0
	s_nop 1
	v_cndmask_b32_e32 v0, v0, v24, vcc
	v_sqrt_f32_e32 v24, v0
	s_nop 0
	v_add_u32_e32 v25, -1, v24
	v_add_u32_e32 v32, 1, v24
	v_fma_f32 v33, -v25, v24, v0
	v_fma_f32 v36, -v32, v24, v0
	v_cmp_ge_f32_e64 s[12:13], 0, v33
	s_nop 1
	v_cndmask_b32_e64 v24, v24, v25, s[12:13]
	v_cmp_lt_f32_e64 s[12:13], 0, v36
	s_nop 1
	v_cndmask_b32_e64 v24, v24, v32, s[12:13]
	v_mul_f32_e32 v25, 0x37800000, v24
	v_cndmask_b32_e32 v24, v24, v25, vcc
	v_cmp_class_f32_e32 vcc, v0, v223
	s_nop 1
	v_cndmask_b32_e32 v0, v24, v0, vcc
	v_div_scale_f32 v24, s[2:3], v0, v0, s69
	v_rcp_f32_e32 v25, v24
	s_nop 0
	v_fma_f32 v32, -v24, v25, 1.0
	v_fmac_f32_e32 v25, v32, v25
	v_div_scale_f32 v32, vcc, s69, v0, s69
	v_mul_f32_e32 v33, v32, v25
	v_fma_f32 v36, -v24, v33, v32
	v_fmac_f32_e32 v33, v36, v25
	v_fma_f32 v24, -v24, v33, v32
	v_div_fmas_f32 v24, v24, v25, v33
	v_cvt_pk_bf16_f32 v32, v26, v27
	v_cvt_pk_bf16_f32 v33, v34, v35
	v_cvt_pk_bf16_f32 v34, v22, v23
	v_lshl_add_u64 v[22:23], v[118:119], 1, v[30:31]
	v_cvt_pk_bf16_f32 v35, v28, v29
	global_store_dwordx4 v[22:23], v[32:35], off offset:256
	v_add_u32_e32 v22, 0xb0, v140
	v_ashrrev_i32_e32 v23, 31, v22
	v_div_fixup_f32 v24, v24, v0, s69
	v_lshlrev_b64 v[28:29], 7, v[22:23]
	v_pk_mul_f32 v[26:27], v[20:21], v[24:25] op_sel_hi:[1,0]
	v_pk_mul_f32 v[18:19], v[18:19], v[24:25] op_sel_hi:[1,0]
	v_pk_mul_f32 v[20:21], v[12:13], v[24:25] op_sel_hi:[1,0]
	v_pk_mul_f32 v[12:13], v[10:11], v[24:25] op_sel_hi:[1,0]
	s_and_b64 vcc, exec, s[8:9]
	v_lshl_add_u64 v[10:11], s[20:21], 0, v[28:29]
	s_cbranch_vccnz .LBB0_743
	v_mov_b32_e32 v127, v1
	v_lshl_add_u64 v[32:33], v[10:11], 0, v[126:127]
	global_load_dwordx4 v[28:31], v[32:33], off
	s_nop 0
	global_load_dwordx4 v[32:35], v[32:33], off offset:16
	s_waitcnt vmcnt(0) lgkmcnt(0)
	v_pk_mul_f32 v[38:39], v[18:19], v[28:29] op_sel:[1,1] op_sel_hi:[0,1]
	v_mul_f32_e32 v0, v27, v31
	v_pk_mul_f32 v[36:37], v[18:19], v[28:29]
	v_pk_fma_f32 v[18:19], v[18:19], v[28:29], v[38:39] op_sel_hi:[1,0,1]
	v_pk_fma_f32 v[28:29], v[26:27], v[30:31], v[0:1] op_sel_hi:[1,1,0] neg_lo:[0,0,1] neg_hi:[0,0,1]
	v_mul_f32_e32 v0, v26, v31
	v_pk_fma_f32 v[30:31], v[26:27], v[30:31], v[0:1] op_sel:[1,0,0] op_sel_hi:[0,1,0]
	v_pk_mul_f32 v[40:41], v[12:13], v[32:33] op_sel:[1,1] op_sel_hi:[0,1]
	v_mul_f32_e32 v0, v21, v35
	v_pk_mul_f32 v[26:27], v[12:13], v[32:33]
	v_pk_fma_f32 v[12:13], v[12:13], v[32:33], v[40:41] op_sel_hi:[1,0,1]
	v_pk_fma_f32 v[32:33], v[20:21], v[34:35], v[0:1] op_sel_hi:[1,1,0] neg_lo:[0,0,1] neg_hi:[0,0,1]
	v_mul_f32_e32 v0, v20, v35
	v_pk_fma_f32 v[34:35], v[20:21], v[34:35], v[0:1] op_sel:[1,0,0] op_sel_hi:[0,1,0]
	v_sub_f32_e32 v18, v36, v38
	v_sub_f32_e32 v12, v26, v40
	v_mov_b32_e32 v26, v28
	v_mov_b32_e32 v27, v30
	v_mov_b32_e32 v20, v32
	v_mov_b32_e32 v21, v34
.LBB0_743:
	v_cvt_pk_bf16_f32 v28, v18, v19
	v_cvt_pk_bf16_f32 v29, v26, v27
	v_cvt_pk_bf16_f32 v30, v12, v13
	v_mov_b64_e32 v[12:13], s[16:17]
	v_mad_i64_i32 v[12:13], s[2:3], v22, s75, v[12:13]
	v_lshl_add_u64 v[18:19], v[128:129], 1, v[12:13]
	v_mov_b32_e32 v25, v24
	v_cvt_pk_bf16_f32 v31, v20, v21
	global_store_dwordx4 v[18:19], v[28:31], off
	v_mov_b32_e32 v18, v24
	v_mov_b32_e32 v19, v24
	v_pk_mul_f32 v[8:9], v[8:9], v[18:19]
	v_pk_mul_f32 v[6:7], v[6:7], v[24:25]
	v_pk_mul_f32 v[4:5], v[4:5], v[18:19]
	s_and_b64 vcc, exec, s[10:11]
	v_pk_mul_f32 v[2:3], v[2:3], v[24:25]
	s_cbranch_vccnz .LBB0_745
	v_mov_b32_e32 v127, v1
	v_lshl_add_u64 v[10:11], v[10:11], 0, v[126:127]
	global_load_dwordx4 v[18:21], v[10:11], off
	global_load_dwordx4 v[22:25], v[10:11], off offset:16
	s_waitcnt vmcnt(0) lgkmcnt(0)
	v_pk_mul_f32 v[26:27], v[6:7], v[18:19] op_sel:[1,1] op_sel_hi:[0,1]
	v_mul_f32_e32 v0, v9, v21
	v_pk_mul_f32 v[10:11], v[6:7], v[18:19]
	v_pk_fma_f32 v[6:7], v[6:7], v[18:19], v[26:27] op_sel_hi:[1,0,1]
	v_pk_fma_f32 v[18:19], v[8:9], v[20:21], v[0:1] op_sel_hi:[1,1,0] neg_lo:[0,0,1] neg_hi:[0,0,1]
	v_mul_f32_e32 v0, v8, v21
	v_pk_fma_f32 v[20:21], v[8:9], v[20:21], v[0:1] op_sel:[1,0,0] op_sel_hi:[0,1,0]
	v_pk_mul_f32 v[28:29], v[2:3], v[22:23] op_sel:[1,1] op_sel_hi:[0,1]
	v_mul_f32_e32 v0, v5, v25
	v_pk_mul_f32 v[8:9], v[2:3], v[22:23]
	v_pk_fma_f32 v[2:3], v[2:3], v[22:23], v[28:29] op_sel_hi:[1,0,1]
	v_pk_fma_f32 v[22:23], v[4:5], v[24:25], v[0:1] op_sel_hi:[1,1,0] neg_lo:[0,0,1] neg_hi:[0,0,1]
	v_mul_f32_e32 v0, v4, v25
	v_pk_fma_f32 v[24:25], v[4:5], v[24:25], v[0:1] op_sel:[1,0,0] op_sel_hi:[0,1,0]
	v_sub_f32_e32 v6, v10, v26
	v_sub_f32_e32 v2, v8, v28
	v_mov_b32_e32 v8, v18
	v_mov_b32_e32 v9, v20
	v_mov_b32_e32 v4, v22
	v_mov_b32_e32 v5, v24
.LBB0_745:
	v_cvt_pk_bf16_f32 v6, v6, v7
	v_cvt_pk_bf16_f32 v7, v8, v9
	v_cvt_pk_bf16_f32 v8, v2, v3
	v_lshl_add_u64 v[2:3], v[118:119], 1, v[12:13]
	s_and_b64 vcc, exec, s[6:7]
	s_mov_b64 s[2:3], -1
	v_cvt_pk_bf16_f32 v9, v4, v5
	global_store_dwordx4 v[2:3], v[6:9], off offset:256
	s_cbranch_vccnz .LBB0_704
	s_andn2_b64 vcc, exec, s[14:15]
	s_cbranch_vccnz .LBB0_703
	s_barrier
	s_branch .LBB0_703

; __device__ __forceinline__ float ssq_val(ssq_t v) { return (float)v * SSQ_IFX; }
;     __device__ __forceinline__ void operator()(const f32x4 (&acc)[2][2][4][2], const Unit& u, int wr, int wc, int fr, int fq) const {
;         const int row0 = u.pm * BM + wr * 64 + fr;
;         ssq_t sv[8]; float rsv[8];
; #pragma unroll
;         for (int i = 0; i < 8; ++i) sv[i] = ssq[row0 + (i >> 2) * HALF + (i & 3) * 16];
; #pragma unroll
;         for (int i = 0; i < 8; ++i) rsv[i] = 1.0f / sqrtf(ssq_val(sv[i]) * (1.0f / 256.0f) + EPS);
.LBB0_761:
	s_lshl_b32 s3, s3, 8
	s_add_i32 s3, s3, s4
	v_mbcnt_lo_u32_b32 v145, -1, 0
	v_mbcnt_hi_u32_b32 v145, -1, v145
	v_mov_b32_e32 v226, 0x358637bd
	v_and_or_b32 v138, v145, 15, s3
	v_ashrrev_i32_e32 v139, 31, v138
	v_lshl_add_u64 v[142:143], v[138:139], 3, s[14:15]
	global_load_dwordx2 v[156:157], v[142:143], off
	global_load_dwordx2 v[158:159], v[142:143], off offset:128
	global_load_dwordx2 v[154:155], v[142:143], off offset:256
	global_load_dwordx2 v[152:153], v[142:143], off offset:384
	v_mov_b32_e32 v223, 0x260
	global_load_dwordx2 v[150:151], v[142:143], off offset:1024
	global_load_dwordx2 v[148:149], v[142:143], off offset:1152
	global_load_dwordx2 v[146:147], v[142:143], off offset:1280
	s_nop 0
	global_load_dwordx2 v[142:143], v[142:143], off offset:1408
	s_lshl_b32 s2, s2, 8
	v_add_u32_e32 v139, 0x80, v138
	v_mov_b32_e32 v222, v224
	v_mov_b64_e32 v[252:253], 0x300
	s_waitcnt vmcnt(0) lgkmcnt(0)
	v_ffbh_u32_e32 v140, v157
	v_min_u32_e32 v140, 32, v140
	v_lshlrev_b64 v[156:157], v140, v[156:157]
	v_min_u32_e32 v144, 1, v156
	v_or_b32_e32 v144, v157, v144
	v_cvt_f32_u32_e32 v144, v144
	v_sub_u32_e32 v140, 32, v140
	v_ldexp_f32 v140, v144, v140
	v_mul_f32_e32 v140, 0x33800000, v140
	v_fmamk_f32 v140, v140, 0x3b800000, v226
	v_cmp_gt_f32_e32 vcc, s71, v140
	v_mul_f32_e32 v144, 0x4f800000, v140
	s_nop 0
	v_cndmask_b32_e32 v140, v140, v144, vcc
	v_sqrt_f32_e32 v144, v140
	s_nop 0
	v_add_u32_e32 v156, -1, v144
	v_fma_f32 v157, -v156, v144, v140
	v_cmp_ge_f32_e64 s[8:9], 0, v157
	v_add_u32_e32 v157, 1, v144
	s_nop 0
	v_cndmask_b32_e64 v156, v144, v156, s[8:9]
	v_fma_f32 v144, -v157, v144, v140
	v_cmp_lt_f32_e64 s[8:9], 0, v144
	s_nop 1
	v_cndmask_b32_e64 v144, v156, v157, s[8:9]
	v_mul_f32_e32 v156, 0x37800000, v144
	v_cndmask_b32_e32 v144, v144, v156, vcc
	v_cmp_class_f32_e32 vcc, v140, v223
	s_nop 1
	v_cndmask_b32_e32 v140, v144, v140, vcc
	v_div_scale_f32 v144, s[8:9], v140, v140, 1.0
	v_rcp_f32_e32 v156, v144
	s_nop 0
	v_fma_f32 v157, -v144, v156, 1.0
	v_fmac_f32_e32 v156, v157, v156
	v_div_scale_f32 v157, vcc, 1.0, v140, 1.0
	v_mul_f32_e32 v160, v157, v156
	v_fma_f32 v161, -v144, v160, v157
	v_fmac_f32_e32 v160, v161, v156
	v_fma_f32 v144, -v144, v160, v157
	v_div_fmas_f32 v144, v144, v156, v160
	v_div_fixup_f32 v140, v144, v140, 1.0
	v_ffbh_u32_e32 v144, v159
	v_min_u32_e32 v144, 32, v144
	v_lshlrev_b64 v[156:157], v144, v[158:159]
	v_min_u32_e32 v156, 1, v156
	v_or_b32_e32 v156, v157, v156
	v_cvt_f32_u32_e32 v156, v156
	v_sub_u32_e32 v144, 32, v144
	v_pk_mul_f32 v[132:133], v[132:133], v[140:141] op_sel_hi:[1,0]
	v_pk_mul_f32 v[130:131], v[130:131], v[140:141] op_sel_hi:[1,0]
	v_ldexp_f32 v144, v156, v144
	v_mul_f32_e32 v144, 0x33800000, v144
	v_fmamk_f32 v144, v144, 0x3b800000, v226
	v_cmp_gt_f32_e32 vcc, s71, v144
	v_mul_f32_e32 v156, 0x4f800000, v144
	v_pk_mul_f32 v[126:127], v[126:127], v[140:141] op_sel_hi:[1,0]
	v_cndmask_b32_e32 v144, v144, v156, vcc
	v_sqrt_f32_e32 v156, v144
	v_pk_mul_f32 v[128:129], v[128:129], v[140:141] op_sel_hi:[1,0]
	v_cvt_pk_bf16_f32 v130, v130, v131
	v_cvt_pk_bf16_f32 v131, v132, v133
	v_add_u32_e32 v157, -1, v156
	v_fma_f32 v158, -v157, v156, v144
	v_cmp_ge_f32_e64 s[8:9], 0, v158
	v_add_u32_e32 v158, 1, v156
	v_cvt_pk_bf16_f32 v132, v126, v127
	v_mov_b64_e32 v[126:127], s[12:13]
	v_cndmask_b32_e64 v157, v156, v157, s[8:9]
	v_fma_f32 v156, -v158, v156, v144
	v_cmp_lt_f32_e64 s[8:9], 0, v156
	v_cvt_pk_bf16_f32 v133, v128, v129
	v_pk_mul_f32 v[124:125], v[124:125], v[140:141] op_sel_hi:[1,0]
	v_pk_mul_f32 v[122:123], v[122:123], v[140:141] op_sel_hi:[1,0]
	v_cndmask_b32_e64 v156, v157, v158, s[8:9]
	v_mul_f32_e32 v157, 0x37800000, v156
	v_cndmask_b32_e32 v156, v156, v157, vcc
	v_cmp_class_f32_e32 vcc, v144, v223
	s_nop 1
	v_cndmask_b32_e32 v144, v156, v144, vcc
	v_div_scale_f32 v156, s[8:9], v144, v144, 1.0
	v_rcp_f32_e32 v157, v156
	s_nop 0
	v_fma_f32 v158, -v156, v157, 1.0
	v_fmac_f32_e32 v157, v158, v157
	v_div_scale_f32 v158, vcc, 1.0, v144, 1.0
	v_mul_f32_e32 v159, v158, v157
	v_fma_f32 v160, -v156, v159, v158
	v_fmac_f32_e32 v159, v160, v157
	v_fma_f32 v156, -v156, v159, v158
	v_div_fmas_f32 v156, v156, v157, v159
	v_div_fixup_f32 v144, v156, v144, 1.0
	v_ffbh_u32_e32 v156, v155
	v_min_u32_e32 v156, 32, v156
	v_lshlrev_b64 v[154:155], v156, v[154:155]
	v_min_u32_e32 v154, 1, v154
	v_or_b32_e32 v154, v155, v154
	v_cvt_f32_u32_e32 v154, v154
	v_sub_u32_e32 v155, 32, v156
	v_pk_mul_f32 v[114:115], v[114:115], v[144:145] op_sel_hi:[1,0]
	v_pk_mul_f32 v[116:117], v[116:117], v[144:145] op_sel_hi:[1,0]
	v_ldexp_f32 v154, v154, v155
	v_mul_f32_e32 v154, 0x33800000, v154
	v_fmamk_f32 v154, v154, 0x3b800000, v226
	v_cmp_gt_f32_e32 vcc, s71, v154
	v_mul_f32_e32 v155, 0x4f800000, v154
	v_pk_mul_f32 v[108:109], v[108:109], v[144:145] op_sel_hi:[1,0]
	v_cndmask_b32_e32 v154, v154, v155, vcc
	v_sqrt_f32_e32 v155, v154
	v_pk_mul_f32 v[106:107], v[106:107], v[144:145] op_sel_hi:[1,0]
	v_add_u32_e32 v156, -1, v155
	v_fma_f32 v157, -v156, v155, v154
	v_cmp_ge_f32_e64 s[8:9], 0, v157
	v_add_u32_e32 v157, 1, v155
	s_nop 0
	v_cndmask_b32_e64 v156, v155, v156, s[8:9]
	v_fma_f32 v155, -v157, v155, v154
	v_cmp_lt_f32_e64 s[8:9], 0, v155
	s_nop 1
	v_cndmask_b32_e64 v155, v156, v157, s[8:9]
	v_mul_f32_e32 v156, 0x37800000, v155
	v_cndmask_b32_e32 v155, v155, v156, vcc
	v_cmp_class_f32_e32 vcc, v154, v223
	s_nop 1
	v_cndmask_b32_e32 v154, v155, v154, vcc
	v_div_scale_f32 v155, s[8:9], v154, v154, 1.0
	v_rcp_f32_e32 v156, v155
	s_nop 0
	v_fma_f32 v157, -v155, v156, 1.0
	v_fmac_f32_e32 v156, v157, v156
	v_div_scale_f32 v157, vcc, 1.0, v154, 1.0
	v_mul_f32_e32 v158, v157, v156
	v_fma_f32 v159, -v155, v158, v157
; __device__ __forceinline__ float ssq_val(ssq_t v) { return (float)v * SSQ_IFX; }
;     __device__ __forceinline__ void operator()(const f32x4 (&acc)[2][2][4][2], const Unit& u, int wr, int wc, int fr, int fq) const {
;     ...
;         for (int i = 0; i < 8; ++i) rsv[i] = 1.0f / sqrtf(ssq_val(sv[i]) * (1.0f / 256.0f) + EPS);
	v_fmac_f32_e32 v158, v159, v156
	v_fma_f32 v155, -v155, v158, v157
	v_div_fmas_f32 v155, v155, v156, v158
	v_div_fixup_f32 v154, v155, v154, 1.0
	v_ffbh_u32_e32 v155, v153
	v_min_u32_e32 v155, 32, v155
	v_lshlrev_b64 v[152:153], v155, v[152:153]
	v_min_u32_e32 v152, 1, v152
	v_or_b32_e32 v152, v153, v152
	v_cvt_f32_u32_e32 v152, v152
	v_sub_u32_e32 v153, 32, v155
	v_ldexp_f32 v152, v152, v153
	v_mul_f32_e32 v152, 0x33800000, v152
	v_fmamk_f32 v152, v152, 0x3b800000, v226
	v_cmp_gt_f32_e32 vcc, s71, v152
	v_mul_f32_e32 v153, 0x4f800000, v152
	s_nop 0
	v_cndmask_b32_e32 v152, v152, v153, vcc
	v_sqrt_f32_e32 v153, v152
	s_nop 0
	v_add_u32_e32 v155, -1, v153
	v_fma_f32 v156, -v155, v153, v152
	v_cmp_ge_f32_e64 s[8:9], 0, v156
	v_add_u32_e32 v156, 1, v153
	s_nop 0
	v_cndmask_b32_e64 v155, v153, v155, s[8:9]
	v_fma_f32 v153, -v156, v153, v152
	v_cmp_lt_f32_e64 s[8:9], 0, v153
	s_nop 1
	v_cndmask_b32_e64 v153, v155, v156, s[8:9]
	v_mul_f32_e32 v155, 0x37800000, v153
	v_cndmask_b32_e32 v153, v153, v155, vcc
	v_cmp_class_f32_e32 vcc, v152, v223
	s_nop 1
	v_cndmask_b32_e32 v152, v153, v152, vcc
	v_div_scale_f32 v153, s[8:9], v152, v152, 1.0
	v_rcp_f32_e32 v155, v153
	s_nop 0
	v_fma_f32 v156, -v153, v155, 1.0
	v_fmac_f32_e32 v155, v156, v155
	v_div_scale_f32 v156, vcc, 1.0, v152, 1.0
	v_mul_f32_e32 v157, v156, v155
	v_fma_f32 v158, -v153, v157, v156
	v_fmac_f32_e32 v157, v158, v155
	v_fma_f32 v153, -v153, v157, v156
	v_div_fmas_f32 v153, v153, v155, v157
	v_div_fixup_f32 v152, v153, v152, 1.0
	v_ffbh_u32_e32 v153, v151
	v_min_u32_e32 v153, 32, v153
	v_lshlrev_b64 v[150:151], v153, v[150:151]
	v_min_u32_e32 v150, 1, v150
	v_or_b32_e32 v150, v151, v150
	v_cvt_f32_u32_e32 v150, v150
	v_sub_u32_e32 v151, 32, v153
	v_ldexp_f32 v150, v150, v151
	v_mul_f32_e32 v150, 0x33800000, v150
	v_fmamk_f32 v150, v150, 0x3b800000, v226
	v_cmp_gt_f32_e32 vcc, s71, v150
	v_mul_f32_e32 v151, 0x4f800000, v150
	s_nop 0
	v_cndmask_b32_e32 v150, v150, v151, vcc
	v_sqrt_f32_e32 v151, v150
	s_nop 0
	v_add_u32_e32 v153, -1, v151
	v_fma_f32 v155, -v153, v151, v150
	v_cmp_ge_f32_e64 s[8:9], 0, v155
	v_add_u32_e32 v155, 1, v151
	s_nop 0
	v_cndmask_b32_e64 v153, v151, v153, s[8:9]
	v_fma_f32 v151, -v155, v151, v150
	v_cmp_lt_f32_e64 s[8:9], 0, v151
	s_nop 1
	v_cndmask_b32_e64 v151, v153, v155, s[8:9]
	v_mul_f32_e32 v153, 0x37800000, v151
	v_cndmask_b32_e32 v151, v151, v153, vcc
	v_cmp_class_f32_e32 vcc, v150, v223
	s_nop 1
	v_cndmask_b32_e32 v150, v151, v150, vcc
	v_div_scale_f32 v151, s[8:9], v150, v150, 1.0
	v_rcp_f32_e32 v153, v151
	s_nop 0
	v_fma_f32 v155, -v151, v153, 1.0
	v_fmac_f32_e32 v153, v155, v153
	v_div_scale_f32 v155, vcc, 1.0, v150, 1.0
	v_mul_f32_e32 v156, v155, v153
	v_fma_f32 v157, -v151, v156, v155
	v_fmac_f32_e32 v156, v157, v153
	v_fma_f32 v151, -v151, v156, v155
	v_div_fmas_f32 v151, v151, v153, v156
	v_div_fixup_f32 v150, v151, v150, 1.0
	v_ffbh_u32_e32 v151, v149
	v_min_u32_e32 v151, 32, v151
	v_lshlrev_b64 v[148:149], v151, v[148:149]
	v_min_u32_e32 v148, 1, v148
	v_or_b32_e32 v148, v149, v148
	v_cvt_f32_u32_e32 v148, v148
	v_sub_u32_e32 v149, 32, v151
	v_ldexp_f32 v148, v148, v149
	v_mul_f32_e32 v148, 0x33800000, v148
	v_fmamk_f32 v148, v148, 0x3b800000, v226
	v_cmp_gt_f32_e32 vcc, s71, v148
	v_mul_f32_e32 v149, 0x4f800000, v148
	s_nop 0
	v_cndmask_b32_e32 v148, v148, v149, vcc
	v_sqrt_f32_e32 v149, v148
	s_nop 0
	v_add_u32_e32 v151, -1, v149
	v_fma_f32 v153, -v151, v149, v148
	v_cmp_ge_f32_e64 s[8:9], 0, v153
	v_add_u32_e32 v153, 1, v149
	s_nop 0
	v_cndmask_b32_e64 v151, v149, v151, s[8:9]
	v_fma_f32 v149, -v153, v149, v148
	v_cmp_lt_f32_e64 s[8:9], 0, v149
	s_nop 1
	v_cndmask_b32_e64 v149, v151, v153, s[8:9]
	v_mul_f32_e32 v151, 0x37800000, v149
	v_cndmask_b32_e32 v149, v149, v151, vcc
	v_cmp_class_f32_e32 vcc, v148, v223
	s_nop 1
	v_cndmask_b32_e32 v148, v149, v148, vcc
	v_div_scale_f32 v149, s[8:9], v148, v148, 1.0
	v_rcp_f32_e32 v151, v149
	s_nop 0
	v_fma_f32 v153, -v149, v151, 1.0
	v_fmac_f32_e32 v151, v153, v151
	v_div_scale_f32 v153, vcc, 1.0, v148, 1.0
	v_mul_f32_e32 v155, v153, v151
	v_fma_f32 v156, -v149, v155, v153
	v_fmac_f32_e32 v155, v156, v151
	v_fma_f32 v149, -v149, v155, v153
	v_div_fmas_f32 v149, v149, v151, v155
	v_div_fixup_f32 v148, v149, v148, 1.0
	v_ffbh_u32_e32 v149, v147
	v_min_u32_e32 v149, 32, v149
	v_lshlrev_b64 v[146:147], v149, v[146:147]
	v_min_u32_e32 v146, 1, v146
	v_or_b32_e32 v146, v147, v146
	v_cvt_f32_u32_e32 v146, v146
	v_sub_u32_e32 v147, 32, v149
	v_ldexp_f32 v146, v146, v147
	v_mul_f32_e32 v146, 0x33800000, v146
	v_fmamk_f32 v146, v146, 0x3b800000, v226
	v_cmp_gt_f32_e32 vcc, s71, v146
	v_mul_f32_e32 v147, 0x4f800000, v146
	s_nop 0
	v_cndmask_b32_e32 v146, v146, v147, vcc
	v_sqrt_f32_e32 v147, v146
	s_nop 0
	v_add_u32_e32 v149, -1, v147
	v_fma_f32 v151, -v149, v147, v146
	v_cmp_ge_f32_e64 s[8:9], 0, v151
	v_add_u32_e32 v151, 1, v147
	s_nop 0
	v_cndmask_b32_e64 v149, v147, v149, s[8:9]
	v_fma_f32 v147, -v151, v147, v146
	v_cmp_lt_f32_e64 s[8:9], 0, v147
	s_nop 1
	v_cndmask_b32_e64 v147, v149, v151, s[8:9]
	v_mul_f32_e32 v149, 0x37800000, v147
	v_cndmask_b32_e32 v147, v147, v149, vcc
	v_cmp_class_f32_e32 vcc, v146, v223
	s_nop 1
	v_cndmask_b32_e32 v146, v147, v146, vcc
	v_div_scale_f32 v147, s[8:9], v146, v146, 1.0
	v_rcp_f32_e32 v149, v147
	s_nop 0
	v_fma_f32 v151, -v147, v149, 1.0
	v_fmac_f32_e32 v149, v151, v149
	v_div_scale_f32 v151, vcc, 1.0, v146, 1.0
	v_mul_f32_e32 v153, v151, v149
	v_fma_f32 v155, -v147, v153, v151
	v_fmac_f32_e32 v153, v155, v149
	v_fma_f32 v147, -v147, v153, v151
	v_div_fmas_f32 v147, v147, v149, v153
	v_div_fixup_f32 v146, v147, v146, 1.0
	v_ffbh_u32_e32 v147, v143
	v_min_u32_e32 v147, 32, v147
; __device__ __forceinline__ unsigned cvt_pk_bf16(float lo, float hi) { unsigned r; asm volatile("v_cvt_pk_bf16_f32 %0, %1, %2" : "=v"(r) : "v"(lo), "v"(hi)); return r; }
; __device__ __forceinline__ float ssq_val(ssq_t v) { return (float)v * SSQ_IFX; }
;     __device__ __forceinline__ void operator()(const f32x4 (&acc)[2][2][4][2], const Unit& u, int wr, int wc, int fr, int fq) const {
;     ...
;         for (int i = 0; i < 8; ++i) rsv[i] = 1.0f / sqrtf(ssq_val(sv[i]) * (1.0f / 256.0f) + EPS);
; #pragma unroll
;         for (int ai = 0; ai < 2; ++ai)
; #pragma unroll
;             for (int m = 0; m < 4; ++m) {
;                 const int row = row0 + ai * HALF + m * 16;
;                 const float rs = rsv[ai * 4 + m];
; #pragma unroll
;                 for (int bj = 0; bj < 2; ++bj) {
;                     const int col0 = u.pn * BM + bj * HALF + wc * 32 + 8 * fq;
;                     const f32x4 v0 = acc[ai][bj][m][0] * rs, v1 = acc[ai][bj][m][1] * rs;
;                     u32x4 w; w.x = cvt_pk_bf16(v0[0], v0[1]); w.y = cvt_pk_bf16(v0[2], v0[3]); w.z = cvt_pk_bf16(v1[0], v1[1]); w.w = cvt_pk_bf16(v1[2], v1[3]);
;                     *(u32x4*)(O + (size_t)row * KVP + col0) = w;
	v_lshlrev_b64 v[142:143], v147, v[142:143]
	v_min_u32_e32 v142, 1, v142
	v_or_b32_e32 v142, v143, v142
	v_cvt_f32_u32_e32 v142, v142
	v_sub_u32_e32 v143, 32, v147
	v_pk_mul_f32 v[98:99], v[98:99], v[154:155] op_sel_hi:[1,0]
	v_pk_mul_f32 v[100:101], v[100:101], v[154:155] op_sel_hi:[1,0]
	v_ldexp_f32 v142, v142, v143
	v_mul_f32_e32 v142, 0x33800000, v142
	v_fmamk_f32 v142, v142, 0x3b800000, v226
	v_cmp_gt_f32_e32 vcc, s71, v142
	v_mul_f32_e32 v143, 0x4f800000, v142
	v_pk_mul_f32 v[92:93], v[92:93], v[154:155] op_sel_hi:[1,0]
	v_cndmask_b32_e32 v142, v142, v143, vcc
	v_sqrt_f32_e32 v143, v142
	v_pk_mul_f32 v[90:91], v[90:91], v[154:155] op_sel_hi:[1,0]
	v_add_u32_e32 v147, -1, v143
	v_fma_f32 v149, -v147, v143, v142
	v_cmp_ge_f32_e64 s[8:9], 0, v149
	v_add_u32_e32 v149, 1, v143
	s_nop 0
	v_cndmask_b32_e64 v147, v143, v147, s[8:9]
	v_fma_f32 v143, -v149, v143, v142
	v_cmp_lt_f32_e64 s[8:9], 0, v143
	s_nop 1
	v_cndmask_b32_e64 v143, v147, v149, s[8:9]
	v_mul_f32_e32 v147, 0x37800000, v143
	v_cndmask_b32_e32 v143, v143, v147, vcc
	v_cmp_class_f32_e32 vcc, v142, v223
	s_nop 1
	v_cndmask_b32_e32 v142, v143, v142, vcc
	v_div_scale_f32 v143, s[8:9], v142, v142, 1.0
	v_rcp_f32_e32 v147, v143
	s_nop 0
	v_fma_f32 v149, -v143, v147, 1.0
	v_fmac_f32_e32 v147, v149, v147
	v_div_scale_f32 v149, vcc, 1.0, v142, 1.0
	v_mul_f32_e32 v151, v149, v147
	v_fma_f32 v153, -v143, v151, v149
	v_fmac_f32_e32 v151, v153, v147
	v_fma_f32 v143, -v143, v151, v149
	v_div_fmas_f32 v143, v143, v147, v151
	v_div_fixup_f32 v142, v143, v142, 1.0
	v_lshrrev_b32_e32 v143, 1, v145
	v_and_or_b32 v143, v143, 24, s2
	v_or_b32_e32 v156, s5, v143
	v_ashrrev_i32_e32 v157, 31, v156
	v_mad_i64_i32 v[158:159], s[2:3], v138, s75, v[126:127]
	v_lshlrev_b64 v[128:129], 1, v[156:157]
	v_lshl_add_u64 v[156:157], v[158:159], 0, v[128:129]
	global_store_dwordx4 v[156:157], v[130:133], off
	v_pk_mul_f32 v[74:75], v[74:75], v[152:153] op_sel_hi:[1,0]
	v_pk_mul_f32 v[76:77], v[76:77], v[152:153] op_sel_hi:[1,0]
	v_pk_mul_f32 v[130:131], v[120:121], v[140:141] op_sel_hi:[1,0]
	v_pk_mul_f32 v[120:121], v[118:119], v[140:141] op_sel_hi:[1,0]
	v_cvt_pk_bf16_f32 v118, v122, v123
	v_cvt_pk_bf16_f32 v119, v124, v125
	v_pk_mul_f32 v[60:61], v[60:61], v[152:153] op_sel_hi:[1,0]
	v_cvt_pk_bf16_f32 v120, v120, v121
	v_cvt_pk_bf16_f32 v121, v130, v131
	global_store_dwordx4 v[156:157], v[118:121], off offset:256
	v_pk_mul_f32 v[58:59], v[58:59], v[152:153] op_sel_hi:[1,0]
	v_pk_mul_f32 v[62:63], v[62:63], v[150:151] op_sel_hi:[1,0]
	v_or_b32_e32 v120, 16, v138
	v_pk_mul_f32 v[118:119], v[112:113], v[144:145] op_sel_hi:[1,0]
	v_pk_mul_f32 v[112:113], v[110:111], v[144:145] op_sel_hi:[1,0]
	v_cvt_pk_bf16_f32 v110, v114, v115
	v_mad_i64_i32 v[114:115], s[2:3], v120, s75, v[126:127]
	v_cvt_pk_bf16_f32 v111, v116, v117
	v_lshl_add_u64 v[114:115], v[114:115], 0, v[128:129]
	v_cvt_pk_bf16_f32 v112, v112, v113
	v_cvt_pk_bf16_f32 v113, v118, v119
	global_store_dwordx4 v[114:115], v[110:113], off
	v_pk_mul_f32 v[50:51], v[50:51], v[148:149] op_sel_hi:[1,0]
	v_pk_mul_f32 v[52:53], v[52:53], v[148:149] op_sel_hi:[1,0]
	v_pk_mul_f32 v[110:111], v[104:105], v[144:145] op_sel_hi:[1,0]
	v_pk_mul_f32 v[104:105], v[102:103], v[144:145] op_sel_hi:[1,0]
	v_cvt_pk_bf16_f32 v102, v106, v107
	v_cvt_pk_bf16_f32 v103, v108, v109
	v_pk_mul_f32 v[44:45], v[44:45], v[148:149] op_sel_hi:[1,0]
	v_cvt_pk_bf16_f32 v104, v104, v105
	v_cvt_pk_bf16_f32 v105, v110, v111
	global_store_dwordx4 v[114:115], v[102:105], off offset:256
	v_pk_mul_f32 v[42:43], v[42:43], v[148:149] op_sel_hi:[1,0]
	v_pk_mul_f32 v[34:35], v[34:35], v[146:147] op_sel_hi:[1,0]
	v_or_b32_e32 v104, 32, v138
	v_pk_mul_f32 v[102:103], v[96:97], v[154:155] op_sel_hi:[1,0]
	v_pk_mul_f32 v[96:97], v[94:95], v[154:155] op_sel_hi:[1,0]
	v_cvt_pk_bf16_f32 v94, v98, v99
	v_mad_i64_i32 v[98:99], s[2:3], v104, s75, v[126:127]
	v_cvt_pk_bf16_f32 v95, v100, v101
	v_lshl_add_u64 v[98:99], v[98:99], 0, v[128:129]
	v_cvt_pk_bf16_f32 v96, v96, v97
	v_cvt_pk_bf16_f32 v97, v102, v103
	global_store_dwordx4 v[98:99], v[94:97], off
	v_pk_mul_f32 v[36:37], v[36:37], v[146:147] op_sel_hi:[1,0]
	v_pk_mul_f32 v[28:29], v[28:29], v[146:147] op_sel_hi:[1,0]
	v_pk_mul_f32 v[94:95], v[88:89], v[154:155] op_sel_hi:[1,0]
	v_pk_mul_f32 v[88:89], v[86:87], v[154:155] op_sel_hi:[1,0]
	v_cvt_pk_bf16_f32 v86, v90, v91
	v_cvt_pk_bf16_f32 v87, v92, v93
	v_pk_mul_f32 v[26:27], v[26:27], v[146:147] op_sel_hi:[1,0]
	v_cvt_pk_bf16_f32 v88, v88, v89
; __device__ __forceinline__ unsigned cvt_pk_bf16(float lo, float hi) { unsigned r; asm volatile("v_cvt_pk_bf16_f32 %0, %1, %2" : "=v"(r) : "v"(lo), "v"(hi)); return r; }
;     __device__ __forceinline__ void operator()(const f32x4 (&acc)[2][2][4][2], const Unit& u, int wr, int wc, int fr, int fq) const {
;     ...
;         for (int ai = 0; ai < 2; ++ai)
; #pragma unroll
;             for (int m = 0; m < 4; ++m) {
;                 const int row = row0 + ai * HALF + m * 16;
;                 const float rs = rsv[ai * 4 + m];
; #pragma unroll
;                 for (int bj = 0; bj < 2; ++bj) {
;                     const int col0 = u.pn * BM + bj * HALF + wc * 32 + 8 * fq;
;                     const f32x4 v0 = acc[ai][bj][m][0] * rs, v1 = acc[ai][bj][m][1] * rs;
;                     u32x4 w; w.x = cvt_pk_bf16(v0[0], v0[1]); w.y = cvt_pk_bf16(v0[2], v0[3]); w.z = cvt_pk_bf16(v1[0], v1[1]); w.w = cvt_pk_bf16(v1[2], v1[3]);
;                     *(u32x4*)(O + (size_t)row * KVP + col0) = w;
;                 }
	v_cvt_pk_bf16_f32 v89, v94, v95
	global_store_dwordx4 v[98:99], v[86:89], off offset:256
	v_pk_mul_f32 v[18:19], v[18:19], v[142:143] op_sel_hi:[1,0]
	v_pk_mul_f32 v[20:21], v[20:21], v[142:143] op_sel_hi:[1,0]
	v_or_b32_e32 v88, 48, v138
	v_pk_mul_f32 v[86:87], v[68:69], v[152:153] op_sel_hi:[1,0]
	v_pk_mul_f32 v[68:69], v[66:67], v[152:153] op_sel_hi:[1,0]
	v_cvt_pk_bf16_f32 v66, v74, v75
	v_mad_i64_i32 v[74:75], s[2:3], v88, s75, v[126:127]
	v_cvt_pk_bf16_f32 v67, v76, v77
	v_lshl_add_u64 v[74:75], v[74:75], 0, v[128:129]
	v_cvt_pk_bf16_f32 v68, v68, v69
	v_cvt_pk_bf16_f32 v69, v86, v87
	global_store_dwordx4 v[74:75], v[66:69], off
	s_and_b64 vcc, exec, s[6:7]
	v_pk_mul_f32 v[8:9], v[8:9], v[142:143] op_sel_hi:[1,0]
	v_pk_mul_f32 v[66:67], v[56:57], v[152:153] op_sel_hi:[1,0]
	v_pk_mul_f32 v[56:57], v[54:55], v[152:153] op_sel_hi:[1,0]
	v_cvt_pk_bf16_f32 v54, v58, v59
	v_cvt_pk_bf16_f32 v55, v60, v61
	v_pk_mul_f32 v[58:59], v[80:81], v[150:151] op_sel_hi:[1,0]
	v_cvt_pk_bf16_f32 v56, v56, v57
	v_cvt_pk_bf16_f32 v57, v66, v67
	global_store_dwordx4 v[74:75], v[54:57], off offset:256
	v_pk_mul_f32 v[60:61], v[78:79], v[150:151] op_sel_hi:[1,0]
	v_pk_mul_f32 v[6:7], v[6:7], v[142:143] op_sel_hi:[1,0]
	v_pk_mul_f32 v[56:57], v[84:85], v[150:151] op_sel_hi:[1,0]
	v_pk_mul_f32 v[54:55], v[82:83], v[150:151] op_sel_hi:[1,0]
	s_nop 0
	v_cvt_pk_bf16_f32 v54, v54, v55
	v_cvt_pk_bf16_f32 v55, v56, v57
	v_cvt_pk_bf16_f32 v56, v60, v61
	v_cvt_pk_bf16_f32 v57, v58, v59
	v_mad_i64_i32 v[58:59], s[2:3], v139, s75, v[126:127]
	v_lshl_add_u64 v[58:59], v[58:59], 0, v[128:129]
	global_store_dwordx4 v[58:59], v[54:57], off
	v_pk_mul_f32 v[60:61], v[64:65], v[150:151] op_sel_hi:[1,0]
	s_nop 0
	v_pk_mul_f32 v[56:57], v[72:73], v[150:151] op_sel_hi:[1,0]
	v_pk_mul_f32 v[54:55], v[70:71], v[150:151] op_sel_hi:[1,0]
	s_nop 0
	v_cvt_pk_bf16_f32 v54, v54, v55
	v_cvt_pk_bf16_f32 v55, v56, v57
	v_cvt_pk_bf16_f32 v56, v62, v63
	v_cvt_pk_bf16_f32 v57, v60, v61
	global_store_dwordx4 v[58:59], v[54:57], off offset:256
	s_nop 1
	v_add_u32_e32 v56, 0x90, v138
	v_pk_mul_f32 v[54:55], v[48:49], v[148:149] op_sel_hi:[1,0]
	v_pk_mul_f32 v[48:49], v[46:47], v[148:149] op_sel_hi:[1,0]
	v_cvt_pk_bf16_f32 v46, v50, v51
	v_mad_i64_i32 v[50:51], s[2:3], v56, s75, v[126:127]
	v_cvt_pk_bf16_f32 v47, v52, v53
	v_lshl_add_u64 v[50:51], v[50:51], 0, v[128:129]
	v_cvt_pk_bf16_f32 v48, v48, v49
	v_cvt_pk_bf16_f32 v49, v54, v55
	global_store_dwordx4 v[50:51], v[46:49], off
	s_nop 1
	v_pk_mul_f32 v[46:47], v[40:41], v[148:149] op_sel_hi:[1,0]
	v_pk_mul_f32 v[40:41], v[38:39], v[148:149] op_sel_hi:[1,0]
	v_cvt_pk_bf16_f32 v38, v42, v43
	v_cvt_pk_bf16_f32 v39, v44, v45
	s_nop 0
	v_cvt_pk_bf16_f32 v40, v40, v41
	v_cvt_pk_bf16_f32 v41, v46, v47
	global_store_dwordx4 v[50:51], v[38:41], off offset:256
	s_nop 1
	v_add_u32_e32 v40, 0xa0, v138
	v_pk_mul_f32 v[38:39], v[32:33], v[146:147] op_sel_hi:[1,0]
	v_pk_mul_f32 v[32:33], v[30:31], v[146:147] op_sel_hi:[1,0]
	v_cvt_pk_bf16_f32 v30, v34, v35
	v_mad_i64_i32 v[34:35], s[2:3], v40, s75, v[126:127]
	v_cvt_pk_bf16_f32 v31, v36, v37
	v_lshl_add_u64 v[34:35], v[34:35], 0, v[128:129]
	v_cvt_pk_bf16_f32 v32, v32, v33
	v_cvt_pk_bf16_f32 v33, v38, v39
	global_store_dwordx4 v[34:35], v[30:33], off
	s_nop 1
	v_pk_mul_f32 v[30:31], v[24:25], v[146:147] op_sel_hi:[1,0]
	v_pk_mul_f32 v[24:25], v[22:23], v[146:147] op_sel_hi:[1,0]
	v_cvt_pk_bf16_f32 v22, v26, v27
	v_cvt_pk_bf16_f32 v23, v28, v29
	s_nop 0
	v_cvt_pk_bf16_f32 v24, v24, v25
	v_cvt_pk_bf16_f32 v25, v30, v31
	global_store_dwordx4 v[34:35], v[22:25], off offset:256
	s_nop 1
	v_add_u32_e32 v24, 0xb0, v138
	v_pk_mul_f32 v[22:23], v[12:13], v[142:143] op_sel_hi:[1,0]
	v_pk_mul_f32 v[12:13], v[10:11], v[142:143] op_sel_hi:[1,0]
	v_cvt_pk_bf16_f32 v10, v18, v19
	v_mad_i64_i32 v[18:19], s[2:3], v24, s75, v[126:127]
	v_cvt_pk_bf16_f32 v11, v20, v21
	v_lshl_add_u64 v[18:19], v[18:19], 0, v[128:129]
	v_cvt_pk_bf16_f32 v12, v12, v13
	v_cvt_pk_bf16_f32 v13, v22, v23
	global_store_dwordx4 v[18:19], v[10:13], off
	s_mov_b64 s[2:3], -1
	s_nop 0
	v_pk_mul_f32 v[10:11], v[4:5], v[142:143] op_sel_hi:[1,0]
	v_pk_mul_f32 v[4:5], v[2:3], v[142:143] op_sel_hi:[1,0]
	v_cvt_pk_bf16_f32 v2, v6, v7
	v_cvt_pk_bf16_f32 v3, v8, v9
	s_nop 0
	v_cvt_pk_bf16_f32 v4, v4, v5
	v_cvt_pk_bf16_f32 v5, v10, v11
	global_store_dwordx4 v[18:19], v[2:5], off offset:256
	s_cbranch_vccnz .LBB0_754
	s_andn2_b64 vcc, exec, s[10:11]
	s_cbranch_vccnz .LBB0_753
	s_barrier
	s_branch .LBB0_753

; __device__ __forceinline__ unsigned cvtpk(float lo, float hi) { unsigned r; asm volatile("v_cvt_pk_bf16_f32 %0, %1, %2" : "=v"(r) : "v"(lo), "v"(hi)); return r; }
; __device__ __forceinline__ float shfl_x(float v, int m, int lane) { return __builtin_bit_cast(float, __builtin_amdgcn_ds_bpermute((lane ^ m) << 2, __builtin_bit_cast(int, v))); }
; __device__ __forceinline__ void swa_unit3(LAS unsigned char* lds, const bf16_t* pb  , bf16_t* Yb  , int q0, int kvh,
;                                           const float* sinks  , unsigned long long* gss, const int wave_s) {
;     ...
;         const float lt = l_run + shfl_x(l_run, 32, lane);
;         const float inv = 1.0f / lt;
;         bf16_t* orow = Yb + (size_t)(qw0 + r32) * DM + 64 * hq + 4 * hi;
; #pragma unroll
;         for (int rg = 0; rg < 4; ++rg) {
;             u32x2 a, b;
;             a.x = cvtpk(o0[4 * rg] * inv, o0[4 * rg + 1] * inv); a.y = cvtpk(o0[4 * rg + 2] * inv, o0[4 * rg + 3] * inv);
;             b.x = cvtpk(o1[4 * rg] * inv, o1[4 * rg + 1] * inv); b.y = cvtpk(o1[4 * rg + 2] * inv, o1[4 * rg + 3] * inv);
;             *(u32x2*)(orow + 8 * rg) = a; *(u32x2*)(orow + 32 + 8 * rg) = b;
;         }
;         { float q = 0.f;
; #pragma unroll
;           for (int r = 0; r < 16; ++r) { const float a = o0[r] * inv, b = o1[r] * inv; q += a * a + b * b; }
;           q += shfl_x(q, 32, lane);
;           if (hi == 0) __hip_atomic_fetch_add(gss + qw0 + r32, (unsigned long long)(q * 16777216.0f), __ATOMIC_RELAXED, __HIP_MEMORY_SCOPE_AGENT); }
.LBB0_804:
	s_ashr_i32 s13, s12, 31
	s_lshl_b32 s25, s2, 6
	s_lshl_b32 s24, s3, 6
	s_lshl_b64 s[2:3], s[12:13], 23
	s_add_u32 s2, s20, s2
	s_addc_u32 s3, s21, s3
	v_lshlrev_b64 v[2:3], 11, v[166:167]
	v_lshl_add_u64 v[2:3], s[2:3], 0, v[2:3]
	v_lshlrev_b32_e32 v0, 1, v168
	s_add_u32 s10, s18, s94
	v_lshl_add_u64 v[2:3], v[2:3], 0, v[0:1]
	ds_bpermute_b32 v0, v17, v173
	s_addc_u32 s11, s19, s95
	s_lshl_b64 s[8:9], s[12:13], 15
	s_add_u32 s10, s10, s8
	s_addc_u32 s11, s11, s9
	s_mov_b64 s[2:3], 0x2c800000
	s_ashr_i32 s17, s16, 31
	v_lshl_add_u64 v[152:153], v[2:3], 0, s[2:3]
	s_lshl_b64 s[2:3], s[16:17], 3
	s_add_u32 s2, s10, s2
	s_waitcnt lgkmcnt(0)
	v_add_f32_e32 v4, v173, v0
	s_addc_u32 s3, s11, s3
	v_div_scale_f32 v5, s[10:11], v4, v4, 1.0
	v_rcp_f32_e32 v6, v5
	v_lshlrev_b32_e32 v0, 3, v170
	v_lshl_add_u64 v[2:3], s[2:3], 0, v[0:1]
	s_mov_b64 s[2:3], 0x3d200000
	v_fma_f32 v0, -v5, v6, 1.0
	v_fmac_f32_e32 v6, v0, v6
	v_div_scale_f32 v0, vcc, 1.0, v4, 1.0
	v_lshl_add_u64 v[150:151], v[2:3], 0, s[2:3]
	v_mul_f32_e32 v2, v0, v6
	v_fma_f32 v3, -v5, v2, v0
	v_fmac_f32_e32 v2, v3, v6
	v_fma_f32 v0, -v5, v2, v0
	v_div_fmas_f32 v0, v0, v6, v2
	v_div_fixup_f32 v0, v0, v4, 1.0
	v_lshl_add_u64 v[4:5], v[152:153], 0, s[52:53]
	v_mul_f32_e32 v8, v34, v0
	v_mul_f32_e32 v9, v35, v0
	v_cvt_pk_bf16_f32 v2, v8, v9
	v_mul_f32_e32 v10, v36, v0
	v_mul_f32_e32 v11, v37, v0
	v_cvt_pk_bf16_f32 v3, v10, v11
	v_mul_f32_e32 v12, v18, v0
	v_mul_f32_e32 v13, v19, v0
	v_cvt_pk_bf16_f32 v6, v12, v13
	v_mul_f32_e32 v14, v20, v0
	v_mul_f32_e32 v15, v21, v0
	v_cvt_pk_bf16_f32 v7, v14, v15
	global_store_dwordx2 v[4:5], v[2:3], off
	global_store_dwordx2 v[4:5], v[6:7], off offset:64
	v_mul_f32_e32 v18, v38, v0
	v_mul_f32_e32 v19, v39, v0
	v_cvt_pk_bf16_f32 v2, v18, v19
	v_mul_f32_e32 v20, v40, v0
	v_mul_f32_e32 v21, v41, v0
	v_cvt_pk_bf16_f32 v3, v20, v21
	v_mul_f32_e32 v22, v22, v0
	v_mul_f32_e32 v23, v23, v0
	v_cvt_pk_bf16_f32 v6, v22, v23
	v_mul_f32_e32 v24, v24, v0
	v_mul_f32_e32 v25, v25, v0
	v_cvt_pk_bf16_f32 v7, v24, v25
	global_store_dwordx2 v[4:5], v[2:3], off offset:16
	global_store_dwordx2 v[4:5], v[6:7], off offset:80
	v_mul_f32_e32 v34, v42, v0
	v_mul_f32_e32 v35, v43, v0
	v_cvt_pk_bf16_f32 v2, v34, v35
	v_mul_f32_e32 v36, v44, v0
	v_mul_f32_e32 v37, v45, v0
	v_cvt_pk_bf16_f32 v3, v36, v37
	v_mul_f32_e32 v26, v26, v0
	v_mul_f32_e32 v27, v27, v0
	v_cvt_pk_bf16_f32 v6, v26, v27
	v_mul_f32_e32 v28, v28, v0
	v_mul_f32_e32 v29, v29, v0
	v_cvt_pk_bf16_f32 v7, v28, v29
	global_store_dwordx2 v[4:5], v[2:3], off offset:32
	global_store_dwordx2 v[4:5], v[6:7], off offset:96
	v_mul_f32_e32 v2, v46, v0
	v_mul_f32_e32 v3, v47, v0
	v_mul_f32_e32 v38, v48, v0
	v_mul_f32_e32 v39, v49, v0
	v_mul_f32_e32 v30, v30, v0
	v_mul_f32_e32 v31, v31, v0
	v_mul_f32_e32 v32, v32, v0
	v_mul_f32_e32 v33, v33, v0
	v_mul_f32_e32 v0, v12, v12
	v_fmac_f32_e32 v0, v8, v8
	v_mul_f32_e32 v8, v13, v13
	v_fmac_f32_e32 v8, v9, v9
	v_add_f32_e32 v0, v0, v8
	v_mul_f32_e32 v8, v14, v14
	v_fmac_f32_e32 v8, v10, v10
	v_add_f32_e32 v0, v8, v0
	v_mul_f32_e32 v8, v15, v15
	v_fmac_f32_e32 v8, v11, v11
	v_add_f32_e32 v0, v8, v0
	v_mul_f32_e32 v8, v22, v22
	v_fmac_f32_e32 v8, v18, v18
	v_add_f32_e32 v0, v8, v0
	v_mul_f32_e32 v8, v23, v23
	v_fmac_f32_e32 v8, v19, v19
	v_add_f32_e32 v0, v8, v0
	v_mul_f32_e32 v8, v24, v24
	v_fmac_f32_e32 v8, v20, v20
	v_add_f32_e32 v0, v8, v0
	v_mul_f32_e32 v8, v25, v25
	v_fmac_f32_e32 v8, v21, v21
	v_add_f32_e32 v0, v8, v0
	v_mul_f32_e32 v8, v26, v26
	v_fmac_f32_e32 v8, v34, v34
	v_add_f32_e32 v0, v8, v0
	v_mul_f32_e32 v8, v27, v27
	v_fmac_f32_e32 v8, v35, v35
	v_add_f32_e32 v0, v8, v0
	v_mul_f32_e32 v8, v28, v28
	v_fmac_f32_e32 v8, v36, v36
	v_add_f32_e32 v0, v8, v0
	v_mul_f32_e32 v8, v29, v29
	v_fmac_f32_e32 v8, v37, v37
	v_add_f32_e32 v0, v8, v0
	v_mul_f32_e32 v8, v30, v30
	v_cvt_pk_bf16_f32 v6, v2, v3
	v_fmac_f32_e32 v8, v2, v2
	v_mul_f32_e32 v2, v31, v31
	v_add_f32_e32 v0, v8, v0
	v_fmac_f32_e32 v2, v3, v3
	v_add_f32_e32 v0, v2, v0
	v_mul_f32_e32 v2, v32, v32
	v_fmac_f32_e32 v2, v38, v38
	v_add_f32_e32 v0, v2, v0
	v_mul_f32_e32 v2, v33, v33
	v_fmac_f32_e32 v2, v39, v39
	v_add_f32_e32 v0, v2, v0
	ds_bpermute_b32 v2, v17, v0
	v_cmp_gt_u32_e64 s[8:9], 32, v171
	v_cvt_pk_bf16_f32 v7, v38, v39
	v_cvt_pk_bf16_f32 v8, v30, v31
	v_cvt_pk_bf16_f32 v9, v32, v33
	global_store_dwordx2 v[4:5], v[6:7], off offset:48
	global_store_dwordx2 v[4:5], v[8:9], off offset:112
	s_and_saveexec_b64 s[2:3], s[8:9]
	s_cbranch_execz .LBB0_806
	s_waitcnt lgkmcnt(0)
	v_add_f32_e32 v0, v0, v2
	v_mul_f32_e32 v0, 0x4b800000, v0
	v_trunc_f32_e32 v0, v0
	v_mul_f32_e32 v2, 0x2f800000, v0
	v_floor_f32_e32 v3, v2
	v_fmac_f32_e32 v0, 0xcf800000, v3
	v_cvt_u32_f32_e32 v2, v0
	v_cvt_u32_f32_e32 v3, v3
	global_atomic_add_x2 v[150:151], v[2:3], off

; __device__ __forceinline__ unsigned cvtpk(float lo, float hi) { unsigned r; asm volatile("v_cvt_pk_bf16_f32 %0, %1, %2" : "=v"(r) : "v"(lo), "v"(hi)); return r; }
; __device__ __forceinline__ float shfl_x(float v, int m, int lane) { return __builtin_bit_cast(float, __builtin_amdgcn_ds_bpermute((lane ^ m) << 2, __builtin_bit_cast(int, v))); }
; __device__ __forceinline__ void swa_unit3(LAS unsigned char* lds, const bf16_t* pb  , bf16_t* Yb  , int q0, int kvh,
;                                           const float* sinks  , unsigned long long* gss, const int wave_s) {
;     ...
;         const float lt = l_run + shfl_x(l_run, 32, lane);
;         const float inv = 1.0f / lt;
;         bf16_t* orow = Yb + (size_t)(qw0 + r32) * DM + 64 * hq + 4 * hi;
; #pragma unroll
;         for (int rg = 0; rg < 4; ++rg) {
;             u32x2 a, b;
;             a.x = cvtpk(o0[4 * rg] * inv, o0[4 * rg + 1] * inv); a.y = cvtpk(o0[4 * rg + 2] * inv, o0[4 * rg + 3] * inv);
;             b.x = cvtpk(o1[4 * rg] * inv, o1[4 * rg + 1] * inv); b.y = cvtpk(o1[4 * rg + 2] * inv, o1[4 * rg + 3] * inv);
;             *(u32x2*)(orow + 8 * rg) = a; *(u32x2*)(orow + 32 + 8 * rg) = b;
;         }
;         { float q = 0.f;
; #pragma unroll
;           for (int r = 0; r < 16; ++r) { const float a = o0[r] * inv, b = o1[r] * inv; q += a * a + b * b; }
;           q += shfl_x(q, 32, lane);
;           if (hi == 0) __hip_atomic_fetch_add(gss + qw0 + r32, (unsigned long long)(q * 16777216.0f), __ATOMIC_RELAXED, __HIP_MEMORY_SCOPE_AGENT); }
.LBB0_816:
	ds_bpermute_b32 v0, v17, v154
	s_lshl_b32 s52, s25, 1
	s_waitcnt lgkmcnt(0)
	v_add_f32_e32 v0, v154, v0
	v_div_scale_f32 v2, s[2:3], v0, v0, 1.0
	v_rcp_f32_e32 v3, v2
	s_nop 0
	v_fma_f32 v4, -v2, v3, 1.0
	v_fmac_f32_e32 v3, v4, v3
	v_div_scale_f32 v4, vcc, 1.0, v0, 1.0
	v_mul_f32_e32 v5, v4, v3
	v_fma_f32 v6, -v2, v5, v4
	v_fmac_f32_e32 v5, v6, v3
	v_fma_f32 v2, -v2, v5, v4
	v_div_fmas_f32 v2, v2, v3, v5
	v_div_fixup_f32 v0, v2, v0, 1.0
	v_lshl_add_u64 v[2:3], v[152:153], 0, s[52:53]
	v_mul_f32_e32 v8, v34, v0
	v_mul_f32_e32 v9, v35, v0
	v_cvt_pk_bf16_f32 v4, v8, v9
	v_mul_f32_e32 v10, v36, v0
	v_mul_f32_e32 v11, v37, v0
	v_cvt_pk_bf16_f32 v5, v10, v11
	v_mul_f32_e32 v12, v18, v0
	v_mul_f32_e32 v13, v19, v0
	v_cvt_pk_bf16_f32 v6, v12, v13
	v_mul_f32_e32 v14, v20, v0
	v_mul_f32_e32 v15, v21, v0
	v_cvt_pk_bf16_f32 v7, v14, v15
	global_store_dwordx2 v[2:3], v[4:5], off
	global_store_dwordx2 v[2:3], v[6:7], off offset:64
	v_mul_f32_e32 v18, v38, v0
	v_mul_f32_e32 v19, v39, v0
	v_cvt_pk_bf16_f32 v4, v18, v19
	v_mul_f32_e32 v20, v40, v0
	v_mul_f32_e32 v21, v41, v0
	v_cvt_pk_bf16_f32 v5, v20, v21
	v_mul_f32_e32 v22, v22, v0
	v_mul_f32_e32 v23, v23, v0
	v_cvt_pk_bf16_f32 v6, v22, v23
	v_mul_f32_e32 v24, v24, v0
	v_mul_f32_e32 v25, v25, v0
	v_cvt_pk_bf16_f32 v7, v24, v25
	global_store_dwordx2 v[2:3], v[4:5], off offset:16
	global_store_dwordx2 v[2:3], v[6:7], off offset:80
	v_mul_f32_e32 v34, v42, v0
	v_mul_f32_e32 v35, v43, v0
	v_cvt_pk_bf16_f32 v4, v34, v35
	v_mul_f32_e32 v36, v44, v0
	v_mul_f32_e32 v37, v45, v0
	v_cvt_pk_bf16_f32 v5, v36, v37
	v_mul_f32_e32 v26, v26, v0
	v_mul_f32_e32 v27, v27, v0
	v_cvt_pk_bf16_f32 v6, v26, v27
	v_mul_f32_e32 v28, v28, v0
	v_mul_f32_e32 v29, v29, v0
	v_cvt_pk_bf16_f32 v7, v28, v29
	global_store_dwordx2 v[2:3], v[4:5], off offset:32
	global_store_dwordx2 v[2:3], v[6:7], off offset:96
	v_mul_f32_e32 v38, v46, v0
	v_mul_f32_e32 v39, v47, v0
	v_cvt_pk_bf16_f32 v4, v38, v39
	v_mul_f32_e32 v40, v48, v0
	v_mul_f32_e32 v41, v49, v0
	v_cvt_pk_bf16_f32 v5, v40, v41
	v_mul_f32_e32 v30, v30, v0
	v_mul_f32_e32 v31, v31, v0
	v_cvt_pk_bf16_f32 v6, v30, v31
	v_mul_f32_e32 v32, v32, v0
	v_mul_f32_e32 v0, v33, v0
	v_cvt_pk_bf16_f32 v7, v32, v0
	global_store_dwordx2 v[2:3], v[4:5], off offset:48
	global_store_dwordx2 v[2:3], v[6:7], off offset:112
	v_mul_f32_e32 v2, v12, v12
	v_mul_f32_e32 v3, v13, v13
	v_fmac_f32_e32 v2, v8, v8
	v_fmac_f32_e32 v3, v9, v9
	v_add_f32_e32 v2, v2, v3
	v_mul_f32_e32 v3, v14, v14
	v_fmac_f32_e32 v3, v10, v10
	v_add_f32_e32 v2, v3, v2
	v_mul_f32_e32 v3, v15, v15
	v_fmac_f32_e32 v3, v11, v11
	v_add_f32_e32 v2, v3, v2
	v_mul_f32_e32 v3, v22, v22
	v_fmac_f32_e32 v3, v18, v18
	v_add_f32_e32 v2, v3, v2
	v_mul_f32_e32 v3, v23, v23
	v_fmac_f32_e32 v3, v19, v19
	v_add_f32_e32 v2, v3, v2
	v_mul_f32_e32 v3, v24, v24
	v_fmac_f32_e32 v3, v20, v20
	v_add_f32_e32 v2, v3, v2
	v_mul_f32_e32 v3, v25, v25
	v_fmac_f32_e32 v3, v21, v21
	v_add_f32_e32 v2, v3, v2
	v_mul_f32_e32 v3, v26, v26
	v_fmac_f32_e32 v3, v34, v34
	v_add_f32_e32 v2, v3, v2
	v_mul_f32_e32 v3, v27, v27
	v_fmac_f32_e32 v3, v35, v35
	v_add_f32_e32 v2, v3, v2
	v_mul_f32_e32 v3, v28, v28
	v_fmac_f32_e32 v3, v36, v36
	v_add_f32_e32 v2, v3, v2
	v_mul_f32_e32 v3, v29, v29
	v_fmac_f32_e32 v3, v37, v37
	v_add_f32_e32 v2, v3, v2
	v_mul_f32_e32 v3, v30, v30
	v_fmac_f32_e32 v3, v38, v38
	v_add_f32_e32 v2, v3, v2
	v_mul_f32_e32 v3, v31, v31
	v_fmac_f32_e32 v3, v39, v39
	v_add_f32_e32 v2, v3, v2
	v_mul_f32_e32 v3, v32, v32
	v_fmac_f32_e32 v3, v40, v40
	v_mul_f32_e32 v0, v0, v0
	v_add_f32_e32 v2, v3, v2
	v_fmac_f32_e32 v0, v41, v41
	v_add_f32_e32 v0, v0, v2
	ds_bpermute_b32 v2, v17, v0
	s_and_saveexec_b64 s[2:3], s[8:9]
	s_cbranch_execz .LBB0_818
	s_waitcnt lgkmcnt(0)
	v_add_f32_e32 v0, v0, v2
	v_mul_f32_e32 v0, 0x4b800000, v0
	v_trunc_f32_e32 v0, v0
	v_mul_f32_e32 v2, 0x2f800000, v0
	v_floor_f32_e32 v3, v2
	v_fmac_f32_e32 v0, 0xcf800000, v3
	v_cvt_u32_f32_e32 v2, v0
	v_cvt_u32_f32_e32 v3, v3
	global_atomic_add_x2 v[150:151], v[2:3], off

; __device__ __forceinline__ unsigned cvtpk(float lo, float hi) { unsigned r; asm volatile("v_cvt_pk_bf16_f32 %0, %1, %2" : "=v"(r) : "v"(lo), "v"(hi)); return r; }
; __device__ __forceinline__ float shfl_x(float v, int m, int lane) { return __builtin_bit_cast(float, __builtin_amdgcn_ds_bpermute((lane ^ m) << 2, __builtin_bit_cast(int, v))); }
; __device__ __forceinline__ void swa_unit3(LAS unsigned char* lds, const bf16_t* pb  , bf16_t* Yb  , int q0, int kvh,
;                                           const float* sinks  , unsigned long long* gss, const int wave_s) {
;     ...
;         const float lt = l_run + shfl_x(l_run, 32, lane);
;         const float inv = 1.0f / lt;
;         bf16_t* orow = Yb + (size_t)(qw0 + r32) * DM + 64 * hq + 4 * hi;
; #pragma unroll
;         for (int rg = 0; rg < 4; ++rg) {
;             u32x2 a, b;
;             a.x = cvtpk(o0[4 * rg] * inv, o0[4 * rg + 1] * inv); a.y = cvtpk(o0[4 * rg + 2] * inv, o0[4 * rg + 3] * inv);
;             b.x = cvtpk(o1[4 * rg] * inv, o1[4 * rg + 1] * inv); b.y = cvtpk(o1[4 * rg + 2] * inv, o1[4 * rg + 3] * inv);
;             *(u32x2*)(orow + 8 * rg) = a; *(u32x2*)(orow + 32 + 8 * rg) = b;
;         }
;         { float q = 0.f;
; #pragma unroll
;           for (int r = 0; r < 16; ++r) { const float a = o0[r] * inv, b = o1[r] * inv; q += a * a + b * b; }
;           q += shfl_x(q, 32, lane);
;           if (hi == 0) __hip_atomic_fetch_add(gss + qw0 + r32, (unsigned long long)(q * 16777216.0f), __ATOMIC_RELAXED, __HIP_MEMORY_SCOPE_AGENT); }
.LBB0_828:
	ds_bpermute_b32 v0, v17, v134
	s_lshl_b32 s52, s24, 1
	v_lshl_add_u64 v[4:5], v[152:153], 0, s[52:53]
	s_waitcnt lgkmcnt(0)
	v_add_f32_e32 v0, v134, v0
	v_div_scale_f32 v2, s[2:3], v0, v0, 1.0
	v_rcp_f32_e32 v3, v2
	v_div_scale_f32 v6, vcc, 1.0, v0, 1.0
	v_fma_f32 v7, -v2, v3, 1.0
	v_fmac_f32_e32 v3, v7, v3
	v_mul_f32_e32 v7, v6, v3
	v_fma_f32 v8, -v2, v7, v6
	v_fmac_f32_e32 v7, v8, v3
	v_fma_f32 v2, -v2, v7, v6
	v_div_fmas_f32 v2, v2, v3, v7
	v_div_fixup_f32 v0, v2, v0, 1.0
	v_mul_f32_e32 v8, v34, v0
	v_mul_f32_e32 v9, v35, v0
	v_cvt_pk_bf16_f32 v2, v8, v9
	v_mul_f32_e32 v10, v36, v0
	v_mul_f32_e32 v11, v37, v0
	v_cvt_pk_bf16_f32 v3, v10, v11
	v_mul_f32_e32 v12, v18, v0
	v_mul_f32_e32 v13, v19, v0
	v_cvt_pk_bf16_f32 v6, v12, v13
	v_mul_f32_e32 v14, v20, v0
	v_mul_f32_e32 v15, v21, v0
	v_cvt_pk_bf16_f32 v7, v14, v15
	global_store_dwordx2 v[4:5], v[2:3], off
	global_store_dwordx2 v[4:5], v[6:7], off offset:64
	v_mul_f32_e32 v18, v38, v0
	v_mul_f32_e32 v19, v39, v0
	v_cvt_pk_bf16_f32 v2, v18, v19
	v_mul_f32_e32 v20, v40, v0
	v_mul_f32_e32 v21, v41, v0
	v_cvt_pk_bf16_f32 v3, v20, v21
	v_mul_f32_e32 v22, v22, v0
	v_mul_f32_e32 v23, v23, v0
	v_cvt_pk_bf16_f32 v6, v22, v23
	v_mul_f32_e32 v24, v24, v0
	v_mul_f32_e32 v25, v25, v0
	v_cvt_pk_bf16_f32 v7, v24, v25
	global_store_dwordx2 v[4:5], v[2:3], off offset:16
	global_store_dwordx2 v[4:5], v[6:7], off offset:80
	v_mul_f32_e32 v34, v42, v0
	v_mul_f32_e32 v35, v43, v0
	v_cvt_pk_bf16_f32 v2, v34, v35
	v_mul_f32_e32 v36, v44, v0
	v_mul_f32_e32 v37, v45, v0
	v_cvt_pk_bf16_f32 v3, v36, v37
	v_mul_f32_e32 v26, v26, v0
	v_mul_f32_e32 v27, v27, v0
	v_cvt_pk_bf16_f32 v6, v26, v27
	v_mul_f32_e32 v28, v28, v0
	v_mul_f32_e32 v29, v29, v0
	v_cvt_pk_bf16_f32 v7, v28, v29
	global_store_dwordx2 v[4:5], v[2:3], off offset:32
	global_store_dwordx2 v[4:5], v[6:7], off offset:96
	v_mul_f32_e32 v2, v46, v0
	v_mul_f32_e32 v3, v47, v0
	v_mul_f32_e32 v38, v48, v0
	v_mul_f32_e32 v39, v49, v0
	v_mul_f32_e32 v30, v30, v0
	v_mul_f32_e32 v31, v31, v0
	v_mul_f32_e32 v32, v32, v0
	v_mul_f32_e32 v33, v33, v0
	v_mul_f32_e32 v0, v12, v12
	v_fmac_f32_e32 v0, v8, v8
	v_mul_f32_e32 v8, v13, v13
	v_fmac_f32_e32 v8, v9, v9
	v_add_f32_e32 v0, v0, v8
	v_mul_f32_e32 v8, v14, v14
	v_fmac_f32_e32 v8, v10, v10
	v_add_f32_e32 v0, v8, v0
	v_mul_f32_e32 v8, v15, v15
	v_fmac_f32_e32 v8, v11, v11
	v_add_f32_e32 v0, v8, v0
	v_mul_f32_e32 v8, v22, v22
	v_fmac_f32_e32 v8, v18, v18
	v_add_f32_e32 v0, v8, v0
	v_mul_f32_e32 v8, v23, v23
	v_fmac_f32_e32 v8, v19, v19
	v_add_f32_e32 v0, v8, v0
	v_mul_f32_e32 v8, v24, v24
	v_fmac_f32_e32 v8, v20, v20
	v_add_f32_e32 v0, v8, v0
	v_mul_f32_e32 v8, v25, v25
	v_fmac_f32_e32 v8, v21, v21
	v_add_f32_e32 v0, v8, v0
	v_mul_f32_e32 v8, v26, v26
	v_fmac_f32_e32 v8, v34, v34
	v_add_f32_e32 v0, v8, v0
	v_mul_f32_e32 v8, v27, v27
	v_fmac_f32_e32 v8, v35, v35
	v_add_f32_e32 v0, v8, v0
	v_mul_f32_e32 v8, v28, v28
	v_fmac_f32_e32 v8, v36, v36
	v_add_f32_e32 v0, v8, v0
	v_mul_f32_e32 v8, v29, v29
	v_fmac_f32_e32 v8, v37, v37
	v_add_f32_e32 v0, v8, v0
	v_mul_f32_e32 v8, v30, v30
	v_cvt_pk_bf16_f32 v6, v2, v3
	v_fmac_f32_e32 v8, v2, v2
	v_mul_f32_e32 v2, v31, v31
	v_add_f32_e32 v0, v8, v0
	v_fmac_f32_e32 v2, v3, v3
	v_add_f32_e32 v0, v2, v0
	v_mul_f32_e32 v2, v32, v32
	v_fmac_f32_e32 v2, v38, v38
	v_add_f32_e32 v0, v2, v0
	v_mul_f32_e32 v2, v33, v33
	v_fmac_f32_e32 v2, v39, v39
	v_add_f32_e32 v0, v2, v0
	ds_bpermute_b32 v2, v17, v0
	v_cvt_pk_bf16_f32 v7, v38, v39
	v_cvt_pk_bf16_f32 v8, v30, v31
	v_cvt_pk_bf16_f32 v9, v32, v33
	global_store_dwordx2 v[4:5], v[6:7], off offset:48
	global_store_dwordx2 v[4:5], v[8:9], off offset:112
	s_and_saveexec_b64 s[2:3], s[8:9]
	s_cbranch_execz .LBB0_769
	s_waitcnt lgkmcnt(0)
	v_add_f32_e32 v0, v0, v2
	v_mul_f32_e32 v0, 0x4b800000, v0
	v_trunc_f32_e32 v0, v0
	v_mul_f32_e32 v2, 0x2f800000, v0
	v_floor_f32_e32 v3, v2
	v_fmac_f32_e32 v0, 0xcf800000, v3
	v_cvt_u32_f32_e32 v2, v0
	v_cvt_u32_f32_e32 v3, v3
	global_atomic_add_x2 v[150:151], v[2:3], off
	s_branch .LBB0_769

; __device__ __forceinline__ float bflo(unsigned w) { return __uint_as_float(w << 16); }
; __device__ __forceinline__ float bfhi(unsigned w) { return __uint_as_float(w & 0xffff0000u); }
; __device__ __forceinline__ float shfl_x(float v, int m, int lane) { return __builtin_bit_cast(float, __builtin_amdgcn_ds_bpermute((lane ^ m) << 2, __builtin_bit_cast(int, v))); }
; __device__ __forceinline__ void sgu_unit(LAS unsigned char* lds, const bf16_t* proj, bf16_t* Y, const bf16_t* wsb  , const float* lnw, const float* lnb, const float* bs  , int row0, unsigned long long* gss, const int wave_s) {
;     ...
;     {
;         const int s = tid >> 2, q = tid & 3;
;         const u32x4* src = (const u32x4*)(proj + (size_t)(row0 + s) * PJP + PC_CV + 64 * q);
;         float v[64]; float sum = 0.f;
; #pragma unroll
;         for (int i = 0; i < 8; ++i) { const u32x4 w = src[i];
;             v[8 * i + 0] = bflo(w.x); v[8 * i + 1] = bfhi(w.x); v[8 * i + 2] = bflo(w.y); v[8 * i + 3] = bfhi(w.y);
;             v[8 * i + 4] = bflo(w.z); v[8 * i + 5] = bfhi(w.z); v[8 * i + 6] = bflo(w.w); v[8 * i + 7] = bfhi(w.w); }
; #pragma unroll
;         for (int i = 0; i < 64; ++i) sum += v[i];
;         sum += shfl_x(sum, 1, lane); sum += shfl_x(sum, 2, lane);
.LBB0_835:
	s_ashr_i32 s2, s4, 31
	s_lshr_b32 s2, s2, 23
	s_add_i32 s2, s4, s2
	s_and_b32 s2, s2, 0x1fffe00
	s_sub_i32 s2, s4, s2
	s_load_dwordx2 s[6:7], s[0:1], 0xb8
	s_waitcnt lgkmcnt(0)
	s_load_dwordx2 s[8:9], s[0:1], 0xb8
	s_waitcnt lgkmcnt(0)
	s_load_dwordx2 s[10:11], s[0:1], 0xb8
	s_waitcnt lgkmcnt(0)
	s_load_dwordx2 s[12:13], s[0:1], 0xb8
	s_waitcnt lgkmcnt(0)
	v_mbcnt_lo_u32_b32 v10, -1, 0
	v_mbcnt_hi_u32_b32 v10, -1, v10
	s_lshl_b32 s2, s2, 7
	v_or_b32_e32 v21, s63, v10
	v_ashrrev_i32_e32 v6, 2, v21
	v_add_u32_e32 v0, s2, v6
	v_mov_b64_e32 v[2:3], s[6:7]
	v_mad_i64_i32 v[4:5], s[6:7], v0, s85, v[2:3]
	v_lshlrev_b32_e32 v0, 6, v10
	v_and_b32_e32 v75, 0xc0, v0
	v_lshlrev_b32_e32 v0, 1, v75
	v_lshl_add_u64 v[4:5], v[4:5], 0, v[0:1]
	s_mov_b64 s[6:7], 0x10000000
	v_lshl_add_u64 v[4:5], v[4:5], 0, s[6:7]
	global_load_dwordx4 v[12:15], v[4:5], off offset:3584
	global_load_dwordx4 v[78:81], v[4:5], off offset:3680
	v_and_b32_e32 v9, 63, v10
	v_readfirstlane_b32 s3, v21
	v_lshlrev_b32_e32 v21, 2, v9
	v_and_b32_e32 v8, 31, v10
	v_bfe_u32 v10, v10, 5, 1
	s_ashr_i32 s22, s2, 31
	v_readlane_b32 s24, v255, 8
	v_readlane_b32 s25, v255, 9
	s_waitcnt vmcnt(0) lgkmcnt(0)
	v_lshlrev_b32_e32 v7, 16, v12
	v_and_b32_e32 v77, 0xffff0000, v12
	v_lshlrev_b32_e32 v76, 16, v13
	v_and_b32_e32 v74, 0xffff0000, v13
	v_lshlrev_b32_e32 v73, 16, v14
	v_and_b32_e32 v72, 0xffff0000, v14
	v_lshlrev_b32_e32 v71, 16, v15
	v_and_b32_e32 v69, 0xffff0000, v15
	global_load_dwordx4 v[12:15], v[4:5], off offset:3600
	v_lshlrev_b32_e32 v23, 16, v78
	v_and_b32_e32 v18, 0xffff0000, v78
	v_lshlrev_b32_e32 v11, 16, v81
	v_and_b32_e32 v0, 0xffff0000, v81
	s_waitcnt vmcnt(0) lgkmcnt(0)
	v_lshlrev_b32_e32 v70, 16, v12
	v_and_b32_e32 v68, 0xffff0000, v12
	v_lshlrev_b32_e32 v67, 16, v13
	v_and_b32_e32 v65, 0xffff0000, v13
	v_lshlrev_b32_e32 v64, 16, v14
	v_and_b32_e32 v63, 0xffff0000, v14
	v_lshlrev_b32_e32 v62, 16, v15
	v_and_b32_e32 v60, 0xffff0000, v15
	global_load_dwordx4 v[12:15], v[4:5], off offset:3616
	s_waitcnt vmcnt(0) lgkmcnt(0)
	v_lshlrev_b32_e32 v61, 16, v12
	v_and_b32_e32 v59, 0xffff0000, v12
	v_lshlrev_b32_e32 v58, 16, v13
	v_and_b32_e32 v57, 0xffff0000, v13
	v_lshlrev_b32_e32 v56, 16, v14
	v_and_b32_e32 v55, 0xffff0000, v14
	v_lshlrev_b32_e32 v54, 16, v15
	v_and_b32_e32 v52, 0xffff0000, v15
	global_load_dwordx4 v[12:15], v[4:5], off offset:3632
	s_waitcnt vmcnt(0) lgkmcnt(0)
	v_lshlrev_b32_e32 v53, 16, v12
	v_and_b32_e32 v51, 0xffff0000, v12
	v_lshlrev_b32_e32 v50, 16, v13
	v_and_b32_e32 v49, 0xffff0000, v13
	v_lshlrev_b32_e32 v47, 16, v14
	v_and_b32_e32 v46, 0xffff0000, v14
	v_lshlrev_b32_e32 v45, 16, v15
	v_and_b32_e32 v43, 0xffff0000, v15
	global_load_dwordx4 v[12:15], v[4:5], off offset:3648
	s_waitcnt vmcnt(0) lgkmcnt(0)
	v_lshlrev_b32_e32 v44, 16, v12
	v_and_b32_e32 v42, 0xffff0000, v12
	v_lshlrev_b32_e32 v41, 16, v13
	v_and_b32_e32 v40, 0xffff0000, v13
	v_lshlrev_b32_e32 v39, 16, v14
	v_and_b32_e32 v38, 0xffff0000, v14
	v_lshlrev_b32_e32 v37, 16, v15
	v_and_b32_e32 v35, 0xffff0000, v15
	global_load_dwordx4 v[12:15], v[4:5], off offset:3664
	s_waitcnt vmcnt(0) lgkmcnt(0)
	v_lshlrev_b32_e32 v36, 16, v12
	v_and_b32_e32 v34, 0xffff0000, v12
	v_lshlrev_b32_e32 v32, 16, v13
	v_and_b32_e32 v30, 0xffff0000, v13
	v_lshlrev_b32_e32 v28, 16, v14
	v_and_b32_e32 v26, 0xffff0000, v14
	v_lshlrev_b32_e32 v24, 16, v15
	v_and_b32_e32 v20, 0xffff0000, v15
	v_lshlrev_b32_e32 v15, 16, v79
	v_and_b32_e32 v14, 0xffff0000, v79
	v_lshlrev_b32_e32 v13, 16, v80
	v_and_b32_e32 v12, 0xffff0000, v80
	global_load_dwordx4 v[78:81], v[4:5], off offset:3696
	v_add_f32_e32 v4, 0, v7
	v_add_f32_e32 v4, v4, v77
	v_add_f32_e32 v4, v4, v76
	v_add_f32_e32 v4, v4, v74
	v_add_f32_e32 v4, v4, v73
	v_add_f32_e32 v4, v4, v72
	v_add_f32_e32 v4, v4, v71
	v_add_f32_e32 v4, v4, v69
	v_add_f32_e32 v4, v4, v70
	v_add_f32_e32 v4, v4, v68
	v_add_f32_e32 v4, v4, v67
	v_add_f32_e32 v4, v4, v65
	v_add_f32_e32 v4, v4, v64
	v_add_f32_e32 v4, v4, v63
	v_add_f32_e32 v4, v4, v62
	v_add_f32_e32 v4, v4, v60
	v_add_f32_e32 v4, v4, v61
	v_add_f32_e32 v4, v4, v59
	v_add_f32_e32 v4, v4, v58
	v_add_f32_e32 v4, v4, v57
	v_add_f32_e32 v4, v4, v56
	v_add_f32_e32 v4, v4, v55
	v_add_f32_e32 v4, v4, v54
	v_add_f32_e32 v4, v4, v52
	v_add_f32_e32 v4, v4, v53
	v_add_f32_e32 v4, v4, v51
	v_add_f32_e32 v4, v4, v50
	v_add_f32_e32 v4, v4, v49
	v_add_f32_e32 v4, v4, v47
	v_add_f32_e32 v4, v4, v46
	v_add_f32_e32 v4, v4, v45
	v_add_f32_e32 v4, v4, v43
	v_add_f32_e32 v4, v4, v44
	v_add_f32_e32 v4, v4, v42
	v_add_f32_e32 v4, v4, v41
	v_add_f32_e32 v4, v4, v40
	v_add_f32_e32 v4, v4, v39
	v_add_f32_e32 v4, v4, v38
	v_add_f32_e32 v4, v4, v37
	v_add_f32_e32 v4, v4, v35
	v_add_f32_e32 v4, v4, v36
	v_add_f32_e32 v4, v4, v34
	v_add_f32_e32 v4, v4, v32
	v_add_f32_e32 v4, v4, v30
	v_add_f32_e32 v4, v4, v28
	v_add_f32_e32 v4, v4, v26
	v_add_f32_e32 v4, v4, v24
	v_add_f32_e32 v4, v4, v20
	v_add_f32_e32 v4, v4, v23
	v_add_f32_e32 v4, v4, v18
	v_add_f32_e32 v4, v4, v15
	v_add_f32_e32 v4, v4, v14
	v_add_f32_e32 v4, v4, v13
	v_add_f32_e32 v4, v4, v12
	v_add_f32_e32 v4, v4, v11
	v_add_f32_e32 v4, v4, v0
	v_xor_b32_e32 v5, 4, v21
	s_waitcnt vmcnt(0) lgkmcnt(0)
	v_lshlrev_b32_e32 v33, 16, v78
	v_and_b32_e32 v31, 0xffff0000, v78
	v_add_f32_e32 v4, v4, v33
	v_lshlrev_b32_e32 v29, 16, v79
	v_add_f32_e32 v4, v4, v31
	v_and_b32_e32 v27, 0xffff0000, v79
	v_add_f32_e32 v4, v4, v29
	v_lshlrev_b32_e32 v25, 16, v80
	v_add_f32_e32 v4, v4, v27
	v_and_b32_e32 v22, 0xffff0000, v80
	v_add_f32_e32 v4, v4, v25
	v_lshlrev_b32_e32 v19, 16, v81
	v_add_f32_e32 v4, v4, v22
	v_and_b32_e32 v17, 0xffff0000, v81
	v_add_f32_e32 v4, v4, v19
	v_add_f32_e32 v4, v4, v17
	ds_bpermute_b32 v48, v5, v4
	s_waitcnt lgkmcnt(0)
; __device__ __forceinline__ float shfl_x(float v, int m, int lane) { return __builtin_bit_cast(float, __builtin_amdgcn_ds_bpermute((lane ^ m) << 2, __builtin_bit_cast(int, v))); }
; __device__ __forceinline__ void sgu_unit(LAS unsigned char* lds, const bf16_t* proj, bf16_t* Y, const bf16_t* wsb  , const float* lnw, const float* lnb, const float* bs  , int row0, unsigned long long* gss, const int wave_s) {
;     ...
;         sum += shfl_x(sum, 1, lane); sum += shfl_x(sum, 2, lane);
;         const float mu = sum * (1.0f / 256.0f); float sq = 0.f;
; #pragma unroll
;         for (int i = 0; i < 64; ++i) { v[i] -= mu; sq += v[i] * v[i]; }
;         sq += shfl_x(sq, 1, lane); sq += shfl_x(sq, 2, lane);
;         const float rstd = 1.0f / sqrtf(sq * (1.0f / 256.0f) + EPS);
; #pragma unroll
;         for (int i = 0; i < 64; i += 2) {
;             const int c = 64 * q + i;
;             const float a = v[i] * rstd * lnw[c] + lnb[c], b = v[i + 1] * rstd * lnw[c + 1] + lnb[c + 1];
	v_add_f32_e32 v4, v4, v48
	v_xor_b32_e32 v48, 8, v21
	ds_bpermute_b32 v66, v48, v4
	s_waitcnt lgkmcnt(0)
	v_add_f32_e32 v4, v4, v66
	v_fmac_f32_e32 v77, 0xbb800000, v4
	v_fmac_f32_e32 v7, 0xbb800000, v4
	v_mul_f32_e32 v66, v77, v77
	v_fmac_f32_e32 v66, v7, v7
	v_fmac_f32_e32 v76, 0xbb800000, v4
	v_fmac_f32_e32 v66, v76, v76
	v_fmac_f32_e32 v74, 0xbb800000, v4
	v_fmac_f32_e32 v66, v74, v74
	v_fmac_f32_e32 v73, 0xbb800000, v4
	v_fmac_f32_e32 v66, v73, v73
	v_fmac_f32_e32 v72, 0xbb800000, v4
	v_fmac_f32_e32 v66, v72, v72
	v_fmac_f32_e32 v71, 0xbb800000, v4
	v_fmac_f32_e32 v66, v71, v71
	v_fmac_f32_e32 v69, 0xbb800000, v4
	v_fmac_f32_e32 v66, v69, v69
	v_fmac_f32_e32 v70, 0xbb800000, v4
	v_fmac_f32_e32 v66, v70, v70
	v_fmac_f32_e32 v68, 0xbb800000, v4
	v_fmac_f32_e32 v66, v68, v68
	v_fmac_f32_e32 v67, 0xbb800000, v4
	v_fmac_f32_e32 v66, v67, v67
	v_fmac_f32_e32 v65, 0xbb800000, v4
	v_fmac_f32_e32 v66, v65, v65
	v_fmac_f32_e32 v64, 0xbb800000, v4
	v_fmac_f32_e32 v66, v64, v64
	v_fmac_f32_e32 v63, 0xbb800000, v4
	v_fmac_f32_e32 v66, v63, v63
	v_fmac_f32_e32 v62, 0xbb800000, v4
	v_fmac_f32_e32 v66, v62, v62
	v_fmac_f32_e32 v60, 0xbb800000, v4
	v_fmac_f32_e32 v66, v60, v60
	v_fmac_f32_e32 v61, 0xbb800000, v4
	v_fmac_f32_e32 v66, v61, v61
	v_fmac_f32_e32 v59, 0xbb800000, v4
	v_fmac_f32_e32 v66, v59, v59
	v_fmac_f32_e32 v58, 0xbb800000, v4
	v_fmac_f32_e32 v66, v58, v58
	v_fmac_f32_e32 v57, 0xbb800000, v4
	v_fmac_f32_e32 v66, v57, v57
	v_fmac_f32_e32 v56, 0xbb800000, v4
	v_fmac_f32_e32 v66, v56, v56
	v_fmac_f32_e32 v55, 0xbb800000, v4
	v_fmac_f32_e32 v66, v55, v55
	v_fmac_f32_e32 v54, 0xbb800000, v4
	v_fmac_f32_e32 v66, v54, v54
	v_fmac_f32_e32 v52, 0xbb800000, v4
	v_fmac_f32_e32 v66, v52, v52
	v_fmac_f32_e32 v53, 0xbb800000, v4
	v_fmac_f32_e32 v66, v53, v53
	v_fmac_f32_e32 v51, 0xbb800000, v4
	v_fmac_f32_e32 v66, v51, v51
	v_fmac_f32_e32 v50, 0xbb800000, v4
	v_fmac_f32_e32 v66, v50, v50
	v_fmac_f32_e32 v49, 0xbb800000, v4
	v_fmac_f32_e32 v66, v49, v49
	v_fmac_f32_e32 v47, 0xbb800000, v4
	v_fmac_f32_e32 v66, v47, v47
	v_fmac_f32_e32 v46, 0xbb800000, v4
	v_fmac_f32_e32 v66, v46, v46
	v_fmac_f32_e32 v45, 0xbb800000, v4
	v_fmac_f32_e32 v66, v45, v45
	v_fmac_f32_e32 v43, 0xbb800000, v4
	v_fmac_f32_e32 v66, v43, v43
	v_fmac_f32_e32 v44, 0xbb800000, v4
	v_fmac_f32_e32 v66, v44, v44
	v_fmac_f32_e32 v42, 0xbb800000, v4
	v_fmac_f32_e32 v66, v42, v42
	v_fmac_f32_e32 v41, 0xbb800000, v4
	v_fmac_f32_e32 v66, v41, v41
	v_fmac_f32_e32 v40, 0xbb800000, v4
	v_fmac_f32_e32 v66, v40, v40
	v_fmac_f32_e32 v39, 0xbb800000, v4
	v_fmac_f32_e32 v66, v39, v39
	v_fmac_f32_e32 v38, 0xbb800000, v4
	v_fmac_f32_e32 v66, v38, v38
	v_fmac_f32_e32 v37, 0xbb800000, v4
	v_fmac_f32_e32 v66, v37, v37
	v_fmac_f32_e32 v35, 0xbb800000, v4
	v_fmac_f32_e32 v66, v35, v35
	v_fmac_f32_e32 v36, 0xbb800000, v4
	v_fmac_f32_e32 v66, v36, v36
	v_fmac_f32_e32 v34, 0xbb800000, v4
	v_fmac_f32_e32 v66, v34, v34
	v_fmac_f32_e32 v32, 0xbb800000, v4
	v_fmac_f32_e32 v66, v32, v32
	v_fmac_f32_e32 v30, 0xbb800000, v4
	v_fmac_f32_e32 v66, v30, v30
	v_fmac_f32_e32 v28, 0xbb800000, v4
	v_fmac_f32_e32 v66, v28, v28
	v_fmac_f32_e32 v26, 0xbb800000, v4
	v_fmac_f32_e32 v66, v26, v26
	v_fmac_f32_e32 v24, 0xbb800000, v4
	v_fmac_f32_e32 v66, v24, v24
	v_fmac_f32_e32 v20, 0xbb800000, v4
	v_fmac_f32_e32 v66, v20, v20
	v_fmac_f32_e32 v23, 0xbb800000, v4
	v_fmac_f32_e32 v66, v23, v23
	v_fmac_f32_e32 v18, 0xbb800000, v4
	v_fmac_f32_e32 v66, v18, v18
	v_fmac_f32_e32 v15, 0xbb800000, v4
	v_fmac_f32_e32 v66, v15, v15
	v_fmac_f32_e32 v14, 0xbb800000, v4
	v_fmac_f32_e32 v66, v14, v14
	v_fmac_f32_e32 v13, 0xbb800000, v4
	v_fmac_f32_e32 v66, v13, v13
	v_fmac_f32_e32 v12, 0xbb800000, v4
	v_fmac_f32_e32 v66, v12, v12
	v_fmac_f32_e32 v11, 0xbb800000, v4
	v_fmac_f32_e32 v66, v11, v11
	v_fmac_f32_e32 v0, 0xbb800000, v4
	v_fmac_f32_e32 v66, v0, v0
	v_fmac_f32_e32 v33, 0xbb800000, v4
	v_fmac_f32_e32 v66, v33, v33
	v_fmac_f32_e32 v31, 0xbb800000, v4
	v_fmac_f32_e32 v66, v31, v31
	v_fmac_f32_e32 v29, 0xbb800000, v4
	v_fmac_f32_e32 v66, v29, v29
	v_fmac_f32_e32 v27, 0xbb800000, v4
	v_fmac_f32_e32 v66, v27, v27
	v_fmac_f32_e32 v25, 0xbb800000, v4
	v_fmac_f32_e32 v66, v25, v25
	v_fmac_f32_e32 v22, 0xbb800000, v4
	v_fmac_f32_e32 v66, v22, v22
	v_fmac_f32_e32 v19, 0xbb800000, v4
	v_fmac_f32_e32 v66, v19, v19
	v_fmac_f32_e32 v17, 0xbb800000, v4
	v_fmac_f32_e32 v66, v17, v17
	ds_bpermute_b32 v4, v5, v66
	s_waitcnt lgkmcnt(0)
	v_add_f32_e32 v4, v66, v4
	ds_bpermute_b32 v5, v48, v4
	s_waitcnt lgkmcnt(0)
	v_add_f32_e32 v4, v4, v5
	v_fmamk_f32 v4, v4, 0x3b800000, v226
	v_cmp_gt_f32_e32 vcc, s71, v4
	v_mul_f32_e32 v5, 0x4f800000, v4
	s_nop 0
	v_cndmask_b32_e32 v4, v4, v5, vcc
	v_sqrt_f32_e32 v5, v4
	s_nop 0
	v_add_u32_e32 v48, -1, v5
	v_fma_f32 v66, -v48, v5, v4
	v_cmp_ge_f32_e64 s[6:7], 0, v66
	v_add_u32_e32 v66, 1, v5
	s_nop 0
	v_cndmask_b32_e64 v48, v5, v48, s[6:7]
	v_fma_f32 v5, -v66, v5, v4
	v_cmp_lt_f32_e64 s[6:7], 0, v5
	s_nop 1
	v_cndmask_b32_e64 v5, v48, v66, s[6:7]
	v_mul_f32_e32 v48, 0x37800000, v5
	v_cndmask_b32_e32 v5, v5, v48, vcc
	v_cmp_class_f32_e32 vcc, v4, v223
	s_nop 1
	v_cndmask_b32_e32 v4, v5, v4, vcc
	v_div_scale_f32 v5, s[6:7], v4, v4, 1.0
	v_rcp_f32_e32 v48, v5
	s_ashr_i32 s6, s3, 7
	s_lshr_b32 s7, s3, 1
	s_lshl_b32 s5, s6, 6
	v_fma_f32 v66, -v5, v48, 1.0
	v_fmac_f32_e32 v48, v66, v48
	v_div_scale_f32 v66, vcc, 1.0, v4, 1.0
	v_mul_f32_e32 v78, v66, v48
	v_fma_f32 v79, -v5, v78, v66
	v_fmac_f32_e32 v78, v79, v48
	v_fma_f32 v5, -v5, v78, v66
	v_div_fmas_f32 v5, v5, v48, v78
	v_div_fixup_f32 v48, v5, v4, 1.0
	v_lshlrev_b32_e32 v66, 2, v75
	v_lshlrev_b32_e32 v78, 1, v6
	v_mul_f32_e32 v79, v7, v48
	global_load_dwordx2 v[4:5], v66, s[14:15]
	global_load_dwordx2 v[6:7], v66, s[16:17]
	v_mul_f32_e32 v0, v0, v48
	s_and_b32 s7, s7, 32
	s_or_b32 s5, s5, s7
	s_movk_i32 s7, 0x88
	s_and_b32 s3, s3, 0xffffff80
	s_waitcnt vmcnt(0)
; __device__ __forceinline__ unsigned cvtpk(float lo, float hi) { unsigned r; asm volatile("v_cvt_pk_bf16_f32 %0, %1, %2" : "=v"(r) : "v"(lo), "v"(hi)); return r; }
; __device__ __forceinline__ void sgu_unit(LAS unsigned char* lds, const bf16_t* proj, bf16_t* Y, const bf16_t* wsb  , const float* lnw, const float* lnb, const float* bs  , int row0, unsigned long long* gss, const int wave_s) {
;     ...
;         for (int i = 0; i < 64; i += 2) {
;             const int c = 64 * q + i;
;             const float a = v[i] * rstd * lnw[c] + lnb[c], b = v[i + 1] * rstd * lnw[c + 1] + lnb[c + 1];
;             const unsigned w = cvtpk(a, b);
;             vt[c * SSTR + s] = (unsigned short)(w & 0xffffu); vt[(c + 1) * SSTR + s] = (unsigned short)(w >> 16);
;         }
	v_fma_f32 v4, v4, v79, v6
	v_mul_f32_e32 v6, v77, v48
	v_fmac_f32_e32 v7, v5, v6
	v_cvt_pk_bf16_f32 v5, v4, v7
	v_mul_u32_u24_e32 v4, 0x110, v75
	v_add3_u32 v4, 0, v78, v4
	ds_write_b16 v4, v5
	ds_write_b16_d16_hi v4, v5 offset:272
	v_mul_f32_e32 v5, v76, v48
	global_load_dwordx2 v[6:7], v66, s[14:15] offset:8
	global_load_dwordx2 v[76:77], v66, s[16:17] offset:8
	s_waitcnt vmcnt(0)
	v_fma_f32 v5, v6, v5, v76
	v_mul_f32_e32 v6, v74, v48
	v_fmac_f32_e32 v77, v7, v6
	v_cvt_pk_bf16_f32 v5, v5, v77
	ds_write_b16 v4, v5 offset:544
	ds_write_b16_d16_hi v4, v5 offset:816
	global_load_dwordx2 v[6:7], v66, s[14:15] offset:16
	global_load_dwordx2 v[74:75], v66, s[16:17] offset:16
	v_mul_f32_e32 v5, v73, v48
	s_waitcnt vmcnt(0)
	v_fma_f32 v5, v6, v5, v74
	v_mul_f32_e32 v6, v72, v48
	v_fmac_f32_e32 v75, v7, v6
	v_cvt_pk_bf16_f32 v5, v5, v75
	ds_write_b16 v4, v5 offset:1088
	ds_write_b16_d16_hi v4, v5 offset:1360
	global_load_dwordx2 v[6:7], v66, s[14:15] offset:24
	global_load_dwordx2 v[72:73], v66, s[16:17] offset:24
	v_mul_f32_e32 v5, v71, v48
	s_waitcnt vmcnt(0)
	v_fma_f32 v5, v6, v5, v72
	v_mul_f32_e32 v6, v69, v48
	v_fmac_f32_e32 v73, v7, v6
	v_cvt_pk_bf16_f32 v5, v5, v73
	ds_write_b16 v4, v5 offset:1632
	ds_write_b16_d16_hi v4, v5 offset:1904
	v_mul_f32_e32 v5, v70, v48
	global_load_dwordx2 v[6:7], v66, s[14:15] offset:32
	global_load_dwordx2 v[70:71], v66, s[16:17] offset:32
	s_waitcnt vmcnt(0)
	v_fma_f32 v5, v6, v5, v70
	v_mul_f32_e32 v6, v68, v48
	v_fmac_f32_e32 v71, v7, v6
	v_cvt_pk_bf16_f32 v5, v5, v71
	ds_write_b16 v4, v5 offset:2176
	ds_write_b16_d16_hi v4, v5 offset:2448
	global_load_dwordx2 v[6:7], v66, s[14:15] offset:40
	global_load_dwordx2 v[68:69], v66, s[16:17] offset:40
	v_mul_f32_e32 v5, v67, v48
	s_waitcnt vmcnt(0)
	v_fma_f32 v5, v6, v5, v68
	v_mul_f32_e32 v6, v65, v48
	v_fmac_f32_e32 v69, v7, v6
	v_cvt_pk_bf16_f32 v5, v5, v69
	ds_write_b16 v4, v5 offset:2720
	ds_write_b16_d16_hi v4, v5 offset:2992
	v_mul_f32_e32 v5, v64, v48
	global_load_dwordx2 v[6:7], v66, s[14:15] offset:48
	global_load_dwordx2 v[64:65], v66, s[16:17] offset:48
	s_waitcnt vmcnt(0)
	v_fma_f32 v5, v6, v5, v64
	v_mul_f32_e32 v6, v63, v48
	v_fmac_f32_e32 v65, v7, v6
	v_cvt_pk_bf16_f32 v5, v5, v65
	ds_write_b16 v4, v5 offset:3264
	ds_write_b16_d16_hi v4, v5 offset:3536
	v_mul_f32_e32 v5, v62, v48
	global_load_dwordx2 v[6:7], v66, s[14:15] offset:56
	global_load_dwordx2 v[62:63], v66, s[16:17] offset:56
	s_waitcnt vmcnt(0)
	v_fma_f32 v5, v6, v5, v62
	v_mul_f32_e32 v6, v60, v48
	v_fmac_f32_e32 v63, v7, v6
	v_cvt_pk_bf16_f32 v5, v5, v63
	ds_write_b16 v4, v5 offset:3808
	ds_write_b16_d16_hi v4, v5 offset:4080
	v_mul_f32_e32 v5, v61, v48
	global_load_dwordx2 v[6:7], v66, s[14:15] offset:64
	global_load_dwordx2 v[60:61], v66, s[16:17] offset:64
	s_waitcnt vmcnt(0)
	v_fma_f32 v5, v6, v5, v60
	v_mul_f32_e32 v6, v59, v48
	v_fmac_f32_e32 v61, v7, v6
	v_cvt_pk_bf16_f32 v5, v5, v61
	ds_write_b16 v4, v5 offset:4352
	ds_write_b16_d16_hi v4, v5 offset:4624
	v_mul_f32_e32 v5, v58, v48
	global_load_dwordx2 v[6:7], v66, s[14:15] offset:72
	global_load_dwordx2 v[58:59], v66, s[16:17] offset:72
	s_waitcnt vmcnt(0)
	v_fma_f32 v5, v6, v5, v58
	v_mul_f32_e32 v6, v57, v48
	v_fmac_f32_e32 v59, v7, v6
	v_cvt_pk_bf16_f32 v5, v5, v59
	ds_write_b16 v4, v5 offset:4896
	ds_write_b16_d16_hi v4, v5 offset:5168
	v_mul_f32_e32 v5, v56, v48
	global_load_dwordx2 v[6:7], v66, s[14:15] offset:80
	global_load_dwordx2 v[56:57], v66, s[16:17] offset:80
	s_waitcnt vmcnt(0)
	v_fma_f32 v5, v6, v5, v56
	v_mul_f32_e32 v6, v55, v48
	v_fmac_f32_e32 v57, v7, v6
	v_cvt_pk_bf16_f32 v5, v5, v57
	ds_write_b16 v4, v5 offset:5440
	ds_write_b16_d16_hi v4, v5 offset:5712
	v_mul_f32_e32 v5, v54, v48
	global_load_dwordx2 v[6:7], v66, s[14:15] offset:88
	global_load_dwordx2 v[54:55], v66, s[16:17] offset:88
	s_waitcnt vmcnt(0)
	v_fma_f32 v5, v6, v5, v54
	v_mul_f32_e32 v6, v52, v48
	v_fmac_f32_e32 v55, v7, v6
	v_cvt_pk_bf16_f32 v5, v5, v55
	ds_write_b16 v4, v5 offset:5984
	ds_write_b16_d16_hi v4, v5 offset:6256
	v_mul_f32_e32 v5, v53, v48
	global_load_dwordx2 v[6:7], v66, s[14:15] offset:96
	global_load_dwordx2 v[52:53], v66, s[16:17] offset:96
	s_waitcnt vmcnt(0)
	v_fma_f32 v5, v6, v5, v52
	v_mul_f32_e32 v6, v51, v48
	v_fmac_f32_e32 v53, v7, v6
	v_cvt_pk_bf16_f32 v5, v5, v53
	ds_write_b16 v4, v5 offset:6528
	ds_write_b16_d16_hi v4, v5 offset:6800
	v_mul_f32_e32 v5, v50, v48
	global_load_dwordx2 v[6:7], v66, s[14:15] offset:104
	global_load_dwordx2 v[50:51], v66, s[16:17] offset:104
	s_waitcnt vmcnt(0)
	v_fma_f32 v5, v6, v5, v50
	v_mul_f32_e32 v6, v49, v48
	v_fmac_f32_e32 v51, v7, v6
	v_cvt_pk_bf16_f32 v5, v5, v51
	ds_write_b16 v4, v5 offset:7072
	ds_write_b16_d16_hi v4, v5 offset:7344
	global_load_dwordx2 v[6:7], v66, s[14:15] offset:112
	global_load_dwordx2 v[50:51], v66, s[16:17] offset:112
	v_mul_f32_e32 v5, v47, v48
	s_waitcnt vmcnt(0)
	v_fma_f32 v5, v6, v5, v50
	v_mul_f32_e32 v6, v46, v48
	v_fmac_f32_e32 v51, v7, v6
	v_cvt_pk_bf16_f32 v5, v5, v51
	ds_write_b16 v4, v5 offset:7616
	ds_write_b16_d16_hi v4, v5 offset:7888
	global_load_dwordx2 v[6:7], v66, s[14:15] offset:120
	global_load_dwordx2 v[46:47], v66, s[16:17] offset:120
	v_mul_f32_e32 v5, v45, v48
	s_waitcnt vmcnt(0)
	v_fma_f32 v5, v6, v5, v46
	v_mul_f32_e32 v6, v43, v48
	v_fmac_f32_e32 v47, v7, v6
	v_cvt_pk_bf16_f32 v5, v5, v47
	ds_write_b16 v4, v5 offset:8160
	ds_write_b16_d16_hi v4, v5 offset:8432
	v_mul_f32_e32 v5, v44, v48
	global_load_dwordx2 v[6:7], v66, s[14:15] offset:128
	global_load_dwordx2 v[44:45], v66, s[16:17] offset:128
	s_waitcnt vmcnt(0)
; #define LAS __attribute__((address_space(3)))
; __device__ __forceinline__ unsigned cvtpk(float lo, float hi) { unsigned r; asm volatile("v_cvt_pk_bf16_f32 %0, %1, %2" : "=v"(r) : "v"(lo), "v"(hi)); return r; }
; __device__ __forceinline__ void sgu_unit(LAS unsigned char* lds, const bf16_t* proj, bf16_t* Y, const bf16_t* wsb  , const float* lnw, const float* lnb, const float* bs  , int row0, unsigned long long* gss, const int wave_s) {
;     ...
;             const int c = 64 * q + i;
;             const float a = v[i] * rstd * lnw[c] + lnb[c], b = v[i + 1] * rstd * lnw[c + 1] + lnb[c + 1];
;             const unsigned w = cvtpk(a, b);
;             vt[c * SSTR + s] = (unsigned short)(w & 0xffffu); vt[(c + 1) * SSTR + s] = (unsigned short)(w >> 16);
;         }
;     ...
;     __syncthreads();
;     const int g = wid >> 1, dh = wid & 1;
;     const LAS unsigned char* ab = lds + ((64 * g + 32 * dh + r32) * SSTR + 8 * hi) * 2;
;     const bf16_t* wg = wsb + (size_t)g * 128 * 128;
; #pragma unroll 1
;     for (int tt = 0; tt < 4; ++tt) {
;         f32x16 acc;
; #pragma unroll
;         for (int r = 0; r < 16; ++r) acc[r] = 0.f;
;         const bf16_t* wrow = wg + (size_t)(32 * tt + r32) * 128 + 8 * hi;
	v_fma_f32 v5, v6, v5, v44
	v_mul_f32_e32 v6, v42, v48
	v_fmac_f32_e32 v45, v7, v6
	v_cvt_pk_bf16_f32 v5, v5, v45
	ds_write_b16 v4, v5 offset:8704
	ds_write_b16_d16_hi v4, v5 offset:8976
	global_load_dwordx2 v[6:7], v66, s[14:15] offset:136
	global_load_dwordx2 v[42:43], v66, s[16:17] offset:136
	v_mul_f32_e32 v5, v41, v48
	s_waitcnt vmcnt(0)
	v_fma_f32 v5, v6, v5, v42
	v_mul_f32_e32 v6, v40, v48
	v_fmac_f32_e32 v43, v7, v6
	v_cvt_pk_bf16_f32 v5, v5, v43
	ds_write_b16 v4, v5 offset:9248
	ds_write_b16_d16_hi v4, v5 offset:9520
	global_load_dwordx2 v[6:7], v66, s[14:15] offset:144
	global_load_dwordx2 v[40:41], v66, s[16:17] offset:144
	v_mul_f32_e32 v5, v39, v48
	s_waitcnt vmcnt(0)
	v_fma_f32 v5, v6, v5, v40
	v_mul_f32_e32 v6, v38, v48
	v_fmac_f32_e32 v41, v7, v6
	v_cvt_pk_bf16_f32 v5, v5, v41
	ds_write_b16 v4, v5 offset:9792
	ds_write_b16_d16_hi v4, v5 offset:10064
	global_load_dwordx2 v[6:7], v66, s[14:15] offset:152
	global_load_dwordx2 v[38:39], v66, s[16:17] offset:152
	v_mul_f32_e32 v5, v37, v48
	s_waitcnt vmcnt(0)
	v_fma_f32 v5, v5, v6, v38
	v_mul_f32_e32 v6, v35, v48
	v_fmac_f32_e32 v39, v6, v7
	v_cvt_pk_bf16_f32 v5, v5, v39
	ds_write_b16 v4, v5 offset:10336
	ds_write_b16_d16_hi v4, v5 offset:10608
	v_mul_f32_e32 v5, v36, v48
	global_load_dwordx2 v[6:7], v66, s[14:15] offset:160
	global_load_dwordx2 v[36:37], v66, s[16:17] offset:160
	s_waitcnt vmcnt(0)
	v_fma_f32 v5, v5, v6, v36
	v_mul_f32_e32 v6, v34, v48
	v_fmac_f32_e32 v37, v6, v7
	v_cvt_pk_bf16_f32 v5, v5, v37
	ds_write_b16 v4, v5 offset:10880
	ds_write_b16_d16_hi v4, v5 offset:11152
	global_load_dwordx2 v[6:7], v66, s[14:15] offset:168
	global_load_dwordx2 v[34:35], v66, s[16:17] offset:168
	v_mul_f32_e32 v5, v32, v48
	s_waitcnt vmcnt(0)
	v_fma_f32 v5, v5, v6, v34
	v_mul_f32_e32 v6, v30, v48
	v_fmac_f32_e32 v35, v6, v7
	v_cvt_pk_bf16_f32 v5, v5, v35
	ds_write_b16 v4, v5 offset:11424
	ds_write_b16_d16_hi v4, v5 offset:11696
	global_load_dwordx2 v[6:7], v66, s[14:15] offset:176
	global_load_dwordx2 v[34:35], v66, s[16:17] offset:176
	v_mul_f32_e32 v5, v28, v48
	s_waitcnt vmcnt(0)
	v_fma_f32 v5, v5, v6, v34
	v_mul_f32_e32 v6, v26, v48
	v_fmac_f32_e32 v35, v6, v7
	v_cvt_pk_bf16_f32 v5, v5, v35
	ds_write_b16 v4, v5 offset:11968
	ds_write_b16_d16_hi v4, v5 offset:12240
	global_load_dwordx2 v[6:7], v66, s[14:15] offset:184
	global_load_dwordx2 v[34:35], v66, s[16:17] offset:184
	v_mul_f32_e32 v5, v24, v48
	s_waitcnt vmcnt(0)
	v_fma_f32 v5, v5, v6, v34
	v_mul_f32_e32 v6, v20, v48
	v_fmac_f32_e32 v35, v6, v7
	v_cvt_pk_bf16_f32 v5, v5, v35
	ds_write_b16 v4, v5 offset:12512
	ds_write_b16_d16_hi v4, v5 offset:12784
	global_load_dwordx2 v[6:7], v66, s[14:15] offset:192
	global_load_dwordx2 v[34:35], v66, s[16:17] offset:192
	v_mul_f32_e32 v5, v23, v48
	s_waitcnt vmcnt(0)
	v_fma_f32 v5, v5, v6, v34
	v_mul_f32_e32 v6, v18, v48
	v_fmac_f32_e32 v35, v6, v7
	v_cvt_pk_bf16_f32 v5, v5, v35
	ds_write_b16 v4, v5 offset:13056
	ds_write_b16_d16_hi v4, v5 offset:13328
	global_load_dwordx2 v[6:7], v66, s[14:15] offset:200
	global_load_dwordx2 v[34:35], v66, s[16:17] offset:200
	v_mul_f32_e32 v5, v15, v48
	s_waitcnt vmcnt(0)
	v_fma_f32 v5, v5, v6, v34
	v_mul_f32_e32 v6, v14, v48
	v_fmac_f32_e32 v35, v6, v7
	v_cvt_pk_bf16_f32 v5, v5, v35
	ds_write_b16 v4, v5 offset:13600
	ds_write_b16_d16_hi v4, v5 offset:13872
	global_load_dwordx2 v[6:7], v66, s[14:15] offset:208
	global_load_dwordx2 v[14:15], v66, s[16:17] offset:208
	v_mul_f32_e32 v5, v13, v48
	s_waitcnt vmcnt(0)
	v_fma_f32 v5, v5, v6, v14
	v_mul_f32_e32 v6, v12, v48
	v_fmac_f32_e32 v15, v6, v7
	v_cvt_pk_bf16_f32 v5, v5, v15
	ds_write_b16 v4, v5 offset:14144
	ds_write_b16_d16_hi v4, v5 offset:14416
	global_load_dwordx2 v[6:7], v66, s[14:15] offset:216
	global_load_dwordx2 v[12:13], v66, s[16:17] offset:216
	v_mul_f32_e32 v5, v11, v48
	v_or_b32_e32 v14, s3, v8
	s_waitcnt vmcnt(0)
	v_fma_f32 v5, v5, v6, v12
	v_fmac_f32_e32 v13, v0, v7
	v_cvt_pk_bf16_f32 v0, v5, v13
	ds_write_b16 v4, v0 offset:14688
	ds_write_b16_d16_hi v4, v0 offset:14960
	global_load_dwordx2 v[6:7], v66, s[14:15] offset:224
	global_load_dwordx2 v[12:13], v66, s[16:17] offset:224
	v_mul_f32_e32 v0, v33, v48
	v_mul_f32_e32 v5, v31, v48
	s_waitcnt vmcnt(0)
	v_fma_f32 v0, v0, v6, v12
	v_fmac_f32_e32 v13, v5, v7
	v_cvt_pk_bf16_f32 v0, v0, v13
	ds_write_b16 v4, v0 offset:15232
	ds_write_b16_d16_hi v4, v0 offset:15504
	global_load_dwordx2 v[6:7], v66, s[14:15] offset:232
	global_load_dwordx2 v[12:13], v66, s[16:17] offset:232
	v_mul_f32_e32 v0, v29, v48
	v_mul_f32_e32 v5, v27, v48
	s_waitcnt vmcnt(0)
	v_fma_f32 v0, v0, v6, v12
	v_fmac_f32_e32 v13, v5, v7
	v_cvt_pk_bf16_f32 v0, v0, v13
	ds_write_b16 v4, v0 offset:15776
	ds_write_b16_d16_hi v4, v0 offset:16048
	global_load_dwordx2 v[6:7], v66, s[14:15] offset:240
	global_load_dwordx2 v[12:13], v66, s[16:17] offset:240
	v_mul_f32_e32 v0, v25, v48
	v_mul_f32_e32 v5, v22, v48
	s_waitcnt vmcnt(0)
	v_fma_f32 v0, v0, v6, v12
	v_fmac_f32_e32 v13, v5, v7
	v_cvt_pk_bf16_f32 v0, v0, v13
	ds_write_b16 v4, v0 offset:16320
	ds_write_b16_d16_hi v4, v0 offset:16592
	global_load_dwordx2 v[6:7], v66, s[14:15] offset:248
	global_load_dwordx2 v[12:13], v66, s[16:17] offset:248
	v_mul_f32_e32 v0, v19, v48
	v_mul_f32_e32 v5, v17, v48
	s_waitcnt vmcnt(0)
	v_fma_f32 v0, v0, v6, v12
	v_fmac_f32_e32 v13, v5, v7
	v_cvt_pk_bf16_f32 v0, v0, v13
	ds_write_b16 v4, v0 offset:16864
	ds_write_b16_d16_hi v4, v0 offset:17136
	v_or_b32_e32 v0, s5, v8
	v_mul_lo_u32 v0, v0, s7
	s_ashr_i32 s7, s6, 31
	s_lshl_b64 s[20:21], s[6:7], 15
	v_lshlrev_b32_e32 v4, 3, v10
	s_add_u32 s12, s12, s24
	v_add_lshl_u32 v11, v0, v4, 1
	s_addc_u32 s13, s13, s25
	v_or_b32_e32 v4, s2, v8
	v_readlane_b32 s2, v255, 10
	v_readlane_b32 s3, v255, 11
	s_add_u32 s2, s10, s2
	v_lshlrev_b32_e32 v6, 8, v8
	v_lshlrev_b32_e32 v7, 4, v10
	s_addc_u32 s3, s11, s3
	v_or3_b32 v6, s20, v6, v7
	v_mov_b32_e32 v7, s21
	v_lshl_add_u64 v[52:53], s[2:3], 0, v[6:7]
	v_lshl_or_b32 v6, v10, 2, s5
	v_mov_b32_e32 v5, s22
	v_ashrrev_i32_e32 v7, 31, v6
	v_lshlrev_b64 v[54:55], 1, v[6:7]
	v_lshlrev_b64 v[6:7], 11, v[4:5]
	v_mad_u64_u32 v[58:59], s[2:3], v4, s85, v[2:3]
	v_mov_b32_e32 v2, 0x1080
	v_xor_b32_e32 v0, 0x80, v21
	v_cmp_gt_u32_e64 s[6:7], 32, v9
	v_lshl_add_u64 v[50:51], v[4:5], 3, s[12:13]
	v_lshl_add_u64 v[56:57], s[8:9], 0, v[6:7]
	v_mad_i32_i24 v59, s22, v2, v59
	s_mov_b32 s5, 0
	s_mov_b64 s[20:21], 0
	v_add_u32_e32 v17, 0, v11
	s_waitcnt lgkmcnt(0)
	s_barrier
	s_branch .LBB0_837

; __device__ __forceinline__ unsigned cvtpk(float lo, float hi) { unsigned r; asm volatile("v_cvt_pk_bf16_f32 %0, %1, %2" : "=v"(r) : "v"(lo), "v"(hi)); return r; }
; __device__ __forceinline__ float bflo(unsigned w) { return __uint_as_float(w << 16); }
; __device__ __forceinline__ float bfhi(unsigned w) { return __uint_as_float(w & 0xffff0000u); }
; __device__ __forceinline__ float shfl_x(float v, int m, int lane) { return __builtin_bit_cast(float, __builtin_amdgcn_ds_bpermute((lane ^ m) << 2, __builtin_bit_cast(int, v))); }
; __device__ __forceinline__ void sgu_unit(LAS unsigned char* lds, const bf16_t* proj, bf16_t* Y, const bf16_t* wsb  , const float* lnw, const float* lnb, const float* bs  , int row0, unsigned long long* gss, const int wave_s) {
;     ...
;         const int t = 32 * tt + r32; const size_t row = (size_t)row0 + t;
;         const float bias = bs[g * 128 + t];
;         const int cb = 64 * g + 32 * dh + 4 * hi; float qs = 0.f;
;         u32x2 uwv[4];
; #pragma unroll
;         for (int rg = 0; rg < 4; ++rg) uwv[rg] = *(const u32x2*)(proj + row * PJP + PC_CU + cb + 8 * rg);
; #pragma unroll
;         for (int rg = 0; rg < 4; ++rg) {
;             const u32x2 uw = uwv[rg];
;             const float y0 = bflo(uw.x) * (acc[4 * rg] + bias), y1 = bfhi(uw.x) * (acc[4 * rg + 1] + bias), y2 = bflo(uw.y) * (acc[4 * rg + 2] + bias), y3 = bfhi(uw.y) * (acc[4 * rg + 3] + bias);
;             u32x2 o; o.x = cvtpk(y0, y1); o.y = cvtpk(y2, y3);
;             *(u32x2*)(Y + row * DM + 768 + cb + 8 * rg) = o;
;             qs += (y0 * y0 + y1 * y1) + (y2 * y2 + y3 * y3);
;         }
;         qs += shfl_x(qs, 32, lane);
;         if (hi == 0) __hip_atomic_fetch_add(gss + row, (unsigned long long)(qs * 16777216.0f), __ATOMIC_RELAXED, __HIP_MEMORY_SCOPE_AGENT);
.LBB0_861:
	v_ashrrev_i32_e32 v15, 31, v14
	v_lshl_add_u64 v[46:47], v[14:15], 2, s[18:19]
	global_load_dword v15, v[46:47], off
	v_lshl_add_u64 v[46:47], v[58:59], 0, v[54:55]
	v_add_co_u32_e32 v46, vcc, 0x10000000, v46
	v_lshl_add_u64 v[64:65], v[56:57], 0, v[54:55]
	s_nop 0
	v_addc_co_u32_e32 v47, vcc, 0, v47, vcc
	global_load_dwordx2 v[48:49], v[46:47], off offset:3072
	global_load_dwordx2 v[60:61], v[46:47], off offset:3088
	global_load_dwordx2 v[62:63], v[46:47], off offset:3104
	s_nop 0
	global_load_dwordx2 v[46:47], v[46:47], off offset:3120
	s_mov_b32 s2, 0x2c800000
	s_waitcnt vmcnt(0)
	v_add_f32_e32 v18, v15, v18
	v_add_f32_e32 v19, v15, v19
	s_waitcnt lgkmcnt(0)
	v_lshlrev_b32_e32 v66, 16, v48
	v_mul_f32_e32 v66, v18, v66
	v_and_b32_e32 v18, 0xffff0000, v48
	v_mul_f32_e32 v48, v19, v18
	v_lshlrev_b32_e32 v18, 16, v49
	v_add_f32_e32 v19, v15, v20
	v_mul_f32_e32 v67, v19, v18
	v_and_b32_e32 v18, 0xffff0000, v49
	v_add_f32_e32 v19, v15, v21
	v_mul_f32_e32 v49, v19, v18
	v_add_co_u32_e32 v18, vcc, s2, v64
	v_cvt_pk_bf16_f32 v20, v66, v48
	v_cvt_pk_bf16_f32 v21, v67, v49
	s_nop 1
	v_addc_co_u32_e32 v19, vcc, 0, v65, vcc
	global_store_dwordx2 v[18:19], v[20:21], off offset:1536
	v_mul_f32_e32 v20, v48, v48
	v_mul_f32_e32 v21, v49, v49
	v_fmac_f32_e32 v20, v66, v66
	v_fmac_f32_e32 v21, v67, v67
	v_add_f32_e32 v48, v20, v21
	v_lshlrev_b32_e32 v20, 16, v60
	v_add_f32_e32 v21, v15, v22
	v_mul_f32_e32 v22, v21, v20
	v_and_b32_e32 v20, 0xffff0000, v60
	v_add_f32_e32 v21, v15, v23
	v_mul_f32_e32 v23, v21, v20
	v_lshlrev_b32_e32 v20, 16, v61
	v_add_f32_e32 v21, v15, v24
	v_mul_f32_e32 v24, v21, v20
	v_and_b32_e32 v20, 0xffff0000, v61
	v_add_f32_e32 v21, v15, v25
	v_mul_f32_e32 v25, v21, v20
	v_cvt_pk_bf16_f32 v20, v22, v23
	v_cvt_pk_bf16_f32 v21, v24, v25
	global_store_dwordx2 v[18:19], v[20:21], off offset:1552
	v_mul_f32_e32 v20, v23, v23
	v_mul_f32_e32 v21, v25, v25
	v_fmac_f32_e32 v20, v22, v22
	v_fmac_f32_e32 v21, v24, v24
	v_add_f32_e32 v20, v20, v21
	v_add_f32_e32 v22, v48, v20
	v_lshlrev_b32_e32 v20, 16, v62
	v_add_f32_e32 v21, v15, v26
	v_mul_f32_e32 v23, v21, v20
	v_and_b32_e32 v20, 0xffff0000, v62
	v_add_f32_e32 v21, v15, v27
	v_mul_f32_e32 v24, v21, v20
	v_lshlrev_b32_e32 v20, 16, v63
	v_add_f32_e32 v21, v15, v28
	v_mul_f32_e32 v25, v21, v20
	v_and_b32_e32 v20, 0xffff0000, v63
	v_add_f32_e32 v21, v15, v29
	v_mul_f32_e32 v26, v21, v20
	v_cvt_pk_bf16_f32 v20, v23, v24
	v_cvt_pk_bf16_f32 v21, v25, v26
	global_store_dwordx2 v[18:19], v[20:21], off offset:1568
	v_mul_f32_e32 v20, v24, v24
	v_mul_f32_e32 v21, v26, v26
	v_fmac_f32_e32 v20, v23, v23
	v_fmac_f32_e32 v21, v25, v25
	v_add_f32_e32 v20, v20, v21
	v_add_f32_e32 v22, v22, v20
	v_lshlrev_b32_e32 v20, 16, v46
	v_add_f32_e32 v21, v15, v30
	v_mul_f32_e32 v23, v21, v20
	v_and_b32_e32 v20, 0xffff0000, v46
	v_add_f32_e32 v21, v15, v31
	v_mul_f32_e32 v24, v21, v20
	v_lshlrev_b32_e32 v20, 16, v47
	v_add_f32_e32 v21, v15, v32
	v_mul_f32_e32 v25, v21, v20
	v_and_b32_e32 v20, 0xffff0000, v47
	v_add_f32_e32 v15, v15, v33
	v_mul_f32_e32 v15, v15, v20
	v_cvt_pk_bf16_f32 v20, v23, v24
	v_cvt_pk_bf16_f32 v21, v25, v15
	global_store_dwordx2 v[18:19], v[20:21], off offset:1584
	v_mul_f32_e32 v18, v24, v24
	v_mul_f32_e32 v15, v15, v15
	v_fmac_f32_e32 v18, v23, v23
	v_fmac_f32_e32 v15, v25, v25
	v_add_f32_e32 v15, v18, v15
	v_add_f32_e32 v15, v22, v15
	ds_bpermute_b32 v18, v0, v15
	s_and_saveexec_b64 s[2:3], s[6:7]
	s_cbranch_execz .LBB0_836
	s_waitcnt lgkmcnt(0)
	v_add_f32_e32 v15, v15, v18
	v_mul_f32_e32 v15, 0x4b800000, v15
	v_trunc_f32_e32 v15, v15
	v_mul_f32_e32 v18, 0x2f800000, v15
	v_floor_f32_e32 v19, v18
	v_fmac_f32_e32 v15, 0xcf800000, v19
	v_cvt_u32_f32_e32 v18, v15
	v_cvt_u32_f32_e32 v19, v19
	global_atomic_add_x2 v[50:51], v[18:19], off
	s_branch .LBB0_836

; __device__ __forceinline__ unsigned cvtpk(float lo, float hi) { unsigned r; asm volatile("v_cvt_pk_bf16_f32 %0, %1, %2" : "=v"(r) : "v"(lo), "v"(hi)); return r; }
; __device__ __forceinline__ float shfl_x(float v, int m, int lane) { return __builtin_bit_cast(float, __builtin_amdgcn_ds_bpermute((lane ^ m) << 2, __builtin_bit_cast(int, v))); }
; template <int NDS, int MODE> ...
;     ...
;     const float lt = l_run + shfl_x(l_run, 32, lane);
;     const float inv = 1.0f / lt;
;     bf16_t* orow = O + (size_t)(qw0 + r32) * op + 4 * hi;
; #pragma unroll
;     for (int rg = 0; rg < 4; ++rg) {
;         u32x2 a, b;
;         a.x = cvtpk(o0[4 * rg] * inv, o0[4 * rg + 1] * inv); a.y = cvtpk(o0[4 * rg + 2] * inv, o0[4 * rg + 3] * inv);
;         b.x = cvtpk(o1[4 * rg] * inv, o1[4 * rg + 1] * inv); b.y = cvtpk(o1[4 * rg + 2] * inv, o1[4 * rg + 3] * inv);
;         *(u32x2*)(orow + 8 * rg) = a; *(u32x2*)(orow + 32 + 8 * rg) = b;
;     }
;     { float q = 0.f;
; #pragma unroll
;       for (int r = 0; r < 16; ++r) { const float a = o0[r] * inv, b = o1[r] * inv; q += a * a + b * b; }
;       q += shfl_x(q, 32, lane);
;       if (hi == 0) __hip_atomic_fetch_add(gss + qw0 + r32, (unsigned long long)(q * 16777216.0f), __ATOMIC_RELAXED, __HIP_MEMORY_SCOPE_AGENT); }
.LBB0_959:
	ds_bpermute_b32 v0, v194, v14
	s_lshl_b64 s[12:13], s[34:35], 12
	s_lshl_b64 s[2:3], s[34:35], 23
	s_add_u32 s4, s28, s2
	s_addc_u32 s6, s29, s3
	s_lshl_b32 s2, s31, 6
	s_ashr_i32 s3, s2, 31
	s_lshl_b64 s[2:3], s[2:3], 1
	s_waitcnt lgkmcnt(0)
	v_add_f32_e32 v0, v14, v0
	s_add_u32 s2, s4, s2
	v_div_scale_f32 v2, s[4:5], v0, v0, 1.0
	v_rcp_f32_e32 v3, v2
	s_addc_u32 s3, s6, s3
	s_add_u32 s28, s2, 0x2c800300
	s_addc_u32 s29, s3, 0
	v_fma_f32 v4, -v2, v3, 1.0
	v_fmac_f32_e32 v3, v4, v3
	v_div_scale_f32 v4, vcc, 1.0, v0, 1.0
	v_mul_f32_e32 v5, v4, v3
	v_fma_f32 v6, -v2, v5, v4
	v_fmac_f32_e32 v5, v6, v3
	v_fma_f32 v2, -v2, v5, v4
	v_div_fmas_f32 v2, v2, v3, v5
	v_div_fixup_f32 v9, v2, v0, 1.0
	v_lshlrev_b64 v[2:3], 11, v[168:169]
	v_lshl_add_u64 v[2:3], s[28:29], 0, v[2:3]
	v_lshlrev_b32_e32 v0, 1, v197
	v_mul_f32_e32 v13, v32, v9
	v_lshl_add_u64 v[4:5], v[2:3], 0, v[0:1]
	v_mul_f32_e32 v0, v48, v9
	v_mul_f32_e32 v10, v49, v9
	v_cvt_pk_bf16_f32 v2, v0, v10
	v_mul_f32_e32 v11, v50, v9
	v_mul_f32_e32 v12, v51, v9
	v_cvt_pk_bf16_f32 v3, v11, v12
	v_mul_f32_e32 v14, v33, v9
	v_cvt_pk_bf16_f32 v6, v13, v14
	v_mul_f32_e32 v13, v13, v13
	v_mul_f32_e32 v15, v34, v9
	v_fmac_f32_e32 v13, v0, v0
	v_mul_f32_e32 v0, v14, v14
	v_fmac_f32_e32 v0, v10, v10
	v_mul_f32_e32 v10, v15, v15
	v_mul_f32_e32 v17, v35, v9
	v_add_f32_e32 v0, v13, v0
	v_fmac_f32_e32 v10, v11, v11
	v_add_f32_e32 v0, v10, v0
	v_mul_f32_e32 v10, v17, v17
	v_mul_f32_e32 v22, v36, v9
	v_fmac_f32_e32 v10, v12, v12
	v_mul_f32_e32 v18, v52, v9
	v_add_f32_e32 v0, v10, v0
	v_mul_f32_e32 v10, v22, v22
	v_mul_f32_e32 v23, v37, v9
	v_fmac_f32_e32 v10, v18, v18
	v_mul_f32_e32 v19, v53, v9
	v_add_f32_e32 v0, v10, v0
	v_mul_f32_e32 v10, v23, v23
	v_mul_f32_e32 v24, v38, v9
	v_fmac_f32_e32 v10, v19, v19
	v_mul_f32_e32 v20, v54, v9
	v_add_f32_e32 v0, v10, v0
	v_mul_f32_e32 v10, v24, v24
	v_mul_f32_e32 v25, v39, v9
	v_fmac_f32_e32 v10, v20, v20
	v_mul_f32_e32 v21, v55, v9
	v_add_f32_e32 v0, v10, v0
	v_mul_f32_e32 v10, v25, v25
	v_mul_f32_e32 v30, v40, v9
	v_fmac_f32_e32 v10, v21, v21
	v_mul_f32_e32 v26, v56, v9
	v_add_f32_e32 v0, v10, v0
	v_mul_f32_e32 v10, v30, v30
	v_mul_f32_e32 v31, v41, v9
	v_fmac_f32_e32 v10, v26, v26
	v_mul_f32_e32 v27, v57, v9
	v_add_f32_e32 v0, v10, v0
	v_mul_f32_e32 v10, v31, v31
	v_mul_f32_e32 v32, v42, v9
	v_fmac_f32_e32 v10, v27, v27
	v_mul_f32_e32 v28, v58, v9
	v_add_f32_e32 v0, v10, v0
	v_mul_f32_e32 v10, v32, v32
	v_mul_f32_e32 v33, v43, v9
	v_fmac_f32_e32 v10, v28, v28
	v_cvt_pk_bf16_f32 v7, v15, v17
	global_store_dwordx2 v[4:5], v[2:3], off
	global_store_dwordx2 v[4:5], v[6:7], off offset:64
	v_cvt_pk_bf16_f32 v2, v18, v19
	v_cvt_pk_bf16_f32 v3, v20, v21
	v_mul_f32_e32 v29, v59, v9
	v_add_f32_e32 v0, v10, v0
	v_mul_f32_e32 v10, v33, v33
	v_cvt_pk_bf16_f32 v6, v22, v23
	v_cvt_pk_bf16_f32 v7, v24, v25
	global_store_dwordx2 v[4:5], v[2:3], off offset:16
	global_store_dwordx2 v[4:5], v[6:7], off offset:80
	v_cvt_pk_bf16_f32 v2, v26, v27
	v_cvt_pk_bf16_f32 v3, v28, v29
	v_mul_f32_e32 v36, v44, v9
	v_fmac_f32_e32 v10, v29, v29
	v_cvt_pk_bf16_f32 v6, v30, v31
	v_cvt_pk_bf16_f32 v7, v32, v33
	global_store_dwordx2 v[4:5], v[2:3], off offset:32
	global_store_dwordx2 v[4:5], v[6:7], off offset:96
	v_mul_f32_e32 v2, v60, v9
	v_mul_f32_e32 v37, v45, v9
	v_add_f32_e32 v0, v10, v0
	v_mul_f32_e32 v10, v36, v36
	v_mul_f32_e32 v3, v61, v9
	v_cvt_pk_bf16_f32 v6, v2, v3
	v_fmac_f32_e32 v10, v2, v2
	v_mul_f32_e32 v2, v37, v37
	v_mul_f32_e32 v38, v46, v9
	v_add_f32_e32 v0, v10, v0
	v_fmac_f32_e32 v2, v3, v3
	v_mul_f32_e32 v34, v62, v9
	v_add_f32_e32 v0, v2, v0
	v_mul_f32_e32 v2, v38, v38
	v_mul_f32_e32 v35, v63, v9
	v_mul_f32_e32 v9, v47, v9
	v_fmac_f32_e32 v2, v34, v34
	v_add_f32_e32 v0, v2, v0
	v_mul_f32_e32 v2, v9, v9
	v_fmac_f32_e32 v2, v35, v35
	v_add_f32_e32 v2, v2, v0
	ds_bpermute_b32 v3, v194, v2
	v_cvt_pk_bf16_f32 v7, v34, v35
	v_cmp_gt_u32_e32 vcc, 32, v177
	v_cvt_pk_bf16_f32 v8, v36, v37
	v_cvt_pk_bf16_f32 v9, v38, v9
	global_store_dwordx2 v[4:5], v[6:7], off offset:48
	global_store_dwordx2 v[4:5], v[8:9], off offset:112
	s_and_saveexec_b64 s[2:3], vcc
	s_cbranch_execz .LBB0_961
	s_add_u32 s6, s22, s94
	s_addc_u32 s7, s23, s95
	s_lshl_b64 s[4:5], s[12:13], 3
	s_add_u32 s6, s6, s4
	s_addc_u32 s7, s7, s5
	s_ashr_i32 s31, s30, 31
	s_lshl_b64 s[4:5], s[30:31], 3
	s_add_u32 s4, s6, s4
	s_addc_u32 s5, s7, s5
	v_lshlrev_b32_e32 v0, 3, v176
	v_lshl_add_u64 v[4:5], s[4:5], 0, v[0:1]
	s_waitcnt lgkmcnt(0)
	v_add_f32_e32 v0, v2, v3
	v_mul_f32_e32 v0, 0x4b800000, v0
	v_trunc_f32_e32 v0, v0
	v_mul_f32_e32 v2, 0x2f800000, v0
	v_floor_f32_e32 v3, v2
	v_fmac_f32_e32 v0, 0xcf800000, v3
	v_cvt_u32_f32_e32 v2, v0
	v_cvt_u32_f32_e32 v3, v3
	v_add_co_u32_e32 v4, vcc, 0x3d280000, v4
	s_nop 1
	v_addc_co_u32_e32 v5, vcc, 0, v5, vcc
	global_atomic_add_x2 v[4:5], v[2:3], off

; __device__ __forceinline__ unsigned cvtpk(float lo, float hi) { unsigned r; asm volatile("v_cvt_pk_bf16_f32 %0, %1, %2" : "=v"(r) : "v"(lo), "v"(hi)); return r; }
; __device__ __forceinline__ float shfl_x(float v, int m, int lane) { return __builtin_bit_cast(float, __builtin_amdgcn_ds_bpermute((lane ^ m) << 2, __builtin_bit_cast(int, v))); }
; template <int NDS, int MODE> ...
;     ...
;     const float lt = l_run + shfl_x(l_run, 32, lane);
;     const float inv = 1.0f / lt;
;     bf16_t* orow = O + (size_t)(qw0 + r32) * op + 4 * hi;
; #pragma unroll
;     for (int rg = 0; rg < 4; ++rg) {
;         u32x2 a, b;
;         a.x = cvtpk(o0[4 * rg] * inv, o0[4 * rg + 1] * inv); a.y = cvtpk(o0[4 * rg + 2] * inv, o0[4 * rg + 3] * inv);
;         b.x = cvtpk(o1[4 * rg] * inv, o1[4 * rg + 1] * inv); b.y = cvtpk(o1[4 * rg + 2] * inv, o1[4 * rg + 3] * inv);
;         *(u32x2*)(orow + 8 * rg) = a; *(u32x2*)(orow + 32 + 8 * rg) = b;
;     }
;     { float q = 0.f;
; #pragma unroll
;       for (int r = 0; r < 16; ++r) { const float a = o0[r] * inv, b = o1[r] * inv; q += a * a + b * b; }
;       q += shfl_x(q, 32, lane);
;       if (hi == 0) __hip_atomic_fetch_add(gss + qw0 + r32, (unsigned long long)(q * 16777216.0f), __ATOMIC_RELAXED, __HIP_MEMORY_SCOPE_AGENT); }
.LBB0_1009:
	ds_bpermute_b32 v4, v174, v197
	v_lshlrev_b64 v[2:3], 11, v[14:15]
	v_lshlrev_b32_e32 v0, 1, v177
	v_lshl_add_u64 v[2:3], s[28:29], 0, v[2:3]
	s_waitcnt lgkmcnt(0)
	v_add_f32_e32 v4, v197, v4
	v_div_scale_f32 v5, s[2:3], v4, v4, 1.0
	v_rcp_f32_e32 v6, v5
	v_div_scale_f32 v7, vcc, 1.0, v4, 1.0
	v_fma_f32 v8, -v5, v6, 1.0
	v_fmac_f32_e32 v6, v8, v6
	v_mul_f32_e32 v8, v7, v6
	v_fma_f32 v9, -v5, v8, v7
	v_fmac_f32_e32 v8, v9, v6
	v_fma_f32 v5, -v5, v8, v7
	v_div_fmas_f32 v5, v5, v6, v8
	v_div_fixup_f32 v9, v5, v4, 1.0
	v_mul_f32_e32 v13, v48, v9
	v_lshl_add_u64 v[4:5], v[2:3], 0, v[0:1]
	v_mul_f32_e32 v0, v32, v9
	v_mul_f32_e32 v10, v33, v9
	v_cvt_pk_bf16_f32 v2, v0, v10
	v_mul_f32_e32 v11, v34, v9
	v_mul_f32_e32 v12, v35, v9
	v_cvt_pk_bf16_f32 v3, v11, v12
	v_mul_f32_e32 v14, v49, v9
	v_cvt_pk_bf16_f32 v6, v13, v14
	v_mul_f32_e32 v13, v13, v13
	v_mul_f32_e32 v15, v50, v9
	v_fmac_f32_e32 v13, v0, v0
	v_mul_f32_e32 v0, v14, v14
	v_fmac_f32_e32 v0, v10, v10
	v_mul_f32_e32 v10, v15, v15
	v_mul_f32_e32 v17, v51, v9
	v_add_f32_e32 v0, v13, v0
	v_fmac_f32_e32 v10, v11, v11
	v_add_f32_e32 v0, v10, v0
	v_mul_f32_e32 v10, v17, v17
	v_mul_f32_e32 v22, v52, v9
	v_fmac_f32_e32 v10, v12, v12
	v_mul_f32_e32 v18, v36, v9
	v_add_f32_e32 v0, v10, v0
	v_mul_f32_e32 v10, v22, v22
	v_mul_f32_e32 v23, v53, v9
	v_fmac_f32_e32 v10, v18, v18
	v_mul_f32_e32 v19, v37, v9
	v_add_f32_e32 v0, v10, v0
	v_mul_f32_e32 v10, v23, v23
	v_mul_f32_e32 v24, v54, v9
	v_fmac_f32_e32 v10, v19, v19
	v_mul_f32_e32 v20, v38, v9
	v_add_f32_e32 v0, v10, v0
	v_mul_f32_e32 v10, v24, v24
	v_mul_f32_e32 v25, v55, v9
	v_fmac_f32_e32 v10, v20, v20
	v_mul_f32_e32 v21, v39, v9
	v_add_f32_e32 v0, v10, v0
	v_mul_f32_e32 v10, v25, v25
	v_mul_f32_e32 v30, v56, v9
	v_fmac_f32_e32 v10, v21, v21
	v_mul_f32_e32 v26, v40, v9
	v_add_f32_e32 v0, v10, v0
	v_mul_f32_e32 v10, v30, v30
	v_mul_f32_e32 v31, v57, v9
	v_fmac_f32_e32 v10, v26, v26
	v_mul_f32_e32 v27, v41, v9
	v_add_f32_e32 v0, v10, v0
	v_mul_f32_e32 v10, v31, v31
	v_mul_f32_e32 v32, v58, v9
	v_fmac_f32_e32 v10, v27, v27
	v_mul_f32_e32 v28, v42, v9
	v_add_f32_e32 v0, v10, v0
	v_mul_f32_e32 v10, v32, v32
	v_mul_f32_e32 v33, v59, v9
	v_fmac_f32_e32 v10, v28, v28
	v_cvt_pk_bf16_f32 v7, v15, v17
	global_store_dwordx2 v[4:5], v[2:3], off
	global_store_dwordx2 v[4:5], v[6:7], off offset:64
	v_cvt_pk_bf16_f32 v2, v18, v19
	v_cvt_pk_bf16_f32 v3, v20, v21
	v_mul_f32_e32 v29, v43, v9
	v_add_f32_e32 v0, v10, v0
	v_mul_f32_e32 v10, v33, v33
	v_cvt_pk_bf16_f32 v6, v22, v23
	v_cvt_pk_bf16_f32 v7, v24, v25
	global_store_dwordx2 v[4:5], v[2:3], off offset:16
	global_store_dwordx2 v[4:5], v[6:7], off offset:80
	v_cvt_pk_bf16_f32 v2, v26, v27
	v_cvt_pk_bf16_f32 v3, v28, v29
	v_mul_f32_e32 v36, v60, v9
	v_fmac_f32_e32 v10, v29, v29
	v_cvt_pk_bf16_f32 v6, v30, v31
	v_cvt_pk_bf16_f32 v7, v32, v33
	global_store_dwordx2 v[4:5], v[2:3], off offset:32
	global_store_dwordx2 v[4:5], v[6:7], off offset:96
	v_mul_f32_e32 v2, v44, v9
	v_mul_f32_e32 v37, v61, v9
	v_add_f32_e32 v0, v10, v0
	v_mul_f32_e32 v10, v36, v36
	v_mul_f32_e32 v3, v45, v9
	v_cvt_pk_bf16_f32 v6, v2, v3
	v_fmac_f32_e32 v10, v2, v2
	v_mul_f32_e32 v2, v37, v37
	v_mul_f32_e32 v38, v62, v9
	v_add_f32_e32 v0, v10, v0
	v_fmac_f32_e32 v2, v3, v3
	v_mul_f32_e32 v34, v46, v9
	v_add_f32_e32 v0, v2, v0
	v_mul_f32_e32 v2, v38, v38
	v_mul_f32_e32 v35, v47, v9
	v_mul_f32_e32 v9, v63, v9
	v_fmac_f32_e32 v2, v34, v34
	v_add_f32_e32 v0, v2, v0
	v_mul_f32_e32 v2, v9, v9
	v_fmac_f32_e32 v2, v35, v35
	v_add_f32_e32 v2, v2, v0
	ds_bpermute_b32 v3, v174, v2
	v_cvt_pk_bf16_f32 v7, v34, v35
	v_cmp_gt_u32_e32 vcc, 32, v173
	v_cvt_pk_bf16_f32 v8, v36, v37
	v_cvt_pk_bf16_f32 v9, v38, v9
	global_store_dwordx2 v[4:5], v[6:7], off offset:48
	global_store_dwordx2 v[4:5], v[8:9], off offset:112
	s_and_saveexec_b64 s[2:3], vcc
	s_cbranch_execz .LBB0_909
	s_add_u32 s6, s22, s94
	s_addc_u32 s7, s23, s95
	s_lshl_b64 s[4:5], s[12:13], 3
	s_add_u32 s6, s6, s4
	s_addc_u32 s7, s7, s5
	s_ashr_i32 s31, s30, 31
	s_lshl_b64 s[4:5], s[30:31], 3
	s_add_u32 s4, s6, s4
	s_addc_u32 s5, s7, s5
	v_lshlrev_b32_e32 v0, 3, v172
	v_lshl_add_u64 v[4:5], s[4:5], 0, v[0:1]
	s_waitcnt lgkmcnt(0)
	v_add_f32_e32 v0, v2, v3
	v_mul_f32_e32 v0, 0x4b800000, v0
	v_trunc_f32_e32 v0, v0
	v_mul_f32_e32 v2, 0x2f800000, v0
	v_floor_f32_e32 v3, v2
	v_fmac_f32_e32 v0, 0xcf800000, v3
	v_cvt_u32_f32_e32 v2, v0
	v_cvt_u32_f32_e32 v3, v3
	v_add_co_u32_e32 v4, vcc, 0x3d280000, v4
	s_nop 1
	v_addc_co_u32_e32 v5, vcc, 0, v5, vcc
	global_atomic_add_x2 v[4:5], v[2:3], off
	s_branch .LBB0_909

; #define PG8_LAS __attribute__((address_space(3)))
; __device__ __forceinline__ float ssq_val(ssq_t v) { return (float)v * SSQ_IFX; }
;     __device__ __forceinline__ void prefetch(const Unit& u, int par, PG8_LAS unsigned char* lds, int tid) const {
;         if (tid < BM) {
;             const int row = u.pm * BM + tid;
;             const float sa = ssq_val(gsa[row]) * (1.0f / 384.0f) + EPS, sb = ssq_val(gsb[row]) * (1.0f / 384.0f) + EPS, sc_ = ssq_val(gsc[row]) * (1.0f / 256.0f) + EPS;
;             PG8_LAS float* rp = (PG8_LAS float*)(lds + STAGE_BYTES + 1024) + par * 512;
;             rp[tid] = sqrtf(sb / sa); rp[256 + tid] = sqrtf(sc_ / sb);
;         }
;     }
.LBB0_1057:
	s_andn2_b64 vcc, exec, s[12:13]
	s_cbranch_vccnz .LBB0_1107
	s_add_u32 s3, s14, s94
	s_addc_u32 s11, s15, s95
	s_add_u32 s12, s3, 0x3d200000
	s_addc_u32 s13, s11, 0
	s_add_u32 s3, s6, s94
	s_addc_u32 s6, s7, s95
	s_add_u32 s14, s3, 0x3d280000
	s_addc_u32 s15, s6, 0
	s_add_u32 s3, s4, s94
	s_addc_u32 s4, s5, s95
	v_mbcnt_lo_u32_b32 v3, -1, 0
	v_mbcnt_hi_u32_b32 v3, -1, v3
	v_writelane_b32 v255, s12, 20
	s_add_u32 s16, s3, 0x3d300000
	v_or_b32_e32 v3, s63, v3
	v_writelane_b32 v255, s13, 21
	s_addc_u32 s17, s4, 0
	v_cmp_gt_i32_e32 vcc, s82, v3
	s_and_saveexec_b64 s[34:35], vcc
	s_cbranch_execz .LBB0_1060
	v_lshl_add_u32 v4, s10, 8, v3
	v_ashrrev_i32_e32 v5, 31, v4
	v_readlane_b32 s4, v255, 20
	v_lshlrev_b64 v[4:5], 3, v[4:5]
	v_readlane_b32 s5, v255, 21
	v_lshl_add_u32 v3, v3, 2, 0
	v_add_u32_e32 v3, 0x20400, v3
	v_lshl_add_u64 v[6:7], s[4:5], 0, v[4:5]
	global_load_dwordx2 v[6:7], v[6:7], off
	s_waitcnt vmcnt(0) lgkmcnt(0)
	v_ffbh_u32_e32 v8, v7
	v_min_u32_e32 v8, 32, v8
	v_lshlrev_b64 v[6:7], v8, v[6:7]
	v_min_u32_e32 v6, 1, v6
	v_or_b32_e32 v6, v7, v6
	v_cvt_f32_u32_e32 v6, v6
	v_sub_u32_e32 v7, 32, v8
	v_ldexp_f32 v6, v6, v7
	v_mul_f32_e32 v6, 0x33800000, v6
	v_fmamk_f32 v8, v6, 0x3b2aaaab, v226
	v_lshl_add_u64 v[6:7], s[14:15], 0, v[4:5]
	global_load_dwordx2 v[6:7], v[6:7], off
	v_lshl_add_u64 v[4:5], s[16:17], 0, v[4:5]
	global_load_dwordx2 v[4:5], v[4:5], off
	s_waitcnt vmcnt(0) lgkmcnt(0)
	v_ffbh_u32_e32 v9, v7
	v_min_u32_e32 v9, 32, v9
	v_lshlrev_b64 v[6:7], v9, v[6:7]
	v_min_u32_e32 v6, 1, v6
	v_or_b32_e32 v6, v7, v6
	v_cvt_f32_u32_e32 v6, v6
	v_sub_u32_e32 v7, 32, v9
	v_ldexp_f32 v6, v6, v7
	v_ffbh_u32_e32 v7, v5
	v_min_u32_e32 v7, 32, v7
	v_lshlrev_b64 v[4:5], v7, v[4:5]
	v_min_u32_e32 v4, 1, v4
	v_or_b32_e32 v4, v5, v4
	v_cvt_f32_u32_e32 v4, v4
	v_mul_f32_e32 v6, 0x33800000, v6
	v_fmamk_f32 v6, v6, 0x3b2aaaab, v226
	v_sub_u32_e32 v5, 32, v7
	v_ldexp_f32 v4, v4, v5
	v_div_scale_f32 v5, s[4:5], v8, v8, v6
	v_rcp_f32_e32 v7, v5
	v_mul_f32_e32 v4, 0x33800000, v4
	v_fmamk_f32 v4, v4, 0x3b800000, v226
	v_fma_f32 v9, -v5, v7, 1.0
	v_fmac_f32_e32 v7, v9, v7
	v_div_scale_f32 v9, vcc, v6, v8, v6
	v_mul_f32_e32 v10, v9, v7
	v_fma_f32 v11, -v5, v10, v9
	v_fmac_f32_e32 v10, v11, v7
	v_fma_f32 v5, -v5, v10, v9
	v_div_fmas_f32 v5, v5, v7, v10
	v_div_fixup_f32 v5, v5, v8, v6
	v_cmp_gt_f32_e32 vcc, s71, v5
	v_mul_f32_e32 v7, 0x4f800000, v5
	s_nop 0
	v_cndmask_b32_e32 v5, v5, v7, vcc
	v_sqrt_f32_e32 v7, v5
	s_nop 0
	v_add_u32_e32 v8, -1, v7
	v_fma_f32 v9, -v8, v7, v5
	v_cmp_ge_f32_e64 s[6:7], 0, v9
	v_add_u32_e32 v9, 1, v7
	s_nop 0
	v_cndmask_b32_e64 v8, v7, v8, s[6:7]
	v_fma_f32 v7, -v9, v7, v5
	v_cmp_lt_f32_e64 s[6:7], 0, v7
	s_nop 1
	v_cndmask_b32_e64 v7, v8, v9, s[6:7]
	v_mul_f32_e32 v8, 0x37800000, v7
	v_cndmask_b32_e32 v7, v7, v8, vcc
	v_cmp_class_f32_e32 vcc, v5, v223
	s_nop 1
	v_cndmask_b32_e32 v5, v7, v5, vcc
	v_div_scale_f32 v7, s[4:5], v6, v6, v4
	v_rcp_f32_e32 v8, v7
	s_nop 0
	v_fma_f32 v9, -v7, v8, 1.0
	v_fmac_f32_e32 v8, v9, v8
	v_div_scale_f32 v9, vcc, v4, v6, v4
	v_mul_f32_e32 v10, v9, v8
	v_fma_f32 v11, -v7, v10, v9
	v_fmac_f32_e32 v10, v11, v8
	v_fma_f32 v7, -v7, v10, v9
	v_div_fmas_f32 v7, v7, v8, v10
	v_div_fixup_f32 v4, v7, v6, v4
	v_cmp_gt_f32_e32 vcc, s71, v4
	v_mul_f32_e32 v6, 0x4f800000, v4
	s_nop 0
	v_cndmask_b32_e32 v4, v4, v6, vcc
	v_sqrt_f32_e32 v6, v4
	s_nop 0
	v_add_u32_e32 v7, -1, v6
	v_fma_f32 v8, -v7, v6, v4
	v_cmp_ge_f32_e64 s[6:7], 0, v8
	v_add_u32_e32 v8, 1, v6
	s_nop 0
	v_cndmask_b32_e64 v7, v6, v7, s[6:7]
	v_fma_f32 v6, -v8, v6, v4
	v_cmp_lt_f32_e64 s[6:7], 0, v6
	s_nop 1
	v_cndmask_b32_e64 v6, v7, v8, s[6:7]
	v_mul_f32_e32 v7, 0x37800000, v6
	v_cndmask_b32_e32 v6, v6, v7, vcc
	v_cmp_class_f32_e32 vcc, v4, v223
	s_nop 1
	v_cndmask_b32_e32 v4, v6, v4, vcc
	ds_write2st64_b32 v3, v5, v4 offset1:4

; #define PG8_LAS __attribute__((address_space(3)))
; __device__ __forceinline__ float ssq_val(ssq_t v) { return (float)v * SSQ_IFX; }
;     __device__ __forceinline__ void prefetch(const Unit& u, int par, PG8_LAS unsigned char* lds, int tid) const {
;         if (tid < BM) {
;             const int row = u.pm * BM + tid;
;             const float sa = ssq_val(gsa[row]) * (1.0f / 384.0f) + EPS, sb = ssq_val(gsb[row]) * (1.0f / 384.0f) + EPS, sc_ = ssq_val(gsc[row]) * (1.0f / 256.0f) + EPS;
;             PG8_LAS float* rp = (PG8_LAS float*)(lds + STAGE_BYTES + 1024) + par * 512;
;             rp[tid] = sqrtf(sb / sa); rp[256 + tid] = sqrtf(sc_ / sb);
;         }
;     }
.LBB0_1083:
	v_cndmask_b32_e64 v0, 0, 1, s[8:9]
	v_cmp_ne_u32_e64 s[6:7], 1, v0
	s_andn2_b64 vcc, exec, s[8:9]
	s_cbranch_vccnz .LBB0_1087
	v_mbcnt_lo_u32_b32 v0, -1, 0
	v_mbcnt_hi_u32_b32 v0, -1, v0
	s_movk_i32 s2, 0x100
	v_or_b32_e32 v0, s63, v0
	v_cmp_gt_i32_e32 vcc, s2, v0
	s_and_saveexec_b64 s[40:41], vcc
	s_cbranch_execz .LBB0_1086
	v_lshl_add_u32 v2, s34, 8, v0
	v_ashrrev_i32_e32 v3, 31, v2
	v_readlane_b32 s2, v255, 20
	v_lshlrev_b64 v[2:3], 3, v[2:3]
	v_readlane_b32 s3, v255, 21
	s_nop 1
	v_lshl_add_u64 v[70:71], s[2:3], 0, v[2:3]
	global_load_dwordx2 v[70:71], v[70:71], off
	s_lshl_b32 s2, s97, 11
	s_and_b32 s2, s2, 0x800
	s_add_i32 s2, s2, 0
	v_lshl_add_u32 v0, v0, 2, s2
	v_add_u32_e32 v0, 0x20400, v0
	s_waitcnt vmcnt(0) lgkmcnt(0)
	v_ffbh_u32_e32 v72, v71
	v_min_u32_e32 v72, 32, v72
	v_lshlrev_b64 v[70:71], v72, v[70:71]
	v_min_u32_e32 v70, 1, v70
	v_or_b32_e32 v70, v71, v70
	v_cvt_f32_u32_e32 v70, v70
	v_sub_u32_e32 v71, 32, v72
	v_ldexp_f32 v70, v70, v71
	v_mul_f32_e32 v70, 0x33800000, v70
	v_fmamk_f32 v72, v70, 0x3b2aaaab, v226
	v_lshl_add_u64 v[70:71], s[14:15], 0, v[2:3]
	global_load_dwordx2 v[70:71], v[70:71], off
	v_lshl_add_u64 v[2:3], s[16:17], 0, v[2:3]
	global_load_dwordx2 v[2:3], v[2:3], off
	s_waitcnt vmcnt(0) lgkmcnt(0)
	v_ffbh_u32_e32 v73, v71
	v_min_u32_e32 v73, 32, v73
	v_lshlrev_b64 v[70:71], v73, v[70:71]
	v_min_u32_e32 v70, 1, v70
	v_or_b32_e32 v70, v71, v70
	v_cvt_f32_u32_e32 v70, v70
	v_sub_u32_e32 v71, 32, v73
	v_ldexp_f32 v70, v70, v71
	v_ffbh_u32_e32 v71, v3
	v_min_u32_e32 v71, 32, v71
	v_lshlrev_b64 v[2:3], v71, v[2:3]
	v_min_u32_e32 v2, 1, v2
	v_or_b32_e32 v2, v3, v2
	v_cvt_f32_u32_e32 v2, v2
	v_mul_f32_e32 v70, 0x33800000, v70
	v_fmamk_f32 v70, v70, 0x3b2aaaab, v226
	v_sub_u32_e32 v3, 32, v71
	v_ldexp_f32 v2, v2, v3
	v_div_scale_f32 v3, s[2:3], v72, v72, v70
	v_rcp_f32_e32 v71, v3
	v_mul_f32_e32 v2, 0x33800000, v2
	v_fmamk_f32 v2, v2, 0x3b800000, v226
	v_fma_f32 v73, -v3, v71, 1.0
	v_fmac_f32_e32 v71, v73, v71
	v_div_scale_f32 v73, vcc, v70, v72, v70
	v_mul_f32_e32 v74, v73, v71
	v_fma_f32 v75, -v3, v74, v73
	v_fmac_f32_e32 v74, v75, v71
	v_fma_f32 v3, -v3, v74, v73
	v_div_fmas_f32 v3, v3, v71, v74
	v_div_fixup_f32 v3, v3, v72, v70
	v_cmp_gt_f32_e32 vcc, s71, v3
	v_mul_f32_e32 v71, 0x4f800000, v3
	s_nop 0
	v_cndmask_b32_e32 v3, v3, v71, vcc
	v_sqrt_f32_e32 v71, v3
	s_nop 0
	v_add_u32_e32 v72, -1, v71
	v_fma_f32 v73, -v72, v71, v3
	v_cmp_ge_f32_e64 s[8:9], 0, v73
	v_add_u32_e32 v73, 1, v71
	s_nop 0
	v_cndmask_b32_e64 v72, v71, v72, s[8:9]
	v_fma_f32 v71, -v73, v71, v3
	v_cmp_lt_f32_e64 s[8:9], 0, v71
	s_nop 1
	v_cndmask_b32_e64 v71, v72, v73, s[8:9]
	v_mul_f32_e32 v72, 0x37800000, v71
	v_cndmask_b32_e32 v71, v71, v72, vcc
	v_cmp_class_f32_e32 vcc, v3, v223
	s_nop 1
	v_cndmask_b32_e32 v3, v71, v3, vcc
	v_div_scale_f32 v71, s[2:3], v70, v70, v2
	v_rcp_f32_e32 v72, v71
	s_nop 0
	v_fma_f32 v73, -v71, v72, 1.0
	v_fmac_f32_e32 v72, v73, v72
	v_div_scale_f32 v73, vcc, v2, v70, v2
	v_mul_f32_e32 v74, v73, v72
	v_fma_f32 v75, -v71, v74, v73
	v_fmac_f32_e32 v74, v75, v72
	v_fma_f32 v71, -v71, v74, v73
	v_div_fmas_f32 v71, v71, v72, v74
	v_div_fixup_f32 v2, v71, v70, v2
	v_cmp_gt_f32_e32 vcc, s71, v2
	v_mul_f32_e32 v70, 0x4f800000, v2
	s_nop 0
	v_cndmask_b32_e32 v2, v2, v70, vcc
	v_sqrt_f32_e32 v70, v2
	s_nop 0
	v_add_u32_e32 v71, -1, v70
	v_fma_f32 v72, -v71, v70, v2
	v_cmp_ge_f32_e64 s[8:9], 0, v72
	v_add_u32_e32 v72, 1, v70
	s_nop 0
	v_cndmask_b32_e64 v71, v70, v71, s[8:9]
	v_fma_f32 v70, -v72, v70, v2
	v_cmp_lt_f32_e64 s[8:9], 0, v70
	s_nop 1
	v_cndmask_b32_e64 v70, v71, v72, s[8:9]
	v_mul_f32_e32 v71, 0x37800000, v70
	v_cndmask_b32_e32 v70, v70, v71, vcc
	v_cmp_class_f32_e32 vcc, v2, v223
	s_nop 1
	v_cndmask_b32_e32 v2, v70, v2, vcc
	ds_write2st64_b32 v0, v3, v2 offset1:4

; #define PG8_GCPTR(p) ((__attribute__((address_space(1))) const char*)(p))
; __device__ __forceinline__ float ssq_val(ssq_t v) { return (float)v * SSQ_IFX; }
;     __device__ __forceinline__ void operator()(const f32x4 (&acc)[2][2][4][2], const Unit& u, int wr, int wc, int fr, int fq) const {
;     ...
;         if constexpr (GN) { ssq_t sc_[8];
; #pragma unroll
;             for (int i = 0; i < 8; ++i) sc_[i] = gsc[u.pm * BM + wr * 64 + fr + (i >> 2) * HALF + (i & 3) * 16];
; #pragma unroll
;             for (int i = 0; i < 8; ++i) rc[i] = 1.0f / sqrtf(ssq_val(sc_[i]) * (1.0f / 256.0f) + EPS); }
;         const int col0 = u.pn * BM + wc * 32 + 8 * fq; const int b = (u.pm * BM) >> 12;
;         const float* gp = gate + (size_t)b * NMOD + col0; const float* sp = sc + (size_t)b * NMOD + col0;
;         f32x4 g[2][2], cf[2][2];
; #pragma unroll
;         for (int bj = 0; bj < 2; ++bj) {
;             g[bj][0] = *(const f32x4*)(gp + bj * HALF); g[bj][1] = *(const f32x4*)(gp + bj * HALF + 4);
;             const f32x4 n0 = *(const f32x4*)(nw + col0 + bj * HALF), n1 = *(const f32x4*)(nw + col0 + bj * HALF + 4);
;             const f32x4 c0 = *(const f32x4*)(sp + bj * HALF), c1 = *(const f32x4*)(sp + bj * HALF + 4);
;             cf[bj][0] = n0 * (c0 + 1.0f); cf[bj][1] = n1 * (c1 + 1.0f);
;         }
; #pragma unroll
;         for (int ai = 0; ai < 2; ++ai)
; #pragma unroll
;         for (int mp = 0; mp < 4; mp += 2) {
;             u32x4 bv[2][2];
; #pragma unroll
;             for (int mm = 0; mm < 2; ++mm)
; #pragma unroll
;                 for (int bj = 0; bj < 2; ++bj)
;                     bv[mm][bj] = *(gl_u32x4*)(PG8_GCPTR(base) + (unsigned)((u.pm * BM + ai * HALF + wr * 64 + (mp + mm) * 16 + fr) * DM + col0 + bj * HALF) * 2u);
.LBB0_1087:
	s_lshl_b32 s2, s10, 8
	v_mbcnt_lo_u32_b32 v0, -1, 0
	v_mbcnt_hi_u32_b32 v0, -1, v0
	s_add_i32 s2, s2, s90
	v_and_b32_e32 v182, 15, v0
	v_or_b32_e32 v216, s2, v182
	v_ashrrev_i32_e32 v217, 31, v216
	v_lshl_add_u64 v[2:3], v[216:217], 3, s[16:17]
	global_load_dwordx2 v[70:71], v[2:3], off
	global_load_dwordx2 v[218:219], v[2:3], off offset:128
	global_load_dwordx2 v[214:215], v[2:3], off offset:256
	global_load_dwordx2 v[212:213], v[2:3], off offset:384
	global_load_dwordx2 v[210:211], v[2:3], off offset:1024
	global_load_dwordx2 v[208:209], v[2:3], off offset:1152
	global_load_dwordx2 v[206:207], v[2:3], off offset:1280
	s_nop 0
	global_load_dwordx2 v[2:3], v[2:3], off offset:1408
	v_bfe_u32 v183, v0, 4, 2
	v_lshlrev_b32_e32 v232, 11, v216
	s_waitcnt vmcnt(0) lgkmcnt(0)
	v_ffbh_u32_e32 v0, v71
	v_min_u32_e32 v0, 32, v0
	v_lshlrev_b64 v[70:71], v0, v[70:71]
	v_min_u32_e32 v70, 1, v70
	v_or_b32_e32 v70, v71, v70
	v_cvt_f32_u32_e32 v70, v70
	v_sub_u32_e32 v0, 32, v0
	v_ldexp_f32 v0, v70, v0
	v_mul_f32_e32 v0, 0x33800000, v0
	v_fmamk_f32 v0, v0, 0x3b800000, v226
	v_cmp_gt_f32_e32 vcc, s71, v0
	v_mul_f32_e32 v70, 0x4f800000, v0
	s_nop 0
	v_cndmask_b32_e32 v0, v0, v70, vcc
	v_sqrt_f32_e32 v70, v0
	s_nop 0
	v_add_u32_e32 v71, -1, v70
	v_fma_f32 v72, -v71, v70, v0
	v_cmp_ge_f32_e64 s[8:9], 0, v72
	v_add_u32_e32 v72, 1, v70
	s_nop 0
	v_cndmask_b32_e64 v71, v70, v71, s[8:9]
	v_fma_f32 v70, -v72, v70, v0
	v_cmp_lt_f32_e64 s[8:9], 0, v70
	s_nop 1
	v_cndmask_b32_e64 v70, v71, v72, s[8:9]
	v_mul_f32_e32 v71, 0x37800000, v70
	v_cndmask_b32_e32 v70, v70, v71, vcc
	v_cmp_class_f32_e32 vcc, v0, v223
	v_cmp_eq_u32_e64 s[8:9], 0, v183
	s_nop 0
	v_cndmask_b32_e32 v0, v70, v0, vcc
	v_div_scale_f32 v70, s[2:3], v0, v0, 1.0
	v_rcp_f32_e32 v71, v70
	s_lshl_b32 s2, s50, 8
	v_fma_f32 v72, -v70, v71, 1.0
	v_fmac_f32_e32 v71, v72, v71
	v_div_scale_f32 v72, vcc, 1.0, v0, 1.0
	v_mul_f32_e32 v73, v72, v71
	v_fma_f32 v74, -v70, v73, v72
	v_fmac_f32_e32 v73, v74, v71
	v_fma_f32 v70, -v70, v73, v72
	v_div_fmas_f32 v70, v70, v71, v73
	v_div_fixup_f32 v0, v70, v0, 1.0
	v_lshl_or_b32 v70, v183, 3, s2
	s_ashr_i32 s2, s10, 4
	v_or_b32_e32 v180, s91, v70
	s_mul_i32 s5, s2, 0x6000
	s_mul_hi_i32 s4, s2, 0x6000
	s_add_u32 s2, s52, s5
	v_ashrrev_i32_e32 v181, 31, v180
	s_addc_u32 s3, s83, s4
	v_lshlrev_b64 v[70:71], 2, v[180:181]
	v_lshl_add_u64 v[158:159], s[2:3], 0, v[70:71]
	s_add_u32 s2, s88, s5
	s_addc_u32 s3, s89, s4
	v_lshl_add_u64 v[174:175], s[2:3], 0, v[70:71]
	v_lshl_add_u64 v[160:161], s[20:21], 0, v[70:71]
	global_load_dwordx4 v[82:85], v[158:159], off
	global_load_dwordx4 v[78:81], v[158:159], off offset:16
	global_load_dwordx4 v[70:73], v[160:161], off offset:16
	global_load_dwordx4 v[74:77], v[160:161], off
	global_load_dwordx4 v[150:153], v[174:175], off
	global_load_dwordx4 v[154:157], v[174:175], off offset:16
	v_lshlrev_b32_e32 v230, 1, v180
	v_add_u32_e32 v231, v230, v232
	v_and_b32_e32 v240, 0xffff8000, v231
	v_bfe_u32 v241, v231, 11, 4
	v_lshl_or_b32 v240, v241, 6, v240
	v_bfe_u32 v241, v231, 9, 2
	v_lshl_or_b32 v240, v241, 13, v240
	v_bfe_u32 v241, v231, 6, 2
	v_lshl_or_b32 v240, v241, 11, v240
	v_and_b32_e32 v241, 48, v231
	v_or_b32_e32 v240, v240, v241
	s_movk_i32 s2, 0x80
	v_pk_mul_f32 v[146:147], v[146:147], v[0:1] op_sel_hi:[1,0]
	v_pk_mul_f32 v[148:149], v[148:149], v[0:1] op_sel_hi:[1,0]
	v_pk_mul_f32 v[142:143], v[142:143], v[0:1] op_sel_hi:[1,0]
	v_pk_mul_f32 v[144:145], v[144:145], v[0:1] op_sel_hi:[1,0]
	v_pk_mul_f32 v[138:139], v[138:139], v[0:1] op_sel_hi:[1,0]
	v_pk_mul_f32 v[140:141], v[140:141], v[0:1] op_sel_hi:[1,0]
	v_pk_mul_f32 v[134:135], v[134:135], v[0:1] op_sel_hi:[1,0]
	v_pk_mul_f32 v[136:137], v[136:137], v[0:1] op_sel_hi:[1,0]
	s_waitcnt vmcnt(0) lgkmcnt(0)
	v_pk_add_f32 v[152:153], v[152:153], 1.0 op_sel_hi:[1,0]
	v_pk_add_f32 v[150:151], v[150:151], 1.0 op_sel_hi:[1,0]
	v_pk_mul_f32 v[200:201], v[76:77], v[152:153]
	v_pk_mul_f32 v[204:205], v[74:75], v[150:151]
	v_pk_add_f32 v[74:75], v[156:157], 1.0 op_sel_hi:[1,0]
	v_pk_add_f32 v[76:77], v[154:155], 1.0 op_sel_hi:[1,0]
	v_pk_mul_f32 v[198:199], v[72:73], v[74:75]
	v_pk_mul_f32 v[202:203], v[70:71], v[76:77]
	global_load_dwordx4 v[74:77], v[158:159], off offset:512
	global_load_dwordx4 v[70:73], v[158:159], off offset:528
	global_load_dwordx4 v[150:153], v[160:161], off offset:528
	global_load_dwordx4 v[154:157], v[160:161], off offset:512
	s_nop 0
	global_load_dwordx4 v[158:161], v[174:175], off offset:512
	global_load_dwordx4 v[176:179], v[174:175], off offset:528
	s_waitcnt vmcnt(0) lgkmcnt(0)
	v_pk_add_f32 v[160:161], v[160:161], 1.0 op_sel_hi:[1,0]
	v_pk_add_f32 v[158:159], v[158:159], 1.0 op_sel_hi:[1,0]
	v_pk_mul_f32 v[196:197], v[156:157], v[160:161]
	v_pk_mul_f32 v[174:175], v[154:155], v[158:159]
	v_pk_add_f32 v[154:155], v[178:179], 1.0 op_sel_hi:[1,0]
	global_load_dwordx4 v[178:181], v240, s[22:23]
	global_load_dwordx4 v[158:161], v240, s[22:23] offset:1024
	v_pk_add_f32 v[156:157], v[176:177], 1.0 op_sel_hi:[1,0]
	v_pk_mul_f32 v[176:177], v[152:153], v[154:155]
	v_pk_mul_f32 v[194:195], v[150:151], v[156:157]
	v_lshlrev_b32_e32 v150, 6, v183
	v_lshlrev_b32_e32 v151, 2, v182
	v_bitop3_b32 v229, v150, 64, v151 bitop3:0x36
	v_bitop3_b32 v228, v150, s2, v151 bitop3:0x36
	v_add_u32_e32 v150, 0x8000, v240
	global_load_dwordx4 v[154:157], v150, s[22:23]
	s_nop 0
	global_load_dwordx4 v[150:153], v150, s[22:23] offset:1024
	s_waitcnt vmcnt(3)
; __device__ __forceinline__ unsigned cvt_pk_bf16(float lo, float hi) { unsigned r; asm volatile("v_cvt_pk_bf16_f32 %0, %1, %2" : "=v"(r) : "v"(lo), "v"(hi)); return r; }
; #define PG8_GPTR(p) ((__attribute__((address_space(1))) char*)(p))
;     __device__ __forceinline__ void operator()(const f32x4 (&acc)[2][2][4][2], const Unit& u, int wr, int wc, int fr, int fq) const {
;     ...
;             for (int mm = 0; mm < 2; ++mm) {
;                 const int m = mp + mm;
;                 const int row = u.pm * BM + ai * HALF + wr * 64 + m * 16 + fr; float q = 0.f;
; #pragma unroll
;                 for (int bj = 0; bj < 2; ++bj) {
;                     const unsigned offb = (unsigned)(row * DM + col0 + bj * HALF) * 2u;
;                     const u32x4 bw = bv[mm][bj];
;                     const f32x4 b0 = (f32x4){__uint_as_float(bw.x << 16), __uint_as_float(bw.x & 0xffff0000u), __uint_as_float(bw.y << 16), __uint_as_float(bw.y & 0xffff0000u)};
;                     const f32x4 b1 = (f32x4){__uint_as_float(bw.z << 16), __uint_as_float(bw.z & 0xffff0000u), __uint_as_float(bw.w << 16), __uint_as_float(bw.w & 0xffff0000u)};
;                     f32x4 a0 = acc[ai][bj][m][0], a1 = acc[ai][bj][m][1]; if constexpr (GN) { a0 *= rc[ai * 4 + m]; a1 *= rc[ai * 4 + m]; }
;                     const f32x4 o0 = b0 + g[bj][0] * a0, o1 = b1 + g[bj][1] * a1;
;                     u32x4 wo; wo.x = cvt_pk_bf16(o0[0], o0[1]); wo.y = cvt_pk_bf16(o0[2], o0[3]); wo.z = cvt_pk_bf16(o1[0], o1[1]); wo.w = cvt_pk_bf16(o1[2], o1[3]);
;                     *(gs_u32x4*)(PG8_GPTR(out) + offb) = wo;
;                     if (xg) {
;                         const f32x4 h0 = o0 * cf[bj][0], h1 = o1 * cf[bj][1];
;                         u32x4 w; w.x = cvt_pk_bf16(h0[0], h0[1]); w.y = cvt_pk_bf16(h0[2], h0[3]); w.z = cvt_pk_bf16(h1[0], h1[1]); w.w = cvt_pk_bf16(h1[2], h1[3]);
;                         *(gs_u32x4*)(PG8_GPTR(xg) + offb) = w;
;                         q += (o0[0] * o0[0] + o0[1] * o0[1]) + (o0[2] * o0[2] + o0[3] * o0[3]) + (o1[0] * o1[0] + o1[1] * o1[1]) + (o1[2] * o1[2] + o1[3] * o1[3]);
;                     }
;                 }
;                 if (xg) ssq_put(ssq, row, q, fr, fq);
	v_lshlrev_b32_e32 v182, 16, v178
	v_and_b32_e32 v183, 0xffff0000, v178
	v_lshlrev_b32_e32 v178, 16, v179
	v_and_b32_e32 v179, 0xffff0000, v179
	v_lshlrev_b32_e32 v184, 16, v180
	v_and_b32_e32 v185, 0xffff0000, v180
	v_lshlrev_b32_e32 v180, 16, v181
	v_and_b32_e32 v181, 0xffff0000, v181
	v_pk_fma_f32 v[148:149], v[84:85], v[148:149], v[178:179]
	v_pk_fma_f32 v[146:147], v[82:83], v[146:147], v[182:183]
	v_pk_fma_f32 v[178:179], v[80:81], v[144:145], v[180:181]
	v_pk_fma_f32 v[180:181], v[78:79], v[142:143], v[184:185]
	v_cvt_pk_bf16_f32 v142, v146, v147
	v_cvt_pk_bf16_f32 v143, v148, v149
	v_pk_mul_f32 v[182:183], v[198:199], v[178:179]
	v_cvt_pk_bf16_f32 v144, v180, v181
	v_cvt_pk_bf16_f32 v145, v178, v179
	global_store_dwordx4 v240, v[142:145], s[24:25]
	v_pk_mul_f32 v[184:185], v[202:203], v[180:181]
	s_nop 0
	v_pk_mul_f32 v[142:143], v[204:205], v[146:147]
	v_pk_mul_f32 v[144:145], v[200:201], v[148:149]
	v_cvt_pk_bf16_f32 v142, v142, v143
	s_nop 0
	v_cvt_pk_bf16_f32 v143, v144, v145
	v_cvt_pk_bf16_f32 v144, v184, v185
	v_cvt_pk_bf16_f32 v145, v182, v183
	global_store_dwordx4 v231, v[142:145], s[26:27]
	s_nop 1
	v_mul_f32_e32 v142, v147, v147
	v_mul_f32_e32 v143, v149, v149
	v_fmac_f32_e32 v142, v146, v146
	v_fmac_f32_e32 v143, v148, v148
	v_add_f32_e32 v142, v142, v143
	v_mul_f32_e32 v143, v181, v181
	v_fmac_f32_e32 v143, v180, v180
	v_add_f32_e32 v142, v143, v142
	v_mul_f32_e32 v143, v179, v179
	v_fmac_f32_e32 v143, v178, v178
	v_add_f32_e32 v178, v143, v142
	s_waitcnt vmcnt(4)
	v_lshlrev_b32_e32 v142, 16, v158
	v_and_b32_e32 v143, 0xffff0000, v158
	v_lshlrev_b32_e32 v144, 16, v159
	v_and_b32_e32 v145, 0xffff0000, v159
	v_lshlrev_b32_e32 v146, 16, v160
	v_and_b32_e32 v147, 0xffff0000, v160
	v_lshlrev_b32_e32 v148, 16, v161
	v_and_b32_e32 v149, 0xffff0000, v161
	v_pk_fma_f32 v[140:141], v[140:141], v[76:77], v[144:145]
	v_pk_fma_f32 v[138:139], v[138:139], v[74:75], v[142:143]
	v_pk_fma_f32 v[142:143], v[136:137], v[72:73], v[148:149]
	v_pk_fma_f32 v[144:145], v[134:135], v[70:71], v[146:147]
	v_cvt_pk_bf16_f32 v134, v138, v139
	v_cvt_pk_bf16_f32 v135, v140, v141
	v_pk_mul_f32 v[146:147], v[176:177], v[142:143]
	v_cvt_pk_bf16_f32 v136, v144, v145
	v_cvt_pk_bf16_f32 v137, v142, v143
	global_store_dwordx4 v240, v[134:137], s[24:25] offset:1024
	v_pk_mul_f32 v[148:149], v[194:195], v[144:145]
	v_mul_f32_e32 v0, v143, v143
	v_pk_mul_f32 v[136:137], v[196:197], v[140:141]
	v_pk_mul_f32 v[134:135], v[174:175], v[138:139]
	v_fmac_f32_e32 v0, v142, v142
	v_cvt_pk_bf16_f32 v134, v134, v135
	v_cvt_pk_bf16_f32 v135, v136, v137
	v_cvt_pk_bf16_f32 v136, v148, v149
	v_cvt_pk_bf16_f32 v137, v146, v147
	global_store_dwordx4 v231, v[134:137], s[26:27] offset:256
	s_nop 1
	v_mul_f32_e32 v135, v139, v139
	v_mul_f32_e32 v136, v141, v141
	v_mul_f32_e32 v134, v145, v145
	v_fmac_f32_e32 v135, v138, v138
	v_fmac_f32_e32 v136, v140, v140
	v_fmac_f32_e32 v134, v144, v144
	v_add_f32_e32 v135, v135, v136
	v_add_f32_e32 v134, v134, v135
	v_add_f32_e32 v0, v0, v134
	v_add_f32_e32 v0, v178, v0
	ds_bpermute_b32 v134, v229, v0
	s_waitcnt lgkmcnt(0)
	v_add_f32_e32 v0, v0, v134
	ds_bpermute_b32 v136, v228, v0
	v_lshl_add_u64 v[134:135], v[216:217], 3, s[28:29]
	s_and_saveexec_b64 s[2:3], s[8:9]
	s_cbranch_execz .LBB0_1089
	s_waitcnt lgkmcnt(0)
	v_add_f32_e32 v0, v0, v136
	v_mul_f32_e32 v0, 0x4b800000, v0
	v_trunc_f32_e32 v0, v0
	v_mul_f32_e32 v136, 0x2f800000, v0
	v_floor_f32_e32 v137, v136
	v_fmac_f32_e32 v0, 0xcf800000, v137
	v_cvt_u32_f32_e32 v136, v0
	v_cvt_u32_f32_e32 v137, v137
	global_atomic_add_x2 v[134:135], v[136:137], off
.LBB0_1089:
	s_or_b64 exec, exec, s[2:3]
	v_ffbh_u32_e32 v0, v219
	v_min_u32_e32 v0, 32, v0
	s_waitcnt lgkmcnt(0)
	v_lshlrev_b64 v[136:137], v0, v[218:219]
	v_min_u32_e32 v136, 1, v136
	v_or_b32_e32 v136, v137, v136
	v_cvt_f32_u32_e32 v136, v136
	v_sub_u32_e32 v0, 32, v0
	s_waitcnt vmcnt(0)
	v_and_b32_e32 v141, 0xffff0000, v155
	v_lshlrev_b32_e32 v142, 16, v156
	v_ldexp_f32 v0, v136, v0
	v_mul_f32_e32 v0, 0x33800000, v0
	v_fmamk_f32 v0, v0, 0x3b800000, v226
	v_mul_f32_e32 v136, 0x4f800000, v0
	v_cmp_gt_f32_e32 vcc, s71, v0
	v_and_b32_e32 v143, 0xffff0000, v156
	v_lshlrev_b32_e32 v144, 16, v157
	v_cndmask_b32_e32 v0, v0, v136, vcc
	v_sqrt_f32_e32 v136, v0
	v_and_b32_e32 v145, 0xffff0000, v157
	v_add_u32_e32 v137, -1, v136
	v_add_u32_e32 v138, 1, v136
	v_fma_f32 v139, -v137, v136, v0
	v_fma_f32 v140, -v138, v136, v0
	v_cmp_ge_f32_e64 s[10:11], 0, v139
	s_nop 1
	v_cndmask_b32_e64 v136, v136, v137, s[10:11]
	v_cmp_lt_f32_e64 s[10:11], 0, v140
	s_nop 1
	v_cndmask_b32_e64 v136, v136, v138, s[10:11]
	v_mul_f32_e32 v137, 0x37800000, v136
	v_cndmask_b32_e32 v136, v136, v137, vcc
	v_cmp_class_f32_e32 vcc, v0, v223
	s_nop 1
	v_cndmask_b32_e32 v0, v136, v0, vcc
	v_div_scale_f32 v136, s[2:3], v0, v0, 1.0
	v_rcp_f32_e32 v137, v136
	s_mov_b32 s2, 0x8000
	v_fma_f32 v138, -v136, v137, 1.0
	v_fmac_f32_e32 v137, v138, v137
	v_div_scale_f32 v138, vcc, 1.0, v0, 1.0
	v_mul_f32_e32 v139, v138, v137
	v_fma_f32 v140, -v136, v139, v138
	v_fmac_f32_e32 v139, v140, v137
	v_fma_f32 v136, -v136, v139, v138
	v_div_fmas_f32 v136, v136, v137, v139
	v_div_fixup_f32 v0, v136, v0, 1.0
	v_lshlrev_b32_e32 v136, 11, v216
	v_lshlrev_b32_e32 v138, 16, v154
	v_and_b32_e32 v139, 0xffff0000, v154
	v_lshlrev_b32_e32 v140, 16, v155
	v_pk_mul_f32 v[130:131], v[130:131], v[0:1] op_sel_hi:[1,0]
	v_pk_mul_f32 v[132:133], v[132:133], v[0:1] op_sel_hi:[1,0]
	v_pk_mul_f32 v[126:127], v[126:127], v[0:1] op_sel_hi:[1,0]
	v_add3_u32 v137, v230, v136, s2
	v_add_u32_e32 v241, s2, v240
	v_pk_mul_f32 v[128:129], v[128:129], v[0:1] op_sel_hi:[1,0]
	v_pk_fma_f32 v[132:133], v[84:85], v[132:133], v[140:141]
; __device__ __forceinline__ unsigned cvt_pk_bf16(float lo, float hi) { unsigned r; asm volatile("v_cvt_pk_bf16_f32 %0, %1, %2" : "=v"(r) : "v"(lo), "v"(hi)); return r; }
; #define PG8_GPTR(p) ((__attribute__((address_space(1))) char*)(p))
;     __device__ __forceinline__ void operator()(const f32x4 (&acc)[2][2][4][2], const Unit& u, int wr, int wc, int fr, int fq) const {
;     ...
;             for (int mm = 0; mm < 2; ++mm) {
;                 const int m = mp + mm;
;                 const int row = u.pm * BM + ai * HALF + wr * 64 + m * 16 + fr; float q = 0.f;
; #pragma unroll
;                 for (int bj = 0; bj < 2; ++bj) {
;                     const unsigned offb = (unsigned)(row * DM + col0 + bj * HALF) * 2u;
;                     const u32x4 bw = bv[mm][bj];
;                     const f32x4 b0 = (f32x4){__uint_as_float(bw.x << 16), __uint_as_float(bw.x & 0xffff0000u), __uint_as_float(bw.y << 16), __uint_as_float(bw.y & 0xffff0000u)};
;                     const f32x4 b1 = (f32x4){__uint_as_float(bw.z << 16), __uint_as_float(bw.z & 0xffff0000u), __uint_as_float(bw.w << 16), __uint_as_float(bw.w & 0xffff0000u)};
;                     f32x4 a0 = acc[ai][bj][m][0], a1 = acc[ai][bj][m][1]; if constexpr (GN) { a0 *= rc[ai * 4 + m]; a1 *= rc[ai * 4 + m]; }
;                     const f32x4 o0 = b0 + g[bj][0] * a0, o1 = b1 + g[bj][1] * a1;
;                     u32x4 wo; wo.x = cvt_pk_bf16(o0[0], o0[1]); wo.y = cvt_pk_bf16(o0[2], o0[3]); wo.z = cvt_pk_bf16(o1[0], o1[1]); wo.w = cvt_pk_bf16(o1[2], o1[3]);
;                     *(gs_u32x4*)(PG8_GPTR(out) + offb) = wo;
;                     if (xg) {
;                         const f32x4 h0 = o0 * cf[bj][0], h1 = o1 * cf[bj][1];
;                         u32x4 w; w.x = cvt_pk_bf16(h0[0], h0[1]); w.y = cvt_pk_bf16(h0[2], h0[3]); w.z = cvt_pk_bf16(h1[0], h1[1]); w.w = cvt_pk_bf16(h1[2], h1[3]);
;                         *(gs_u32x4*)(PG8_GPTR(xg) + offb) = w;
;                         q += (o0[0] * o0[0] + o0[1] * o0[1]) + (o0[2] * o0[2] + o0[3] * o0[3]) + (o1[0] * o1[0] + o1[1] * o1[1]) + (o1[2] * o1[2] + o1[3] * o1[3]);
;                     }
;                 }
;                 if (xg) ssq_put(ssq, row, q, fr, fq);
	v_pk_fma_f32 v[130:131], v[82:83], v[130:131], v[138:139]
	v_pk_fma_f32 v[140:141], v[78:79], v[126:127], v[142:143]
	v_cvt_pk_bf16_f32 v126, v130, v131
	v_cvt_pk_bf16_f32 v127, v132, v133
	v_pk_fma_f32 v[138:139], v[80:81], v[128:129], v[144:145]
	v_cvt_pk_bf16_f32 v128, v140, v141
	v_pk_mul_f32 v[144:145], v[202:203], v[140:141]
	v_cvt_pk_bf16_f32 v129, v138, v139
	global_store_dwordx4 v241, v[126:129], s[24:25]
	v_pk_mul_f32 v[142:143], v[198:199], v[138:139]
	v_pk_mul_f32 v[122:123], v[122:123], v[0:1] op_sel_hi:[1,0]
	v_pk_mul_f32 v[126:127], v[204:205], v[130:131]
	v_pk_mul_f32 v[128:129], v[200:201], v[132:133]
	v_cvt_pk_bf16_f32 v126, v126, v127
	v_pk_mul_f32 v[124:125], v[124:125], v[0:1] op_sel_hi:[1,0]
	v_cvt_pk_bf16_f32 v127, v128, v129
	v_cvt_pk_bf16_f32 v128, v144, v145
	v_cvt_pk_bf16_f32 v129, v142, v143
	global_store_dwordx4 v137, v[126:129], s[26:27]
	v_pk_mul_f32 v[118:119], v[118:119], v[0:1] op_sel_hi:[1,0]
	v_pk_mul_f32 v[120:121], v[120:121], v[0:1] op_sel_hi:[1,0]
	v_mul_f32_e32 v126, v131, v131
	v_mul_f32_e32 v127, v133, v133
	v_fmac_f32_e32 v126, v130, v130
	v_fmac_f32_e32 v127, v132, v132
	v_add_f32_e32 v126, v126, v127
	v_mul_f32_e32 v127, v141, v141
	v_fmac_f32_e32 v127, v140, v140
	v_add_f32_e32 v126, v127, v126
	v_mul_f32_e32 v127, v139, v139
	v_fmac_f32_e32 v127, v138, v138
	v_add_f32_e32 v138, v127, v126
	v_lshlrev_b32_e32 v126, 16, v150
	v_and_b32_e32 v127, 0xffff0000, v150
	v_lshlrev_b32_e32 v128, 16, v151
	v_and_b32_e32 v129, 0xffff0000, v151
	v_lshlrev_b32_e32 v130, 16, v152
	v_and_b32_e32 v131, 0xffff0000, v152
	v_lshlrev_b32_e32 v132, 16, v153
	v_and_b32_e32 v133, 0xffff0000, v153
	v_pk_fma_f32 v[124:125], v[124:125], v[76:77], v[128:129]
	v_pk_fma_f32 v[122:123], v[122:123], v[74:75], v[126:127]
	v_pk_fma_f32 v[126:127], v[120:121], v[72:73], v[132:133]
	v_pk_fma_f32 v[128:129], v[118:119], v[70:71], v[130:131]
	v_cvt_pk_bf16_f32 v118, v122, v123
	v_cvt_pk_bf16_f32 v119, v124, v125
	v_mul_f32_e32 v0, v127, v127
	v_cvt_pk_bf16_f32 v120, v128, v129
	v_cvt_pk_bf16_f32 v121, v126, v127
	global_store_dwordx4 v241, v[118:121], s[24:25] offset:1024
	v_fmac_f32_e32 v0, v126, v126
	v_pk_mul_f32 v[130:131], v[196:197], v[124:125]
	v_mul_f32_e32 v119, v123, v123
	v_mul_f32_e32 v120, v125, v125
	v_mul_f32_e32 v118, v129, v129
	v_fmac_f32_e32 v119, v122, v122
	v_fmac_f32_e32 v120, v124, v124
	v_fmac_f32_e32 v118, v128, v128
	v_add_f32_e32 v119, v119, v120
	v_add_f32_e32 v118, v118, v119
	v_add_f32_e32 v0, v0, v118
	v_add_f32_e32 v0, v138, v0
	ds_bpermute_b32 v121, v229, v0
	v_pk_mul_f32 v[118:119], v[174:175], v[122:123]
	v_pk_mul_f32 v[122:123], v[194:195], v[128:129]
	v_cvt_pk_bf16_f32 v120, v118, v119
	v_pk_mul_f32 v[124:125], v[176:177], v[126:127]
	s_waitcnt lgkmcnt(0)
	v_add_f32_e32 v0, v0, v121
	ds_bpermute_b32 v118, v228, v0
	v_cvt_pk_bf16_f32 v121, v130, v131
	v_cvt_pk_bf16_f32 v122, v122, v123
	v_cvt_pk_bf16_f32 v123, v124, v125
	global_store_dwordx4 v137, v[120:123], s[26:27] offset:256
	s_and_saveexec_b64 s[2:3], s[8:9]
	s_cbranch_execz .LBB0_1091
	s_waitcnt lgkmcnt(0)
	v_add_f32_e32 v0, v0, v118
	v_mul_f32_e32 v0, 0x4b800000, v0
	v_trunc_f32_e32 v0, v0
	v_mul_f32_e32 v118, 0x2f800000, v0
	v_floor_f32_e32 v119, v118
	v_fmac_f32_e32 v0, 0xcf800000, v119
	v_cvt_u32_f32_e32 v118, v0
	v_cvt_u32_f32_e32 v119, v119
	global_atomic_add_x2 v[134:135], v[118:119], off offset:128
.LBB0_1091:
	s_or_b64 exec, exec, s[2:3]
	v_ffbh_u32_e32 v0, v215
	v_min_u32_e32 v0, 32, v0
	s_waitcnt lgkmcnt(0)
	v_lshlrev_b64 v[118:119], v0, v[214:215]
	v_min_u32_e32 v118, 1, v118
	v_or_b32_e32 v118, v119, v118
	v_cvt_f32_u32_e32 v118, v118
	v_sub_u32_e32 v0, 32, v0
	v_ldexp_f32 v0, v118, v0
	v_mul_f32_e32 v0, 0x33800000, v0
	v_fmamk_f32 v0, v0, 0x3b800000, v226
	v_cmp_gt_f32_e32 vcc, s71, v0
	v_mul_f32_e32 v118, 0x4f800000, v0
	s_nop 0
	v_cndmask_b32_e32 v0, v0, v118, vcc
	v_sqrt_f32_e32 v118, v0
	s_nop 0
	v_add_u32_e32 v119, -1, v118
	v_fma_f32 v120, -v119, v118, v0
	v_cmp_ge_f32_e64 s[10:11], 0, v120
	v_add_u32_e32 v120, 1, v118
	s_nop 0
	v_cndmask_b32_e64 v119, v118, v119, s[10:11]
	v_fma_f32 v118, -v120, v118, v0
	v_cmp_lt_f32_e64 s[10:11], 0, v118
	s_nop 1
	v_cndmask_b32_e64 v118, v119, v120, s[10:11]
	v_mul_f32_e32 v119, 0x37800000, v118
	v_cndmask_b32_e32 v118, v118, v119, vcc
	v_cmp_class_f32_e32 vcc, v0, v223
	s_nop 1
	v_cndmask_b32_e32 v0, v118, v0, vcc
	v_div_scale_f32 v118, s[2:3], v0, v0, 1.0
	v_rcp_f32_e32 v119, v118
	s_mov_b32 s2, 0x10000
	v_add3_u32 v137, v230, v136, s2
	v_add_u32_e32 v241, s2, v240
	v_fma_f32 v120, -v118, v119, 1.0
	v_fmac_f32_e32 v119, v120, v119
	v_div_scale_f32 v120, vcc, 1.0, v0, 1.0
	v_mul_f32_e32 v121, v120, v119
	v_fma_f32 v122, -v118, v121, v120
	v_fmac_f32_e32 v121, v122, v119
	v_fma_f32 v118, -v118, v121, v120
	v_div_fmas_f32 v118, v118, v119, v121
	v_div_fixup_f32 v0, v118, v0, 1.0
	v_add_u32_e32 v118, 0x10000, v240
	global_load_dwordx4 v[130:133], v118, s[22:23]
	global_load_dwordx4 v[126:129], v118, s[22:23] offset:1024
	v_add_u32_e32 v118, 0x18000, v240
	global_load_dwordx4 v[122:125], v118, s[22:23]
	s_nop 0
	global_load_dwordx4 v[118:121], v118, s[22:23] offset:1024
	v_pk_mul_f32 v[114:115], v[114:115], v[0:1] op_sel_hi:[1,0]
	v_pk_mul_f32 v[116:117], v[116:117], v[0:1] op_sel_hi:[1,0]
	v_pk_mul_f32 v[110:111], v[110:111], v[0:1] op_sel_hi:[1,0]
	v_pk_mul_f32 v[112:113], v[112:113], v[0:1] op_sel_hi:[1,0]
	v_pk_mul_f32 v[106:107], v[106:107], v[0:1] op_sel_hi:[1,0]
	v_pk_mul_f32 v[108:109], v[108:109], v[0:1] op_sel_hi:[1,0]
	v_pk_mul_f32 v[102:103], v[102:103], v[0:1] op_sel_hi:[1,0]
	v_pk_mul_f32 v[104:105], v[104:105], v[0:1] op_sel_hi:[1,0]
	s_waitcnt vmcnt(0)
; __device__ __forceinline__ unsigned cvt_pk_bf16(float lo, float hi) { unsigned r; asm volatile("v_cvt_pk_bf16_f32 %0, %1, %2" : "=v"(r) : "v"(lo), "v"(hi)); return r; }
; #define PG8_GPTR(p) ((__attribute__((address_space(1))) char*)(p))
;     __device__ __forceinline__ void operator()(const f32x4 (&acc)[2][2][4][2], const Unit& u, int wr, int wc, int fr, int fq) const {
;     ...
;             for (int mm = 0; mm < 2; ++mm) {
;                 const int m = mp + mm;
;                 const int row = u.pm * BM + ai * HALF + wr * 64 + m * 16 + fr; float q = 0.f;
; #pragma unroll
;                 for (int bj = 0; bj < 2; ++bj) {
;                     const unsigned offb = (unsigned)(row * DM + col0 + bj * HALF) * 2u;
;                     const u32x4 bw = bv[mm][bj];
;                     const f32x4 b0 = (f32x4){__uint_as_float(bw.x << 16), __uint_as_float(bw.x & 0xffff0000u), __uint_as_float(bw.y << 16), __uint_as_float(bw.y & 0xffff0000u)};
;                     const f32x4 b1 = (f32x4){__uint_as_float(bw.z << 16), __uint_as_float(bw.z & 0xffff0000u), __uint_as_float(bw.w << 16), __uint_as_float(bw.w & 0xffff0000u)};
;                     f32x4 a0 = acc[ai][bj][m][0], a1 = acc[ai][bj][m][1]; if constexpr (GN) { a0 *= rc[ai * 4 + m]; a1 *= rc[ai * 4 + m]; }
;                     const f32x4 o0 = b0 + g[bj][0] * a0, o1 = b1 + g[bj][1] * a1;
;                     u32x4 wo; wo.x = cvt_pk_bf16(o0[0], o0[1]); wo.y = cvt_pk_bf16(o0[2], o0[3]); wo.z = cvt_pk_bf16(o1[0], o1[1]); wo.w = cvt_pk_bf16(o1[2], o1[3]);
;                     *(gs_u32x4*)(PG8_GPTR(out) + offb) = wo;
;                     if (xg) {
;                         const f32x4 h0 = o0 * cf[bj][0], h1 = o1 * cf[bj][1];
;                         u32x4 w; w.x = cvt_pk_bf16(h0[0], h0[1]); w.y = cvt_pk_bf16(h0[2], h0[3]); w.z = cvt_pk_bf16(h1[0], h1[1]); w.w = cvt_pk_bf16(h1[2], h1[3]);
;                         *(gs_u32x4*)(PG8_GPTR(xg) + offb) = w;
;                         q += (o0[0] * o0[0] + o0[1] * o0[1]) + (o0[2] * o0[2] + o0[3] * o0[3]) + (o1[0] * o1[0] + o1[1] * o1[1]) + (o1[2] * o1[2] + o1[3] * o1[3]);
;                     }
;                 }
;                 if (xg) ssq_put(ssq, row, q, fr, fq);
	v_lshlrev_b32_e32 v138, 16, v130
	v_and_b32_e32 v139, 0xffff0000, v130
	v_lshlrev_b32_e32 v130, 16, v131
	v_and_b32_e32 v131, 0xffff0000, v131
	v_lshlrev_b32_e32 v140, 16, v132
	v_and_b32_e32 v141, 0xffff0000, v132
	v_lshlrev_b32_e32 v132, 16, v133
	v_and_b32_e32 v133, 0xffff0000, v133
	v_pk_fma_f32 v[116:117], v[84:85], v[116:117], v[130:131]
	v_pk_fma_f32 v[114:115], v[82:83], v[114:115], v[138:139]
	v_pk_fma_f32 v[130:131], v[80:81], v[112:113], v[132:133]
	v_pk_fma_f32 v[132:133], v[78:79], v[110:111], v[140:141]
	v_cvt_pk_bf16_f32 v110, v114, v115
	v_cvt_pk_bf16_f32 v111, v116, v117
	v_pk_mul_f32 v[138:139], v[198:199], v[130:131]
	v_cvt_pk_bf16_f32 v112, v132, v133
	v_cvt_pk_bf16_f32 v113, v130, v131
	global_store_dwordx4 v241, v[110:113], s[24:25]
	v_pk_mul_f32 v[140:141], v[202:203], v[132:133]
	s_nop 0
	v_pk_mul_f32 v[110:111], v[204:205], v[114:115]
	v_pk_mul_f32 v[112:113], v[200:201], v[116:117]
	v_cvt_pk_bf16_f32 v110, v110, v111
	s_nop 0
	v_cvt_pk_bf16_f32 v111, v112, v113
	v_cvt_pk_bf16_f32 v112, v140, v141
	v_cvt_pk_bf16_f32 v113, v138, v139
	global_store_dwordx4 v137, v[110:113], s[26:27]
	s_nop 1
	v_mul_f32_e32 v110, v115, v115
	v_mul_f32_e32 v111, v117, v117
	v_fmac_f32_e32 v110, v114, v114
	v_fmac_f32_e32 v111, v116, v116
	v_add_f32_e32 v110, v110, v111
	v_mul_f32_e32 v111, v133, v133
	v_fmac_f32_e32 v111, v132, v132
	v_add_f32_e32 v110, v111, v110
	v_mul_f32_e32 v111, v131, v131
	v_fmac_f32_e32 v111, v130, v130
	v_add_f32_e32 v130, v111, v110
	v_lshlrev_b32_e32 v110, 16, v126
	v_and_b32_e32 v111, 0xffff0000, v126
	v_lshlrev_b32_e32 v112, 16, v127
	v_and_b32_e32 v113, 0xffff0000, v127
	v_lshlrev_b32_e32 v114, 16, v128
	v_and_b32_e32 v115, 0xffff0000, v128
	v_lshlrev_b32_e32 v116, 16, v129
	v_and_b32_e32 v117, 0xffff0000, v129
	v_pk_fma_f32 v[108:109], v[108:109], v[76:77], v[112:113]
	v_pk_fma_f32 v[106:107], v[106:107], v[74:75], v[110:111]
	v_pk_fma_f32 v[110:111], v[104:105], v[72:73], v[116:117]
	v_pk_fma_f32 v[112:113], v[102:103], v[70:71], v[114:115]
	v_cvt_pk_bf16_f32 v102, v106, v107
	v_cvt_pk_bf16_f32 v103, v108, v109
	v_pk_mul_f32 v[114:115], v[176:177], v[110:111]
	v_cvt_pk_bf16_f32 v104, v112, v113
	v_cvt_pk_bf16_f32 v105, v110, v111
	global_store_dwordx4 v241, v[102:105], s[24:25] offset:1024
	v_pk_mul_f32 v[116:117], v[194:195], v[112:113]
	v_mul_f32_e32 v0, v111, v111
	v_pk_mul_f32 v[104:105], v[196:197], v[108:109]
	v_pk_mul_f32 v[102:103], v[174:175], v[106:107]
	v_fmac_f32_e32 v0, v110, v110
	v_cvt_pk_bf16_f32 v102, v102, v103
	v_cvt_pk_bf16_f32 v103, v104, v105
	v_cvt_pk_bf16_f32 v104, v116, v117
	v_cvt_pk_bf16_f32 v105, v114, v115
	global_store_dwordx4 v137, v[102:105], s[26:27] offset:256
	s_nop 1
	v_mul_f32_e32 v103, v107, v107
	v_mul_f32_e32 v104, v109, v109
	v_mul_f32_e32 v102, v113, v113
	v_fmac_f32_e32 v103, v106, v106
	v_fmac_f32_e32 v104, v108, v108
	v_fmac_f32_e32 v102, v112, v112
	v_add_f32_e32 v103, v103, v104
	v_add_f32_e32 v102, v102, v103
	v_add_f32_e32 v0, v0, v102
	v_add_f32_e32 v0, v130, v0
	ds_bpermute_b32 v102, v229, v0
	s_waitcnt lgkmcnt(0)
	v_add_f32_e32 v0, v0, v102
	ds_bpermute_b32 v102, v228, v0
	s_and_saveexec_b64 s[2:3], s[8:9]
	s_cbranch_execz .LBB0_1093
	s_waitcnt lgkmcnt(0)
	v_add_f32_e32 v0, v0, v102
	v_mul_f32_e32 v0, 0x4b800000, v0
	v_trunc_f32_e32 v0, v0
	v_mul_f32_e32 v102, 0x2f800000, v0
	v_floor_f32_e32 v103, v102
	v_fmac_f32_e32 v0, 0xcf800000, v103
	v_cvt_u32_f32_e32 v102, v0
	v_cvt_u32_f32_e32 v103, v103
	global_atomic_add_x2 v[134:135], v[102:103], off offset:256
.LBB0_1093:
	s_or_b64 exec, exec, s[2:3]
	v_ffbh_u32_e32 v0, v213
	v_min_u32_e32 v0, 32, v0
	s_waitcnt lgkmcnt(0)
	v_lshlrev_b64 v[102:103], v0, v[212:213]
	v_min_u32_e32 v102, 1, v102
	v_or_b32_e32 v102, v103, v102
	v_cvt_f32_u32_e32 v102, v102
	v_sub_u32_e32 v0, 32, v0
	v_and_b32_e32 v107, 0xffff0000, v124
	v_lshlrev_b32_e32 v108, 16, v125
	v_ldexp_f32 v0, v102, v0
	v_mul_f32_e32 v0, 0x33800000, v0
	v_fmamk_f32 v0, v0, 0x3b800000, v226
	v_mul_f32_e32 v102, 0x4f800000, v0
	v_cmp_gt_f32_e32 vcc, s71, v0
	v_and_b32_e32 v109, 0xffff0000, v125
	s_nop 0
	v_cndmask_b32_e32 v0, v0, v102, vcc
	v_sqrt_f32_e32 v102, v0
	s_nop 0
	v_add_u32_e32 v103, -1, v102
	v_add_u32_e32 v104, 1, v102
	v_fma_f32 v105, -v103, v102, v0
	v_fma_f32 v106, -v104, v102, v0
	v_cmp_ge_f32_e64 s[10:11], 0, v105
	s_nop 1
	v_cndmask_b32_e64 v102, v102, v103, s[10:11]
	v_cmp_lt_f32_e64 s[10:11], 0, v106
	s_nop 1
	v_cndmask_b32_e64 v102, v102, v104, s[10:11]
	v_mul_f32_e32 v103, 0x37800000, v102
	v_cndmask_b32_e32 v102, v102, v103, vcc
	v_cmp_class_f32_e32 vcc, v0, v223
	s_nop 1
	v_cndmask_b32_e32 v0, v102, v0, vcc
	v_div_scale_f32 v102, s[2:3], v0, v0, 1.0
	v_rcp_f32_e32 v103, v102
	s_mov_b32 s2, 0x18000
	v_add3_u32 v110, v230, v136, s2
	v_add_u32_e32 v241, s2, v240
	v_fma_f32 v104, -v102, v103, 1.0
	v_fmac_f32_e32 v103, v104, v103
	v_div_scale_f32 v104, vcc, 1.0, v0, 1.0
	v_mul_f32_e32 v105, v104, v103
	v_fma_f32 v106, -v102, v105, v104
	v_fmac_f32_e32 v105, v106, v103
	v_fma_f32 v102, -v102, v105, v104
	v_div_fmas_f32 v102, v102, v103, v105
	v_div_fixup_f32 v0, v102, v0, 1.0
	v_lshlrev_b32_e32 v102, 16, v122
	v_and_b32_e32 v103, 0xffff0000, v122
	v_lshlrev_b32_e32 v104, 16, v123
	v_and_b32_e32 v105, 0xffff0000, v123
	v_lshlrev_b32_e32 v106, 16, v124
	v_pk_mul_f32 v[98:99], v[98:99], v[0:1] op_sel_hi:[1,0]
	v_pk_mul_f32 v[100:101], v[100:101], v[0:1] op_sel_hi:[1,0]
	v_pk_mul_f32 v[94:95], v[94:95], v[0:1] op_sel_hi:[1,0]
	v_pk_mul_f32 v[96:97], v[96:97], v[0:1] op_sel_hi:[1,0]
	v_pk_fma_f32 v[100:101], v[84:85], v[100:101], v[104:105]
	v_pk_fma_f32 v[98:99], v[82:83], v[98:99], v[102:103]
	v_pk_fma_f32 v[104:105], v[78:79], v[94:95], v[106:107]
; __device__ __forceinline__ unsigned cvt_pk_bf16(float lo, float hi) { unsigned r; asm volatile("v_cvt_pk_bf16_f32 %0, %1, %2" : "=v"(r) : "v"(lo), "v"(hi)); return r; }
; #define PG8_GPTR(p) ((__attribute__((address_space(1))) char*)(p))
;     __device__ __forceinline__ void operator()(const f32x4 (&acc)[2][2][4][2], const Unit& u, int wr, int wc, int fr, int fq) const {
;     ...
;             for (int mm = 0; mm < 2; ++mm) {
;                 const int m = mp + mm;
;                 const int row = u.pm * BM + ai * HALF + wr * 64 + m * 16 + fr; float q = 0.f;
; #pragma unroll
;                 for (int bj = 0; bj < 2; ++bj) {
;                     const unsigned offb = (unsigned)(row * DM + col0 + bj * HALF) * 2u;
;                     const u32x4 bw = bv[mm][bj];
;                     const f32x4 b0 = (f32x4){__uint_as_float(bw.x << 16), __uint_as_float(bw.x & 0xffff0000u), __uint_as_float(bw.y << 16), __uint_as_float(bw.y & 0xffff0000u)};
;                     const f32x4 b1 = (f32x4){__uint_as_float(bw.z << 16), __uint_as_float(bw.z & 0xffff0000u), __uint_as_float(bw.w << 16), __uint_as_float(bw.w & 0xffff0000u)};
;                     f32x4 a0 = acc[ai][bj][m][0], a1 = acc[ai][bj][m][1]; if constexpr (GN) { a0 *= rc[ai * 4 + m]; a1 *= rc[ai * 4 + m]; }
;                     const f32x4 o0 = b0 + g[bj][0] * a0, o1 = b1 + g[bj][1] * a1;
;                     u32x4 wo; wo.x = cvt_pk_bf16(o0[0], o0[1]); wo.y = cvt_pk_bf16(o0[2], o0[3]); wo.z = cvt_pk_bf16(o1[0], o1[1]); wo.w = cvt_pk_bf16(o1[2], o1[3]);
;                     *(gs_u32x4*)(PG8_GPTR(out) + offb) = wo;
;                     if (xg) {
;                         const f32x4 h0 = o0 * cf[bj][0], h1 = o1 * cf[bj][1];
;                         u32x4 w; w.x = cvt_pk_bf16(h0[0], h0[1]); w.y = cvt_pk_bf16(h0[2], h0[3]); w.z = cvt_pk_bf16(h1[0], h1[1]); w.w = cvt_pk_bf16(h1[2], h1[3]);
;                         *(gs_u32x4*)(PG8_GPTR(xg) + offb) = w;
;                         q += (o0[0] * o0[0] + o0[1] * o0[1]) + (o0[2] * o0[2] + o0[3] * o0[3]) + (o1[0] * o1[0] + o1[1] * o1[1]) + (o1[2] * o1[2] + o1[3] * o1[3]);
;                     }
;                 }
;                 if (xg) ssq_put(ssq, row, q, fr, fq);
	v_cvt_pk_bf16_f32 v94, v98, v99
	v_cvt_pk_bf16_f32 v95, v100, v101
	v_pk_fma_f32 v[102:103], v[80:81], v[96:97], v[108:109]
	v_cvt_pk_bf16_f32 v96, v104, v105
	v_pk_mul_f32 v[108:109], v[202:203], v[104:105]
	v_cvt_pk_bf16_f32 v97, v102, v103
	global_store_dwordx4 v241, v[94:97], s[24:25]
	v_pk_mul_f32 v[106:107], v[198:199], v[102:103]
	v_pk_mul_f32 v[90:91], v[90:91], v[0:1] op_sel_hi:[1,0]
	v_pk_mul_f32 v[94:95], v[204:205], v[98:99]
	v_pk_mul_f32 v[96:97], v[200:201], v[100:101]
	v_cvt_pk_bf16_f32 v94, v94, v95
	v_pk_mul_f32 v[92:93], v[92:93], v[0:1] op_sel_hi:[1,0]
	v_cvt_pk_bf16_f32 v95, v96, v97
	v_cvt_pk_bf16_f32 v96, v108, v109
	v_cvt_pk_bf16_f32 v97, v106, v107
	global_store_dwordx4 v110, v[94:97], s[26:27]
	v_pk_mul_f32 v[86:87], v[86:87], v[0:1] op_sel_hi:[1,0]
	v_pk_mul_f32 v[88:89], v[88:89], v[0:1] op_sel_hi:[1,0]
	v_mul_f32_e32 v94, v99, v99
	v_mul_f32_e32 v95, v101, v101
	v_fmac_f32_e32 v94, v98, v98
	v_fmac_f32_e32 v95, v100, v100
	v_add_f32_e32 v94, v94, v95
	v_mul_f32_e32 v95, v105, v105
	v_fmac_f32_e32 v95, v104, v104
	v_add_f32_e32 v94, v95, v94
	v_mul_f32_e32 v95, v103, v103
	v_fmac_f32_e32 v95, v102, v102
	v_add_f32_e32 v102, v95, v94
	v_lshlrev_b32_e32 v94, 16, v118
	v_and_b32_e32 v95, 0xffff0000, v118
	v_lshlrev_b32_e32 v96, 16, v119
	v_and_b32_e32 v97, 0xffff0000, v119
	v_lshlrev_b32_e32 v98, 16, v120
	v_and_b32_e32 v99, 0xffff0000, v120
	v_lshlrev_b32_e32 v100, 16, v121
	v_and_b32_e32 v101, 0xffff0000, v121
	v_pk_fma_f32 v[92:93], v[92:93], v[76:77], v[96:97]
	v_pk_fma_f32 v[90:91], v[90:91], v[74:75], v[94:95]
	v_pk_fma_f32 v[94:95], v[88:89], v[72:73], v[100:101]
	v_pk_fma_f32 v[96:97], v[86:87], v[70:71], v[98:99]
	v_cvt_pk_bf16_f32 v86, v90, v91
	v_cvt_pk_bf16_f32 v87, v92, v93
	v_mul_f32_e32 v0, v95, v95
	v_cvt_pk_bf16_f32 v88, v96, v97
	v_cvt_pk_bf16_f32 v89, v94, v95
	global_store_dwordx4 v241, v[86:89], s[24:25] offset:1024
	v_fmac_f32_e32 v0, v94, v94
	v_pk_mul_f32 v[98:99], v[196:197], v[92:93]
	v_mul_f32_e32 v87, v91, v91
	v_mul_f32_e32 v88, v93, v93
	v_mul_f32_e32 v86, v97, v97
	v_fmac_f32_e32 v87, v90, v90
	v_fmac_f32_e32 v88, v92, v92
	v_fmac_f32_e32 v86, v96, v96
	v_add_f32_e32 v87, v87, v88
	v_add_f32_e32 v86, v86, v87
	v_add_f32_e32 v0, v0, v86
	v_add_f32_e32 v0, v102, v0
	ds_bpermute_b32 v89, v229, v0
	v_pk_mul_f32 v[86:87], v[174:175], v[90:91]
	v_pk_mul_f32 v[90:91], v[194:195], v[96:97]
	v_cvt_pk_bf16_f32 v88, v86, v87
	v_pk_mul_f32 v[92:93], v[176:177], v[94:95]
	s_waitcnt lgkmcnt(0)
	v_add_f32_e32 v0, v0, v89
	ds_bpermute_b32 v86, v228, v0
	v_cvt_pk_bf16_f32 v89, v98, v99
	v_cvt_pk_bf16_f32 v90, v90, v91
	v_cvt_pk_bf16_f32 v91, v92, v93
	global_store_dwordx4 v110, v[88:91], s[26:27] offset:256
	s_and_saveexec_b64 s[2:3], s[8:9]
	s_cbranch_execz .LBB0_1095
	s_waitcnt lgkmcnt(0)
	v_add_f32_e32 v0, v0, v86
	v_mul_f32_e32 v0, 0x4b800000, v0
	v_trunc_f32_e32 v0, v0
	v_mul_f32_e32 v86, 0x2f800000, v0
	v_floor_f32_e32 v87, v86
	v_fmac_f32_e32 v0, 0xcf800000, v87
	v_cvt_u32_f32_e32 v86, v0
	v_cvt_u32_f32_e32 v87, v87
	global_atomic_add_x2 v[134:135], v[86:87], off offset:384
.LBB0_1095:
	s_or_b64 exec, exec, s[2:3]
	v_ffbh_u32_e32 v0, v211
	v_min_u32_e32 v0, 32, v0
	s_waitcnt lgkmcnt(0)
	v_lshlrev_b64 v[86:87], v0, v[210:211]
	v_min_u32_e32 v86, 1, v86
	v_or_b32_e32 v86, v87, v86
	v_cvt_f32_u32_e32 v86, v86
	v_sub_u32_e32 v0, 32, v0
	v_ldexp_f32 v0, v86, v0
	v_mul_f32_e32 v0, 0x33800000, v0
	v_fmamk_f32 v0, v0, 0x3b800000, v226
	v_cmp_gt_f32_e32 vcc, s71, v0
	v_mul_f32_e32 v86, 0x4f800000, v0
	s_nop 0
	v_cndmask_b32_e32 v0, v0, v86, vcc
	v_sqrt_f32_e32 v86, v0
	s_nop 0
	v_add_u32_e32 v87, -1, v86
	v_fma_f32 v88, -v87, v86, v0
	v_cmp_ge_f32_e64 s[10:11], 0, v88
	v_add_u32_e32 v88, 1, v86
	s_nop 0
	v_cndmask_b32_e64 v87, v86, v87, s[10:11]
	v_fma_f32 v86, -v88, v86, v0
	v_cmp_lt_f32_e64 s[10:11], 0, v86
	s_nop 1
	v_cndmask_b32_e64 v86, v87, v88, s[10:11]
	v_mul_f32_e32 v87, 0x37800000, v86
	v_cndmask_b32_e32 v86, v86, v87, vcc
	v_cmp_class_f32_e32 vcc, v0, v223
	s_nop 1
	v_cndmask_b32_e32 v0, v86, v0, vcc
	v_div_scale_f32 v86, s[2:3], v0, v0, 1.0
	v_rcp_f32_e32 v87, v86
	s_mov_b32 s2, 0x40000
	v_add3_u32 v106, v232, v230, s2
	v_add_u32_e32 v241, s2, v240
	v_fma_f32 v88, -v86, v87, 1.0
	v_fmac_f32_e32 v87, v88, v87
	v_div_scale_f32 v88, vcc, 1.0, v0, 1.0
	v_mul_f32_e32 v89, v88, v87
	v_fma_f32 v90, -v86, v89, v88
	v_fmac_f32_e32 v89, v90, v87
	v_fma_f32 v86, -v86, v89, v88
	v_div_fmas_f32 v86, v86, v87, v89
	v_div_fixup_f32 v0, v86, v0, 1.0
	v_add_u32_e32 v86, 0x40000, v240
	global_load_dwordx4 v[98:101], v86, s[22:23]
	global_load_dwordx4 v[94:97], v86, s[22:23] offset:1024
	v_add_u32_e32 v86, 0x48000, v240
	global_load_dwordx4 v[90:93], v86, s[22:23]
	s_nop 0
	global_load_dwordx4 v[86:89], v86, s[22:23] offset:1024
	v_pk_mul_f32 v[66:67], v[66:67], v[0:1] op_sel_hi:[1,0]
	v_pk_mul_f32 v[68:69], v[68:69], v[0:1] op_sel_hi:[1,0]
	v_pk_mul_f32 v[62:63], v[62:63], v[0:1] op_sel_hi:[1,0]
	v_pk_mul_f32 v[64:65], v[64:65], v[0:1] op_sel_hi:[1,0]
	v_pk_mul_f32 v[58:59], v[58:59], v[0:1] op_sel_hi:[1,0]
	v_pk_mul_f32 v[60:61], v[60:61], v[0:1] op_sel_hi:[1,0]
	v_pk_mul_f32 v[54:55], v[54:55], v[0:1] op_sel_hi:[1,0]
	v_pk_mul_f32 v[56:57], v[56:57], v[0:1] op_sel_hi:[1,0]
	s_waitcnt vmcnt(0)
; __device__ __forceinline__ unsigned cvt_pk_bf16(float lo, float hi) { unsigned r; asm volatile("v_cvt_pk_bf16_f32 %0, %1, %2" : "=v"(r) : "v"(lo), "v"(hi)); return r; }
; #define PG8_GPTR(p) ((__attribute__((address_space(1))) char*)(p))
;     __device__ __forceinline__ void operator()(const f32x4 (&acc)[2][2][4][2], const Unit& u, int wr, int wc, int fr, int fq) const {
;     ...
;             for (int mm = 0; mm < 2; ++mm) {
;                 const int m = mp + mm;
;                 const int row = u.pm * BM + ai * HALF + wr * 64 + m * 16 + fr; float q = 0.f;
; #pragma unroll
;                 for (int bj = 0; bj < 2; ++bj) {
;                     const unsigned offb = (unsigned)(row * DM + col0 + bj * HALF) * 2u;
;                     const u32x4 bw = bv[mm][bj];
;                     const f32x4 b0 = (f32x4){__uint_as_float(bw.x << 16), __uint_as_float(bw.x & 0xffff0000u), __uint_as_float(bw.y << 16), __uint_as_float(bw.y & 0xffff0000u)};
;                     const f32x4 b1 = (f32x4){__uint_as_float(bw.z << 16), __uint_as_float(bw.z & 0xffff0000u), __uint_as_float(bw.w << 16), __uint_as_float(bw.w & 0xffff0000u)};
;                     f32x4 a0 = acc[ai][bj][m][0], a1 = acc[ai][bj][m][1]; if constexpr (GN) { a0 *= rc[ai * 4 + m]; a1 *= rc[ai * 4 + m]; }
;                     const f32x4 o0 = b0 + g[bj][0] * a0, o1 = b1 + g[bj][1] * a1;
;                     u32x4 wo; wo.x = cvt_pk_bf16(o0[0], o0[1]); wo.y = cvt_pk_bf16(o0[2], o0[3]); wo.z = cvt_pk_bf16(o1[0], o1[1]); wo.w = cvt_pk_bf16(o1[2], o1[3]);
;                     *(gs_u32x4*)(PG8_GPTR(out) + offb) = wo;
;                     if (xg) {
;                         const f32x4 h0 = o0 * cf[bj][0], h1 = o1 * cf[bj][1];
;                         u32x4 w; w.x = cvt_pk_bf16(h0[0], h0[1]); w.y = cvt_pk_bf16(h0[2], h0[3]); w.z = cvt_pk_bf16(h1[0], h1[1]); w.w = cvt_pk_bf16(h1[2], h1[3]);
;                         *(gs_u32x4*)(PG8_GPTR(xg) + offb) = w;
;                         q += (o0[0] * o0[0] + o0[1] * o0[1]) + (o0[2] * o0[2] + o0[3] * o0[3]) + (o1[0] * o1[0] + o1[1] * o1[1]) + (o1[2] * o1[2] + o1[3] * o1[3]);
;                     }
;                 }
;                 if (xg) ssq_put(ssq, row, q, fr, fq);
	v_lshlrev_b32_e32 v102, 16, v98
	v_and_b32_e32 v103, 0xffff0000, v98
	v_lshlrev_b32_e32 v98, 16, v99
	v_and_b32_e32 v99, 0xffff0000, v99
	v_lshlrev_b32_e32 v104, 16, v100
	v_and_b32_e32 v105, 0xffff0000, v100
	v_lshlrev_b32_e32 v100, 16, v101
	v_and_b32_e32 v101, 0xffff0000, v101
	v_pk_fma_f32 v[68:69], v[84:85], v[68:69], v[98:99]
	v_pk_fma_f32 v[66:67], v[82:83], v[66:67], v[102:103]
	v_pk_fma_f32 v[98:99], v[80:81], v[64:65], v[100:101]
	v_pk_fma_f32 v[100:101], v[78:79], v[62:63], v[104:105]
	v_cvt_pk_bf16_f32 v62, v66, v67
	v_cvt_pk_bf16_f32 v63, v68, v69
	v_pk_mul_f32 v[102:103], v[198:199], v[98:99]
	v_cvt_pk_bf16_f32 v64, v100, v101
	v_cvt_pk_bf16_f32 v65, v98, v99
	global_store_dwordx4 v241, v[62:65], s[24:25]
	v_pk_mul_f32 v[104:105], v[202:203], v[100:101]
	s_nop 0
	v_pk_mul_f32 v[62:63], v[204:205], v[66:67]
	v_pk_mul_f32 v[64:65], v[200:201], v[68:69]
	v_cvt_pk_bf16_f32 v62, v62, v63
	s_nop 0
	v_cvt_pk_bf16_f32 v63, v64, v65
	v_cvt_pk_bf16_f32 v64, v104, v105
	v_cvt_pk_bf16_f32 v65, v102, v103
	global_store_dwordx4 v106, v[62:65], s[26:27]
	s_nop 1
	v_mul_f32_e32 v62, v67, v67
	v_mul_f32_e32 v63, v69, v69
	v_fmac_f32_e32 v62, v66, v66
	v_fmac_f32_e32 v63, v68, v68
	v_add_f32_e32 v62, v62, v63
	v_mul_f32_e32 v63, v101, v101
	v_fmac_f32_e32 v63, v100, v100
	v_add_f32_e32 v62, v63, v62
	v_mul_f32_e32 v63, v99, v99
	v_fmac_f32_e32 v63, v98, v98
	v_add_f32_e32 v98, v63, v62
	v_lshlrev_b32_e32 v62, 16, v94
	v_and_b32_e32 v63, 0xffff0000, v94
	v_lshlrev_b32_e32 v64, 16, v95
	v_and_b32_e32 v65, 0xffff0000, v95
	v_lshlrev_b32_e32 v66, 16, v96
	v_and_b32_e32 v67, 0xffff0000, v96
	v_lshlrev_b32_e32 v68, 16, v97
	v_and_b32_e32 v69, 0xffff0000, v97
	v_pk_fma_f32 v[60:61], v[60:61], v[76:77], v[64:65]
	v_pk_fma_f32 v[58:59], v[58:59], v[74:75], v[62:63]
	v_pk_fma_f32 v[62:63], v[56:57], v[72:73], v[68:69]
	v_pk_fma_f32 v[64:65], v[54:55], v[70:71], v[66:67]
	v_cvt_pk_bf16_f32 v54, v58, v59
	v_cvt_pk_bf16_f32 v55, v60, v61
	v_pk_mul_f32 v[66:67], v[176:177], v[62:63]
	v_cvt_pk_bf16_f32 v56, v64, v65
	v_cvt_pk_bf16_f32 v57, v62, v63
	global_store_dwordx4 v241, v[54:57], s[24:25] offset:1024
	v_pk_mul_f32 v[68:69], v[194:195], v[64:65]
	v_mul_f32_e32 v0, v63, v63
	v_pk_mul_f32 v[56:57], v[196:197], v[60:61]
	v_pk_mul_f32 v[54:55], v[174:175], v[58:59]
	v_fmac_f32_e32 v0, v62, v62
	v_cvt_pk_bf16_f32 v54, v54, v55
	v_cvt_pk_bf16_f32 v55, v56, v57
	v_cvt_pk_bf16_f32 v56, v68, v69
	v_cvt_pk_bf16_f32 v57, v66, v67
	global_store_dwordx4 v106, v[54:57], s[26:27] offset:256
	s_nop 1
	v_mul_f32_e32 v55, v59, v59
	v_mul_f32_e32 v56, v61, v61
	v_mul_f32_e32 v54, v65, v65
	v_fmac_f32_e32 v55, v58, v58
	v_fmac_f32_e32 v56, v60, v60
	v_fmac_f32_e32 v54, v64, v64
	v_add_f32_e32 v55, v55, v56
	v_add_f32_e32 v54, v54, v55
	v_add_f32_e32 v0, v0, v54
	v_add_f32_e32 v0, v98, v0
	ds_bpermute_b32 v54, v229, v0
	s_waitcnt lgkmcnt(0)
	v_add_f32_e32 v0, v0, v54
	ds_bpermute_b32 v54, v228, v0
	s_and_saveexec_b64 s[2:3], s[8:9]
	s_cbranch_execz .LBB0_1097
	s_waitcnt lgkmcnt(0)
	v_add_f32_e32 v0, v0, v54
	v_mul_f32_e32 v0, 0x4b800000, v0
	v_trunc_f32_e32 v0, v0
	v_mul_f32_e32 v54, 0x2f800000, v0
	v_floor_f32_e32 v55, v54
	v_fmac_f32_e32 v0, 0xcf800000, v55
	v_cvt_u32_f32_e32 v54, v0
	v_cvt_u32_f32_e32 v55, v55
	global_atomic_add_x2 v[134:135], v[54:55], off offset:1024
.LBB0_1097:
	s_or_b64 exec, exec, s[2:3]
	v_ffbh_u32_e32 v0, v209
	v_min_u32_e32 v0, 32, v0
	s_waitcnt lgkmcnt(0)
	v_lshlrev_b64 v[54:55], v0, v[208:209]
	v_min_u32_e32 v54, 1, v54
	v_or_b32_e32 v54, v55, v54
	v_cvt_f32_u32_e32 v54, v54
	v_sub_u32_e32 v0, 32, v0
	v_and_b32_e32 v59, 0xffff0000, v92
	v_lshlrev_b32_e32 v60, 16, v93
	v_ldexp_f32 v0, v54, v0
	v_mul_f32_e32 v0, 0x33800000, v0
	v_fmamk_f32 v0, v0, 0x3b800000, v226
	v_mul_f32_e32 v54, 0x4f800000, v0
	v_cmp_gt_f32_e32 vcc, s71, v0
	v_and_b32_e32 v61, 0xffff0000, v93
	s_nop 0
	v_cndmask_b32_e32 v0, v0, v54, vcc
	v_sqrt_f32_e32 v54, v0
	s_nop 0
	v_add_u32_e32 v55, -1, v54
	v_add_u32_e32 v56, 1, v54
	v_fma_f32 v57, -v55, v54, v0
	v_fma_f32 v58, -v56, v54, v0
	v_cmp_ge_f32_e64 s[10:11], 0, v57
	s_nop 1
	v_cndmask_b32_e64 v54, v54, v55, s[10:11]
	v_cmp_lt_f32_e64 s[10:11], 0, v58
	s_nop 1
	v_cndmask_b32_e64 v54, v54, v56, s[10:11]
	v_mul_f32_e32 v55, 0x37800000, v54
	v_cndmask_b32_e32 v54, v54, v55, vcc
	v_cmp_class_f32_e32 vcc, v0, v223
	s_nop 1
	v_cndmask_b32_e32 v0, v54, v0, vcc
	v_div_scale_f32 v54, s[2:3], v0, v0, 1.0
	v_rcp_f32_e32 v55, v54
	s_mov_b32 s2, 0x48000
	v_add3_u32 v62, v136, v230, s2
	v_add_u32_e32 v241, s2, v240
	v_fma_f32 v56, -v54, v55, 1.0
	v_fmac_f32_e32 v55, v56, v55
	v_div_scale_f32 v56, vcc, 1.0, v0, 1.0
	v_mul_f32_e32 v57, v56, v55
	v_fma_f32 v58, -v54, v57, v56
	v_fmac_f32_e32 v57, v58, v55
	v_fma_f32 v54, -v54, v57, v56
	v_div_fmas_f32 v54, v54, v55, v57
	v_div_fixup_f32 v0, v54, v0, 1.0
	v_lshlrev_b32_e32 v54, 16, v90
	v_and_b32_e32 v55, 0xffff0000, v90
	v_lshlrev_b32_e32 v56, 16, v91
	v_and_b32_e32 v57, 0xffff0000, v91
	v_lshlrev_b32_e32 v58, 16, v92
	v_pk_mul_f32 v[50:51], v[50:51], v[0:1] op_sel_hi:[1,0]
	v_pk_mul_f32 v[52:53], v[52:53], v[0:1] op_sel_hi:[1,0]
	v_pk_mul_f32 v[46:47], v[46:47], v[0:1] op_sel_hi:[1,0]
	v_pk_mul_f32 v[48:49], v[48:49], v[0:1] op_sel_hi:[1,0]
	v_pk_fma_f32 v[52:53], v[84:85], v[52:53], v[56:57]
	v_pk_fma_f32 v[50:51], v[82:83], v[50:51], v[54:55]
	v_pk_fma_f32 v[56:57], v[78:79], v[46:47], v[58:59]
	v_cvt_pk_bf16_f32 v46, v50, v51
	v_cvt_pk_bf16_f32 v47, v52, v53
	v_pk_fma_f32 v[54:55], v[80:81], v[48:49], v[60:61]
	v_cvt_pk_bf16_f32 v48, v56, v57
	v_pk_mul_f32 v[60:61], v[202:203], v[56:57]
	v_cvt_pk_bf16_f32 v49, v54, v55
	global_store_dwordx4 v241, v[46:49], s[24:25]
; __device__ __forceinline__ unsigned cvt_pk_bf16(float lo, float hi) { unsigned r; asm volatile("v_cvt_pk_bf16_f32 %0, %1, %2" : "=v"(r) : "v"(lo), "v"(hi)); return r; }
; #define PG8_GPTR(p) ((__attribute__((address_space(1))) char*)(p))
;     __device__ __forceinline__ void operator()(const f32x4 (&acc)[2][2][4][2], const Unit& u, int wr, int wc, int fr, int fq) const {
;     ...
;             for (int mm = 0; mm < 2; ++mm) {
;                 const int m = mp + mm;
;                 const int row = u.pm * BM + ai * HALF + wr * 64 + m * 16 + fr; float q = 0.f;
; #pragma unroll
;                 for (int bj = 0; bj < 2; ++bj) {
;                     const unsigned offb = (unsigned)(row * DM + col0 + bj * HALF) * 2u;
;                     const u32x4 bw = bv[mm][bj];
;                     const f32x4 b0 = (f32x4){__uint_as_float(bw.x << 16), __uint_as_float(bw.x & 0xffff0000u), __uint_as_float(bw.y << 16), __uint_as_float(bw.y & 0xffff0000u)};
;                     const f32x4 b1 = (f32x4){__uint_as_float(bw.z << 16), __uint_as_float(bw.z & 0xffff0000u), __uint_as_float(bw.w << 16), __uint_as_float(bw.w & 0xffff0000u)};
;                     f32x4 a0 = acc[ai][bj][m][0], a1 = acc[ai][bj][m][1]; if constexpr (GN) { a0 *= rc[ai * 4 + m]; a1 *= rc[ai * 4 + m]; }
;                     const f32x4 o0 = b0 + g[bj][0] * a0, o1 = b1 + g[bj][1] * a1;
;                     u32x4 wo; wo.x = cvt_pk_bf16(o0[0], o0[1]); wo.y = cvt_pk_bf16(o0[2], o0[3]); wo.z = cvt_pk_bf16(o1[0], o1[1]); wo.w = cvt_pk_bf16(o1[2], o1[3]);
;                     *(gs_u32x4*)(PG8_GPTR(out) + offb) = wo;
;                     if (xg) {
;                         const f32x4 h0 = o0 * cf[bj][0], h1 = o1 * cf[bj][1];
;                         u32x4 w; w.x = cvt_pk_bf16(h0[0], h0[1]); w.y = cvt_pk_bf16(h0[2], h0[3]); w.z = cvt_pk_bf16(h1[0], h1[1]); w.w = cvt_pk_bf16(h1[2], h1[3]);
;                         *(gs_u32x4*)(PG8_GPTR(xg) + offb) = w;
;                         q += (o0[0] * o0[0] + o0[1] * o0[1]) + (o0[2] * o0[2] + o0[3] * o0[3]) + (o1[0] * o1[0] + o1[1] * o1[1]) + (o1[2] * o1[2] + o1[3] * o1[3]);
;                     }
;                 }
;                 if (xg) ssq_put(ssq, row, q, fr, fq);
	v_pk_mul_f32 v[58:59], v[198:199], v[54:55]
	v_pk_mul_f32 v[42:43], v[42:43], v[0:1] op_sel_hi:[1,0]
	v_pk_mul_f32 v[46:47], v[204:205], v[50:51]
	v_pk_mul_f32 v[48:49], v[200:201], v[52:53]
	v_cvt_pk_bf16_f32 v46, v46, v47
	v_pk_mul_f32 v[44:45], v[44:45], v[0:1] op_sel_hi:[1,0]
	v_cvt_pk_bf16_f32 v47, v48, v49
	v_cvt_pk_bf16_f32 v48, v60, v61
	v_cvt_pk_bf16_f32 v49, v58, v59
	global_store_dwordx4 v62, v[46:49], s[26:27]
	v_pk_mul_f32 v[38:39], v[38:39], v[0:1] op_sel_hi:[1,0]
	v_pk_mul_f32 v[40:41], v[40:41], v[0:1] op_sel_hi:[1,0]
	v_mul_f32_e32 v46, v51, v51
	v_mul_f32_e32 v47, v53, v53
	v_fmac_f32_e32 v46, v50, v50
	v_fmac_f32_e32 v47, v52, v52
	v_add_f32_e32 v46, v46, v47
	v_mul_f32_e32 v47, v57, v57
	v_fmac_f32_e32 v47, v56, v56
	v_add_f32_e32 v46, v47, v46
	v_mul_f32_e32 v47, v55, v55
	v_fmac_f32_e32 v47, v54, v54
	v_add_f32_e32 v54, v47, v46
	v_lshlrev_b32_e32 v46, 16, v86
	v_and_b32_e32 v47, 0xffff0000, v86
	v_lshlrev_b32_e32 v48, 16, v87
	v_and_b32_e32 v49, 0xffff0000, v87
	v_lshlrev_b32_e32 v50, 16, v88
	v_and_b32_e32 v51, 0xffff0000, v88
	v_lshlrev_b32_e32 v52, 16, v89
	v_and_b32_e32 v53, 0xffff0000, v89
	v_pk_fma_f32 v[44:45], v[76:77], v[44:45], v[48:49]
	v_pk_fma_f32 v[42:43], v[74:75], v[42:43], v[46:47]
	v_pk_fma_f32 v[46:47], v[40:41], v[72:73], v[52:53]
	v_pk_fma_f32 v[48:49], v[38:39], v[70:71], v[50:51]
	v_cvt_pk_bf16_f32 v38, v42, v43
	v_cvt_pk_bf16_f32 v39, v44, v45
	v_mul_f32_e32 v0, v47, v47
	v_cvt_pk_bf16_f32 v40, v48, v49
	v_cvt_pk_bf16_f32 v41, v46, v47
	global_store_dwordx4 v241, v[38:41], s[24:25] offset:1024
	v_fmac_f32_e32 v0, v46, v46
	v_pk_mul_f32 v[50:51], v[196:197], v[44:45]
	v_mul_f32_e32 v39, v43, v43
	v_mul_f32_e32 v40, v45, v45
	v_mul_f32_e32 v38, v49, v49
	v_fmac_f32_e32 v39, v42, v42
	v_fmac_f32_e32 v40, v44, v44
	v_fmac_f32_e32 v38, v48, v48
	v_add_f32_e32 v39, v39, v40
	v_add_f32_e32 v38, v38, v39
	v_add_f32_e32 v0, v0, v38
	v_add_f32_e32 v0, v54, v0
	ds_bpermute_b32 v41, v229, v0
	v_pk_mul_f32 v[38:39], v[174:175], v[42:43]
	v_pk_mul_f32 v[42:43], v[194:195], v[48:49]
	v_cvt_pk_bf16_f32 v40, v38, v39
	v_pk_mul_f32 v[44:45], v[176:177], v[46:47]
	s_waitcnt lgkmcnt(0)
	v_add_f32_e32 v0, v0, v41
	ds_bpermute_b32 v38, v228, v0
	v_cvt_pk_bf16_f32 v41, v50, v51
	v_cvt_pk_bf16_f32 v42, v42, v43
	v_cvt_pk_bf16_f32 v43, v44, v45
	global_store_dwordx4 v62, v[40:43], s[26:27] offset:256
	s_and_saveexec_b64 s[2:3], s[8:9]
	s_cbranch_execz .LBB0_1099
	s_waitcnt lgkmcnt(0)
	v_add_f32_e32 v0, v0, v38
	v_mul_f32_e32 v0, 0x4b800000, v0
	v_trunc_f32_e32 v0, v0
	v_mul_f32_e32 v38, 0x2f800000, v0
	v_floor_f32_e32 v39, v38
	v_fmac_f32_e32 v0, 0xcf800000, v39
	v_cvt_u32_f32_e32 v38, v0
	v_cvt_u32_f32_e32 v39, v39
	global_atomic_add_x2 v[134:135], v[38:39], off offset:1152
.LBB0_1099:
	s_or_b64 exec, exec, s[2:3]
	v_ffbh_u32_e32 v0, v207
	v_min_u32_e32 v0, 32, v0
	s_waitcnt lgkmcnt(0)
	v_lshlrev_b64 v[38:39], v0, v[206:207]
	v_min_u32_e32 v38, 1, v38
	v_or_b32_e32 v38, v39, v38
	v_cvt_f32_u32_e32 v38, v38
	v_sub_u32_e32 v0, 32, v0
	v_ldexp_f32 v0, v38, v0
	v_mul_f32_e32 v0, 0x33800000, v0
	v_fmamk_f32 v0, v0, 0x3b800000, v226
	v_cmp_gt_f32_e32 vcc, s71, v0
	v_mul_f32_e32 v38, 0x4f800000, v0
	s_nop 0
	v_cndmask_b32_e32 v0, v0, v38, vcc
	v_sqrt_f32_e32 v38, v0
	s_nop 0
	v_add_u32_e32 v39, -1, v38
	v_fma_f32 v40, -v39, v38, v0
	v_cmp_ge_f32_e64 s[10:11], 0, v40
	v_add_u32_e32 v40, 1, v38
	s_nop 0
	v_cndmask_b32_e64 v39, v38, v39, s[10:11]
	v_fma_f32 v38, -v40, v38, v0
	v_cmp_lt_f32_e64 s[10:11], 0, v38
	s_nop 1
	v_cndmask_b32_e64 v38, v39, v40, s[10:11]
	v_mul_f32_e32 v39, 0x37800000, v38
	v_cndmask_b32_e32 v38, v38, v39, vcc
	v_cmp_class_f32_e32 vcc, v0, v223
	s_nop 1
	v_cndmask_b32_e32 v0, v38, v0, vcc
	v_div_scale_f32 v38, s[2:3], v0, v0, 1.0
	v_rcp_f32_e32 v39, v38
	s_mov_b32 s2, 0x50000
	v_add3_u32 v58, v136, v230, s2
	v_add_u32_e32 v241, s2, v240
	v_fma_f32 v40, -v38, v39, 1.0
	v_fmac_f32_e32 v39, v40, v39
	v_div_scale_f32 v40, vcc, 1.0, v0, 1.0
	v_mul_f32_e32 v41, v40, v39
	v_fma_f32 v42, -v38, v41, v40
	v_fmac_f32_e32 v41, v42, v39
	v_fma_f32 v38, -v38, v41, v40
	v_div_fmas_f32 v38, v38, v39, v41
	v_div_fixup_f32 v0, v38, v0, 1.0
	v_add_u32_e32 v38, 0x50000, v240
	global_load_dwordx4 v[50:53], v38, s[22:23]
	global_load_dwordx4 v[46:49], v38, s[22:23] offset:1024
	v_add_u32_e32 v38, 0x58000, v240
	global_load_dwordx4 v[42:45], v38, s[22:23]
	s_nop 0
	global_load_dwordx4 v[38:41], v38, s[22:23] offset:1024
	v_pk_mul_f32 v[34:35], v[34:35], v[0:1] op_sel_hi:[1,0]
	v_pk_mul_f32 v[36:37], v[36:37], v[0:1] op_sel_hi:[1,0]
	v_pk_mul_f32 v[30:31], v[30:31], v[0:1] op_sel_hi:[1,0]
	v_pk_mul_f32 v[32:33], v[32:33], v[0:1] op_sel_hi:[1,0]
	v_pk_mul_f32 v[26:27], v[26:27], v[0:1] op_sel_hi:[1,0]
	v_pk_mul_f32 v[28:29], v[28:29], v[0:1] op_sel_hi:[1,0]
	v_pk_mul_f32 v[22:23], v[22:23], v[0:1] op_sel_hi:[1,0]
	v_pk_mul_f32 v[24:25], v[24:25], v[0:1] op_sel_hi:[1,0]
	s_waitcnt vmcnt(0)
; __device__ __forceinline__ unsigned cvt_pk_bf16(float lo, float hi) { unsigned r; asm volatile("v_cvt_pk_bf16_f32 %0, %1, %2" : "=v"(r) : "v"(lo), "v"(hi)); return r; }
; #define PG8_GPTR(p) ((__attribute__((address_space(1))) char*)(p))
;     __device__ __forceinline__ void operator()(const f32x4 (&acc)[2][2][4][2], const Unit& u, int wr, int wc, int fr, int fq) const {
;     ...
;             for (int mm = 0; mm < 2; ++mm) {
;                 const int m = mp + mm;
;                 const int row = u.pm * BM + ai * HALF + wr * 64 + m * 16 + fr; float q = 0.f;
; #pragma unroll
;                 for (int bj = 0; bj < 2; ++bj) {
;                     const unsigned offb = (unsigned)(row * DM + col0 + bj * HALF) * 2u;
;                     const u32x4 bw = bv[mm][bj];
;                     const f32x4 b0 = (f32x4){__uint_as_float(bw.x << 16), __uint_as_float(bw.x & 0xffff0000u), __uint_as_float(bw.y << 16), __uint_as_float(bw.y & 0xffff0000u)};
;                     const f32x4 b1 = (f32x4){__uint_as_float(bw.z << 16), __uint_as_float(bw.z & 0xffff0000u), __uint_as_float(bw.w << 16), __uint_as_float(bw.w & 0xffff0000u)};
;                     f32x4 a0 = acc[ai][bj][m][0], a1 = acc[ai][bj][m][1]; if constexpr (GN) { a0 *= rc[ai * 4 + m]; a1 *= rc[ai * 4 + m]; }
;                     const f32x4 o0 = b0 + g[bj][0] * a0, o1 = b1 + g[bj][1] * a1;
;                     u32x4 wo; wo.x = cvt_pk_bf16(o0[0], o0[1]); wo.y = cvt_pk_bf16(o0[2], o0[3]); wo.z = cvt_pk_bf16(o1[0], o1[1]); wo.w = cvt_pk_bf16(o1[2], o1[3]);
;                     *(gs_u32x4*)(PG8_GPTR(out) + offb) = wo;
;                     if (xg) {
;                         const f32x4 h0 = o0 * cf[bj][0], h1 = o1 * cf[bj][1];
;                         u32x4 w; w.x = cvt_pk_bf16(h0[0], h0[1]); w.y = cvt_pk_bf16(h0[2], h0[3]); w.z = cvt_pk_bf16(h1[0], h1[1]); w.w = cvt_pk_bf16(h1[2], h1[3]);
;                         *(gs_u32x4*)(PG8_GPTR(xg) + offb) = w;
;                         q += (o0[0] * o0[0] + o0[1] * o0[1]) + (o0[2] * o0[2] + o0[3] * o0[3]) + (o1[0] * o1[0] + o1[1] * o1[1]) + (o1[2] * o1[2] + o1[3] * o1[3]);
;                     }
;                 }
;                 if (xg) ssq_put(ssq, row, q, fr, fq);
	v_lshlrev_b32_e32 v54, 16, v50
	v_and_b32_e32 v55, 0xffff0000, v50
	v_lshlrev_b32_e32 v50, 16, v51
	v_and_b32_e32 v51, 0xffff0000, v51
	v_lshlrev_b32_e32 v56, 16, v52
	v_and_b32_e32 v57, 0xffff0000, v52
	v_lshlrev_b32_e32 v52, 16, v53
	v_and_b32_e32 v53, 0xffff0000, v53
	v_pk_fma_f32 v[36:37], v[84:85], v[36:37], v[50:51]
	v_pk_fma_f32 v[34:35], v[82:83], v[34:35], v[54:55]
	v_pk_fma_f32 v[50:51], v[80:81], v[32:33], v[52:53]
	v_pk_fma_f32 v[52:53], v[78:79], v[30:31], v[56:57]
	v_cvt_pk_bf16_f32 v30, v34, v35
	v_cvt_pk_bf16_f32 v31, v36, v37
	v_pk_mul_f32 v[54:55], v[198:199], v[50:51]
	v_cvt_pk_bf16_f32 v32, v52, v53
	v_cvt_pk_bf16_f32 v33, v50, v51
	global_store_dwordx4 v241, v[30:33], s[24:25]
	v_pk_mul_f32 v[56:57], v[202:203], v[52:53]
	s_nop 0
	v_pk_mul_f32 v[30:31], v[204:205], v[34:35]
	v_pk_mul_f32 v[32:33], v[200:201], v[36:37]
	v_cvt_pk_bf16_f32 v30, v30, v31
	s_nop 0
	v_cvt_pk_bf16_f32 v31, v32, v33
	v_cvt_pk_bf16_f32 v32, v56, v57
	v_cvt_pk_bf16_f32 v33, v54, v55
	global_store_dwordx4 v58, v[30:33], s[26:27]
	s_nop 1
	v_mul_f32_e32 v30, v35, v35
	v_mul_f32_e32 v31, v37, v37
	v_fmac_f32_e32 v30, v34, v34
	v_fmac_f32_e32 v31, v36, v36
	v_add_f32_e32 v30, v30, v31
	v_mul_f32_e32 v31, v53, v53
	v_fmac_f32_e32 v31, v52, v52
	v_add_f32_e32 v30, v31, v30
	v_mul_f32_e32 v31, v51, v51
	v_fmac_f32_e32 v31, v50, v50
	v_add_f32_e32 v50, v31, v30
	v_lshlrev_b32_e32 v30, 16, v46
	v_and_b32_e32 v31, 0xffff0000, v46
	v_lshlrev_b32_e32 v32, 16, v47
	v_and_b32_e32 v33, 0xffff0000, v47
	v_lshlrev_b32_e32 v34, 16, v48
	v_and_b32_e32 v35, 0xffff0000, v48
	v_lshlrev_b32_e32 v36, 16, v49
	v_and_b32_e32 v37, 0xffff0000, v49
	v_pk_fma_f32 v[28:29], v[76:77], v[28:29], v[32:33]
	v_pk_fma_f32 v[26:27], v[74:75], v[26:27], v[30:31]
	v_pk_fma_f32 v[30:31], v[72:73], v[24:25], v[36:37]
	v_pk_fma_f32 v[32:33], v[70:71], v[22:23], v[34:35]
	v_cvt_pk_bf16_f32 v22, v26, v27
	v_cvt_pk_bf16_f32 v23, v28, v29
	v_pk_mul_f32 v[34:35], v[176:177], v[30:31]
	v_cvt_pk_bf16_f32 v24, v32, v33
	v_cvt_pk_bf16_f32 v25, v30, v31
	global_store_dwordx4 v241, v[22:25], s[24:25] offset:1024
	v_pk_mul_f32 v[36:37], v[194:195], v[32:33]
	v_mul_f32_e32 v0, v31, v31
	v_pk_mul_f32 v[24:25], v[196:197], v[28:29]
	v_pk_mul_f32 v[22:23], v[174:175], v[26:27]
	v_fmac_f32_e32 v0, v30, v30
	v_cvt_pk_bf16_f32 v22, v22, v23
	v_cvt_pk_bf16_f32 v23, v24, v25
	v_cvt_pk_bf16_f32 v24, v36, v37
	v_cvt_pk_bf16_f32 v25, v34, v35
	global_store_dwordx4 v58, v[22:25], s[26:27] offset:256
	s_nop 1
	v_mul_f32_e32 v23, v27, v27
	v_mul_f32_e32 v24, v29, v29
	v_mul_f32_e32 v22, v33, v33
	v_fmac_f32_e32 v23, v26, v26
	v_fmac_f32_e32 v24, v28, v28
	v_fmac_f32_e32 v22, v32, v32
	v_add_f32_e32 v23, v23, v24
	v_add_f32_e32 v22, v22, v23
	v_add_f32_e32 v0, v0, v22
	v_add_f32_e32 v0, v50, v0
	ds_bpermute_b32 v22, v229, v0
	s_waitcnt lgkmcnt(0)
	v_add_f32_e32 v0, v0, v22
	ds_bpermute_b32 v22, v228, v0
	s_and_saveexec_b64 s[2:3], s[8:9]
	s_cbranch_execz .LBB0_1101
	s_waitcnt lgkmcnt(0)
	v_add_f32_e32 v0, v0, v22
	v_mul_f32_e32 v0, 0x4b800000, v0
	v_trunc_f32_e32 v0, v0
	v_mul_f32_e32 v22, 0x2f800000, v0
	v_floor_f32_e32 v23, v22
	v_fmac_f32_e32 v0, 0xcf800000, v23
	v_cvt_u32_f32_e32 v22, v0
	v_cvt_u32_f32_e32 v23, v23
	global_atomic_add_x2 v[134:135], v[22:23], off offset:1280
; __device__ __forceinline__ unsigned cvt_pk_bf16(float lo, float hi) { unsigned r; asm volatile("v_cvt_pk_bf16_f32 %0, %1, %2" : "=v"(r) : "v"(lo), "v"(hi)); return r; }
; #define PG8_GPTR(p) ((__attribute__((address_space(1))) char*)(p))
;     __device__ __forceinline__ void operator()(const f32x4 (&acc)[2][2][4][2], const Unit& u, int wr, int wc, int fr, int fq) const {
;     ...
;             for (int mm = 0; mm < 2; ++mm) {
;                 const int m = mp + mm;
;                 const int row = u.pm * BM + ai * HALF + wr * 64 + m * 16 + fr; float q = 0.f;
; #pragma unroll
;                 for (int bj = 0; bj < 2; ++bj) {
;                     const unsigned offb = (unsigned)(row * DM + col0 + bj * HALF) * 2u;
;                     const u32x4 bw = bv[mm][bj];
;                     const f32x4 b0 = (f32x4){__uint_as_float(bw.x << 16), __uint_as_float(bw.x & 0xffff0000u), __uint_as_float(bw.y << 16), __uint_as_float(bw.y & 0xffff0000u)};
;                     const f32x4 b1 = (f32x4){__uint_as_float(bw.z << 16), __uint_as_float(bw.z & 0xffff0000u), __uint_as_float(bw.w << 16), __uint_as_float(bw.w & 0xffff0000u)};
;                     f32x4 a0 = acc[ai][bj][m][0], a1 = acc[ai][bj][m][1]; if constexpr (GN) { a0 *= rc[ai * 4 + m]; a1 *= rc[ai * 4 + m]; }
;                     const f32x4 o0 = b0 + g[bj][0] * a0, o1 = b1 + g[bj][1] * a1;
;                     u32x4 wo; wo.x = cvt_pk_bf16(o0[0], o0[1]); wo.y = cvt_pk_bf16(o0[2], o0[3]); wo.z = cvt_pk_bf16(o1[0], o1[1]); wo.w = cvt_pk_bf16(o1[2], o1[3]);
;                     *(gs_u32x4*)(PG8_GPTR(out) + offb) = wo;
;                     if (xg) {
;                         const f32x4 h0 = o0 * cf[bj][0], h1 = o1 * cf[bj][1];
;                         u32x4 w; w.x = cvt_pk_bf16(h0[0], h0[1]); w.y = cvt_pk_bf16(h0[2], h0[3]); w.z = cvt_pk_bf16(h1[0], h1[1]); w.w = cvt_pk_bf16(h1[2], h1[3]);
;                         *(gs_u32x4*)(PG8_GPTR(xg) + offb) = w;
;                         q += (o0[0] * o0[0] + o0[1] * o0[1]) + (o0[2] * o0[2] + o0[3] * o0[3]) + (o1[0] * o1[0] + o1[1] * o1[1]) + (o1[2] * o1[2] + o1[3] * o1[3]);
;                     }
;                 }
;                 if (xg) ssq_put(ssq, row, q, fr, fq);
.LBB0_1101:
	s_or_b64 exec, exec, s[2:3]
	v_ffbh_u32_e32 v0, v3
	v_min_u32_e32 v0, 32, v0
	v_lshlrev_b64 v[2:3], v0, v[2:3]
	v_min_u32_e32 v2, 1, v2
	v_or_b32_e32 v2, v3, v2
	v_cvt_f32_u32_e32 v2, v2
	v_sub_u32_e32 v0, 32, v0
	v_and_b32_e32 v25, 0xffff0000, v44
	v_lshlrev_b32_e32 v26, 16, v45
	v_ldexp_f32 v0, v2, v0
	v_mul_f32_e32 v0, 0x33800000, v0
	v_fmamk_f32 v0, v0, 0x3b800000, v226
	v_mul_f32_e32 v2, 0x4f800000, v0
	v_cmp_gt_f32_e32 vcc, s71, v0
	v_and_b32_e32 v27, 0xffff0000, v45
	s_nop 0
	v_cndmask_b32_e32 v0, v0, v2, vcc
	v_sqrt_f32_e32 v2, v0
	s_nop 0
	v_add_u32_e32 v3, -1, v2
	s_waitcnt lgkmcnt(0)
	v_add_u32_e32 v22, 1, v2
	v_fma_f32 v23, -v3, v2, v0
	v_fma_f32 v24, -v22, v2, v0
	v_cmp_ge_f32_e64 s[10:11], 0, v23
	s_nop 1
	v_cndmask_b32_e64 v2, v2, v3, s[10:11]
	v_cmp_lt_f32_e64 s[10:11], 0, v24
	s_nop 1
	v_cndmask_b32_e64 v2, v2, v22, s[10:11]
	v_mul_f32_e32 v3, 0x37800000, v2
	v_cndmask_b32_e32 v2, v2, v3, vcc
	v_cmp_class_f32_e32 vcc, v0, v223
	s_nop 1
	v_cndmask_b32_e32 v0, v2, v0, vcc
	v_div_scale_f32 v2, s[2:3], v0, v0, 1.0
	v_rcp_f32_e32 v3, v2
	s_mov_b32 s2, 0x58000
	v_add3_u32 v28, v136, v230, s2
	v_add_u32_e32 v241, s2, v240
	v_fma_f32 v22, -v2, v3, 1.0
	v_fmac_f32_e32 v3, v22, v3
	v_div_scale_f32 v22, vcc, 1.0, v0, 1.0
	v_mul_f32_e32 v23, v22, v3
	v_fma_f32 v24, -v2, v23, v22
	v_fmac_f32_e32 v23, v24, v3
	v_fma_f32 v2, -v2, v23, v22
	v_div_fmas_f32 v2, v2, v3, v23
	v_div_fixup_f32 v0, v2, v0, 1.0
	v_lshlrev_b32_e32 v2, 16, v42
	v_and_b32_e32 v3, 0xffff0000, v42
	v_lshlrev_b32_e32 v22, 16, v43
	v_and_b32_e32 v23, 0xffff0000, v43
	v_lshlrev_b32_e32 v24, 16, v44
	v_pk_mul_f32 v[18:19], v[18:19], v[0:1] op_sel_hi:[1,0]
	v_pk_mul_f32 v[20:21], v[20:21], v[0:1] op_sel_hi:[1,0]
	v_pk_mul_f32 v[12:13], v[12:13], v[0:1] op_sel_hi:[1,0]
	v_pk_mul_f32 v[14:15], v[14:15], v[0:1] op_sel_hi:[1,0]
	v_pk_fma_f32 v[20:21], v[84:85], v[20:21], v[22:23]
	v_pk_fma_f32 v[2:3], v[82:83], v[18:19], v[2:3]
	v_pk_fma_f32 v[22:23], v[78:79], v[12:13], v[24:25]
	v_cvt_pk_bf16_f32 v12, v2, v3
	v_cvt_pk_bf16_f32 v13, v20, v21
	v_pk_fma_f32 v[18:19], v[80:81], v[14:15], v[26:27]
	v_cvt_pk_bf16_f32 v14, v22, v23
	v_pk_mul_f32 v[26:27], v[202:203], v[22:23]
	v_cvt_pk_bf16_f32 v15, v18, v19
	global_store_dwordx4 v241, v[12:15], s[24:25]
	v_pk_mul_f32 v[24:25], v[198:199], v[18:19]
	v_pk_mul_f32 v[8:9], v[8:9], v[0:1] op_sel_hi:[1,0]
	v_pk_mul_f32 v[12:13], v[204:205], v[2:3]
	v_mul_f32_e32 v3, v3, v3
	v_fmac_f32_e32 v3, v2, v2
	v_mul_f32_e32 v2, v21, v21
	v_fmac_f32_e32 v2, v20, v20
	v_add_f32_e32 v2, v3, v2
	v_mul_f32_e32 v3, v23, v23
	v_fmac_f32_e32 v3, v22, v22
	v_pk_mul_f32 v[14:15], v[200:201], v[20:21]
	v_add_f32_e32 v2, v3, v2
	v_mul_f32_e32 v3, v19, v19
	v_cvt_pk_bf16_f32 v12, v12, v13
	v_cvt_pk_bf16_f32 v13, v14, v15
	v_cvt_pk_bf16_f32 v14, v26, v27
	v_cvt_pk_bf16_f32 v15, v24, v25
	v_fmac_f32_e32 v3, v18, v18
	global_store_dwordx4 v28, v[12:15], s[26:27]
	v_add_f32_e32 v20, v3, v2
	v_lshlrev_b32_e32 v2, 16, v38
	v_and_b32_e32 v3, 0xffff0000, v38
	v_lshlrev_b32_e32 v12, 16, v39
	v_and_b32_e32 v13, 0xffff0000, v39
	v_lshlrev_b32_e32 v14, 16, v40
	v_and_b32_e32 v15, 0xffff0000, v40
	v_pk_mul_f32 v[10:11], v[10:11], v[0:1] op_sel_hi:[1,0]
	v_pk_mul_f32 v[4:5], v[4:5], v[0:1] op_sel_hi:[1,0]
	v_lshlrev_b32_e32 v18, 16, v41
	v_and_b32_e32 v19, 0xffff0000, v41
	v_pk_mul_f32 v[6:7], v[6:7], v[0:1] op_sel_hi:[1,0]
	v_pk_fma_f32 v[10:11], v[76:77], v[10:11], v[12:13]
	v_pk_fma_f32 v[8:9], v[74:75], v[8:9], v[2:3]
	v_pk_fma_f32 v[12:13], v[70:71], v[4:5], v[14:15]
	v_cvt_pk_bf16_f32 v2, v8, v9
	v_cvt_pk_bf16_f32 v3, v10, v11
	v_pk_fma_f32 v[6:7], v[72:73], v[6:7], v[18:19]
	v_cvt_pk_bf16_f32 v4, v12, v13
	v_pk_mul_f32 v[14:15], v[196:197], v[10:11]
	v_cvt_pk_bf16_f32 v5, v6, v7
	global_store_dwordx4 v241, v[2:5], s[24:25] offset:1024
	v_mul_f32_e32 v0, v7, v7
	v_fmac_f32_e32 v0, v6, v6
	v_mul_f32_e32 v3, v9, v9
	v_mul_f32_e32 v4, v11, v11
	v_mul_f32_e32 v2, v13, v13
	v_fmac_f32_e32 v3, v8, v8
	v_fmac_f32_e32 v4, v10, v10
	v_fmac_f32_e32 v2, v12, v12
	v_add_f32_e32 v3, v3, v4
	v_add_f32_e32 v2, v2, v3
	v_add_f32_e32 v0, v0, v2
	v_add_f32_e32 v0, v20, v0
	ds_bpermute_b32 v5, v229, v0
	v_pk_mul_f32 v[2:3], v[174:175], v[8:9]
	v_pk_mul_f32 v[8:9], v[176:177], v[6:7]
	v_cvt_pk_bf16_f32 v4, v2, v3
	v_pk_mul_f32 v[6:7], v[194:195], v[12:13]
	s_waitcnt lgkmcnt(0)
	v_add_f32_e32 v0, v0, v5
	ds_bpermute_b32 v2, v228, v0
	v_cvt_pk_bf16_f32 v5, v14, v15
	v_cvt_pk_bf16_f32 v6, v6, v7
	v_cvt_pk_bf16_f32 v7, v8, v9
	global_store_dwordx4 v28, v[4:7], s[26:27] offset:256
	s_and_saveexec_b64 s[2:3], s[8:9]
	s_cbranch_execz .LBB0_1103
	s_waitcnt lgkmcnt(0)
	v_add_f32_e32 v0, v0, v2
	v_mul_f32_e32 v0, 0x4b800000, v0
	v_trunc_f32_e32 v0, v0
	v_mul_f32_e32 v2, 0x2f800000, v0
	v_floor_f32_e32 v3, v2
	v_fmac_f32_e32 v0, 0xcf800000, v3
	v_cvt_u32_f32_e32 v2, v0
	v_cvt_u32_f32_e32 v3, v3
	global_atomic_add_x2 v[134:135], v[2:3], off offset:1408

; #define PG8_LAS __attribute__((address_space(3)))
; __device__ __forceinline__ float ssq_val(ssq_t v) { return (float)v * SSQ_IFX; }
;     __host__ __device__ bool next(int i, Unit& u) const {
;         const long L = (long)i * G + c; if (L >= (long)nwg * rep) return false;
;         int wgid = (int)(L % nwg); { const int q = nwg / NXCD, r = nwg % NXCD, xcd = wgid % NXCD, off = wgid / NXCD; wgid = (xcd < r ? xcd * (q + 1) : r * (q + 1) + (xcd - r) * q) + off; }
;         const int nig = WGM * nN, gid = wgid / nig, fm = gid * WGM, gsz = (nM - fm) < WGM ? (nM - fm) : WGM;
;         u.pm = fm + ((wgid % nig) % gsz); u.pn = (wgid % nig) / gsz; return true;
;     }
;     __device__ __forceinline__ void prefetch(const Unit& u, int par, PG8_LAS unsigned char* lds, int tid) const {
;         PG8_LAS float* rp = (PG8_LAS float*)(lds + STAGE_BYTES + 5120) + par * 512;
;         if (tid < BM) rp[tid] = 1.0f / sqrtf(ssq_val(ssqx[u.pm * BM + tid]) * (1.0f / DM) + EPS);
;         else rp[tid] = shw[(size_t)((u.pm * BM) >> 12) * 7680 + u.pn * BM + (tid - BM)];
;     }
.LBB0_1152:
	s_or_b64 exec, exec, s[46:47]
	s_waitcnt lgkmcnt(0)
	s_barrier
	s_load_dwordx2 s[12:13], s[0:1], 0xb8
	s_waitcnt lgkmcnt(0)
	s_load_dwordx2 s[4:5], s[0:1], 0xb8
	s_waitcnt lgkmcnt(0)
	v_mov_b32 v0, 0x20180
	ds_read_b32 v0, v0
	s_waitcnt lgkmcnt(0)
	s_load_dwordx2 s[8:9], s[0:1], 0xb8
	s_waitcnt lgkmcnt(0)
	s_load_dwordx2 s[6:7], s[0:1], 0xb8
	s_waitcnt lgkmcnt(0)
	s_load_dwordx2 s[2:3], s[0:1], 0xb8
	s_waitcnt lgkmcnt(0)
	v_mbcnt_lo_u32_b32 v10, -1, 0
	v_mbcnt_hi_u32_b32 v10, -1, v10
	s_nop 0
	v_readfirstlane_b32 s34, v0
	v_or_b32_e32 v2, s63, v10
	s_cmpk_gt_i32 s34, 0x15ff
	v_readfirstlane_b32 s16, v2
	s_cbranch_scc1 .LBB0_1178
	s_add_u32 s6, s6, s94
	s_addc_u32 s7, s7, s95
	s_add_u32 s10, s6, 0x3d080000
	s_addc_u32 s11, s7, 0
	v_readlane_b32 s6, v255, 16
	v_readlane_b32 s7, v255, 17
	s_lshl_b64 s[6:7], s[6:7], 2
	s_add_u32 s2, s2, s6
	s_addc_u32 s3, s3, s7
	s_add_u32 s35, s2, 0x34d02000
	s_mul_hi_i32 s2, s34, 0x2e8ba2e9
	s_addc_u32 s36, s3, 0
	s_lshr_b32 s3, s2, 31
	s_ashr_i32 s2, s2, 10
	s_add_i32 s2, s2, s3
	s_mulk_i32 s2, 0x1600
	s_sub_i32 s2, s34, s2
	s_sext_i32_i16 s3, s2
	s_bfe_u32 s3, s3, 0x3001c
	s_add_i32 s3, s2, s3
	s_sext_i32_i16 s6, s3
	s_and_b32 s3, s3, 0xfff8
	s_sub_i32 s2, s2, s3
	s_ashr_i32 s6, s6, 3
	s_sext_i32_i16 s3, s2
	s_cmp_lt_i32 s3, 0
	s_movk_i32 s3, 0x2c1
	s_cselect_b32 s3, s3, 0x2c0
	s_mul_i32 s2, s2, s3
	s_add_i32 s2, s2, s6
	s_sext_i32_i16 s3, s2
	s_mulk_i32 s3, 0xba3
	s_lshr_b32 s6, s3, 31
	s_ashr_i32 s3, s3, 19
	s_add_i32 s3, s3, s6
	s_lshl_b32 s6, s3, 3
	s_mulk_i32 s3, 0xb0
	s_sub_i32 s2, s2, s3
	s_sext_i32_i16 s3, s2
	s_bfe_u32 s3, s3, 0x3001c
	s_add_i32 s3, s2, s3
	s_sext_i32_i16 s7, s3
	s_and_b32 s3, s3, 0xfff8
	s_sub_i32 s2, s2, s3
	v_mbcnt_lo_u32_b32 v0, -1, 0
	v_mbcnt_hi_u32_b32 v0, -1, v0
	s_sext_i32_i16 s2, s2
	v_or_b32_e32 v0, s63, v0
	s_add_i32 s28, s6, s2
	s_ashr_i32 s26, s7, 3
	v_cmp_lt_i32_e32 vcc, s96, v0
	s_and_saveexec_b64 s[2:3], vcc
	s_xor_b64 s[2:3], exec, s[2:3]
	s_cbranch_execz .LBB0_1155
	s_lshr_b32 s14, s28, 4
	s_lshl_b32 s6, s26, 8
	s_mulk_i32 s14, 0x7800
	s_ashr_i32 s7, s6, 31
	s_ashr_i32 s15, s14, 31
	s_add_u32 s14, s35, s14
	s_addc_u32 s15, s36, s15
	s_lshl_b64 s[6:7], s[6:7], 2
	s_add_u32 s6, s14, s6
	s_addc_u32 s7, s15, s7
	v_lshl_add_u64 v[4:5], v[0:1], 2, s[6:7]
	v_add_co_u32_e32 v4, vcc, 0xfffffc00, v4
	s_nop 1
	v_addc_co_u32_e32 v5, vcc, -1, v5, vcc
	global_load_dword v3, v[4:5], off
.LBB0_1155:
	s_andn2_saveexec_b64 s[14:15], s[2:3]
	s_cbranch_execz .LBB0_1157
	v_lshl_add_u32 v4, s28, 8, v0
	v_ashrrev_i32_e32 v5, 31, v4
	v_lshl_add_u64 v[4:5], v[4:5], 3, s[10:11]
	global_load_dwordx2 v[4:5], v[4:5], off
	s_waitcnt vmcnt(0) lgkmcnt(0)
	v_ffbh_u32_e32 v3, v5
	v_min_u32_e32 v3, 32, v3
	v_lshlrev_b64 v[4:5], v3, v[4:5]
	v_min_u32_e32 v4, 1, v4
	v_or_b32_e32 v4, v5, v4
	v_cvt_f32_u32_e32 v4, v4
	v_sub_u32_e32 v3, 32, v3
	v_ldexp_f32 v3, v4, v3
	v_mul_f32_e32 v3, 0x33800000, v3
	v_fmamk_f32 v3, v3, 0x3a800000, v226
	v_mul_f32_e32 v4, 0x4f800000, v3
	v_cmp_gt_f32_e32 vcc, s71, v3
	s_nop 1
	v_cndmask_b32_e32 v3, v3, v4, vcc
	v_sqrt_f32_e32 v4, v3
	s_nop 0
	v_add_u32_e32 v5, -1, v4
	v_add_u32_e32 v6, 1, v4
	v_fma_f32 v7, -v5, v4, v3
	v_fma_f32 v8, -v6, v4, v3
	v_cmp_ge_f32_e64 s[6:7], 0, v7
	s_nop 1
	v_cndmask_b32_e64 v4, v4, v5, s[6:7]
	v_cmp_lt_f32_e64 s[6:7], 0, v8
	s_nop 1
	v_cndmask_b32_e64 v4, v4, v6, s[6:7]
	v_mul_f32_e32 v5, 0x37800000, v4
	v_cndmask_b32_e32 v4, v4, v5, vcc
	v_cmp_class_f32_e32 vcc, v3, v223
	s_nop 1
	v_cndmask_b32_e32 v3, v4, v3, vcc
	v_div_scale_f32 v4, s[2:3], v3, v3, 1.0
	v_rcp_f32_e32 v5, v4
	v_div_scale_f32 v6, vcc, 1.0, v3, 1.0
	v_fma_f32 v7, -v4, v5, 1.0
	v_fmac_f32_e32 v5, v7, v5
	v_mul_f32_e32 v7, v6, v5
	v_fma_f32 v8, -v4, v7, v6
	v_fmac_f32_e32 v7, v8, v5
	v_fma_f32 v4, -v4, v7, v6
	v_div_fmas_f32 v4, v4, v5, v7
	v_div_fixup_f32 v3, v4, v3, 1.0

; #define PG8_LAS __attribute__((address_space(3)))
; __device__ __forceinline__ float ssq_val(ssq_t v) { return (float)v * SSQ_IFX; }
;     __device__ __forceinline__ void prefetch(const Unit& u, int par, PG8_LAS unsigned char* lds, int tid) const {
;         PG8_LAS float* rp = (PG8_LAS float*)(lds + STAGE_BYTES + 5120) + par * 512;
;         if (tid < BM) rp[tid] = 1.0f / sqrtf(ssq_val(ssqx[u.pm * BM + tid]) * (1.0f / DM) + EPS);
;         else rp[tid] = shw[(size_t)((u.pm * BM) >> 12) * 7680 + u.pn * BM + (tid - BM)];
;     }
.LBB0_1168:
	v_cndmask_b32_e64 v0, 0, 1, s[8:9]
	v_cmp_ne_u32_e64 s[6:7], 1, v0
	s_andn2_b64 vcc, exec, s[8:9]
	s_cbranch_vccnz .LBB0_1174
	v_mbcnt_lo_u32_b32 v0, -1, 0
	v_mbcnt_hi_u32_b32 v0, -1, v0
	s_nop 0
	v_or_b32_e32 v0, s63, v0
	v_cmp_lt_i32_e32 vcc, s96, v0
	s_and_saveexec_b64 s[2:3], vcc
	s_xor_b64 s[2:3], exec, s[2:3]
	s_cbranch_execz .LBB0_1171
	s_ashr_i32 s8, s18, 4
	s_lshl_b32 s4, s20, 8
	s_ashr_i32 s5, s4, 31
	s_mul_hi_i32 s9, s8, 0x7800
	s_mulk_i32 s8, 0x7800
	s_add_u32 s8, s35, s8
	s_addc_u32 s9, s36, s9
	s_lshl_b64 s[4:5], s[4:5], 2
	s_add_u32 s4, s8, s4
	s_addc_u32 s5, s9, s5
	v_lshl_add_u64 v[90:91], v[0:1], 2, s[4:5]
	v_add_co_u32_e32 v90, vcc, 0xfffffc00, v90
	s_nop 1
	v_addc_co_u32_e32 v91, vcc, -1, v91, vcc
	global_load_dword v90, v[90:91], off
.LBB0_1171:
	s_andn2_saveexec_b64 s[4:5], s[2:3]
	s_cbranch_execz .LBB0_1173
	s_waitcnt vmcnt(0) lgkmcnt(0)
	v_lshl_add_u32 v90, s18, 8, v0
	v_ashrrev_i32_e32 v91, 31, v90
	v_lshl_add_u64 v[90:91], v[90:91], 3, s[10:11]
	global_load_dwordx2 v[90:91], v[90:91], off
	s_waitcnt vmcnt(0) lgkmcnt(0)
	v_ffbh_u32_e32 v92, v91
	v_min_u32_e32 v92, 32, v92
	v_lshlrev_b64 v[90:91], v92, v[90:91]
	v_min_u32_e32 v90, 1, v90
	v_or_b32_e32 v90, v91, v90
	v_cvt_f32_u32_e32 v90, v90
	v_sub_u32_e32 v91, 32, v92
	v_ldexp_f32 v90, v90, v91
	v_mul_f32_e32 v90, 0x33800000, v90
	v_fmamk_f32 v90, v90, 0x3a800000, v226
	v_mul_f32_e32 v91, 0x4f800000, v90
	v_cmp_gt_f32_e32 vcc, s71, v90
	s_nop 1
	v_cndmask_b32_e32 v90, v90, v91, vcc
	v_sqrt_f32_e32 v91, v90
	s_nop 0
	v_add_u32_e32 v92, -1, v91
	v_add_u32_e32 v93, 1, v91
	v_fma_f32 v98, -v92, v91, v90
	v_fma_f32 v99, -v93, v91, v90
	v_cmp_ge_f32_e64 s[8:9], 0, v98
	s_nop 1
	v_cndmask_b32_e64 v91, v91, v92, s[8:9]
	v_cmp_lt_f32_e64 s[8:9], 0, v99
	s_nop 1
	v_cndmask_b32_e64 v91, v91, v93, s[8:9]
	v_mul_f32_e32 v92, 0x37800000, v91
	v_cndmask_b32_e32 v91, v91, v92, vcc
	v_cmp_class_f32_e32 vcc, v90, v223
	s_nop 1
	v_cndmask_b32_e32 v90, v91, v90, vcc
	v_div_scale_f32 v91, s[2:3], v90, v90, 1.0
	v_rcp_f32_e32 v92, v91
	v_div_scale_f32 v93, vcc, 1.0, v90, 1.0
	v_fma_f32 v98, -v91, v92, 1.0
	v_fmac_f32_e32 v92, v98, v92
	v_mul_f32_e32 v98, v93, v92
	v_fma_f32 v99, -v91, v98, v93
	v_fmac_f32_e32 v98, v99, v92
	v_fma_f32 v91, -v91, v98, v93
	v_div_fmas_f32 v91, v91, v92, v98
	v_div_fixup_f32 v90, v91, v90, 1.0

; #define PG8_GCPTR(p) ((__attribute__((address_space(1))) const char*)(p))
;     __device__ __forceinline__ void operator()(const f32x4 (&acc)[2][2][4][2], const Unit& u, int wr, int wc, int fr, int fq) const {
;     ...
;         const int col0 = u.pn * BM + wc * 32 + 8 * fq; const int b = (u.pm * BM) >> 12;
;         const float* gp = gate + (size_t)b * NMOD + col0; const float* sp = sc + (size_t)b * NMOD + col0;
;         f32x4 g[2][2], cf[2][2];
; #pragma unroll
;         for (int bj = 0; bj < 2; ++bj) {
;             g[bj][0] = *(const f32x4*)(gp + bj * HALF); g[bj][1] = *(const f32x4*)(gp + bj * HALF + 4);
;             const f32x4 n0 = *(const f32x4*)(nw + col0 + bj * HALF), n1 = *(const f32x4*)(nw + col0 + bj * HALF + 4);
;             const f32x4 c0 = *(const f32x4*)(sp + bj * HALF), c1 = *(const f32x4*)(sp + bj * HALF + 4);
;             cf[bj][0] = n0 * (c0 + 1.0f); cf[bj][1] = n1 * (c1 + 1.0f);
;         }
; #pragma unroll
;         for (int ai = 0; ai < 2; ++ai)
; #pragma unroll
;         for (int mp = 0; mp < 4; mp += 2) {
;             u32x4 bv[2][2];
; #pragma unroll
;             for (int mm = 0; mm < 2; ++mm)
; #pragma unroll
;                 for (int bj = 0; bj < 2; ++bj)
;                     bv[mm][bj] = *(gl_u32x4*)(PG8_GCPTR(base) + (unsigned)((u.pm * BM + ai * HALF + wr * 64 + (mp + mm) * 16 + fr) * DM + col0 + bj * HALF) * 2u);
; #pragma unroll
;             for (int mm = 0; mm < 2; ++mm) {
;                 const int m = mp + mm;
;                 const int row = u.pm * BM + ai * HALF + wr * 64 + m * 16 + fr; float q = 0.f;
; #pragma unroll
;                 for (int bj = 0; bj < 2; ++bj) {
;                     const unsigned offb = (unsigned)(row * DM + col0 + bj * HALF) * 2u;
;                     const u32x4 bw = bv[mm][bj];
;                     const f32x4 b0 = (f32x4){__uint_as_float(bw.x << 16), __uint_as_float(bw.x & 0xffff0000u), __uint_as_float(bw.y << 16), __uint_as_float(bw.y & 0xffff0000u)};
;                     const f32x4 b1 = (f32x4){__uint_as_float(bw.z << 16), __uint_as_float(bw.z & 0xffff0000u), __uint_as_float(bw.w << 16), __uint_as_float(bw.w & 0xffff0000u)};
;                     f32x4 a0 = acc[ai][bj][m][0], a1 = acc[ai][bj][m][1]; if constexpr (GN) { a0 *= rc[ai * 4 + m]; a1 *= rc[ai * 4 + m]; }
;                     const f32x4 o0 = b0 + g[bj][0] * a0, o1 = b1 + g[bj][1] * a1;
.LBB0_1246:
	v_mbcnt_lo_u32_b32 v0, -1, 0
	v_mbcnt_hi_u32_b32 v0, -1, v0
	s_lshl_b32 s2, s88, 8
	v_bfe_u32 v205, v0, 4, 2
	v_and_b32_e32 v219, 15, v0
	v_lshl_or_b32 v0, v205, 3, s2
	s_ashr_i32 s2, s87, 4
	v_or_b32_e32 v174, s51, v0
	s_mul_i32 s5, s2, 0x6000
	s_mul_hi_i32 s4, s2, 0x6000
	s_add_u32 s2, s67, s5
	v_ashrrev_i32_e32 v175, 31, v174
	s_addc_u32 s3, s73, s4
	v_lshlrev_b64 v[62:63], 2, v[174:175]
	v_lshl_add_u64 v[158:159], s[2:3], 0, v[62:63]
	s_add_u32 s2, s48, s5
	s_addc_u32 s3, s49, s4
	v_lshl_add_u64 v[162:163], s[2:3], 0, v[62:63]
	v_lshl_add_u64 v[164:165], s[18:19], 0, v[62:63]
	global_load_dwordx4 v[74:77], v[158:159], off
	global_load_dwordx4 v[70:73], v[158:159], off offset:16
	global_load_dwordx4 v[62:65], v[164:165], off offset:16
	global_load_dwordx4 v[66:69], v[164:165], off
	global_load_dwordx4 v[150:153], v[162:163], off
	global_load_dwordx4 v[154:157], v[162:163], off offset:16
	s_lshl_b32 s2, s87, 8
	s_add_i32 s2, s2, s50
	v_or_b32_e32 v204, s2, v219
	v_lshlrev_b32_e32 v217, 1, v174
	v_lshlrev_b32_e32 v218, 11, v204
	v_add_u32_e32 v0, v217, v218
	v_and_b32_e32 v240, 0xffff8000, v0
	v_bfe_u32 v241, v0, 11, 4
	v_lshl_or_b32 v240, v241, 6, v240
	v_bfe_u32 v241, v0, 9, 2
	v_lshl_or_b32 v240, v241, 13, v240
	v_bfe_u32 v241, v0, 6, 2
	v_lshl_or_b32 v240, v241, 11, v240
	v_and_b32_e32 v241, 48, v0
	v_or_b32_e32 v240, v240, v241
	s_andn2_b64 vcc, exec, s[26:27]
	v_lshl_add_u64 v[214:215], s[12:13], 0, v[0:1]
	s_waitcnt vmcnt(0) lgkmcnt(0)
	v_pk_add_f32 v[152:153], v[152:153], 1.0 op_sel_hi:[1,0]
	v_pk_add_f32 v[150:151], v[150:151], 1.0 op_sel_hi:[1,0]
	v_pk_mul_f32 v[210:211], v[68:69], v[152:153]
	v_pk_mul_f32 v[212:213], v[66:67], v[150:151]
	v_pk_add_f32 v[66:67], v[156:157], 1.0 op_sel_hi:[1,0]
	v_pk_add_f32 v[68:69], v[154:155], 1.0 op_sel_hi:[1,0]
	v_pk_mul_f32 v[206:207], v[64:65], v[66:67]
	v_pk_mul_f32 v[208:209], v[62:63], v[68:69]
	global_load_dwordx4 v[66:69], v[158:159], off offset:512
	global_load_dwordx4 v[62:65], v[158:159], off offset:528
	s_nop 0
	global_load_dwordx4 v[158:161], v[164:165], off offset:528
	global_load_dwordx4 v[166:169], v[164:165], off offset:512
	global_load_dwordx4 v[170:173], v[162:163], off offset:512
	s_nop 0
	global_load_dwordx4 v[162:165], v[162:163], off offset:528
	s_nop 0
	global_load_dwordx4 v[178:181], v240, s[20:21]
	global_load_dwordx4 v[174:177], v240, s[20:21] offset:1024
	v_add_u32_e32 v150, 0x8000, v240
	global_load_dwordx4 v[154:157], v150, s[20:21]
	s_nop 0
	global_load_dwordx4 v[150:153], v150, s[20:21] offset:1024
	s_waitcnt vmcnt(0)
	v_lshlrev_b32_e32 v182, 16, v178
	v_and_b32_e32 v183, 0xffff0000, v178
	v_lshlrev_b32_e32 v178, 16, v179
	v_and_b32_e32 v179, 0xffff0000, v179
	v_lshlrev_b32_e32 v184, 16, v180
	v_and_b32_e32 v185, 0xffff0000, v180
	v_lshlrev_b32_e32 v180, 16, v181
	v_and_b32_e32 v181, 0xffff0000, v181
	v_pk_fma_f32 v[148:149], v[148:149], v[76:77], v[178:179]
	v_pk_fma_f32 v[146:147], v[146:147], v[74:75], v[182:183]
	v_pk_fma_f32 v[144:145], v[144:145], v[72:73], v[180:181]
	v_cvt_pk_bf16_f32 v178, v146, v147
	v_pk_fma_f32 v[142:143], v[142:143], v[70:71], v[184:185]
	v_cvt_pk_bf16_f32 v179, v148, v149
	s_nop 0
	v_cvt_pk_bf16_f32 v180, v142, v143
	v_cvt_pk_bf16_f32 v181, v144, v145
	global_store_dwordx4 v240, v[178:181], s[22:23]
	s_nop 1
	v_cndmask_b32_e64 v178, 0, 1, s[26:27]
	v_cmp_ne_u32_e64 s[8:9], 1, v178
	s_cbranch_vccnz .LBB0_1248
	v_pk_mul_f32 v[178:179], v[212:213], v[146:147]
	v_pk_mul_f32 v[180:181], v[210:211], v[148:149]
	v_cvt_pk_bf16_f32 v178, v178, v179
	v_pk_mul_f32 v[148:149], v[148:149], v[148:149]
	v_cvt_pk_bf16_f32 v179, v180, v181
	v_pk_mul_f32 v[146:147], v[146:147], v[146:147]
	v_pk_mul_f32 v[182:183], v[206:207], v[144:145]
	v_pk_mul_f32 v[184:185], v[208:209], v[142:143]
	v_pk_mul_f32 v[144:145], v[144:145], v[144:145]
	v_cvt_pk_bf16_f32 v180, v184, v185
	v_cvt_pk_bf16_f32 v181, v182, v183
	global_store_dwordx4 v[214:215], v[178:181], off
	v_pk_mul_f32 v[142:143], v[142:143], v[142:143]
	s_nop 0
	v_mov_b32_e32 v178, v146
	v_mov_b32_e32 v179, v149
	v_pk_mov_b32 v[146:147], v[146:147], v[148:149] op_sel:[1,0]
	v_mov_b32_e32 v148, v144
	v_pk_add_f32 v[146:147], v[146:147], v[178:179]
	v_mov_b32_e32 v149, v142
	v_mov_b32_e32 v142, v145
	v_pk_add_f32 v[142:143], v[148:149], v[142:143]
	v_add_f32_e32 v144, v146, v147
	v_add_f32_e32 v143, v143, v144
	v_add_f32_e32 v227, v142, v143
	s_branch .LBB0_1249

; __device__ __forceinline__ unsigned cvt_pk_bf16(float lo, float hi) { unsigned r; asm volatile("v_cvt_pk_bf16_f32 %0, %1, %2" : "=v"(r) : "v"(lo), "v"(hi)); return r; }
; #define PG8_GPTR(p) ((__attribute__((address_space(1))) char*)(p))
;     __device__ __forceinline__ void operator()(const f32x4 (&acc)[2][2][4][2], const Unit& u, int wr, int wc, int fr, int fq) const {
;     ...
;             for (int mm = 0; mm < 2; ++mm) {
;                 const int m = mp + mm;
;                 const int row = u.pm * BM + ai * HALF + wr * 64 + m * 16 + fr; float q = 0.f;
; #pragma unroll
;                 for (int bj = 0; bj < 2; ++bj) {
;                     const unsigned offb = (unsigned)(row * DM + col0 + bj * HALF) * 2u;
;                     const u32x4 bw = bv[mm][bj];
;                     const f32x4 b0 = (f32x4){__uint_as_float(bw.x << 16), __uint_as_float(bw.x & 0xffff0000u), __uint_as_float(bw.y << 16), __uint_as_float(bw.y & 0xffff0000u)};
;                     const f32x4 b1 = (f32x4){__uint_as_float(bw.z << 16), __uint_as_float(bw.z & 0xffff0000u), __uint_as_float(bw.w << 16), __uint_as_float(bw.w & 0xffff0000u)};
;                     f32x4 a0 = acc[ai][bj][m][0], a1 = acc[ai][bj][m][1]; if constexpr (GN) { a0 *= rc[ai * 4 + m]; a1 *= rc[ai * 4 + m]; }
;                     const f32x4 o0 = b0 + g[bj][0] * a0, o1 = b1 + g[bj][1] * a1;
;                     u32x4 wo; wo.x = cvt_pk_bf16(o0[0], o0[1]); wo.y = cvt_pk_bf16(o0[2], o0[3]); wo.z = cvt_pk_bf16(o1[0], o1[1]); wo.w = cvt_pk_bf16(o1[2], o1[3]);
;                     *(gs_u32x4*)(PG8_GPTR(out) + offb) = wo;
;                     if (xg) {
;                         const f32x4 h0 = o0 * cf[bj][0], h1 = o1 * cf[bj][1];
;                         u32x4 w; w.x = cvt_pk_bf16(h0[0], h0[1]); w.y = cvt_pk_bf16(h0[2], h0[3]); w.z = cvt_pk_bf16(h1[0], h1[1]); w.w = cvt_pk_bf16(h1[2], h1[3]);
;                         *(gs_u32x4*)(PG8_GPTR(xg) + offb) = w;
;                         q += (o0[0] * o0[0] + o0[1] * o0[1]) + (o0[2] * o0[2] + o0[3] * o0[3]) + (o1[0] * o1[0] + o1[1] * o1[1]) + (o1[2] * o1[2] + o1[3] * o1[3]);
;                     }
;                 }
;                 if (xg) ssq_put(ssq, row, q, fr, fq);
.LBB0_1249:
	s_waitcnt lgkmcnt(0)
	v_pk_add_f32 v[142:143], v[172:173], 1.0 op_sel_hi:[1,0]
	v_pk_add_f32 v[144:145], v[170:171], 1.0 op_sel_hi:[1,0]
	v_pk_mul_f32 v[148:149], v[168:169], v[142:143]
	v_pk_mul_f32 v[142:143], v[166:167], v[144:145]
	v_pk_add_f32 v[144:145], v[164:165], 1.0 op_sel_hi:[1,0]
	v_pk_add_f32 v[146:147], v[162:163], 1.0 op_sel_hi:[1,0]
	v_pk_mul_f32 v[144:145], v[160:161], v[144:145]
	v_pk_mul_f32 v[146:147], v[158:159], v[146:147]
	v_lshlrev_b32_e32 v158, 6, v205
	v_lshlrev_b32_e32 v160, 2, v219
	s_movk_i32 s2, 0x80
	v_bitop3_b32 v159, v158, 64, v160 bitop3:0x36
	v_bitop3_b32 v158, v158, s2, v160 bitop3:0x36
	v_lshlrev_b32_e32 v160, 16, v174
	v_and_b32_e32 v161, 0xffff0000, v174
	v_lshlrev_b32_e32 v162, 16, v175
	v_and_b32_e32 v163, 0xffff0000, v175
	v_lshlrev_b32_e32 v164, 16, v176
	v_and_b32_e32 v165, 0xffff0000, v176
	v_lshlrev_b32_e32 v166, 16, v177
	v_and_b32_e32 v167, 0xffff0000, v177
	v_lshl_add_u64 v[178:179], s[22:23], 0, v[0:1]
	v_cmp_eq_u32_e64 s[10:11], 0, v205
	v_pk_fma_f32 v[140:141], v[140:141], v[68:69], v[162:163]
	v_pk_fma_f32 v[138:139], v[138:139], v[66:67], v[160:161]
	v_pk_fma_f32 v[136:137], v[136:137], v[64:65], v[166:167]
	v_pk_fma_f32 v[134:135], v[134:135], v[62:63], v[164:165]
	s_and_b64 vcc, exec, s[8:9]
	v_cvt_pk_bf16_f32 v160, v138, v139
	v_cvt_pk_bf16_f32 v161, v140, v141
	v_cvt_pk_bf16_f32 v162, v134, v135
	v_cvt_pk_bf16_f32 v163, v136, v137
	global_store_dwordx4 v240, v[160:163], s[22:23] offset:1024
	s_cbranch_vccnz .LBB0_1253
	s_nop 0
	v_pk_mul_f32 v[160:161], v[148:149], v[140:141]
	v_mul_f32_e32 v164, v139, v139
	v_mul_f32_e32 v141, v141, v141
	v_mul_f32_e32 v163, v135, v135
	v_fmac_f32_e32 v164, v138, v138
	v_fmac_f32_e32 v141, v140, v140
	v_mul_f32_e32 v162, v137, v137
	v_fmac_f32_e32 v163, v134, v134
	v_add_f32_e32 v140, v164, v141
	v_fmac_f32_e32 v162, v136, v136
	v_add_f32_e32 v140, v163, v140
	v_add_f32_e32 v140, v162, v140
	v_add_f32_e32 v164, v140, v227
	ds_bpermute_b32 v165, v159, v164
	v_pk_mul_f32 v[162:163], v[146:147], v[134:135]
	v_pk_mul_f32 v[138:139], v[142:143], v[138:139]
	v_pk_mul_f32 v[140:141], v[144:145], v[136:137]
	v_cvt_pk_bf16_f32 v136, v138, v139
	s_waitcnt lgkmcnt(0)
	v_add_f32_e32 v134, v164, v165
	ds_bpermute_b32 v135, v158, v134
	v_cvt_pk_bf16_f32 v137, v160, v161
	v_cvt_pk_bf16_f32 v138, v162, v163
	v_cvt_pk_bf16_f32 v139, v140, v141
	global_store_dwordx4 v[214:215], v[136:139], off offset:256
	s_and_saveexec_b64 s[2:3], s[10:11]
	s_cbranch_execz .LBB0_1252
	s_waitcnt lgkmcnt(0)
	v_add_f32_e32 v134, v134, v135
	v_mul_f32_e32 v134, 0x4b800000, v134
	v_trunc_f32_e32 v134, v134
	v_mul_f32_e32 v135, 0x2f800000, v134
	v_floor_f32_e32 v135, v135
	v_fmac_f32_e32 v134, 0xcf800000, v135
	v_cvt_u32_f32_e32 v134, v134
	v_cvt_u32_f32_e32 v135, v135
	v_ashrrev_i32_e32 v205, 31, v204
	v_lshl_add_u64 v[136:137], v[204:205], 3, s[16:17]
	global_atomic_add_x2 v[136:137], v[134:135], off

; __device__ __forceinline__ unsigned cvt_pk_bf16(float lo, float hi) { unsigned r; asm volatile("v_cvt_pk_bf16_f32 %0, %1, %2" : "=v"(r) : "v"(lo), "v"(hi)); return r; }
; #define PG8_GPTR(p) ((__attribute__((address_space(1))) char*)(p))
;     __device__ __forceinline__ void operator()(const f32x4 (&acc)[2][2][4][2], const Unit& u, int wr, int wc, int fr, int fq) const {
;     ...
;             for (int mm = 0; mm < 2; ++mm) {
;                 const int m = mp + mm;
;                 const int row = u.pm * BM + ai * HALF + wr * 64 + m * 16 + fr; float q = 0.f;
; #pragma unroll
;                 for (int bj = 0; bj < 2; ++bj) {
;                     const unsigned offb = (unsigned)(row * DM + col0 + bj * HALF) * 2u;
;                     const u32x4 bw = bv[mm][bj];
;                     const f32x4 b0 = (f32x4){__uint_as_float(bw.x << 16), __uint_as_float(bw.x & 0xffff0000u), __uint_as_float(bw.y << 16), __uint_as_float(bw.y & 0xffff0000u)};
;                     const f32x4 b1 = (f32x4){__uint_as_float(bw.z << 16), __uint_as_float(bw.z & 0xffff0000u), __uint_as_float(bw.w << 16), __uint_as_float(bw.w & 0xffff0000u)};
;                     f32x4 a0 = acc[ai][bj][m][0], a1 = acc[ai][bj][m][1]; if constexpr (GN) { a0 *= rc[ai * 4 + m]; a1 *= rc[ai * 4 + m]; }
;                     const f32x4 o0 = b0 + g[bj][0] * a0, o1 = b1 + g[bj][1] * a1;
;                     u32x4 wo; wo.x = cvt_pk_bf16(o0[0], o0[1]); wo.y = cvt_pk_bf16(o0[2], o0[3]); wo.z = cvt_pk_bf16(o1[0], o1[1]); wo.w = cvt_pk_bf16(o1[2], o1[3]);
;                     *(gs_u32x4*)(PG8_GPTR(out) + offb) = wo;
;                     if (xg) {
;                         const f32x4 h0 = o0 * cf[bj][0], h1 = o1 * cf[bj][1];
;                         u32x4 w; w.x = cvt_pk_bf16(h0[0], h0[1]); w.y = cvt_pk_bf16(h0[2], h0[3]); w.z = cvt_pk_bf16(h1[0], h1[1]); w.w = cvt_pk_bf16(h1[2], h1[3]);
;                         *(gs_u32x4*)(PG8_GPTR(xg) + offb) = w;
;                         q += (o0[0] * o0[0] + o0[1] * o0[1]) + (o0[2] * o0[2] + o0[3] * o0[3]) + (o1[0] * o1[0] + o1[1] * o1[1]) + (o1[2] * o1[2] + o1[3] * o1[3]);
;                     }
;                 }
;                 if (xg) ssq_put(ssq, row, q, fr, fq);
.LBB0_1256:
	v_lshlrev_b32_e32 v130, 16, v150
	v_and_b32_e32 v131, 0xffff0000, v150
	v_lshlrev_b32_e32 v132, 16, v151
	v_and_b32_e32 v133, 0xffff0000, v151
	v_lshlrev_b32_e32 v136, 16, v152
	v_and_b32_e32 v137, 0xffff0000, v152
	v_lshlrev_b32_e32 v138, 16, v153
	v_and_b32_e32 v139, 0xffff0000, v153
	v_lshl_add_u64 v[134:135], s[22:23], 0, v[134:135]
	v_pk_fma_f32 v[124:125], v[124:125], v[68:69], v[132:133]
	v_pk_fma_f32 v[122:123], v[122:123], v[66:67], v[130:131]
	v_pk_fma_f32 v[120:121], v[120:121], v[64:65], v[138:139]
	v_pk_fma_f32 v[118:119], v[118:119], v[62:63], v[136:137]
	s_and_b64 vcc, exec, s[8:9]
	v_cvt_pk_bf16_f32 v130, v122, v123
	v_cvt_pk_bf16_f32 v131, v124, v125
	v_cvt_pk_bf16_f32 v132, v118, v119
	v_cvt_pk_bf16_f32 v133, v120, v121
	global_store_dwordx4 v241, v[130:133], s[22:23] offset:1024
	s_cbranch_vccnz .LBB0_1260
	s_nop 0
	v_pk_mul_f32 v[130:131], v[148:149], v[124:125]
	v_mul_f32_e32 v133, v123, v123
	v_mul_f32_e32 v125, v125, v125
	v_mul_f32_e32 v132, v119, v119
	v_fmac_f32_e32 v133, v122, v122
	v_fmac_f32_e32 v125, v124, v124
	v_mul_f32_e32 v129, v121, v121
	v_fmac_f32_e32 v132, v118, v118
	v_add_f32_e32 v124, v133, v125
	v_fmac_f32_e32 v129, v120, v120
	v_add_f32_e32 v124, v132, v124
	v_add_f32_e32 v124, v129, v124
	v_add_f32_e32 v132, v124, v128
	ds_bpermute_b32 v133, v159, v132
	v_pk_mul_f32 v[128:129], v[146:147], v[118:119]
	v_pk_mul_f32 v[122:123], v[142:143], v[122:123]
	v_pk_mul_f32 v[124:125], v[144:145], v[120:121]
	v_cvt_pk_bf16_f32 v120, v122, v123
	s_waitcnt lgkmcnt(0)
	v_add_f32_e32 v118, v132, v133
	ds_bpermute_b32 v119, v158, v118
	v_cvt_pk_bf16_f32 v121, v130, v131
	v_cvt_pk_bf16_f32 v122, v128, v129
	v_cvt_pk_bf16_f32 v123, v124, v125
	global_store_dwordx4 v[126:127], v[120:123], off offset:256
	s_and_saveexec_b64 s[2:3], s[10:11]
	s_cbranch_execz .LBB0_1259
	s_waitcnt lgkmcnt(0)
	v_add_f32_e32 v118, v118, v119
	v_mul_f32_e32 v118, 0x4b800000, v118
	v_trunc_f32_e32 v118, v118
	v_mul_f32_e32 v119, 0x2f800000, v118
	v_floor_f32_e32 v119, v119
	v_fmac_f32_e32 v118, 0xcf800000, v119
	v_cvt_u32_f32_e32 v118, v118
	v_cvt_u32_f32_e32 v119, v119
	v_ashrrev_i32_e32 v205, 31, v204
	v_lshl_add_u64 v[120:121], v[204:205], 3, s[16:17]
	global_atomic_add_x2 v[120:121], v[118:119], off offset:128

; __device__ __forceinline__ unsigned cvt_pk_bf16(float lo, float hi) { unsigned r; asm volatile("v_cvt_pk_bf16_f32 %0, %1, %2" : "=v"(r) : "v"(lo), "v"(hi)); return r; }
; #define PG8_GPTR(p) ((__attribute__((address_space(1))) char*)(p))
;     __device__ __forceinline__ void operator()(const f32x4 (&acc)[2][2][4][2], const Unit& u, int wr, int wc, int fr, int fq) const {
;     ...
;             for (int mm = 0; mm < 2; ++mm) {
;                 const int m = mp + mm;
;                 const int row = u.pm * BM + ai * HALF + wr * 64 + m * 16 + fr; float q = 0.f;
; #pragma unroll
;                 for (int bj = 0; bj < 2; ++bj) {
;                     const unsigned offb = (unsigned)(row * DM + col0 + bj * HALF) * 2u;
;                     const u32x4 bw = bv[mm][bj];
;                     const f32x4 b0 = (f32x4){__uint_as_float(bw.x << 16), __uint_as_float(bw.x & 0xffff0000u), __uint_as_float(bw.y << 16), __uint_as_float(bw.y & 0xffff0000u)};
;                     const f32x4 b1 = (f32x4){__uint_as_float(bw.z << 16), __uint_as_float(bw.z & 0xffff0000u), __uint_as_float(bw.w << 16), __uint_as_float(bw.w & 0xffff0000u)};
;                     f32x4 a0 = acc[ai][bj][m][0], a1 = acc[ai][bj][m][1]; if constexpr (GN) { a0 *= rc[ai * 4 + m]; a1 *= rc[ai * 4 + m]; }
;                     const f32x4 o0 = b0 + g[bj][0] * a0, o1 = b1 + g[bj][1] * a1;
;                     u32x4 wo; wo.x = cvt_pk_bf16(o0[0], o0[1]); wo.y = cvt_pk_bf16(o0[2], o0[3]); wo.z = cvt_pk_bf16(o1[0], o1[1]); wo.w = cvt_pk_bf16(o1[2], o1[3]);
;                     *(gs_u32x4*)(PG8_GPTR(out) + offb) = wo;
;                     if (xg) {
;                         const f32x4 h0 = o0 * cf[bj][0], h1 = o1 * cf[bj][1];
;                         u32x4 w; w.x = cvt_pk_bf16(h0[0], h0[1]); w.y = cvt_pk_bf16(h0[2], h0[3]); w.z = cvt_pk_bf16(h1[0], h1[1]); w.w = cvt_pk_bf16(h1[2], h1[3]);
;                         *(gs_u32x4*)(PG8_GPTR(xg) + offb) = w;
;                         q += (o0[0] * o0[0] + o0[1] * o0[1]) + (o0[2] * o0[2] + o0[3] * o0[3]) + (o1[0] * o1[0] + o1[1] * o1[1]) + (o1[2] * o1[2] + o1[3] * o1[3]);
;                     }
;                 }
;                 if (xg) ssq_put(ssq, row, q, fr, fq);
.LBB0_1263:
	v_lshlrev_b32_e32 v112, 16, v126
	v_and_b32_e32 v113, 0xffff0000, v126
	v_lshlrev_b32_e32 v114, 16, v127
	v_and_b32_e32 v115, 0xffff0000, v127
	v_lshlrev_b32_e32 v126, 16, v128
	v_and_b32_e32 v127, 0xffff0000, v128
	v_lshlrev_b32_e32 v128, 16, v129
	v_and_b32_e32 v129, 0xffff0000, v129
	v_lshl_add_u64 v[116:117], s[22:23], 0, v[130:131]
	v_pk_fma_f32 v[108:109], v[108:109], v[68:69], v[114:115]
	v_pk_fma_f32 v[106:107], v[106:107], v[66:67], v[112:113]
	v_pk_fma_f32 v[104:105], v[104:105], v[64:65], v[128:129]
	v_pk_fma_f32 v[102:103], v[102:103], v[62:63], v[126:127]
	s_and_b64 vcc, exec, s[8:9]
	v_cvt_pk_bf16_f32 v112, v106, v107
	v_cvt_pk_bf16_f32 v113, v108, v109
	v_cvt_pk_bf16_f32 v114, v102, v103
	v_cvt_pk_bf16_f32 v115, v104, v105
	global_store_dwordx4 v241, v[112:115], s[22:23] offset:1024
	s_cbranch_vccnz .LBB0_1267
	s_nop 0
	v_pk_mul_f32 v[112:113], v[148:149], v[108:109]
	v_mul_f32_e32 v115, v107, v107
	v_mul_f32_e32 v109, v109, v109
	v_mul_f32_e32 v114, v103, v103
	v_fmac_f32_e32 v115, v106, v106
	v_fmac_f32_e32 v109, v108, v108
	v_mul_f32_e32 v111, v105, v105
	v_fmac_f32_e32 v114, v102, v102
	v_add_f32_e32 v108, v115, v109
	v_fmac_f32_e32 v111, v104, v104
	v_add_f32_e32 v108, v114, v108
	v_add_f32_e32 v108, v111, v108
	v_add_f32_e32 v114, v108, v110
	ds_bpermute_b32 v115, v159, v114
	v_pk_mul_f32 v[110:111], v[146:147], v[102:103]
	v_pk_mul_f32 v[106:107], v[142:143], v[106:107]
	v_pk_mul_f32 v[108:109], v[144:145], v[104:105]
	v_cvt_pk_bf16_f32 v104, v106, v107
	s_waitcnt lgkmcnt(0)
	v_add_f32_e32 v102, v114, v115
	ds_bpermute_b32 v103, v158, v102
	v_cvt_pk_bf16_f32 v105, v112, v113
	v_cvt_pk_bf16_f32 v106, v110, v111
	v_cvt_pk_bf16_f32 v107, v108, v109
	global_store_dwordx4 v[132:133], v[104:107], off offset:256
	s_and_saveexec_b64 s[2:3], s[10:11]
	s_cbranch_execz .LBB0_1266
	s_waitcnt lgkmcnt(0)
	v_add_f32_e32 v102, v102, v103
	v_mul_f32_e32 v102, 0x4b800000, v102
	v_trunc_f32_e32 v102, v102
	v_mul_f32_e32 v103, 0x2f800000, v102
	v_floor_f32_e32 v103, v103
	v_fmac_f32_e32 v102, 0xcf800000, v103
	v_cvt_u32_f32_e32 v102, v102
	v_cvt_u32_f32_e32 v103, v103
	v_ashrrev_i32_e32 v205, 31, v204
	v_lshl_add_u64 v[104:105], v[204:205], 3, s[16:17]
	global_atomic_add_x2 v[104:105], v[102:103], off offset:256

; __device__ __forceinline__ unsigned cvt_pk_bf16(float lo, float hi) { unsigned r; asm volatile("v_cvt_pk_bf16_f32 %0, %1, %2" : "=v"(r) : "v"(lo), "v"(hi)); return r; }
; #define PG8_GPTR(p) ((__attribute__((address_space(1))) char*)(p))
;     __device__ __forceinline__ void operator()(const f32x4 (&acc)[2][2][4][2], const Unit& u, int wr, int wc, int fr, int fq) const {
;     ...
;             for (int mm = 0; mm < 2; ++mm) {
;                 const int m = mp + mm;
;                 const int row = u.pm * BM + ai * HALF + wr * 64 + m * 16 + fr; float q = 0.f;
; #pragma unroll
;                 for (int bj = 0; bj < 2; ++bj) {
;                     const unsigned offb = (unsigned)(row * DM + col0 + bj * HALF) * 2u;
;                     const u32x4 bw = bv[mm][bj];
;                     const f32x4 b0 = (f32x4){__uint_as_float(bw.x << 16), __uint_as_float(bw.x & 0xffff0000u), __uint_as_float(bw.y << 16), __uint_as_float(bw.y & 0xffff0000u)};
;                     const f32x4 b1 = (f32x4){__uint_as_float(bw.z << 16), __uint_as_float(bw.z & 0xffff0000u), __uint_as_float(bw.w << 16), __uint_as_float(bw.w & 0xffff0000u)};
;                     f32x4 a0 = acc[ai][bj][m][0], a1 = acc[ai][bj][m][1]; if constexpr (GN) { a0 *= rc[ai * 4 + m]; a1 *= rc[ai * 4 + m]; }
;                     const f32x4 o0 = b0 + g[bj][0] * a0, o1 = b1 + g[bj][1] * a1;
;                     u32x4 wo; wo.x = cvt_pk_bf16(o0[0], o0[1]); wo.y = cvt_pk_bf16(o0[2], o0[3]); wo.z = cvt_pk_bf16(o1[0], o1[1]); wo.w = cvt_pk_bf16(o1[2], o1[3]);
;                     *(gs_u32x4*)(PG8_GPTR(out) + offb) = wo;
;                     if (xg) {
;                         const f32x4 h0 = o0 * cf[bj][0], h1 = o1 * cf[bj][1];
;                         u32x4 w; w.x = cvt_pk_bf16(h0[0], h0[1]); w.y = cvt_pk_bf16(h0[2], h0[3]); w.z = cvt_pk_bf16(h1[0], h1[1]); w.w = cvt_pk_bf16(h1[2], h1[3]);
;                         *(gs_u32x4*)(PG8_GPTR(xg) + offb) = w;
;                         q += (o0[0] * o0[0] + o0[1] * o0[1]) + (o0[2] * o0[2] + o0[3] * o0[3]) + (o1[0] * o1[0] + o1[1] * o1[1]) + (o1[2] * o1[2] + o1[3] * o1[3]);
;                     }
;                 }
;                 if (xg) ssq_put(ssq, row, q, fr, fq);
.LBB0_1270:
	v_lshlrev_b32_e32 v98, 16, v118
	v_and_b32_e32 v99, 0xffff0000, v118
	v_lshlrev_b32_e32 v100, 16, v119
	v_and_b32_e32 v101, 0xffff0000, v119
	v_lshlrev_b32_e32 v104, 16, v120
	v_and_b32_e32 v105, 0xffff0000, v120
	v_lshlrev_b32_e32 v106, 16, v121
	v_and_b32_e32 v107, 0xffff0000, v121
	v_lshl_add_u64 v[102:103], s[22:23], 0, v[102:103]
	v_pk_fma_f32 v[92:93], v[92:93], v[68:69], v[100:101]
	v_pk_fma_f32 v[90:91], v[90:91], v[66:67], v[98:99]
	v_pk_fma_f32 v[88:89], v[88:89], v[64:65], v[106:107]
	v_pk_fma_f32 v[86:87], v[86:87], v[62:63], v[104:105]
	s_and_b64 vcc, exec, s[8:9]
	v_cvt_pk_bf16_f32 v98, v90, v91
	v_cvt_pk_bf16_f32 v99, v92, v93
	v_cvt_pk_bf16_f32 v100, v86, v87
	v_cvt_pk_bf16_f32 v101, v88, v89
	global_store_dwordx4 v241, v[98:101], s[22:23] offset:1024
	s_cbranch_vccnz .LBB0_1274
	s_nop 0
	v_pk_mul_f32 v[98:99], v[148:149], v[92:93]
	v_mul_f32_e32 v101, v91, v91
	v_mul_f32_e32 v93, v93, v93
	v_mul_f32_e32 v100, v87, v87
	v_fmac_f32_e32 v101, v90, v90
	v_fmac_f32_e32 v93, v92, v92
	v_mul_f32_e32 v97, v89, v89
	v_fmac_f32_e32 v100, v86, v86
	v_add_f32_e32 v92, v101, v93
	v_fmac_f32_e32 v97, v88, v88
	v_add_f32_e32 v92, v100, v92
	v_add_f32_e32 v92, v97, v92
	v_add_f32_e32 v100, v92, v96
	ds_bpermute_b32 v101, v159, v100
	v_pk_mul_f32 v[96:97], v[146:147], v[86:87]
	v_pk_mul_f32 v[90:91], v[142:143], v[90:91]
	v_pk_mul_f32 v[92:93], v[144:145], v[88:89]
	v_cvt_pk_bf16_f32 v88, v90, v91
	s_waitcnt lgkmcnt(0)
	v_add_f32_e32 v86, v100, v101
	ds_bpermute_b32 v87, v158, v86
	v_cvt_pk_bf16_f32 v89, v98, v99
	v_cvt_pk_bf16_f32 v90, v96, v97
	v_cvt_pk_bf16_f32 v91, v92, v93
	global_store_dwordx4 v[94:95], v[88:91], off offset:256
	s_and_saveexec_b64 s[2:3], s[10:11]
	s_cbranch_execz .LBB0_1273
	s_waitcnt lgkmcnt(0)
	v_add_f32_e32 v86, v86, v87
	v_mul_f32_e32 v86, 0x4b800000, v86
	v_trunc_f32_e32 v86, v86
	v_mul_f32_e32 v87, 0x2f800000, v86
	v_floor_f32_e32 v87, v87
	v_fmac_f32_e32 v86, 0xcf800000, v87
	v_cvt_u32_f32_e32 v86, v86
	v_cvt_u32_f32_e32 v87, v87
	v_ashrrev_i32_e32 v205, 31, v204
	v_lshl_add_u64 v[88:89], v[204:205], 3, s[16:17]
	global_atomic_add_x2 v[88:89], v[86:87], off offset:384

; __device__ __forceinline__ unsigned cvt_pk_bf16(float lo, float hi) { unsigned r; asm volatile("v_cvt_pk_bf16_f32 %0, %1, %2" : "=v"(r) : "v"(lo), "v"(hi)); return r; }
; #define PG8_GPTR(p) ((__attribute__((address_space(1))) char*)(p))
;     __device__ __forceinline__ void operator()(const f32x4 (&acc)[2][2][4][2], const Unit& u, int wr, int wc, int fr, int fq) const {
;     ...
;             for (int mm = 0; mm < 2; ++mm) {
;                 const int m = mp + mm;
;                 const int row = u.pm * BM + ai * HALF + wr * 64 + m * 16 + fr; float q = 0.f;
; #pragma unroll
;                 for (int bj = 0; bj < 2; ++bj) {
;                     const unsigned offb = (unsigned)(row * DM + col0 + bj * HALF) * 2u;
;                     const u32x4 bw = bv[mm][bj];
;                     const f32x4 b0 = (f32x4){__uint_as_float(bw.x << 16), __uint_as_float(bw.x & 0xffff0000u), __uint_as_float(bw.y << 16), __uint_as_float(bw.y & 0xffff0000u)};
;                     const f32x4 b1 = (f32x4){__uint_as_float(bw.z << 16), __uint_as_float(bw.z & 0xffff0000u), __uint_as_float(bw.w << 16), __uint_as_float(bw.w & 0xffff0000u)};
;                     f32x4 a0 = acc[ai][bj][m][0], a1 = acc[ai][bj][m][1]; if constexpr (GN) { a0 *= rc[ai * 4 + m]; a1 *= rc[ai * 4 + m]; }
;                     const f32x4 o0 = b0 + g[bj][0] * a0, o1 = b1 + g[bj][1] * a1;
;                     u32x4 wo; wo.x = cvt_pk_bf16(o0[0], o0[1]); wo.y = cvt_pk_bf16(o0[2], o0[3]); wo.z = cvt_pk_bf16(o1[0], o1[1]); wo.w = cvt_pk_bf16(o1[2], o1[3]);
;                     *(gs_u32x4*)(PG8_GPTR(out) + offb) = wo;
;                     if (xg) {
;                         const f32x4 h0 = o0 * cf[bj][0], h1 = o1 * cf[bj][1];
;                         u32x4 w; w.x = cvt_pk_bf16(h0[0], h0[1]); w.y = cvt_pk_bf16(h0[2], h0[3]); w.z = cvt_pk_bf16(h1[0], h1[1]); w.w = cvt_pk_bf16(h1[2], h1[3]);
;                         *(gs_u32x4*)(PG8_GPTR(xg) + offb) = w;
;                         q += (o0[0] * o0[0] + o0[1] * o0[1]) + (o0[2] * o0[2] + o0[3] * o0[3]) + (o1[0] * o1[0] + o1[1] * o1[1]) + (o1[2] * o1[2] + o1[3] * o1[3]);
;                     }
;                 }
;                 if (xg) ssq_put(ssq, row, q, fr, fq);
.LBB0_1277:
	v_lshlrev_b32_e32 v80, 16, v94
	v_and_b32_e32 v81, 0xffff0000, v94
	v_lshlrev_b32_e32 v82, 16, v95
	v_and_b32_e32 v83, 0xffff0000, v95
	v_lshlrev_b32_e32 v94, 16, v96
	v_and_b32_e32 v95, 0xffff0000, v96
	v_lshlrev_b32_e32 v96, 16, v97
	v_and_b32_e32 v97, 0xffff0000, v97
	v_lshl_add_u64 v[84:85], s[22:23], 0, v[98:99]
	v_pk_fma_f32 v[60:61], v[60:61], v[68:69], v[82:83]
	v_pk_fma_f32 v[58:59], v[58:59], v[66:67], v[80:81]
	v_pk_fma_f32 v[56:57], v[56:57], v[64:65], v[96:97]
	v_pk_fma_f32 v[54:55], v[54:55], v[62:63], v[94:95]
	s_and_b64 vcc, exec, s[8:9]
	v_cvt_pk_bf16_f32 v80, v58, v59
	v_cvt_pk_bf16_f32 v81, v60, v61
	v_cvt_pk_bf16_f32 v82, v54, v55
	v_cvt_pk_bf16_f32 v83, v56, v57
	global_store_dwordx4 v241, v[80:83], s[22:23] offset:1024
	s_cbranch_vccnz .LBB0_1281
	s_nop 0
	v_pk_mul_f32 v[80:81], v[148:149], v[60:61]
	v_mul_f32_e32 v83, v59, v59
	v_mul_f32_e32 v61, v61, v61
	v_mul_f32_e32 v82, v55, v55
	v_fmac_f32_e32 v83, v58, v58
	v_fmac_f32_e32 v61, v60, v60
	v_mul_f32_e32 v79, v57, v57
	v_fmac_f32_e32 v82, v54, v54
	v_add_f32_e32 v60, v83, v61
	v_fmac_f32_e32 v79, v56, v56
	v_add_f32_e32 v60, v82, v60
	v_add_f32_e32 v60, v79, v60
	v_add_f32_e32 v82, v60, v78
	ds_bpermute_b32 v83, v159, v82
	v_pk_mul_f32 v[78:79], v[146:147], v[54:55]
	v_pk_mul_f32 v[58:59], v[142:143], v[58:59]
	v_pk_mul_f32 v[60:61], v[144:145], v[56:57]
	v_cvt_pk_bf16_f32 v56, v58, v59
	s_waitcnt lgkmcnt(0)
	v_add_f32_e32 v54, v82, v83
	ds_bpermute_b32 v55, v158, v54
	v_cvt_pk_bf16_f32 v57, v80, v81
	v_cvt_pk_bf16_f32 v58, v78, v79
	v_cvt_pk_bf16_f32 v59, v60, v61
	global_store_dwordx4 v[100:101], v[56:59], off offset:256
	s_and_saveexec_b64 s[2:3], s[10:11]
	s_cbranch_execz .LBB0_1280
	s_waitcnt lgkmcnt(0)
	v_add_f32_e32 v54, v54, v55
	v_mul_f32_e32 v54, 0x4b800000, v54
	v_trunc_f32_e32 v54, v54
	v_mul_f32_e32 v55, 0x2f800000, v54
	v_floor_f32_e32 v55, v55
	v_fmac_f32_e32 v54, 0xcf800000, v55
	v_cvt_u32_f32_e32 v54, v54
	v_cvt_u32_f32_e32 v55, v55
	v_ashrrev_i32_e32 v205, 31, v204
	v_lshl_add_u64 v[56:57], v[204:205], 3, s[16:17]
	global_atomic_add_x2 v[56:57], v[54:55], off offset:1024

; __device__ __forceinline__ unsigned cvt_pk_bf16(float lo, float hi) { unsigned r; asm volatile("v_cvt_pk_bf16_f32 %0, %1, %2" : "=v"(r) : "v"(lo), "v"(hi)); return r; }
; #define PG8_GPTR(p) ((__attribute__((address_space(1))) char*)(p))
;     __device__ __forceinline__ void operator()(const f32x4 (&acc)[2][2][4][2], const Unit& u, int wr, int wc, int fr, int fq) const {
;     ...
;             for (int mm = 0; mm < 2; ++mm) {
;                 const int m = mp + mm;
;                 const int row = u.pm * BM + ai * HALF + wr * 64 + m * 16 + fr; float q = 0.f;
; #pragma unroll
;                 for (int bj = 0; bj < 2; ++bj) {
;                     const unsigned offb = (unsigned)(row * DM + col0 + bj * HALF) * 2u;
;                     const u32x4 bw = bv[mm][bj];
;                     const f32x4 b0 = (f32x4){__uint_as_float(bw.x << 16), __uint_as_float(bw.x & 0xffff0000u), __uint_as_float(bw.y << 16), __uint_as_float(bw.y & 0xffff0000u)};
;                     const f32x4 b1 = (f32x4){__uint_as_float(bw.z << 16), __uint_as_float(bw.z & 0xffff0000u), __uint_as_float(bw.w << 16), __uint_as_float(bw.w & 0xffff0000u)};
;                     f32x4 a0 = acc[ai][bj][m][0], a1 = acc[ai][bj][m][1]; if constexpr (GN) { a0 *= rc[ai * 4 + m]; a1 *= rc[ai * 4 + m]; }
;                     const f32x4 o0 = b0 + g[bj][0] * a0, o1 = b1 + g[bj][1] * a1;
;                     u32x4 wo; wo.x = cvt_pk_bf16(o0[0], o0[1]); wo.y = cvt_pk_bf16(o0[2], o0[3]); wo.z = cvt_pk_bf16(o1[0], o1[1]); wo.w = cvt_pk_bf16(o1[2], o1[3]);
;                     *(gs_u32x4*)(PG8_GPTR(out) + offb) = wo;
;                     if (xg) {
;                         const f32x4 h0 = o0 * cf[bj][0], h1 = o1 * cf[bj][1];
;                         u32x4 w; w.x = cvt_pk_bf16(h0[0], h0[1]); w.y = cvt_pk_bf16(h0[2], h0[3]); w.z = cvt_pk_bf16(h1[0], h1[1]); w.w = cvt_pk_bf16(h1[2], h1[3]);
;                         *(gs_u32x4*)(PG8_GPTR(xg) + offb) = w;
;                         q += (o0[0] * o0[0] + o0[1] * o0[1]) + (o0[2] * o0[2] + o0[3] * o0[3]) + (o1[0] * o1[0] + o1[1] * o1[1]) + (o1[2] * o1[2] + o1[3] * o1[3]);
;                     }
;                 }
;                 if (xg) ssq_put(ssq, row, q, fr, fq);
.LBB0_1284:
	v_lshlrev_b32_e32 v50, 16, v86
	v_and_b32_e32 v51, 0xffff0000, v86
	v_lshlrev_b32_e32 v52, 16, v87
	v_and_b32_e32 v53, 0xffff0000, v87
	v_lshlrev_b32_e32 v56, 16, v88
	v_and_b32_e32 v57, 0xffff0000, v88
	v_lshlrev_b32_e32 v58, 16, v89
	v_and_b32_e32 v59, 0xffff0000, v89
	v_lshl_add_u64 v[54:55], s[22:23], 0, v[54:55]
	v_pk_fma_f32 v[44:45], v[44:45], v[68:69], v[52:53]
	v_pk_fma_f32 v[42:43], v[42:43], v[66:67], v[50:51]
	v_pk_fma_f32 v[40:41], v[40:41], v[64:65], v[58:59]
	v_pk_fma_f32 v[38:39], v[38:39], v[62:63], v[56:57]
	s_and_b64 vcc, exec, s[8:9]
	v_cvt_pk_bf16_f32 v50, v42, v43
	v_cvt_pk_bf16_f32 v51, v44, v45
	v_cvt_pk_bf16_f32 v52, v38, v39
	v_cvt_pk_bf16_f32 v53, v40, v41
	global_store_dwordx4 v241, v[50:53], s[22:23] offset:1024
	s_cbranch_vccnz .LBB0_1288
	s_nop 0
	v_pk_mul_f32 v[50:51], v[148:149], v[44:45]
	v_mul_f32_e32 v53, v43, v43
	v_mul_f32_e32 v45, v45, v45
	v_mul_f32_e32 v52, v39, v39
	v_fmac_f32_e32 v53, v42, v42
	v_fmac_f32_e32 v45, v44, v44
	v_mul_f32_e32 v49, v41, v41
	v_fmac_f32_e32 v52, v38, v38
	v_add_f32_e32 v44, v53, v45
	v_fmac_f32_e32 v49, v40, v40
	v_add_f32_e32 v44, v52, v44
	v_add_f32_e32 v44, v49, v44
	v_add_f32_e32 v52, v44, v48
	ds_bpermute_b32 v53, v159, v52
	v_pk_mul_f32 v[48:49], v[146:147], v[38:39]
	v_pk_mul_f32 v[42:43], v[142:143], v[42:43]
	v_pk_mul_f32 v[44:45], v[144:145], v[40:41]
	v_cvt_pk_bf16_f32 v40, v42, v43
	s_waitcnt lgkmcnt(0)
	v_add_f32_e32 v38, v52, v53
	ds_bpermute_b32 v39, v158, v38
	v_cvt_pk_bf16_f32 v41, v50, v51
	v_cvt_pk_bf16_f32 v42, v48, v49
	v_cvt_pk_bf16_f32 v43, v44, v45
	global_store_dwordx4 v[46:47], v[40:43], off offset:256
	s_and_saveexec_b64 s[2:3], s[10:11]
	s_cbranch_execz .LBB0_1287
	s_waitcnt lgkmcnt(0)
	v_add_f32_e32 v38, v38, v39
	v_mul_f32_e32 v38, 0x4b800000, v38
	v_trunc_f32_e32 v38, v38
	v_mul_f32_e32 v39, 0x2f800000, v38
	v_floor_f32_e32 v39, v39
	v_fmac_f32_e32 v38, 0xcf800000, v39
	v_cvt_u32_f32_e32 v38, v38
	v_cvt_u32_f32_e32 v39, v39
	v_ashrrev_i32_e32 v205, 31, v204
	v_lshl_add_u64 v[40:41], v[204:205], 3, s[16:17]
	global_atomic_add_x2 v[40:41], v[38:39], off offset:1152

; __device__ __forceinline__ unsigned cvt_pk_bf16(float lo, float hi) { unsigned r; asm volatile("v_cvt_pk_bf16_f32 %0, %1, %2" : "=v"(r) : "v"(lo), "v"(hi)); return r; }
; #define PG8_GPTR(p) ((__attribute__((address_space(1))) char*)(p))
;     __device__ __forceinline__ void operator()(const f32x4 (&acc)[2][2][4][2], const Unit& u, int wr, int wc, int fr, int fq) const {
;     ...
;             for (int mm = 0; mm < 2; ++mm) {
;                 const int m = mp + mm;
;                 const int row = u.pm * BM + ai * HALF + wr * 64 + m * 16 + fr; float q = 0.f;
; #pragma unroll
;                 for (int bj = 0; bj < 2; ++bj) {
;                     const unsigned offb = (unsigned)(row * DM + col0 + bj * HALF) * 2u;
;                     const u32x4 bw = bv[mm][bj];
;                     const f32x4 b0 = (f32x4){__uint_as_float(bw.x << 16), __uint_as_float(bw.x & 0xffff0000u), __uint_as_float(bw.y << 16), __uint_as_float(bw.y & 0xffff0000u)};
;                     const f32x4 b1 = (f32x4){__uint_as_float(bw.z << 16), __uint_as_float(bw.z & 0xffff0000u), __uint_as_float(bw.w << 16), __uint_as_float(bw.w & 0xffff0000u)};
;                     f32x4 a0 = acc[ai][bj][m][0], a1 = acc[ai][bj][m][1]; if constexpr (GN) { a0 *= rc[ai * 4 + m]; a1 *= rc[ai * 4 + m]; }
;                     const f32x4 o0 = b0 + g[bj][0] * a0, o1 = b1 + g[bj][1] * a1;
;                     u32x4 wo; wo.x = cvt_pk_bf16(o0[0], o0[1]); wo.y = cvt_pk_bf16(o0[2], o0[3]); wo.z = cvt_pk_bf16(o1[0], o1[1]); wo.w = cvt_pk_bf16(o1[2], o1[3]);
;                     *(gs_u32x4*)(PG8_GPTR(out) + offb) = wo;
;                     if (xg) {
;                         const f32x4 h0 = o0 * cf[bj][0], h1 = o1 * cf[bj][1];
;                         u32x4 w; w.x = cvt_pk_bf16(h0[0], h0[1]); w.y = cvt_pk_bf16(h0[2], h0[3]); w.z = cvt_pk_bf16(h1[0], h1[1]); w.w = cvt_pk_bf16(h1[2], h1[3]);
;                         *(gs_u32x4*)(PG8_GPTR(xg) + offb) = w;
;                         q += (o0[0] * o0[0] + o0[1] * o0[1]) + (o0[2] * o0[2] + o0[3] * o0[3]) + (o1[0] * o1[0] + o1[1] * o1[1]) + (o1[2] * o1[2] + o1[3] * o1[3]);
;                     }
;                 }
;                 if (xg) ssq_put(ssq, row, q, fr, fq);
.LBB0_1291:
	v_lshlrev_b32_e32 v34, 16, v46
	v_and_b32_e32 v35, 0xffff0000, v46
	v_lshlrev_b32_e32 v36, 16, v47
	v_and_b32_e32 v37, 0xffff0000, v47
	v_lshlrev_b32_e32 v46, 16, v48
	v_and_b32_e32 v47, 0xffff0000, v48
	v_lshlrev_b32_e32 v48, 16, v49
	v_and_b32_e32 v49, 0xffff0000, v49
	v_lshl_add_u64 v[50:51], s[22:23], 0, v[0:1]
	v_pk_fma_f32 v[28:29], v[28:29], v[68:69], v[36:37]
	v_pk_fma_f32 v[26:27], v[26:27], v[66:67], v[34:35]
	v_pk_fma_f32 v[24:25], v[24:25], v[64:65], v[48:49]
	v_pk_fma_f32 v[22:23], v[22:23], v[62:63], v[46:47]
	s_and_b64 vcc, exec, s[8:9]
	v_cvt_pk_bf16_f32 v34, v26, v27
	v_cvt_pk_bf16_f32 v35, v28, v29
	v_cvt_pk_bf16_f32 v36, v22, v23
	v_cvt_pk_bf16_f32 v37, v24, v25
	global_store_dwordx4 v241, v[34:37], s[22:23] offset:1024
	s_cbranch_vccnz .LBB0_1295
	s_nop 0
	v_pk_mul_f32 v[34:35], v[148:149], v[28:29]
	v_mul_f32_e32 v36, v27, v27
	v_mul_f32_e32 v29, v29, v29
	v_mul_f32_e32 v33, v23, v23
	v_fmac_f32_e32 v36, v26, v26
	v_fmac_f32_e32 v29, v28, v28
	v_mul_f32_e32 v0, v25, v25
	v_fmac_f32_e32 v33, v22, v22
	v_add_f32_e32 v28, v36, v29
	v_fmac_f32_e32 v0, v24, v24
	v_add_f32_e32 v28, v33, v28
	v_add_f32_e32 v0, v0, v28
	v_add_f32_e32 v0, v0, v32
	ds_bpermute_b32 v36, v159, v0
	v_pk_mul_f32 v[32:33], v[146:147], v[22:23]
	v_pk_mul_f32 v[26:27], v[142:143], v[26:27]
	v_pk_mul_f32 v[28:29], v[144:145], v[24:25]
	v_cvt_pk_bf16_f32 v24, v26, v27
	s_waitcnt lgkmcnt(0)
	v_add_f32_e32 v0, v0, v36
	ds_bpermute_b32 v22, v158, v0
	v_cvt_pk_bf16_f32 v25, v34, v35
	v_cvt_pk_bf16_f32 v26, v32, v33
	v_cvt_pk_bf16_f32 v27, v28, v29
	global_store_dwordx4 v[30:31], v[24:27], off offset:256
	s_and_saveexec_b64 s[2:3], s[10:11]
	s_cbranch_execz .LBB0_1294
	s_waitcnt lgkmcnt(0)
	v_add_f32_e32 v0, v0, v22
	v_mul_f32_e32 v0, 0x4b800000, v0
	v_trunc_f32_e32 v0, v0
	v_mul_f32_e32 v22, 0x2f800000, v0
	v_floor_f32_e32 v23, v22
	v_fmac_f32_e32 v0, 0xcf800000, v23
	v_cvt_u32_f32_e32 v22, v0
	v_cvt_u32_f32_e32 v23, v23
	v_ashrrev_i32_e32 v205, 31, v204
	v_lshl_add_u64 v[24:25], v[204:205], 3, s[16:17]
	global_atomic_add_x2 v[24:25], v[22:23], off offset:1280

; __device__ __forceinline__ unsigned cvt_pk_bf16(float lo, float hi) { unsigned r; asm volatile("v_cvt_pk_bf16_f32 %0, %1, %2" : "=v"(r) : "v"(lo), "v"(hi)); return r; }
; #define PG8_GPTR(p) ((__attribute__((address_space(1))) char*)(p))
;     __device__ __forceinline__ void operator()(const f32x4 (&acc)[2][2][4][2], const Unit& u, int wr, int wc, int fr, int fq) const {
;     ...
;             for (int mm = 0; mm < 2; ++mm) {
;                 const int m = mp + mm;
;                 const int row = u.pm * BM + ai * HALF + wr * 64 + m * 16 + fr; float q = 0.f;
; #pragma unroll
;                 for (int bj = 0; bj < 2; ++bj) {
;                     const unsigned offb = (unsigned)(row * DM + col0 + bj * HALF) * 2u;
;                     const u32x4 bw = bv[mm][bj];
;                     const f32x4 b0 = (f32x4){__uint_as_float(bw.x << 16), __uint_as_float(bw.x & 0xffff0000u), __uint_as_float(bw.y << 16), __uint_as_float(bw.y & 0xffff0000u)};
;                     const f32x4 b1 = (f32x4){__uint_as_float(bw.z << 16), __uint_as_float(bw.z & 0xffff0000u), __uint_as_float(bw.w << 16), __uint_as_float(bw.w & 0xffff0000u)};
;                     f32x4 a0 = acc[ai][bj][m][0], a1 = acc[ai][bj][m][1]; if constexpr (GN) { a0 *= rc[ai * 4 + m]; a1 *= rc[ai * 4 + m]; }
;                     const f32x4 o0 = b0 + g[bj][0] * a0, o1 = b1 + g[bj][1] * a1;
;                     u32x4 wo; wo.x = cvt_pk_bf16(o0[0], o0[1]); wo.y = cvt_pk_bf16(o0[2], o0[3]); wo.z = cvt_pk_bf16(o1[0], o1[1]); wo.w = cvt_pk_bf16(o1[2], o1[3]);
;                     *(gs_u32x4*)(PG8_GPTR(out) + offb) = wo;
;                     if (xg) {
;                         const f32x4 h0 = o0 * cf[bj][0], h1 = o1 * cf[bj][1];
;                         u32x4 w; w.x = cvt_pk_bf16(h0[0], h0[1]); w.y = cvt_pk_bf16(h0[2], h0[3]); w.z = cvt_pk_bf16(h1[0], h1[1]); w.w = cvt_pk_bf16(h1[2], h1[3]);
;                         *(gs_u32x4*)(PG8_GPTR(xg) + offb) = w;
;                         q += (o0[0] * o0[0] + o0[1] * o0[1]) + (o0[2] * o0[2] + o0[3] * o0[3]) + (o1[0] * o1[0] + o1[1] * o1[1]) + (o1[2] * o1[2] + o1[3] * o1[3]);
;                     }
;                 }
;                 if (xg) ssq_put(ssq, row, q, fr, fq);
.LBB0_1298:
	v_lshlrev_b32_e32 v18, 16, v38
	v_and_b32_e32 v19, 0xffff0000, v38
	v_lshlrev_b32_e32 v20, 16, v39
	v_and_b32_e32 v21, 0xffff0000, v39
	v_lshlrev_b32_e32 v24, 16, v40
	v_and_b32_e32 v25, 0xffff0000, v40
	v_lshlrev_b32_e32 v26, 16, v41
	v_and_b32_e32 v27, 0xffff0000, v41
	v_lshl_add_u64 v[22:23], s[22:23], 0, v[0:1]
	v_pk_fma_f32 v[8:9], v[8:9], v[68:69], v[20:21]
	v_pk_fma_f32 v[6:7], v[6:7], v[66:67], v[18:19]
	v_pk_fma_f32 v[4:5], v[4:5], v[64:65], v[26:27]
	v_pk_fma_f32 v[2:3], v[2:3], v[62:63], v[24:25]
	s_and_b64 vcc, exec, s[8:9]
	v_cvt_pk_bf16_f32 v18, v6, v7
	v_cvt_pk_bf16_f32 v19, v8, v9
	v_cvt_pk_bf16_f32 v20, v2, v3
	v_cvt_pk_bf16_f32 v21, v4, v5
	global_store_dwordx4 v241, v[18:21], s[22:23] offset:1024
	s_cbranch_vccnz .LBB0_1302
	s_nop 0
	v_pk_mul_f32 v[18:19], v[148:149], v[8:9]
	v_mul_f32_e32 v20, v7, v7
	v_mul_f32_e32 v9, v9, v9
	v_mul_f32_e32 v13, v3, v3
	v_fmac_f32_e32 v20, v6, v6
	v_fmac_f32_e32 v9, v8, v8
	v_mul_f32_e32 v0, v5, v5
	v_fmac_f32_e32 v13, v2, v2
	v_add_f32_e32 v8, v20, v9
	v_fmac_f32_e32 v0, v4, v4
	v_add_f32_e32 v8, v13, v8
	v_add_f32_e32 v0, v0, v8
	v_add_f32_e32 v0, v0, v12
	ds_bpermute_b32 v20, v159, v0
	v_pk_mul_f32 v[12:13], v[146:147], v[2:3]
	v_pk_mul_f32 v[6:7], v[142:143], v[6:7]
	v_pk_mul_f32 v[8:9], v[144:145], v[4:5]
	v_cvt_pk_bf16_f32 v4, v6, v7
	s_waitcnt lgkmcnt(0)
	v_add_f32_e32 v0, v0, v20
	ds_bpermute_b32 v2, v158, v0
	v_cvt_pk_bf16_f32 v5, v18, v19
	v_cvt_pk_bf16_f32 v6, v12, v13
	v_cvt_pk_bf16_f32 v7, v8, v9
	global_store_dwordx4 v[10:11], v[4:7], off offset:256
	s_and_saveexec_b64 s[2:3], s[10:11]
	s_cbranch_execz .LBB0_1301
	s_waitcnt lgkmcnt(0)
	v_add_f32_e32 v0, v0, v2
	v_mul_f32_e32 v0, 0x4b800000, v0
	v_trunc_f32_e32 v0, v0
	v_mul_f32_e32 v2, 0x2f800000, v0
	v_floor_f32_e32 v3, v2
	v_fmac_f32_e32 v0, 0xcf800000, v3
	v_cvt_u32_f32_e32 v2, v0
	v_cvt_u32_f32_e32 v3, v3
	v_ashrrev_i32_e32 v205, 31, v204
	v_lshl_add_u64 v[4:5], v[204:205], 3, s[16:17]
	global_atomic_add_x2 v[4:5], v[2:3], off offset:1408

; __device__ __forceinline__ float bflo(unsigned w) { return __uint_as_float(w << 16); }
; __device__ __forceinline__ float bfhi(unsigned w) { return __uint_as_float(w & 0xffff0000u); }
; __device__ __forceinline__ void final_norm_pass(const bf16_t* x16, float* out, const float* nw, int vcu, int ngw, const int wave_s) {
;     ...
;     for (int m0 = 4 * gw; m0 < MTOK; m0 += 4 * ngw) {
;         u32x4 a[4], b[4];
; #pragma unroll
;         for (int i = 0; i < 4; ++i) { const u32x4* xr = (const u32x4*)(x16 + (size_t)(m0 + i) * DM + 16 * lane); a[i] = xr[0]; b[i] = xr[1]; }
; #pragma unroll
;         for (int i = 0; i < 4; ++i) {
;             f32x4 v[4];
;             v[0] = (f32x4){bflo(a[i].x), bfhi(a[i].x), bflo(a[i].y), bfhi(a[i].y)}; v[1] = (f32x4){bflo(a[i].z), bfhi(a[i].z), bflo(a[i].w), bfhi(a[i].w)};
;             v[2] = (f32x4){bflo(b[i].x), bfhi(b[i].x), bflo(b[i].y), bfhi(b[i].y)}; v[3] = (f32x4){bflo(b[i].z), bfhi(b[i].z), bflo(b[i].w), bfhi(b[i].w)};
;             float s = 0.f;
; #pragma unroll
;             for (int j = 0; j < 4; ++j) s += (v[j].x * v[j].x + v[j].y * v[j].y) + (v[j].z * v[j].z + v[j].w * v[j].w);
;             const float rstd = 1.0f / sqrtf(wave_sum(s, lane) * (1.0f / DM) + EPS);
.LBB0_1353:
	v_lshl_add_u64 v[164:165], v[20:21], 0, v[162:163]
	v_add_co_u32_e32 v38, vcc, 0xffffe7f0, v20
	v_add_co_u32_e64 v40, s[0:1], -16, v20
	s_nop 0
	v_addc_co_u32_e32 v39, vcc, -1, v21, vcc
	v_addc_co_u32_e64 v41, s[0:1], -1, v21, s[0:1]
	global_load_dwordx4 v[64:67], v[164:165], off offset:208
	global_load_dwordx4 v[58:61], v[164:165], off offset:192
	v_add_co_u32_e32 v40, vcc, 0xffffe800, v20
	global_load_dwordx4 v[70:73], v[164:165], off offset:0
	s_nop 0
	v_addc_co_u32_e32 v41, vcc, -1, v21, vcc
	v_add_co_u32_e32 v38, vcc, 0xffffeff0, v20
	global_load_dwordx4 v[78:81], v[164:165], off offset:16
	s_nop 0
	v_addc_co_u32_e32 v39, vcc, -1, v21, vcc
	v_add_co_u32_e32 v40, vcc, 0xfffff000, v20
	global_load_dwordx4 v[90:93], v[164:165], off offset:64
	s_nop 0
	v_addc_co_u32_e32 v41, vcc, -1, v21, vcc
	v_add_co_u32_e32 v38, vcc, 0xfffff7f0, v20
	global_load_dwordx4 v[96:99], v[164:165], off offset:80
	s_nop 0
	v_addc_co_u32_e32 v39, vcc, -1, v21, vcc
	v_add_co_u32_e32 v40, vcc, 0xfffff800, v20
	v_add_co_u32_e64 v22, s[0:1], s20, v18
	s_nop 0
	v_addc_co_u32_e32 v41, vcc, -1, v21, vcc
	global_load_dwordx4 v[100:103], v[164:165], off offset:128
	global_load_dwordx4 v[118:121], v[164:165], off offset:144
	v_addc_co_u32_e64 v23, s[0:1], -1, v19, s[0:1]
	v_add_co_u32_e64 v24, s[0:1], s21, v18
	v_add_u32_e32 v16, s10, v16
	s_nop 0
	v_addc_co_u32_e64 v25, s[0:1], -1, v19, s[0:1]
	v_add_co_u32_e64 v26, s[0:1], s22, v18
	v_lshl_add_u64 v[20:21], v[20:21], 0, s[14:15]
	s_nop 0
	v_addc_co_u32_e64 v27, s[0:1], -1, v19, s[0:1]
	v_add_co_u32_e64 v28, s[0:1], s23, v18
	s_waitcnt vmcnt(0) lgkmcnt(0)
	v_lshlrev_b32_e32 v62, 16, v64
	v_lshlrev_b32_e32 v56, 16, v58
	v_and_b32_e32 v57, 0xffff0000, v58
	v_lshlrev_b32_e32 v58, 16, v59
	v_lshlrev_b32_e32 v68, 16, v70
	v_and_b32_e32 v69, 0xffff0000, v70
	v_lshlrev_b32_e32 v70, 16, v71
	v_lshlrev_b32_e32 v83, 16, v61
	v_lshlrev_b32_e32 v82, 16, v60
	v_and_b32_e32 v61, 0xffff0000, v61
	v_and_b32_e32 v60, 0xffff0000, v60
	v_and_b32_e32 v63, 0xffff0000, v64
	v_lshlrev_b32_e32 v64, 16, v65
	v_and_b32_e32 v71, 0xffff0000, v71
	v_lshlrev_b32_e32 v95, 16, v73
	v_lshlrev_b32_e32 v94, 16, v72
	v_and_b32_e32 v73, 0xffff0000, v73
	v_and_b32_e32 v72, 0xffff0000, v72
	v_lshlrev_b32_e32 v74, 16, v80
	v_and_b32_e32 v135, 0xffff0000, v80
	v_mul_f32_e32 v80, v68, v68
	v_mul_f32_e32 v128, v70, v70
	v_and_b32_e32 v59, 0xffff0000, v59
	v_and_b32_e32 v65, 0xffff0000, v65
	v_mul_f32_e32 v104, v56, v56
	v_mul_f32_e32 v106, v58, v58
	v_pk_mul_f32 v[108:109], v[60:61], v[60:61]
	v_mul_f32_e32 v122, v62, v62
	v_mul_f32_e32 v124, v64, v64
	v_pk_mul_f32 v[130:131], v[72:73], v[72:73]
	v_lshlrev_b32_e32 v84, 16, v78
	v_lshlrev_b32_e32 v86, 16, v79
	v_pk_fma_f32 v[132:133], v[68:69], v[68:69], v[80:81] op_sel_hi:[1,1,0]
	v_pk_fma_f32 v[128:129], v[70:71], v[70:71], v[128:129] op_sel_hi:[1,1,0]
	v_lshlrev_b32_e32 v38, 16, v66
	v_lshlrev_b32_e32 v40, 16, v67
	v_and_b32_e32 v41, 0xffff0000, v67
	v_and_b32_e32 v85, 0xffff0000, v78
	v_and_b32_e32 v87, 0xffff0000, v79
	v_mov_b32_e32 v88, v94
	v_mov_b32_e32 v89, v72
	v_mov_b32_e32 v72, v95
	v_pk_fma_f32 v[104:105], v[56:57], v[56:57], v[104:105] op_sel_hi:[1,1,0]
	v_pk_fma_f32 v[106:107], v[58:59], v[58:59], v[106:107] op_sel_hi:[1,1,0]
	v_pk_fma_f32 v[108:109], v[82:83], v[82:83], v[108:109]
	v_pk_fma_f32 v[122:123], v[62:63], v[62:63], v[122:123] op_sel_hi:[1,1,0]
	v_pk_fma_f32 v[124:125], v[64:65], v[64:65], v[124:125] op_sel_hi:[1,1,0]
	v_pk_fma_f32 v[94:95], v[94:95], v[94:95], v[130:131]
	v_mul_f32_e32 v130, v84, v84
	v_mul_f32_e32 v134, v86, v86
	v_lshlrev_b32_e32 v78, 16, v90
	v_lshlrev_b32_e32 v80, 16, v91
	v_mov_b32_e32 v137, v129
	v_pk_add_f32 v[128:129], v[132:133], v[128:129]
	v_mov_b32_e32 v126, v38
	v_lshlrev_b32_e32 v76, 16, v81
	v_and_b32_e32 v77, 0xffff0000, v81
	v_mov_b32_e32 v136, v74
	v_and_b32_e32 v79, 0xffff0000, v90
	v_and_b32_e32 v81, 0xffff0000, v91
	v_pk_add_f32 v[140:141], v[108:109], v[108:109] op_sel_hi:[0,1]
	v_mul_f32_e32 v122, v40, v40
	v_mul_f32_e32 v124, v41, v41
	v_mov_b32_e32 v39, v105
	v_mov_b32_e32 v127, v107
	v_pk_add_f32 v[90:91], v[104:105], v[106:107]
	v_pk_add_f32 v[142:143], v[94:95], v[94:95] op_sel_hi:[0,1]
	v_pk_fma_f32 v[106:107], v[84:85], v[84:85], v[130:131] op_sel_hi:[1,1,0]
	v_pk_fma_f32 v[108:109], v[86:87], v[86:87], v[134:135] op_sel_hi:[1,1,0]
	v_mov_b32_e32 v75, v133
	v_mul_f32_e32 v128, v78, v78
	v_mul_f32_e32 v130, v80, v80
	v_and_b32_e32 v117, 0xffff0000, v66
	v_mov_b32_e32 v66, v82
	v_mov_b32_e32 v67, v60
	v_mov_b32_e32 v60, v83
	v_and_b32_e32 v83, 0xffff0000, v93
	v_and_b32_e32 v82, 0xffff0000, v92
	v_lshlrev_b32_e32 v90, 16, v98
	v_and_b32_e32 v154, 0xffff0000, v98
	v_lshlrev_b32_e32 v94, 16, v96
	v_lshlrev_b32_e32 v98, 16, v97
	v_pk_mul_f32 v[126:127], v[38:39], v[126:127]
	v_pk_add_f32 v[122:123], v[122:123], v[124:125]
	v_mul_f32_e32 v142, v135, v135
	v_mul_f32_e32 v106, v76, v76
	v_mul_f32_e32 v108, v77, v77
	v_pk_mul_f32 v[124:125], v[74:75], v[136:137]
	v_mov_b32_e32 v75, v135
	v_pk_fma_f32 v[134:135], v[78:79], v[78:79], v[128:129] op_sel_hi:[1,1,0]
	v_pk_fma_f32 v[130:131], v[80:81], v[80:81], v[130:131] op_sel_hi:[1,1,0]
	v_lshlrev_b32_e32 v139, 16, v93
	v_lshlrev_b32_e32 v138, 16, v92
	v_lshlrev_b32_e32 v92, 16, v99
	v_and_b32_e32 v93, 0xffff0000, v99
	v_pk_mul_f32 v[132:133], v[82:83], v[82:83]
	v_and_b32_e32 v95, 0xffff0000, v96
	v_and_b32_e32 v99, 0xffff0000, v97
	v_mul_f32_e32 v140, v117, v117
	v_mul_f32_e32 v128, v94, v94
	v_mul_f32_e32 v136, v98, v98
	v_lshlrev_b32_e32 v96, 16, v100
	v_and_b32_e32 v97, 0xffff0000, v100
	v_lshlrev_b32_e32 v100, 16, v101
	v_lshlrev_b32_e32 v145, 16, v103
	v_lshlrev_b32_e32 v144, 16, v102
; __device__ __forceinline__ float shfl_x(float v, int m, int lane) { return __builtin_bit_cast(float, __builtin_amdgcn_ds_bpermute((lane ^ m) << 2, __builtin_bit_cast(int, v))); }
; __device__ __forceinline__ float wave_sum(float v, int lane) {
; #pragma unroll
;     for (int o = 1; o < 64; o <<= 1) v += shfl_x(v, o, lane);
;     return v;
; __device__ __forceinline__ void final_norm_pass(const bf16_t* x16, float* out, const float* nw, int vcu, int ngw, const int wave_s) {
;     ...
;             float s = 0.f;
; #pragma unroll
;             for (int j = 0; j < 4; ++j) s += (v[j].x * v[j].x + v[j].y * v[j].y) + (v[j].z * v[j].z + v[j].w * v[j].w);
;             const float rstd = 1.0f / sqrtf(wave_sum(s, lane) * (1.0f / DM) + EPS);
	v_and_b32_e32 v103, 0xffff0000, v103
	v_and_b32_e32 v102, 0xffff0000, v102
	v_mov_b32_e32 v127, v91
	v_pk_add_f32 v[146:147], v[106:107], v[108:109]
	v_pk_add_f32 v[106:107], v[134:135], v[130:131]
	v_mov_b32_e32 v104, v138
	v_mov_b32_e32 v105, v82
	v_mov_b32_e32 v82, v139
	v_mov_b32_e32 v39, v117
	v_pk_fma_f32 v[132:133], v[138:139], v[138:139], v[132:133]
	v_mov_b32_e32 v138, v90
	v_and_b32_e32 v101, 0xffff0000, v101
	v_mov_b32_e32 v125, v129
	v_pk_fma_f32 v[128:129], v[94:95], v[94:95], v[128:129] op_sel_hi:[1,1,0]
	v_pk_fma_f32 v[136:137], v[98:99], v[98:99], v[136:137] op_sel_hi:[1,1,0]
	v_mov_b32_e32 v91, v135
	v_mov_b32_e32 v139, v131
	v_lshlrev_b32_e32 v106, 16, v120
	v_and_b32_e32 v117, 0xffff0000, v120
	v_mul_f32_e32 v120, v96, v96
	v_mul_f32_e32 v130, v100, v100
	v_pk_mul_f32 v[134:135], v[102:103], v[102:103]
	v_lshlrev_b32_e32 v148, 16, v118
	v_and_b32_e32 v149, 0xffff0000, v118
	v_lshlrev_b32_e32 v150, 16, v119
	v_and_b32_e32 v151, 0xffff0000, v119
	v_pk_add_f32 v[118:119], v[126:127], v[140:141]
	v_pk_add_f32 v[132:133], v[132:133], v[132:133] op_sel_hi:[0,1]
	v_lshlrev_b32_e32 v108, 16, v121
	v_and_b32_e32 v109, 0xffff0000, v121
	v_pk_add_f32 v[124:125], v[124:125], v[142:143]
	v_mul_f32_e32 v128, v92, v92
	v_mul_f32_e32 v136, v93, v93
	v_pk_mul_f32 v[126:127], v[90:91], v[138:139]
	v_pk_fma_f32 v[120:121], v[96:97], v[96:97], v[120:121] op_sel_hi:[1,1,0]
	v_pk_fma_f32 v[130:131], v[100:101], v[100:101], v[130:131] op_sel_hi:[1,1,0]
	v_pk_fma_f32 v[134:135], v[144:145], v[144:145], v[134:135]
	v_pk_add_f32 v[118:119], v[118:119], v[122:123]
	v_mul_f32_e32 v132, v154, v154
	v_mul_f32_e32 v138, v148, v148
	v_mul_f32_e32 v140, v150, v150
	v_mov_b32_e32 v142, v106
	v_pk_add_f32 v[122:123], v[124:125], v[146:147]
	v_mov_b32_e32 v127, v107
	v_pk_add_f32 v[124:125], v[128:129], v[136:137]
	v_pk_add_f32 v[128:129], v[134:135], v[134:135] op_sel_hi:[0,1]
	v_mov_b32_e32 v107, v121
	v_mov_b32_e32 v143, v131
	v_pk_add_f32 v[120:121], v[120:121], v[130:131]
	v_add_f32_e32 v130, v118, v119
	v_pk_fma_f32 v[134:135], v[148:149], v[148:149], v[138:139] op_sel_hi:[1,1,0]
	v_pk_fma_f32 v[136:137], v[150:151], v[150:151], v[140:141] op_sel_hi:[1,1,0]
	v_add_f32_e32 v131, v122, v123
	v_pk_add_f32 v[118:119], v[126:127], v[132:133]
	v_mul_f32_e32 v128, v117, v117
	v_pk_mul_f32 v[122:123], v[106:107], v[142:143]
	v_mov_b32_e32 v107, v117
	ds_bpermute_b32 v117, v110, v130
	v_mul_f32_e32 v134, v108, v108
	v_mul_f32_e32 v136, v109, v109
	ds_bpermute_b32 v126, v110, v131
	v_pk_add_f32 v[118:119], v[118:119], v[124:125]
	v_mov_b32_e32 v123, v121
	v_pk_add_f32 v[120:121], v[134:135], v[136:137]
	v_add_f32_e32 v124, v118, v119
	v_pk_add_f32 v[118:119], v[122:123], v[128:129]
	ds_bpermute_b32 v122, v110, v124
	v_pk_add_f32 v[118:119], v[118:119], v[120:121]
	s_waitcnt lgkmcnt(2)
	v_add_f32_e32 v117, v130, v117
	v_add_f32_e32 v118, v118, v119
	ds_bpermute_b32 v119, v110, v118
	s_waitcnt lgkmcnt(2)
	v_add_f32_e32 v120, v131, v126
	ds_bpermute_b32 v121, v111, v117
	ds_bpermute_b32 v123, v111, v120
	s_waitcnt lgkmcnt(3)
	v_add_f32_e32 v122, v124, v122
	ds_bpermute_b32 v124, v111, v122
	s_waitcnt lgkmcnt(3)
	v_add_f32_e32 v118, v118, v119
	ds_bpermute_b32 v119, v111, v118
	s_waitcnt lgkmcnt(3)
	v_add_f32_e32 v117, v117, v121
	s_waitcnt lgkmcnt(2)
	v_add_f32_e32 v120, v120, v123
	ds_bpermute_b32 v121, v112, v117
	ds_bpermute_b32 v123, v112, v120
	v_addc_co_u32_e64 v29, s[0:1], -1, v19, s[0:1]
	s_waitcnt lgkmcnt(3)
	v_add_f32_e32 v122, v122, v124
	v_add_co_u32_e64 v30, s[0:1], s24, v18
	ds_bpermute_b32 v124, v112, v122
	s_nop 0
	v_addc_co_u32_e64 v31, s[0:1], -1, v19, s[0:1]
	s_waitcnt lgkmcnt(3)
	v_add_f32_e32 v118, v118, v119
	v_add_co_u32_e64 v32, s[0:1], s25, v18
	ds_bpermute_b32 v119, v112, v118
	s_waitcnt lgkmcnt(3)
	v_add_f32_e32 v117, v117, v121
	v_addc_co_u32_e64 v33, s[0:1], -1, v19, s[0:1]
	s_waitcnt lgkmcnt(2)
	v_add_f32_e32 v120, v120, v123
	ds_bpermute_b32 v121, v113, v117
	v_add_co_u32_e64 v34, s[0:1], s26, v18
	ds_bpermute_b32 v123, v113, v120
	s_nop 0
	v_addc_co_u32_e64 v35, s[0:1], -1, v19, s[0:1]
	s_waitcnt lgkmcnt(3)
	v_add_f32_e32 v122, v122, v124
	v_add_co_u32_e64 v36, s[0:1], s27, v18
	ds_bpermute_b32 v124, v113, v122
	s_nop 0
	v_addc_co_u32_e64 v37, s[0:1], -1, v19, s[0:1]
	s_waitcnt lgkmcnt(3)
	v_add_f32_e32 v118, v118, v119
	v_add_co_u32_e64 v42, s[0:1], s28, v18
	ds_bpermute_b32 v119, v113, v118
	s_waitcnt lgkmcnt(3)
	v_add_f32_e32 v117, v117, v121
	v_addc_co_u32_e64 v43, s[0:1], -1, v19, s[0:1]
	s_waitcnt lgkmcnt(2)
	v_add_f32_e32 v120, v120, v123
	ds_bpermute_b32 v121, v114, v117
	v_add_co_u32_e64 v44, s[0:1], s29, v18
	ds_bpermute_b32 v123, v114, v120
	s_nop 0
	v_addc_co_u32_e64 v45, s[0:1], -1, v19, s[0:1]
	s_waitcnt lgkmcnt(3)
	v_add_f32_e32 v122, v122, v124
	v_add_co_u32_e64 v46, s[0:1], s11, v18
	ds_bpermute_b32 v124, v114, v122
	s_nop 0
	v_addc_co_u32_e64 v47, s[0:1], -1, v19, s[0:1]
	s_waitcnt lgkmcnt(3)
	v_add_f32_e32 v118, v118, v119
	v_add_co_u32_e64 v48, s[0:1], s18, v18
	ds_bpermute_b32 v119, v114, v118
	s_waitcnt lgkmcnt(3)
	v_add_f32_e32 v117, v117, v121
	v_addc_co_u32_e64 v49, s[0:1], -1, v19, s[0:1]
	s_waitcnt lgkmcnt(2)
	v_add_f32_e32 v120, v120, v123
	ds_bpermute_b32 v121, v115, v117
	v_add_co_u32_e64 v50, s[0:1], s30, v18
	ds_bpermute_b32 v123, v115, v120
	s_nop 0
	v_addc_co_u32_e64 v51, s[0:1], -1, v19, s[0:1]
	s_waitcnt lgkmcnt(3)
	v_add_f32_e32 v122, v122, v124
	v_add_co_u32_e64 v52, s[0:1], s31, v18
	ds_bpermute_b32 v124, v115, v122
	s_nop 0
	v_addc_co_u32_e64 v53, s[0:1], -1, v19, s[0:1]
	s_waitcnt lgkmcnt(3)
	v_add_f32_e32 v118, v118, v119
	v_add_co_u32_e64 v54, s[0:1], -16, v18
	ds_bpermute_b32 v119, v115, v118
	s_waitcnt lgkmcnt(3)
; __device__ __forceinline__ float shfl_x(float v, int m, int lane) { return __builtin_bit_cast(float, __builtin_amdgcn_ds_bpermute((lane ^ m) << 2, __builtin_bit_cast(int, v))); }
; __device__ __forceinline__ float wave_sum(float v, int lane) {
;     ...
;     for (int o = 1; o < 64; o <<= 1) v += shfl_x(v, o, lane);
;     return v;
; __device__ __forceinline__ void final_norm_pass(const bf16_t* x16, float* out, const float* nw, int vcu, int ngw, const int wave_s) {
;     ...
; #pragma unroll
;             for (int j = 0; j < 4; ++j) s += (v[j].x * v[j].x + v[j].y * v[j].y) + (v[j].z * v[j].z + v[j].w * v[j].w);
;             const float rstd = 1.0f / sqrtf(wave_sum(s, lane) * (1.0f / DM) + EPS);
	v_add_f32_e32 v117, v117, v121
	v_addc_co_u32_e64 v55, s[0:1], -1, v19, s[0:1]
	s_waitcnt lgkmcnt(2)
	v_add_f32_e32 v120, v120, v123
	v_fmamk_f32 v117, v117, 0x3a800000, v17
	v_cmp_lt_i32_e64 s[0:1], s33, v16
	v_fmamk_f32 v120, v120, 0x3a800000, v17
	v_mul_f32_e32 v121, 0x4f800000, v117
	v_cmp_gt_f32_e32 vcc, s19, v117
	s_or_b64 s[16:17], s[0:1], s[16:17]
	v_mul_f32_e32 v123, 0x4f800000, v120
	s_waitcnt lgkmcnt(1)
	v_add_f32_e32 v122, v122, v124
	v_cndmask_b32_e32 v117, v117, v121, vcc
	v_cmp_gt_f32_e64 s[0:1], s19, v120
	v_fmamk_f32 v121, v122, 0x3a800000, v17
	v_sqrt_f32_e32 v122, v117
	v_cndmask_b32_e64 v120, v120, v123, s[0:1]
	v_sqrt_f32_e32 v123, v120
	v_mul_f32_e32 v124, 0x4f800000, v121
	s_waitcnt lgkmcnt(0)
	v_add_f32_e32 v118, v118, v119
	v_cmp_gt_f32_e64 s[2:3], s19, v121
	v_fmamk_f32 v118, v118, 0x3a800000, v17
	v_cmp_gt_f32_e64 s[4:5], s19, v118
	v_cndmask_b32_e64 v119, v121, v124, s[2:3]
	v_sqrt_f32_e32 v121, v119
	v_mul_f32_e32 v124, 0x4f800000, v118
	v_cndmask_b32_e64 v118, v118, v124, s[4:5]
	v_add_u32_e32 v124, -1, v122
	v_add_u32_e32 v125, 1, v122
	v_add_u32_e32 v126, -1, v123
	v_fma_f32 v129, -v124, v122, v117
	v_add_u32_e32 v127, 1, v123
	v_sqrt_f32_e32 v128, v118
	v_fma_f32 v130, -v125, v122, v117
	v_fma_f32 v131, -v126, v123, v120
	v_cmp_ge_f32_e64 s[6:7], 0, v129
	v_fma_f32 v132, -v127, v123, v120
	v_cmp_ge_f32_e64 s[8:9], 0, v131
	v_cndmask_b32_e64 v122, v122, v124, s[6:7]
	v_cmp_lt_f32_e64 s[6:7], 0, v130
	v_add_u32_e32 v124, -1, v121
	v_cndmask_b32_e64 v123, v123, v126, s[8:9]
	v_add_u32_e32 v126, 1, v121
	v_cndmask_b32_e64 v122, v122, v125, s[6:7]
	v_cmp_lt_f32_e64 s[6:7], 0, v132
	v_fma_f32 v125, -v124, v121, v119
	v_mul_f32_e32 v129, 0x37800000, v122
	v_cndmask_b32_e64 v123, v123, v127, s[6:7]
	v_fma_f32 v127, -v126, v121, v119
	v_cmp_ge_f32_e64 s[6:7], 0, v125
	v_mul_f32_e32 v130, 0x37800000, v123
	v_cndmask_b32_e32 v122, v122, v129, vcc
	v_cndmask_b32_e64 v121, v121, v124, s[6:7]
	v_cmp_lt_f32_e64 s[6:7], 0, v127
	v_add_u32_e32 v124, -1, v128
	v_cmp_class_f32_e32 vcc, v117, v116
	v_add_u32_e32 v125, 1, v128
	v_cndmask_b32_e64 v123, v123, v130, s[0:1]
	v_cndmask_b32_e64 v121, v121, v126, s[6:7]
	v_fma_f32 v126, -v124, v128, v118
	v_cndmask_b32_e32 v117, v122, v117, vcc
	v_cmp_class_f32_e32 vcc, v120, v116
	v_fma_f32 v127, -v125, v128, v118
	v_mul_f32_e32 v122, 0x37800000, v121
	v_cndmask_b32_e32 v120, v123, v120, vcc
	v_cmp_ge_f32_e32 vcc, 0, v126
	v_cndmask_b32_e64 v121, v121, v122, s[2:3]
	v_cmp_class_f32_e64 s[2:3], v119, v116
	v_cndmask_b32_e32 v123, v128, v124, vcc
	v_cmp_lt_f32_e32 vcc, 0, v127
	v_div_scale_f32 v124, s[0:1], v117, v117, 1.0
	v_div_scale_f32 v127, s[6:7], v120, v120, 1.0
	v_cndmask_b32_e32 v122, v123, v125, vcc
	v_rcp_f32_e32 v125, v124
	v_rcp_f32_e32 v123, v127
	v_cndmask_b32_e64 v129, v121, v119, s[2:3]
	v_mul_f32_e32 v119, 0x37800000, v122
	v_div_scale_f32 v121, s[2:3], v129, v129, 1.0
	v_cndmask_b32_e64 v119, v122, v119, s[4:5]
	v_cmp_class_f32_e32 vcc, v118, v116
	v_rcp_f32_e32 v131, v121
	v_div_scale_f32 v126, s[0:1], 1.0, v117, 1.0
	v_cndmask_b32_e32 v132, v119, v118, vcc
	v_div_scale_f32 v133, s[4:5], v132, v132, 1.0
	v_fma_f32 v118, -v124, v125, 1.0
	v_fma_f32 v119, -v127, v123, 1.0
	v_rcp_f32_e32 v135, v133
	v_div_scale_f32 v128, s[6:7], 1.0, v120, 1.0
	v_fmac_f32_e32 v125, v118, v125
	v_fmac_f32_e32 v123, v119, v123
	v_mul_f32_e32 v136, v126, v125
	v_mul_f32_e32 v118, v128, v123
	v_fma_f32 v119, -v121, v131, 1.0
	v_div_scale_f32 v130, s[2:3], 1.0, v129, 1.0
	v_fma_f32 v122, -v124, v136, v126
	v_fma_f32 v137, -v127, v118, v128
	v_fmac_f32_e32 v131, v119, v131
	v_fmac_f32_e32 v136, v122, v125
	v_fmac_f32_e32 v118, v137, v123
	v_mul_f32_e32 v119, v130, v131
	v_fma_f32 v122, -v133, v135, 1.0
	v_div_scale_f32 v134, s[4:5], 1.0, v132, 1.0
	v_fma_f32 v124, -v124, v136, v126
	v_fma_f32 v126, -v127, v118, v128
	v_fma_f32 v127, -v121, v119, v130
	v_fmac_f32_e32 v135, v122, v135
	s_mov_b64 vcc, s[6:7]
	v_div_fmas_f32 v118, v126, v123, v118
	v_fmac_f32_e32 v119, v127, v131
	v_mul_f32_e32 v126, v134, v135
	v_div_fixup_f32 v118, v118, v120, 1.0
	v_fma_f32 v120, -v121, v119, v130
	v_fma_f32 v121, -v133, v126, v134
	s_mov_b64 vcc, s[2:3]
	v_pk_mul_f32 v[68:69], v[118:119], v[68:69] op_sel_hi:[0,1]
	v_pk_mul_f32 v[70:71], v[118:119], v[70:71] op_sel_hi:[0,1]
	v_pk_mul_f32 v[88:89], v[118:119], v[88:89] op_sel_hi:[0,1]
; __device__ __forceinline__ void final_norm_pass(const bf16_t* x16, float* out, const float* nw, int vcu, int ngw, const int wave_s) {
;     ...
;             const float rstd = 1.0f / sqrtf(wave_sum(s, lane) * (1.0f / DM) + EPS);
;             f32x4* orow = (f32x4*)(out + (size_t)(m0 + i) * DM + 16 * lane);
; #pragma unroll
;             for (int j = 0; j < 4; ++j) orow[j] = v[j] * rstd * wv[j];
	v_pk_mul_f32 v[72:73], v[118:119], v[72:73] op_sel_hi:[0,1]
	v_pk_mul_f32 v[76:77], v[76:77], v[118:119] op_sel_hi:[1,0]
	v_div_fmas_f32 v127, v120, v131, v119
	v_fmac_f32_e32 v126, v121, v135
	v_mov_b32_e32 v91, v154
	v_pk_mul_f32 v[84:85], v[118:119], v[84:85] op_sel_hi:[0,1]
	v_pk_mul_f32 v[86:87], v[118:119], v[86:87] op_sel_hi:[0,1]
	v_pk_mul_f32 v[122:123], v[74:75], v[118:119] op_sel_hi:[1,0]
	v_pk_mul_f32 v[70:71], v[14:15], v[70:71]
	v_pk_mul_f32 v[68:69], v[12:13], v[68:69]
	v_pk_mul_f32 v[74:75], v[10:11], v[72:73]
	v_pk_mul_f32 v[72:73], v[8:9], v[88:89]
	v_pk_mul_f32 v[120:121], v[2:3], v[76:77]
	v_div_fixup_f32 v76, v127, v129, 1.0
	v_fma_f32 v77, -v133, v126, v134
	s_mov_b64 vcc, s[4:5]
	v_pk_mul_f32 v[86:87], v[6:7], v[86:87]
	v_pk_mul_f32 v[84:85], v[4:5], v[84:85]
	v_pk_mul_f32 v[118:119], v[0:1], v[122:123]
	global_store_dwordx4 v[22:23], v[68:71], off
	global_store_dwordx4 v[24:25], v[72:75], off
	global_store_dwordx4 v[26:27], v[84:87], off
	global_store_dwordx4 v[28:29], v[118:121], off
	v_pk_mul_f32 v[22:23], v[76:77], v[78:79] op_sel_hi:[0,1]
	v_pk_mul_f32 v[24:25], v[76:77], v[80:81] op_sel_hi:[0,1]
	v_pk_mul_f32 v[26:27], v[76:77], v[104:105] op_sel_hi:[0,1]
	v_pk_mul_f32 v[28:29], v[76:77], v[82:83] op_sel_hi:[0,1]
	v_pk_mul_f32 v[68:69], v[76:77], v[94:95] op_sel_hi:[0,1]
	v_pk_mul_f32 v[70:71], v[76:77], v[98:99] op_sel_hi:[0,1]
	v_pk_mul_f32 v[72:73], v[90:91], v[76:77] op_sel_hi:[1,0]
	v_pk_mul_f32 v[74:75], v[92:93], v[76:77] op_sel_hi:[1,0]
	v_div_fmas_f32 v76, v77, v135, v126
	s_mov_b64 vcc, s[0:1]
	v_pk_mul_f32 v[24:25], v[14:15], v[24:25]
	v_pk_mul_f32 v[22:23], v[12:13], v[22:23]
	v_pk_mul_f32 v[68:69], v[4:5], v[68:69]
	v_div_fixup_f32 v76, v76, v132, 1.0
	v_div_fmas_f32 v77, v124, v125, v136
	v_mov_b32_e32 v152, v144
	v_mov_b32_e32 v153, v102
	v_mov_b32_e32 v102, v145
	v_pk_mul_f32 v[28:29], v[10:11], v[28:29]
	v_pk_mul_f32 v[26:27], v[8:9], v[26:27]
	v_pk_mul_f32 v[70:71], v[6:7], v[70:71]
	v_pk_mul_f32 v[74:75], v[2:3], v[74:75]
	v_pk_mul_f32 v[72:73], v[0:1], v[72:73]
	global_store_dwordx4 v[30:31], v[22:25], off
	global_store_dwordx4 v[32:33], v[26:29], off
	global_store_dwordx4 v[34:35], v[68:71], off
	global_store_dwordx4 v[36:37], v[72:75], off
	v_pk_mul_f32 v[22:23], v[76:77], v[96:97] op_sel_hi:[0,1]
	v_pk_mul_f32 v[24:25], v[76:77], v[100:101] op_sel_hi:[0,1]
	v_div_fixup_f32 v68, v77, v117, 1.0
	v_pk_mul_f32 v[26:27], v[76:77], v[152:153] op_sel_hi:[0,1]
	v_pk_mul_f32 v[28:29], v[76:77], v[102:103] op_sel_hi:[0,1]
	v_pk_mul_f32 v[30:31], v[76:77], v[148:149] op_sel_hi:[0,1]
	v_pk_mul_f32 v[32:33], v[76:77], v[150:151] op_sel_hi:[0,1]
	v_pk_mul_f32 v[34:35], v[106:107], v[76:77] op_sel_hi:[1,0]
	v_pk_mul_f32 v[36:37], v[108:109], v[76:77] op_sel_hi:[1,0]
	v_pk_mul_f32 v[24:25], v[14:15], v[24:25]
	v_pk_mul_f32 v[22:23], v[12:13], v[22:23]
	v_pk_mul_f32 v[56:57], v[68:69], v[56:57] op_sel_hi:[0,1]
	v_pk_mul_f32 v[58:59], v[68:69], v[58:59] op_sel_hi:[0,1]
	v_pk_mul_f32 v[28:29], v[10:11], v[28:29]
	v_pk_mul_f32 v[26:27], v[8:9], v[26:27]
	v_pk_mul_f32 v[32:33], v[6:7], v[32:33]
	v_pk_mul_f32 v[30:31], v[4:5], v[30:31]
	v_pk_mul_f32 v[36:37], v[2:3], v[36:37]
	v_pk_mul_f32 v[34:35], v[0:1], v[34:35]
	v_pk_mul_f32 v[66:67], v[68:69], v[66:67] op_sel_hi:[0,1]
	v_pk_mul_f32 v[60:61], v[68:69], v[60:61] op_sel_hi:[0,1]
	v_pk_mul_f32 v[62:63], v[68:69], v[62:63] op_sel_hi:[0,1]
	v_pk_mul_f32 v[64:65], v[68:69], v[64:65] op_sel_hi:[0,1]
	v_pk_mul_f32 v[38:39], v[38:39], v[68:69] op_sel_hi:[1,0]
	v_pk_mul_f32 v[40:41], v[40:41], v[68:69] op_sel_hi:[1,0]
	global_store_dwordx4 v[42:43], v[22:25], off
	global_store_dwordx4 v[44:45], v[26:29], off
	global_store_dwordx4 v[46:47], v[30:33], off
	global_store_dwordx4 v[48:49], v[34:37], off
	v_pk_mul_f32 v[24:25], v[14:15], v[58:59]
	v_pk_mul_f32 v[22:23], v[12:13], v[56:57]
	v_pk_mul_f32 v[28:29], v[10:11], v[60:61]
	v_pk_mul_f32 v[26:27], v[8:9], v[66:67]
	v_pk_mul_f32 v[32:33], v[6:7], v[64:65]
	v_pk_mul_f32 v[30:31], v[4:5], v[62:63]
	v_pk_mul_f32 v[36:37], v[2:3], v[40:41]
	v_pk_mul_f32 v[34:35], v[0:1], v[38:39]
	global_store_dwordx4 v[50:51], v[22:25], off
	global_store_dwordx4 v[52:53], v[26:29], off
	global_store_dwordx4 v[54:55], v[30:33], off
	global_store_dwordx4 v[18:19], v[34:37], off
	v_lshl_add_u64 v[18:19], v[18:19], 0, s[12:13]
	s_andn2_b64 exec, exec, s[16:17]
	s_cbranch_execnz .LBB0_1353
